# v44 + static priority: s_setprio 1 once for the trailing wave half (wr=1) at each GEMM phase start, all per-MFMA-block setprio toggles removed
# speedup vs baseline: 1.0079x; 1.0079x over previous
; __device__ __forceinline__ int mk_lane() { int l; asm volatile("v_mbcnt_lo_u32_b32 %0, -1, 0\n\tv_mbcnt_hi_u32_b32 %0, -1, %0" : "=v"(l)); return l; }
; #define PG8_STAGE(bufoff, gbase, voff) do { _Pragma("unroll") for (int _i = 0; _i < 2; ++_i) glds16_s((gbase), (voff)[_i], ldsb + (unsigned)((bufoff) + _i * 8192)); } while (0)
; #define PG8_BAR __builtin_amdgcn_s_barrier()
;     __device__ bool next(int i, Unit& u) const { return S.next(i, u); }
;     __device__ unsigned a_rowoff(int R) const { const int r = upmap ? (128 * (R >> 6) + 8 * (R & 15) + ((R >> 4) & 3)) : R; return (unsigned)r * (unsigned)lda * 2u; }
; template <class Prob, class Epi, bool I8 = false, bool ALIGN_EPI = true, bool SP2 = true>
; __device__ __forceinline__ void gemm_phase(LAS unsigned char* lds, int wave, const Prob& P, const Epi& E) {
;     const int tid_ = wave * 64 + mk_lane();
;     const int tid = tid_, wid = __builtin_amdgcn_readfirstlane(tid >> 6), lane = tid & 63, wr = wid >> 2, wc = wid & 3, fr = lane & 15, fq = lane >> 4;
;     const int K = P.K, nt = K / BK;
;     unsigned voffA[2], voffB[2];
; #pragma unroll
;     for (int i = 0; i < 2; ++i) { int R, C; stage_rc(tid * 16 + i * 8192, R, C); const int Rb = (R & ~31) + perm32(R & 31);
;         voffA[i] = P.a_rowoff(R) + (unsigned)C * 2u; voffB[i] = P.b_rowoff(Rb) + (unsigned)C * 2u; }
;     const size_t kstep = (size_t)(BK * 2);
;     const size_t hstepA = P.a_hstep(), hstepB = P.b_hstep();
;     const unsigned ldsw = (unsigned)wid * 1024u;
;     const unsigned ldsb = (unsigned)(size_t)lds + ldsw;
;     const int aoff = lds_byte(wr * 64 + fr, fq * 8), boff = lds_byte(wc * 32 + fr, fq * 8);
;     ...
;     Unit cur, nxt; int ui = 0;
;     if (!P.next(0, cur)) return;
;     Acc acc;
; #pragma unroll
;     for (int a = 0; a < 2; ++a)
; #pragma unroll
;         for (int b = 0; b < 2; ++b)
; #pragma unroll
;             for (int m = 0; m < 4; ++m)
; #pragma unroll
;                 for (int n = 0; n < 2; ++n) acc[a][b][m][n] = (f32x4){0.f, 0.f, 0.f, 0.f};
;     h16x8 At[4][2], B0[2][2], B1[2][2];
;     const char* cA = P.a_tile(cur); const char* cB = P.b_tile(cur);
;     if constexpr (SP2) {
;         PG8_STAGE(PG8_SB(0, 0), cB, voffB); PG8_STAGE(PG8_SB(0, 1), cB + hstepB, voffB); PG8_STAGE(PG8_SA(0, 0), cA, voffA); PG8_STAGE(PG8_SA(0, 1), cA + hstepA, voffA);
;         if (wr == 1) PG8_BAR;
.LBB0_215:
	s_mov_b64 s[52:53], 0
	s_add_u32 s30, s96, s52
	s_addc_u32 s31, s97, s53
	s_add_u32 s54, s30, 0x1b200000
	s_mov_b64 s[14:15], -1
	s_addc_u32 s55, s31, 0
	v_writelane_b32 v253, s0, 63
	s_and_b64 vcc, exec, s[0:1]
	s_nop 0
	v_writelane_b32 v255, s1, 0
	s_cbranch_vccnz .LBB0_526
	v_readlane_b32 s0, v254, 42
	v_readlane_b32 s4, v254, 43
	s_add_u32 s26, s30, 0x2d200000
	v_mbcnt_lo_u32_b32 v0, -1, 0
	v_mbcnt_hi_u32_b32 v0, -1, v0
	v_readlane_b32 s5, v254, 44
	v_add_u32_e32 v1, s0, v0
	s_addc_u32 s27, s31, 0
	v_readfirstlane_b32 s0, v1
	s_and_b64 vcc, exec, s[4:5]
	s_cbranch_vccz .LBB0_232
	v_ashrrev_i32_e32 v3, 31, v1
	v_lshrrev_b32_e32 v3, 26, v3
	v_lshlrev_b32_e32 v2, 4, v1
	v_add_u32_e32 v3, v1, v3
	v_bfe_i32 v1, v1, 27, 1
	v_lshrrev_b32_e32 v1, 22, v1
	v_add_u32_e32 v1, v2, v1
	v_and_b32_e32 v1, 0xfffffc00, v1
	v_sub_u32_e32 v1, v2, v1
	v_lshrrev_b32_e32 v4, 4, v1
	v_bitop3_b32 v1, v4, v1, 32 bitop3:0x6c
	s_add_u32 s2, s30, 0x5200000
	v_ashrrev_i32_e32 v5, 31, v1
	s_addc_u32 s19, s31, 0
	v_readlane_b32 s4, v254, 51
	v_ashrrev_i32_e32 v3, 6, v3
	v_lshrrev_b32_e32 v5, 26, v5
	v_readlane_b32 s5, v254, 52
	s_add_u32 s1, s54, s4
	v_lshlrev_b32_e32 v4, 3, v3
	v_add_u32_e32 v5, v1, v5
	s_addc_u32 s4, s55, s5
	v_readlane_b32 s5, v254, 48
	v_and_b32_e32 v4, -16, v4
	v_ashrrev_i32_e32 v6, 6, v5
	v_and_b32_e32 v5, 0xc0, v5
	s_add_u32 s44, s1, s5
	v_add_u32_e32 v4, v6, v4
	v_sub_u32_e32 v1, v1, v5
	v_mov_b32_e32 v8, 1
	s_addc_u32 s45, s4, 0
	v_lshlrev_b32_e32 v3, 5, v3
	v_ashrrev_i16_sdwa v1, v8, sext(v1) dst_sel:DWORD dst_unused:UNUSED_PAD src0_sel:DWORD src1_sel:BYTE_0
	v_lshlrev_b32_e32 v5, 1, v4
	v_lshrrev_b32_e32 v7, 2, v4
	v_and_b32_e32 v6, 3, v6
	s_mov_b32 s4, 0xfffe0
	v_and_b32_e32 v3, 32, v3
	v_bfe_i32 v1, v1, 0, 16
	v_and_b32_e32 v5, 24, v5
	v_and_b32_e32 v7, 4, v7
	v_and_or_b32 v6, v4, s4, v6
	v_or3_b32 v5, v6, v7, v5
	v_add_lshl_u32 v1, v3, v1, 1
	v_lshl_add_u32 v128, v4, 10, v1
	v_lshl_add_u32 v129, v5, 12, v1
	v_add_u32_e32 v1, 0x2000, v2
	v_ashrrev_i32_e32 v2, 31, v1
	v_lshrrev_b32_e32 v2, 22, v2
	v_add_u32_e32 v2, v1, v2
	v_ashrrev_i32_e32 v2, 10, v2
	v_mul_i32_i24_e32 v3, 0x400, v2
	v_sub_u32_e32 v1, v1, v3
	v_lshrrev_b32_e32 v3, 4, v1
	v_bitop3_b32 v1, v3, v1, 32 bitop3:0x6c
	v_ashrrev_i32_e32 v4, 31, v1
	v_lshrrev_b32_e32 v4, 26, v4
	v_lshlrev_b32_e32 v3, 3, v2
	v_add_u32_e32 v4, v1, v4
	v_readlane_b32 s1, v254, 46
	v_and_b32_e32 v3, -16, v3
	v_ashrrev_i32_e32 v5, 6, v4
	s_add_u32 s42, s2, s1
	v_add_u32_e32 v3, v5, v3
	v_and_b32_e32 v5, 3, v5
	s_addc_u32 s43, s19, 0
	v_and_or_b32 v5, v3, s4, v5
	s_ashr_i32 s4, s0, 6
	s_lshl_b32 s5, s4, 10
	s_ashr_i32 s1, s0, 8
	v_and_b32_e32 v4, 0xc0, v4
	s_add_i32 s56, s5, 0
	v_sub_u32_e32 v1, v1, v4
	s_add_u32 s14, s42, 0x20000
	v_lshlrev_b32_e32 v2, 5, v2
	v_ashrrev_i16_sdwa v1, v8, sext(v1) dst_sel:DWORD dst_unused:UNUSED_PAD src0_sel:DWORD src1_sel:BYTE_0
	v_lshlrev_b32_e32 v4, 1, v3
	v_lshrrev_b32_e32 v6, 2, v3
	s_addc_u32 s15, s43, 0
	v_and_b32_e32 v2, 32, v2
	v_bfe_i32 v1, v1, 0, 16
	v_and_b32_e32 v4, 24, v4
	v_and_b32_e32 v6, 4, v6
	s_add_u32 s16, s44, 0x80000
	v_or3_b32 v4, v5, v6, v4
	v_add_lshl_u32 v1, v2, v1, 1
	s_addc_u32 s17, s45, 0
	s_add_i32 s57, s56, 0x10000
	s_mov_b32 s5, m0
	s_mov_b32 m0, s57
	s_nop 0
	global_load_lds_dwordx4 v129, s[44:45]
	s_mov_b32 m0, s5
	v_lshl_add_u32 v131, v4, 12, v1
	s_add_i32 s60, s56, 0x12000
	s_mov_b32 s5, m0
	s_mov_b32 m0, s60
	s_nop 0
	global_load_lds_dwordx4 v131, s[44:45]
	s_mov_b32 m0, s5
	s_add_i32 s61, s56, 0x14000
	s_mov_b32 s5, m0
	s_mov_b32 m0, s61
	s_nop 0
	global_load_lds_dwordx4 v129, s[16:17]
	s_mov_b32 m0, s5
	s_add_i32 s62, s56, 0x16000
	s_mov_b32 s5, m0
	s_mov_b32 m0, s62
	s_nop 0
	global_load_lds_dwordx4 v131, s[16:17]
	s_mov_b32 m0, s5
	v_lshl_add_u32 v130, v3, 10, v1
	s_mov_b32 s5, m0
	s_mov_b32 m0, s56
	s_nop 0
	global_load_lds_dwordx4 v128, s[42:43]
	s_mov_b32 m0, s5
	s_add_i32 s63, s56, 0x2000
	s_mov_b32 s5, m0
	s_mov_b32 m0, s63
	s_nop 0
	global_load_lds_dwordx4 v130, s[42:43]
	s_mov_b32 m0, s5
	s_add_i32 s64, s56, 0x4000
	s_mov_b32 s5, m0
	s_mov_b32 m0, s64
	s_nop 0
	global_load_lds_dwordx4 v128, s[14:15]
	s_mov_b32 m0, s5
	s_add_i32 s68, s56, 0x6000
	s_mov_b32 s5, m0
	s_mov_b32 m0, s68
	s_nop 0
	global_load_lds_dwordx4 v130, s[14:15]
	s_mov_b32 m0, s5
	s_cmp_eq_u32 s1, 1
	s_cselect_b64 s[14:15], -1, 0
	s_cmp_lg_u32 s1, 1
	s_cbranch_scc1 .LBB0_219
	s_barrier
	s_setprio 1

; #define PG8_STAGE(bufoff, gbase, voff) do { _Pragma("unroll") for (int _i = 0; _i < 2; ++_i) glds16_s((gbase), (voff)[_i], ldsb + (unsigned)((bufoff) + _i * 8192)); } while (0)
; #define PG8_LDA(dst, b, h) do { _Pragma("unroll") for (int m = 0; m < 4; ++m) _Pragma("unroll") for (int k = 0; k < 2; ++k) dst[m][k] = *(const LAS h16x8*)(lds + PG8_SA(b, h) + aoff + m * 2048 + k * 1024); } while (0)
; #define PG8_LDB(dst, b, h) do { _Pragma("unroll") for (int n = 0; n < 2; ++n) _Pragma("unroll") for (int k = 0; k < 2; ++k) dst[n][k] = *(const LAS h16x8*)(lds + PG8_SB(b, h) + boff + n * 2048 + k * 1024); } while (0)
; #define PG8_MMA(ai, bj, At, Bt) do { __builtin_amdgcn_s_setprio(1); _Pragma("unroll") for (int m = 0; m < 4; ++m) _Pragma("unroll") for (int n = 0; n < 2; ++n) _Pragma("unroll") for (int k = 0; k < 2; ++k) \
;         acc[ai][bj][m][n] = mma_step<I8>(Bt[n][k], At[m][k], acc[ai][bj][m][n]); __builtin_amdgcn_s_setprio(0); } while (0)
; #define PG8_WAIT_V(n) asm volatile("s_waitcnt vmcnt(" #n ")" ::: "memory")
; #define PG8_WAIT_L(n) asm volatile("s_waitcnt lgkmcnt(" #n ")" ::: "memory")
; #define PG8_BAR __builtin_amdgcn_s_barrier()
; #define PG8_SCHED __builtin_amdgcn_sched_barrier(0)
; template <class Prob, class Epi, bool I8 = false, bool ALIGN_EPI = true, bool SP2 = true>
; __device__ __forceinline__ void gemm_phase(LAS unsigned char* lds, int wave, const Prob& P, const Epi& E) {
;     ...
;             PG8_LDB(B0, 0, 0); PG8_LDB(B1, 0, 1); PG8_SCHED; PG8_LDA(At, 0, 0); PG8_STAGE(PG8_SA(1, 1), a1 + hstepA, voffA);
;             PG8_WAIT_V(8); PG8_WAIT_L(0); PG8_BAR; PG8_MMA(0, 0, At, B0); PG8_MMA(0, 1, At, B1); PG8_BAR; PG8_SCHED;
;             PG8_LDA(At, 0, 1); PG8_STAGE(PG8_SB(0, 0), b2, voffB); PG8_STAGE(PG8_SB(0, 1), b2 + hstepB, voffB); PG8_STAGE(PG8_SA(0, 0), a2, voffA);
;             PG8_WAIT_V(8); PG8_WAIT_L(0); PG8_BAR; PG8_MMA(1, 0, At, B0); PG8_MMA(1, 1, At, B1); PG8_BAR; PG8_SCHED;
.Lpeel_225:
	ds_read_b128 v[138:141], v132
	ds_read_b128 v[142:145], v132 offset:1024
	ds_read_b128 v[146:149], v132 offset:2048
	ds_read_b128 v[150:153], v132 offset:3072
	ds_read_b128 v[154:157], v133
	ds_read_b128 v[158:161], v133 offset:1024
	ds_read_b128 v[162:165], v133 offset:2048
	ds_read_b128 v[166:169], v133 offset:3072
	s_add_u32 s44, s42, 0x100
	s_addc_u32 s45, s43, 0
	s_cmp_eq_u32 s29, 4
	s_cselect_b32 s50, s87, s44
	s_cselect_b32 s51, s23, s45
	s_cselect_b32 s48, s1, s4
	s_cselect_b32 s49, s0, s5
	s_add_u32 s46, s50, 0x80
	s_addc_u32 s47, s51, 0
	ds_read_b128 v[170:173], v134
	ds_read_b128 v[174:177], v134 offset:1024
	ds_read_b128 v[178:181], v134 offset:2048
	ds_read_b128 v[182:185], v134 offset:3072
	ds_read_b128 v[186:189], v134 offset:4096
	ds_read_b128 v[190:193], v134 offset:5120
	ds_read_b128 v[194:197], v134 offset:6144
	ds_read_b128 v[198:201], v134 offset:7168
	s_add_u32 s42, s42, 0x20080
	s_addc_u32 s43, s43, 0
	s_mov_b32 s6, m0
	s_mov_b32 m0, s80
	s_nop 0
	global_load_lds_dwordx4 v128, s[42:43]
	s_mov_b32 m0, s6
	s_nop 0
	s_mov_b32 s6, m0
	s_mov_b32 m0, s81
	s_nop 0
	global_load_lds_dwordx4 v130, s[42:43]
	s_mov_b32 m0, s6
	s_waitcnt vmcnt(8)
	s_waitcnt lgkmcnt(0)
	s_barrier
	s_waitcnt lgkmcnt(7)
	v_mfma_f32_16x16x32_f16 v[124:127], v[138:141], v[170:173], 0
	v_mfma_f32_16x16x32_f16 v[120:123], v[146:149], v[170:173], 0
	s_waitcnt lgkmcnt(5)
	v_mfma_f32_16x16x32_f16 v[116:119], v[138:141], v[178:181], 0
	v_mfma_f32_16x16x32_f16 v[112:115], v[146:149], v[178:181], 0
	s_waitcnt lgkmcnt(3)
	v_mfma_f32_16x16x32_f16 v[100:103], v[138:141], v[186:189], 0
	v_mfma_f32_16x16x32_f16 v[96:99], v[146:149], v[186:189], 0
	s_waitcnt lgkmcnt(1)
	v_mfma_f32_16x16x32_f16 v[84:87], v[138:141], v[194:197], 0
	v_mfma_f32_16x16x32_f16 v[80:83], v[146:149], v[194:197], 0
	v_mfma_f32_16x16x32_f16 v[124:127], v[142:145], v[174:177], v[124:127]
	v_mfma_f32_16x16x32_f16 v[120:123], v[150:153], v[174:177], v[120:123]
	v_mfma_f32_16x16x32_f16 v[116:119], v[142:145], v[182:185], v[116:119]
	v_mfma_f32_16x16x32_f16 v[112:115], v[150:153], v[182:185], v[112:115]
	v_mfma_f32_16x16x32_f16 v[100:103], v[142:145], v[190:193], v[100:103]
	v_mfma_f32_16x16x32_f16 v[96:99], v[150:153], v[190:193], v[96:99]
	s_waitcnt lgkmcnt(0)
	v_mfma_f32_16x16x32_f16 v[84:87], v[142:145], v[198:201], v[84:87]
	v_mfma_f32_16x16x32_f16 v[80:83], v[150:153], v[198:201], v[80:83]
	v_mfma_f32_16x16x32_f16 v[108:111], v[154:157], v[170:173], 0
	v_mfma_f32_16x16x32_f16 v[104:107], v[162:165], v[170:173], 0
	v_mfma_f32_16x16x32_f16 v[92:95], v[154:157], v[178:181], 0
	v_mfma_f32_16x16x32_f16 v[88:91], v[162:165], v[178:181], 0
	v_mfma_f32_16x16x32_f16 v[76:79], v[154:157], v[186:189], 0
	v_mfma_f32_16x16x32_f16 v[72:75], v[162:165], v[186:189], 0
	v_mfma_f32_16x16x32_f16 v[68:71], v[154:157], v[194:197], 0
	v_mfma_f32_16x16x32_f16 v[64:67], v[162:165], v[194:197], 0
	v_mfma_f32_16x16x32_f16 v[108:111], v[158:161], v[174:177], v[108:111]
	v_mfma_f32_16x16x32_f16 v[104:107], v[166:169], v[174:177], v[104:107]
	v_mfma_f32_16x16x32_f16 v[92:95], v[158:161], v[182:185], v[92:95]
	v_mfma_f32_16x16x32_f16 v[88:91], v[166:169], v[182:185], v[88:91]
	v_mfma_f32_16x16x32_f16 v[76:79], v[158:161], v[190:193], v[76:79]
	v_mfma_f32_16x16x32_f16 v[72:75], v[166:169], v[190:193], v[72:75]
	v_mfma_f32_16x16x32_f16 v[68:71], v[158:161], v[198:201], v[68:71]
	v_mfma_f32_16x16x32_f16 v[64:67], v[166:169], v[198:201], v[64:67]
	s_barrier
	ds_read_b128 v[170:173], v134 offset:16384
	ds_read_b128 v[174:177], v134 offset:17408
	ds_read_b128 v[178:181], v134 offset:18432
	ds_read_b128 v[182:185], v134 offset:19456
	ds_read_b128 v[186:189], v134 offset:20480
	ds_read_b128 v[190:193], v134 offset:21504
	ds_read_b128 v[194:197], v134 offset:22528
	ds_read_b128 v[198:201], v134 offset:23552
	s_mov_b32 s6, m0
	s_mov_b32 m0, s57
	s_nop 0
	global_load_lds_dwordx4 v129, s[48:49]
	s_mov_b32 m0, s6
	s_add_u32 s42, s48, 0x80000
	s_mov_b32 s6, m0
	s_mov_b32 m0, s60
	s_nop 0
	global_load_lds_dwordx4 v131, s[48:49]
	s_mov_b32 m0, s6
	s_addc_u32 s43, s49, 0
	s_mov_b32 s6, m0
	s_mov_b32 m0, s61
	s_nop 0
	global_load_lds_dwordx4 v129, s[42:43]
	s_mov_b32 m0, s6
	s_nop 0
	s_mov_b32 s6, m0
	s_mov_b32 m0, s62
	s_nop 0
	global_load_lds_dwordx4 v131, s[42:43]
	s_mov_b32 m0, s6
	s_nop 0
	s_mov_b32 s6, m0
	s_mov_b32 m0, s56
	s_nop 0
	global_load_lds_dwordx4 v128, s[50:51]
	s_mov_b32 m0, s6
	s_nop 0
	s_mov_b32 s6, m0
	s_mov_b32 m0, s63
	s_nop 0
	global_load_lds_dwordx4 v130, s[50:51]
	s_mov_b32 m0, s6
	s_waitcnt vmcnt(8)
	s_waitcnt lgkmcnt(0)
	s_barrier
; #define PG8_STAGE(bufoff, gbase, voff) do { _Pragma("unroll") for (int _i = 0; _i < 2; ++_i) glds16_s((gbase), (voff)[_i], ldsb + (unsigned)((bufoff) + _i * 8192)); } while (0)
; #define PG8_LDA(dst, b, h) do { _Pragma("unroll") for (int m = 0; m < 4; ++m) _Pragma("unroll") for (int k = 0; k < 2; ++k) dst[m][k] = *(const LAS h16x8*)(lds + PG8_SA(b, h) + aoff + m * 2048 + k * 1024); } while (0)
; #define PG8_LDB(dst, b, h) do { _Pragma("unroll") for (int n = 0; n < 2; ++n) _Pragma("unroll") for (int k = 0; k < 2; ++k) dst[n][k] = *(const LAS h16x8*)(lds + PG8_SB(b, h) + boff + n * 2048 + k * 1024); } while (0)
; #define PG8_MMA(ai, bj, At, Bt) do { __builtin_amdgcn_s_setprio(1); _Pragma("unroll") for (int m = 0; m < 4; ++m) _Pragma("unroll") for (int n = 0; n < 2; ++n) _Pragma("unroll") for (int k = 0; k < 2; ++k) \
;         acc[ai][bj][m][n] = mma_step<I8>(Bt[n][k], At[m][k], acc[ai][bj][m][n]); __builtin_amdgcn_s_setprio(0); } while (0)
; #define PG8_WAIT_V(n) asm volatile("s_waitcnt vmcnt(" #n ")" ::: "memory")
; #define PG8_WAIT_L(n) asm volatile("s_waitcnt lgkmcnt(" #n ")" ::: "memory")
; #define PG8_BAR __builtin_amdgcn_s_barrier()
; #define PG8_SCHED __builtin_amdgcn_sched_barrier(0)
; template <class Prob, class Epi, bool I8 = false, bool ALIGN_EPI = true, bool SP2 = true>
; __device__ __forceinline__ void gemm_phase(LAS unsigned char* lds, int wave, const Prob& P, const Epi& E) {
;     ...
;             PG8_WAIT_V(8); PG8_WAIT_L(0); PG8_BAR; PG8_MMA(1, 0, At, B0); PG8_MMA(1, 1, At, B1); PG8_BAR; PG8_SCHED;
;             PG8_LDB(B0, 1, 0); PG8_LDB(B1, 1, 1); PG8_SCHED; PG8_LDA(At, 1, 0); PG8_STAGE(PG8_SA(0, 1), a2 + hstepA, voffA);
;             PG8_WAIT_V(8); PG8_WAIT_L(0); PG8_BAR; PG8_MMA(0, 0, At, B0); PG8_MMA(0, 1, At, B1); PG8_BAR; PG8_SCHED;
	s_waitcnt lgkmcnt(7)
	v_mfma_f32_16x16x32_f16 v[60:63], v[138:141], v[170:173], 0
	v_mfma_f32_16x16x32_f16 v[56:59], v[146:149], v[170:173], 0
	s_waitcnt lgkmcnt(5)
	v_mfma_f32_16x16x32_f16 v[52:55], v[138:141], v[178:181], 0
	v_mfma_f32_16x16x32_f16 v[48:51], v[146:149], v[178:181], 0
	s_waitcnt lgkmcnt(3)
	v_mfma_f32_16x16x32_f16 v[36:39], v[138:141], v[186:189], 0
	v_mfma_f32_16x16x32_f16 v[32:35], v[146:149], v[186:189], 0
	s_waitcnt lgkmcnt(1)
	v_mfma_f32_16x16x32_f16 v[20:23], v[138:141], v[194:197], 0
	v_mfma_f32_16x16x32_f16 v[16:19], v[146:149], v[194:197], 0
	v_mfma_f32_16x16x32_f16 v[60:63], v[142:145], v[174:177], v[60:63]
	v_mfma_f32_16x16x32_f16 v[56:59], v[150:153], v[174:177], v[56:59]
	v_mfma_f32_16x16x32_f16 v[52:55], v[142:145], v[182:185], v[52:55]
	v_mfma_f32_16x16x32_f16 v[48:51], v[150:153], v[182:185], v[48:51]
	v_mfma_f32_16x16x32_f16 v[36:39], v[142:145], v[190:193], v[36:39]
	v_mfma_f32_16x16x32_f16 v[32:35], v[150:153], v[190:193], v[32:35]
	s_waitcnt lgkmcnt(0)
	v_mfma_f32_16x16x32_f16 v[20:23], v[142:145], v[198:201], v[20:23]
	v_mfma_f32_16x16x32_f16 v[16:19], v[150:153], v[198:201], v[16:19]
	v_mfma_f32_16x16x32_f16 v[44:47], v[154:157], v[170:173], 0
	v_mfma_f32_16x16x32_f16 v[40:43], v[162:165], v[170:173], 0
	v_mfma_f32_16x16x32_f16 v[28:31], v[154:157], v[178:181], 0
	v_mfma_f32_16x16x32_f16 v[24:27], v[162:165], v[178:181], 0
	v_mfma_f32_16x16x32_f16 v[12:15], v[154:157], v[186:189], 0
	v_mfma_f32_16x16x32_f16 v[8:11], v[162:165], v[186:189], 0
	v_mfma_f32_16x16x32_f16 v[4:7], v[154:157], v[194:197], 0
	v_mfma_f32_16x16x32_f16 v[0:3], v[162:165], v[194:197], 0
	v_mfma_f32_16x16x32_f16 v[44:47], v[158:161], v[174:177], v[44:47]
	v_mfma_f32_16x16x32_f16 v[40:43], v[166:169], v[174:177], v[40:43]
	v_mfma_f32_16x16x32_f16 v[28:31], v[158:161], v[182:185], v[28:31]
	v_mfma_f32_16x16x32_f16 v[24:27], v[166:169], v[182:185], v[24:27]
	v_mfma_f32_16x16x32_f16 v[12:15], v[158:161], v[190:193], v[12:15]
	v_mfma_f32_16x16x32_f16 v[8:11], v[166:169], v[190:193], v[8:11]
	v_mfma_f32_16x16x32_f16 v[4:7], v[158:161], v[198:201], v[4:7]
	v_mfma_f32_16x16x32_f16 v[0:3], v[166:169], v[198:201], v[0:3]
	s_barrier
	ds_read_b128 v[138:141], v135
	ds_read_b128 v[142:145], v135 offset:1024
	ds_read_b128 v[146:149], v135 offset:2048
	ds_read_b128 v[150:153], v135 offset:3072
	ds_read_b128 v[154:157], v136
	ds_read_b128 v[158:161], v136 offset:1024
	ds_read_b128 v[162:165], v136 offset:2048
	ds_read_b128 v[166:169], v136 offset:3072
	ds_read_b128 v[170:173], v134 offset:32768
	ds_read_b128 v[174:177], v134 offset:33792
	ds_read_b128 v[178:181], v134 offset:34816
	ds_read_b128 v[182:185], v134 offset:35840
	ds_read_b128 v[186:189], v134 offset:36864
	ds_read_b128 v[190:193], v134 offset:37888
	ds_read_b128 v[194:197], v134 offset:38912
	ds_read_b128 v[198:201], v134 offset:39936
	s_add_u32 s42, s50, 0x20000
	s_addc_u32 s43, s51, 0
	s_mov_b32 s6, m0
	s_mov_b32 m0, s64
	s_nop 0
	global_load_lds_dwordx4 v128, s[42:43]
	s_mov_b32 m0, s6
	s_nop 0
	s_mov_b32 s6, m0
	s_mov_b32 m0, s68
	s_nop 0
	global_load_lds_dwordx4 v130, s[42:43]
	s_mov_b32 m0, s6
	s_waitcnt vmcnt(8)
	s_waitcnt lgkmcnt(0)
	s_barrier
	s_waitcnt lgkmcnt(7)
	v_mfma_f32_16x16x32_f16 v[124:127], v[138:141], v[170:173], v[124:127]
	v_mfma_f32_16x16x32_f16 v[120:123], v[146:149], v[170:173], v[120:123]
	s_waitcnt lgkmcnt(5)
	v_mfma_f32_16x16x32_f16 v[116:119], v[138:141], v[178:181], v[116:119]
	v_mfma_f32_16x16x32_f16 v[112:115], v[146:149], v[178:181], v[112:115]
	s_waitcnt lgkmcnt(3)
	v_mfma_f32_16x16x32_f16 v[100:103], v[138:141], v[186:189], v[100:103]
	v_mfma_f32_16x16x32_f16 v[96:99], v[146:149], v[186:189], v[96:99]
	s_waitcnt lgkmcnt(1)
	v_mfma_f32_16x16x32_f16 v[84:87], v[138:141], v[194:197], v[84:87]
	v_mfma_f32_16x16x32_f16 v[80:83], v[146:149], v[194:197], v[80:83]
	v_mfma_f32_16x16x32_f16 v[124:127], v[142:145], v[174:177], v[124:127]
	v_mfma_f32_16x16x32_f16 v[120:123], v[150:153], v[174:177], v[120:123]
	v_mfma_f32_16x16x32_f16 v[116:119], v[142:145], v[182:185], v[116:119]
	v_mfma_f32_16x16x32_f16 v[112:115], v[150:153], v[182:185], v[112:115]
	v_mfma_f32_16x16x32_f16 v[100:103], v[142:145], v[190:193], v[100:103]
	v_mfma_f32_16x16x32_f16 v[96:99], v[150:153], v[190:193], v[96:99]
	s_waitcnt lgkmcnt(0)
	v_mfma_f32_16x16x32_f16 v[84:87], v[142:145], v[198:201], v[84:87]
	v_mfma_f32_16x16x32_f16 v[80:83], v[150:153], v[198:201], v[80:83]
	v_mfma_f32_16x16x32_f16 v[108:111], v[154:157], v[170:173], v[108:111]
	v_mfma_f32_16x16x32_f16 v[104:107], v[162:165], v[170:173], v[104:107]
	v_mfma_f32_16x16x32_f16 v[92:95], v[154:157], v[178:181], v[92:95]
	v_mfma_f32_16x16x32_f16 v[88:91], v[162:165], v[178:181], v[88:91]
	v_mfma_f32_16x16x32_f16 v[76:79], v[154:157], v[186:189], v[76:79]
	v_mfma_f32_16x16x32_f16 v[72:75], v[162:165], v[186:189], v[72:75]
	v_mfma_f32_16x16x32_f16 v[68:71], v[154:157], v[194:197], v[68:71]
	v_mfma_f32_16x16x32_f16 v[64:67], v[162:165], v[194:197], v[64:67]
	v_mfma_f32_16x16x32_f16 v[108:111], v[158:161], v[174:177], v[108:111]
	v_mfma_f32_16x16x32_f16 v[104:107], v[166:169], v[174:177], v[104:107]
	v_mfma_f32_16x16x32_f16 v[92:95], v[158:161], v[182:185], v[92:95]
	v_mfma_f32_16x16x32_f16 v[88:91], v[166:169], v[182:185], v[88:91]
	v_mfma_f32_16x16x32_f16 v[76:79], v[158:161], v[190:193], v[76:79]
	v_mfma_f32_16x16x32_f16 v[72:75], v[166:169], v[190:193], v[72:75]
	v_mfma_f32_16x16x32_f16 v[68:71], v[158:161], v[198:201], v[68:71]
	v_mfma_f32_16x16x32_f16 v[64:67], v[166:169], v[198:201], v[64:67]
	s_barrier
; #define PG8_STAGE(bufoff, gbase, voff) do { _Pragma("unroll") for (int _i = 0; _i < 2; ++_i) glds16_s((gbase), (voff)[_i], ldsb + (unsigned)((bufoff) + _i * 8192)); } while (0)
; #define PG8_LDA(dst, b, h) do { _Pragma("unroll") for (int m = 0; m < 4; ++m) _Pragma("unroll") for (int k = 0; k < 2; ++k) dst[m][k] = *(const LAS h16x8*)(lds + PG8_SA(b, h) + aoff + m * 2048 + k * 1024); } while (0)
; #define PG8_LDB(dst, b, h) do { _Pragma("unroll") for (int n = 0; n < 2; ++n) _Pragma("unroll") for (int k = 0; k < 2; ++k) dst[n][k] = *(const LAS h16x8*)(lds + PG8_SB(b, h) + boff + n * 2048 + k * 1024); } while (0)
; #define PG8_MMA(ai, bj, At, Bt) do { __builtin_amdgcn_s_setprio(1); _Pragma("unroll") for (int m = 0; m < 4; ++m) _Pragma("unroll") for (int n = 0; n < 2; ++n) _Pragma("unroll") for (int k = 0; k < 2; ++k) \
;         acc[ai][bj][m][n] = mma_step<I8>(Bt[n][k], At[m][k], acc[ai][bj][m][n]); __builtin_amdgcn_s_setprio(0); } while (0)
; #define PG8_WAIT_V(n) asm volatile("s_waitcnt vmcnt(" #n ")" ::: "memory")
; #define PG8_WAIT_L(n) asm volatile("s_waitcnt lgkmcnt(" #n ")" ::: "memory")
; #define PG8_BAR __builtin_amdgcn_s_barrier()
; #define PG8_SCHED __builtin_amdgcn_sched_barrier(0)
; template <class Prob, class Epi, bool I8 = false, bool ALIGN_EPI = true, bool SP2 = true>
; __device__ __forceinline__ void gemm_phase(LAS unsigned char* lds, int wave, const Prob& P, const Epi& E) {
;     ...
;             PG8_LDB(B0, 0, 0); PG8_LDB(B1, 0, 1); PG8_SCHED; PG8_LDA(At, 0, 0); PG8_STAGE(PG8_SA(1, 1), a1 + hstepA, voffA);
;             PG8_WAIT_V(8); PG8_WAIT_L(0); PG8_BAR; PG8_MMA(0, 0, At, B0); PG8_MMA(0, 1, At, B1); PG8_BAR; PG8_SCHED;
;             PG8_LDA(At, 0, 1); PG8_STAGE(PG8_SB(0, 0), b2, voffB); PG8_STAGE(PG8_SB(0, 1), b2 + hstepB, voffB); PG8_STAGE(PG8_SA(0, 0), a2, voffA);
;     ...
;             PG8_LDB(B0, 1, 0); PG8_LDB(B1, 1, 1); PG8_SCHED; PG8_LDA(At, 1, 0); PG8_STAGE(PG8_SA(0, 1), a2 + hstepA, voffA);
;             PG8_WAIT_V(8); PG8_WAIT_L(0); PG8_BAR; PG8_MMA(0, 0, At, B0); PG8_MMA(0, 1, At, B1); PG8_BAR; PG8_SCHED;
;             PG8_LDA(At, 1, 1); PG8_STAGE(PG8_SB(1, 0), b3, voffB); PG8_STAGE(PG8_SB(1, 1), b3 + hstepB, voffB); PG8_STAGE(PG8_SA(1, 0), a3, voffA);
;             PG8_WAIT_V(8); PG8_WAIT_L(0); PG8_BAR; PG8_MMA(1, 0, At, B0); PG8_MMA(1, 1, At, B1); PG8_BAR; PG8_SCHED;
	ds_read_b128 v[170:173], v134 offset:49152
	ds_read_b128 v[174:177], v134 offset:50176
	ds_read_b128 v[178:181], v134 offset:51200
	ds_read_b128 v[182:185], v134 offset:52224
	ds_read_b128 v[186:189], v134 offset:53248
	ds_read_b128 v[190:193], v134 offset:54272
	ds_read_b128 v[194:197], v134 offset:55296
	ds_read_b128 v[198:201], v134 offset:56320
	s_add_u32 s42, s48, 0x80
	s_addc_u32 s43, s49, 0
	s_mov_b32 s6, m0
	s_mov_b32 m0, s73
	s_nop 0
	global_load_lds_dwordx4 v129, s[42:43]
	s_mov_b32 m0, s6
	s_nop 0
	s_mov_b32 s6, m0
	s_mov_b32 m0, s74
	s_nop 0
	global_load_lds_dwordx4 v131, s[42:43]
	s_mov_b32 m0, s6
	s_add_u32 s42, s48, 0x80080
	s_addc_u32 s43, s49, 0
	s_mov_b32 s6, m0
	s_mov_b32 m0, s77
	s_nop 0
	global_load_lds_dwordx4 v129, s[42:43]
	s_mov_b32 m0, s6
	s_nop 0
	s_mov_b32 s6, m0
	s_mov_b32 m0, s79
	s_nop 0
	global_load_lds_dwordx4 v131, s[42:43]
	s_mov_b32 m0, s6
	s_nop 0
	s_mov_b32 s6, m0
	s_mov_b32 m0, s75
	s_nop 0
	global_load_lds_dwordx4 v128, s[46:47]
	s_mov_b32 m0, s6
	s_nop 0
	s_mov_b32 s6, m0
	s_mov_b32 m0, s76
	s_nop 0
	global_load_lds_dwordx4 v130, s[46:47]
	s_mov_b32 m0, s6
	s_waitcnt vmcnt(8)
	s_waitcnt lgkmcnt(0)
	s_barrier
	s_waitcnt lgkmcnt(7)
	v_mfma_f32_16x16x32_f16 v[60:63], v[138:141], v[170:173], v[60:63]
	v_mfma_f32_16x16x32_f16 v[56:59], v[146:149], v[170:173], v[56:59]
	s_waitcnt lgkmcnt(5)
	v_mfma_f32_16x16x32_f16 v[52:55], v[138:141], v[178:181], v[52:55]
	v_mfma_f32_16x16x32_f16 v[48:51], v[146:149], v[178:181], v[48:51]
	s_waitcnt lgkmcnt(3)
	v_mfma_f32_16x16x32_f16 v[36:39], v[138:141], v[186:189], v[36:39]
	v_mfma_f32_16x16x32_f16 v[32:35], v[146:149], v[186:189], v[32:35]
	s_waitcnt lgkmcnt(1)
	v_mfma_f32_16x16x32_f16 v[20:23], v[138:141], v[194:197], v[20:23]
	v_mfma_f32_16x16x32_f16 v[16:19], v[146:149], v[194:197], v[16:19]
	v_mfma_f32_16x16x32_f16 v[60:63], v[142:145], v[174:177], v[60:63]
	v_mfma_f32_16x16x32_f16 v[56:59], v[150:153], v[174:177], v[56:59]
	v_mfma_f32_16x16x32_f16 v[52:55], v[142:145], v[182:185], v[52:55]
	v_mfma_f32_16x16x32_f16 v[48:51], v[150:153], v[182:185], v[48:51]
	v_mfma_f32_16x16x32_f16 v[36:39], v[142:145], v[190:193], v[36:39]
	v_mfma_f32_16x16x32_f16 v[32:35], v[150:153], v[190:193], v[32:35]
	s_waitcnt lgkmcnt(0)
	v_mfma_f32_16x16x32_f16 v[20:23], v[142:145], v[198:201], v[20:23]
	v_mfma_f32_16x16x32_f16 v[16:19], v[150:153], v[198:201], v[16:19]
	v_mfma_f32_16x16x32_f16 v[44:47], v[154:157], v[170:173], v[44:47]
	v_mfma_f32_16x16x32_f16 v[40:43], v[162:165], v[170:173], v[40:43]
	v_mfma_f32_16x16x32_f16 v[28:31], v[154:157], v[178:181], v[28:31]
	v_mfma_f32_16x16x32_f16 v[24:27], v[162:165], v[178:181], v[24:27]
	v_mfma_f32_16x16x32_f16 v[12:15], v[154:157], v[186:189], v[12:15]
	v_mfma_f32_16x16x32_f16 v[8:11], v[162:165], v[186:189], v[8:11]
	v_mfma_f32_16x16x32_f16 v[4:7], v[154:157], v[194:197], v[4:7]
	v_mfma_f32_16x16x32_f16 v[0:3], v[162:165], v[194:197], v[0:3]
	v_mfma_f32_16x16x32_f16 v[44:47], v[158:161], v[174:177], v[44:47]
	v_mfma_f32_16x16x32_f16 v[40:43], v[166:169], v[174:177], v[40:43]
	v_mfma_f32_16x16x32_f16 v[28:31], v[158:161], v[182:185], v[28:31]
	v_mfma_f32_16x16x32_f16 v[24:27], v[166:169], v[182:185], v[24:27]
	v_mfma_f32_16x16x32_f16 v[12:15], v[158:161], v[190:193], v[12:15]
	v_mfma_f32_16x16x32_f16 v[8:11], v[166:169], v[190:193], v[8:11]
	v_mfma_f32_16x16x32_f16 v[4:7], v[158:161], v[198:201], v[4:7]
	v_mfma_f32_16x16x32_f16 v[0:3], v[166:169], v[198:201], v[0:3]
	s_barrier
	s_add_i32 s29, s29, 2
	s_add_u32 s4, s4, 0x100
	s_addc_u32 s5, s5, 0
	s_cmp_gt_u32 s29, 5
	s_mov_b64 s[42:43], s[44:45]
.LBB0_225:
	ds_read_b128 v[138:141], v132
	ds_read_b128 v[142:145], v132 offset:1024
	ds_read_b128 v[146:149], v132 offset:2048
	ds_read_b128 v[150:153], v132 offset:3072
	ds_read_b128 v[154:157], v133
	ds_read_b128 v[158:161], v133 offset:1024
	ds_read_b128 v[162:165], v133 offset:2048
	ds_read_b128 v[166:169], v133 offset:3072
	s_add_u32 s44, s42, 0x100
	s_addc_u32 s45, s43, 0
	s_cmp_eq_u32 s29, 4
	s_cselect_b32 s50, s87, s44
	s_cselect_b32 s51, s23, s45
	s_cselect_b32 s48, s1, s4
	s_cselect_b32 s49, s0, s5
	s_add_u32 s46, s50, 0x80
	s_addc_u32 s47, s51, 0
	ds_read_b128 v[170:173], v134
	ds_read_b128 v[174:177], v134 offset:1024
	ds_read_b128 v[178:181], v134 offset:2048
	ds_read_b128 v[182:185], v134 offset:3072
	ds_read_b128 v[186:189], v134 offset:4096
	ds_read_b128 v[190:193], v134 offset:5120
	ds_read_b128 v[194:197], v134 offset:6144
	ds_read_b128 v[198:201], v134 offset:7168
	s_add_u32 s42, s42, 0x20080
	s_addc_u32 s43, s43, 0
	s_mov_b32 s6, m0
	s_mov_b32 m0, s80
	s_nop 0
	global_load_lds_dwordx4 v128, s[42:43]
	s_mov_b32 m0, s6
	s_nop 0
	s_mov_b32 s6, m0
	s_mov_b32 m0, s81
	s_nop 0
	global_load_lds_dwordx4 v130, s[42:43]
	s_mov_b32 m0, s6
	s_waitcnt vmcnt(8)
	s_waitcnt lgkmcnt(0)
	s_barrier
; #define PG8_STAGE(bufoff, gbase, voff) do { _Pragma("unroll") for (int _i = 0; _i < 2; ++_i) glds16_s((gbase), (voff)[_i], ldsb + (unsigned)((bufoff) + _i * 8192)); } while (0)
; #define PG8_LDA(dst, b, h) do { _Pragma("unroll") for (int m = 0; m < 4; ++m) _Pragma("unroll") for (int k = 0; k < 2; ++k) dst[m][k] = *(const LAS h16x8*)(lds + PG8_SA(b, h) + aoff + m * 2048 + k * 1024); } while (0)
; #define PG8_LDB(dst, b, h) do { _Pragma("unroll") for (int n = 0; n < 2; ++n) _Pragma("unroll") for (int k = 0; k < 2; ++k) dst[n][k] = *(const LAS h16x8*)(lds + PG8_SB(b, h) + boff + n * 2048 + k * 1024); } while (0)
; #define PG8_MMA(ai, bj, At, Bt) do { __builtin_amdgcn_s_setprio(1); _Pragma("unroll") for (int m = 0; m < 4; ++m) _Pragma("unroll") for (int n = 0; n < 2; ++n) _Pragma("unroll") for (int k = 0; k < 2; ++k) \
;         acc[ai][bj][m][n] = mma_step<I8>(Bt[n][k], At[m][k], acc[ai][bj][m][n]); __builtin_amdgcn_s_setprio(0); } while (0)
; #define PG8_WAIT_V(n) asm volatile("s_waitcnt vmcnt(" #n ")" ::: "memory")
; #define PG8_WAIT_L(n) asm volatile("s_waitcnt lgkmcnt(" #n ")" ::: "memory")
; #define PG8_BAR __builtin_amdgcn_s_barrier()
; #define PG8_SCHED __builtin_amdgcn_sched_barrier(0)
; template <class Prob, class Epi, bool I8 = false, bool ALIGN_EPI = true, bool SP2 = true>
; __device__ __forceinline__ void gemm_phase(LAS unsigned char* lds, int wave, const Prob& P, const Epi& E) {
;     ...
;             PG8_WAIT_V(8); PG8_WAIT_L(0); PG8_BAR; PG8_MMA(0, 0, At, B0); PG8_MMA(0, 1, At, B1); PG8_BAR; PG8_SCHED;
;             PG8_LDA(At, 0, 1); PG8_STAGE(PG8_SB(0, 0), b2, voffB); PG8_STAGE(PG8_SB(0, 1), b2 + hstepB, voffB); PG8_STAGE(PG8_SA(0, 0), a2, voffA);
;             PG8_WAIT_V(8); PG8_WAIT_L(0); PG8_BAR; PG8_MMA(1, 0, At, B0); PG8_MMA(1, 1, At, B1); PG8_BAR; PG8_SCHED;
;             PG8_LDB(B0, 1, 0); PG8_LDB(B1, 1, 1); PG8_SCHED; PG8_LDA(At, 1, 0); PG8_STAGE(PG8_SA(0, 1), a2 + hstepA, voffA);
;             PG8_WAIT_V(8); PG8_WAIT_L(0); PG8_BAR; PG8_MMA(0, 0, At, B0); PG8_MMA(0, 1, At, B1); PG8_BAR; PG8_SCHED;
	s_waitcnt lgkmcnt(7)
	v_mfma_f32_16x16x32_f16 v[124:127], v[138:141], v[170:173], v[124:127]
	v_mfma_f32_16x16x32_f16 v[120:123], v[146:149], v[170:173], v[120:123]
	s_waitcnt lgkmcnt(5)
	v_mfma_f32_16x16x32_f16 v[116:119], v[138:141], v[178:181], v[116:119]
	v_mfma_f32_16x16x32_f16 v[112:115], v[146:149], v[178:181], v[112:115]
	s_waitcnt lgkmcnt(3)
	v_mfma_f32_16x16x32_f16 v[100:103], v[138:141], v[186:189], v[100:103]
	v_mfma_f32_16x16x32_f16 v[96:99], v[146:149], v[186:189], v[96:99]
	s_waitcnt lgkmcnt(1)
	v_mfma_f32_16x16x32_f16 v[84:87], v[138:141], v[194:197], v[84:87]
	v_mfma_f32_16x16x32_f16 v[80:83], v[146:149], v[194:197], v[80:83]
	v_mfma_f32_16x16x32_f16 v[124:127], v[142:145], v[174:177], v[124:127]
	v_mfma_f32_16x16x32_f16 v[120:123], v[150:153], v[174:177], v[120:123]
	v_mfma_f32_16x16x32_f16 v[116:119], v[142:145], v[182:185], v[116:119]
	v_mfma_f32_16x16x32_f16 v[112:115], v[150:153], v[182:185], v[112:115]
	v_mfma_f32_16x16x32_f16 v[100:103], v[142:145], v[190:193], v[100:103]
	v_mfma_f32_16x16x32_f16 v[96:99], v[150:153], v[190:193], v[96:99]
	s_waitcnt lgkmcnt(0)
	v_mfma_f32_16x16x32_f16 v[84:87], v[142:145], v[198:201], v[84:87]
	v_mfma_f32_16x16x32_f16 v[80:83], v[150:153], v[198:201], v[80:83]
	v_mfma_f32_16x16x32_f16 v[108:111], v[154:157], v[170:173], v[108:111]
	v_mfma_f32_16x16x32_f16 v[104:107], v[162:165], v[170:173], v[104:107]
	v_mfma_f32_16x16x32_f16 v[92:95], v[154:157], v[178:181], v[92:95]
	v_mfma_f32_16x16x32_f16 v[88:91], v[162:165], v[178:181], v[88:91]
	v_mfma_f32_16x16x32_f16 v[76:79], v[154:157], v[186:189], v[76:79]
	v_mfma_f32_16x16x32_f16 v[72:75], v[162:165], v[186:189], v[72:75]
	v_mfma_f32_16x16x32_f16 v[68:71], v[154:157], v[194:197], v[68:71]
	v_mfma_f32_16x16x32_f16 v[64:67], v[162:165], v[194:197], v[64:67]
	v_mfma_f32_16x16x32_f16 v[108:111], v[158:161], v[174:177], v[108:111]
	v_mfma_f32_16x16x32_f16 v[104:107], v[166:169], v[174:177], v[104:107]
	v_mfma_f32_16x16x32_f16 v[92:95], v[158:161], v[182:185], v[92:95]
	v_mfma_f32_16x16x32_f16 v[88:91], v[166:169], v[182:185], v[88:91]
	v_mfma_f32_16x16x32_f16 v[76:79], v[158:161], v[190:193], v[76:79]
	v_mfma_f32_16x16x32_f16 v[72:75], v[166:169], v[190:193], v[72:75]
	v_mfma_f32_16x16x32_f16 v[68:71], v[158:161], v[198:201], v[68:71]
	v_mfma_f32_16x16x32_f16 v[64:67], v[166:169], v[198:201], v[64:67]
	s_barrier
	ds_read_b128 v[170:173], v134 offset:16384
	ds_read_b128 v[174:177], v134 offset:17408
	ds_read_b128 v[178:181], v134 offset:18432
	ds_read_b128 v[182:185], v134 offset:19456
	ds_read_b128 v[186:189], v134 offset:20480
	ds_read_b128 v[190:193], v134 offset:21504
	ds_read_b128 v[194:197], v134 offset:22528
	ds_read_b128 v[198:201], v134 offset:23552
	s_mov_b32 s6, m0
	s_mov_b32 m0, s57
	s_nop 0
	global_load_lds_dwordx4 v129, s[48:49]
	s_mov_b32 m0, s6
	s_add_u32 s42, s48, 0x80000
	s_mov_b32 s6, m0
	s_mov_b32 m0, s60
	s_nop 0
	global_load_lds_dwordx4 v131, s[48:49]
	s_mov_b32 m0, s6
	s_addc_u32 s43, s49, 0
	s_mov_b32 s6, m0
	s_mov_b32 m0, s61
	s_nop 0
	global_load_lds_dwordx4 v129, s[42:43]
	s_mov_b32 m0, s6
	s_nop 0
	s_mov_b32 s6, m0
	s_mov_b32 m0, s62
	s_nop 0
	global_load_lds_dwordx4 v131, s[42:43]
	s_mov_b32 m0, s6
	s_nop 0
	s_mov_b32 s6, m0
	s_mov_b32 m0, s56
	s_nop 0
	global_load_lds_dwordx4 v128, s[50:51]
	s_mov_b32 m0, s6
	s_nop 0
	s_mov_b32 s6, m0
	s_mov_b32 m0, s63
	s_nop 0
	global_load_lds_dwordx4 v130, s[50:51]
	s_mov_b32 m0, s6
	s_waitcnt vmcnt(8)
	s_waitcnt lgkmcnt(0)
	s_barrier
	s_waitcnt lgkmcnt(7)
	v_mfma_f32_16x16x32_f16 v[60:63], v[138:141], v[170:173], v[60:63]
	v_mfma_f32_16x16x32_f16 v[56:59], v[146:149], v[170:173], v[56:59]
	s_waitcnt lgkmcnt(5)
	v_mfma_f32_16x16x32_f16 v[52:55], v[138:141], v[178:181], v[52:55]
	v_mfma_f32_16x16x32_f16 v[48:51], v[146:149], v[178:181], v[48:51]
	s_waitcnt lgkmcnt(3)
	v_mfma_f32_16x16x32_f16 v[36:39], v[138:141], v[186:189], v[36:39]
	v_mfma_f32_16x16x32_f16 v[32:35], v[146:149], v[186:189], v[32:35]
	s_waitcnt lgkmcnt(1)
	v_mfma_f32_16x16x32_f16 v[20:23], v[138:141], v[194:197], v[20:23]
	v_mfma_f32_16x16x32_f16 v[16:19], v[146:149], v[194:197], v[16:19]
	v_mfma_f32_16x16x32_f16 v[60:63], v[142:145], v[174:177], v[60:63]
	v_mfma_f32_16x16x32_f16 v[56:59], v[150:153], v[174:177], v[56:59]
	v_mfma_f32_16x16x32_f16 v[52:55], v[142:145], v[182:185], v[52:55]
	v_mfma_f32_16x16x32_f16 v[48:51], v[150:153], v[182:185], v[48:51]
	v_mfma_f32_16x16x32_f16 v[36:39], v[142:145], v[190:193], v[36:39]
	v_mfma_f32_16x16x32_f16 v[32:35], v[150:153], v[190:193], v[32:35]
	s_waitcnt lgkmcnt(0)
	v_mfma_f32_16x16x32_f16 v[20:23], v[142:145], v[198:201], v[20:23]
	v_mfma_f32_16x16x32_f16 v[16:19], v[150:153], v[198:201], v[16:19]
	v_mfma_f32_16x16x32_f16 v[44:47], v[154:157], v[170:173], v[44:47]
	v_mfma_f32_16x16x32_f16 v[40:43], v[162:165], v[170:173], v[40:43]
	v_mfma_f32_16x16x32_f16 v[28:31], v[154:157], v[178:181], v[28:31]
	v_mfma_f32_16x16x32_f16 v[24:27], v[162:165], v[178:181], v[24:27]
	v_mfma_f32_16x16x32_f16 v[12:15], v[154:157], v[186:189], v[12:15]
	v_mfma_f32_16x16x32_f16 v[8:11], v[162:165], v[186:189], v[8:11]
	v_mfma_f32_16x16x32_f16 v[4:7], v[154:157], v[194:197], v[4:7]
	v_mfma_f32_16x16x32_f16 v[0:3], v[162:165], v[194:197], v[0:3]
	v_mfma_f32_16x16x32_f16 v[44:47], v[158:161], v[174:177], v[44:47]
	v_mfma_f32_16x16x32_f16 v[40:43], v[166:169], v[174:177], v[40:43]
	v_mfma_f32_16x16x32_f16 v[28:31], v[158:161], v[182:185], v[28:31]
	v_mfma_f32_16x16x32_f16 v[24:27], v[166:169], v[182:185], v[24:27]
	v_mfma_f32_16x16x32_f16 v[12:15], v[158:161], v[190:193], v[12:15]
	v_mfma_f32_16x16x32_f16 v[8:11], v[166:169], v[190:193], v[8:11]
	v_mfma_f32_16x16x32_f16 v[4:7], v[158:161], v[198:201], v[4:7]
	v_mfma_f32_16x16x32_f16 v[0:3], v[166:169], v[198:201], v[0:3]
	s_barrier
; #define PG8_STAGE(bufoff, gbase, voff) do { _Pragma("unroll") for (int _i = 0; _i < 2; ++_i) glds16_s((gbase), (voff)[_i], ldsb + (unsigned)((bufoff) + _i * 8192)); } while (0)
; #define PG8_WAIT_V(n) asm volatile("s_waitcnt vmcnt(" #n ")" ::: "memory")
; #define PG8_BAR __builtin_amdgcn_s_barrier()
; template <class Prob, class Epi, bool I8 = false, bool ALIGN_EPI = true, bool SP2 = true>
; __device__ __forceinline__ void gemm_phase(LAS unsigned char* lds, int wave, const Prob& P, const Epi& E) {
;     ...
;             PG8_LDB(B0, 1, 0); PG8_LDB(B1, 1, 1); PG8_SCHED; PG8_LDA(At, 1, 0); PG8_STAGE(PG8_SA(0, 1), a2 + hstepA, voffA);
;             PG8_WAIT_V(8); PG8_WAIT_L(0); PG8_BAR; PG8_MMA(0, 0, At, B0); PG8_MMA(0, 1, At, B1); PG8_BAR; PG8_SCHED;
;             PG8_LDA(At, 1, 1); PG8_STAGE(PG8_SB(1, 0), b3, voffB); PG8_STAGE(PG8_SB(1, 1), b3 + hstepB, voffB); PG8_STAGE(PG8_SA(1, 0), a3, voffA);
;             PG8_WAIT_V(8); PG8_WAIT_L(0); PG8_BAR; PG8_MMA(1, 0, At, B0); PG8_MMA(1, 1, At, B1); PG8_BAR; PG8_SCHED;
;             } else {
;             PG8_LDB(B0, 0, 0); PG8_SCHED; PG8_LDA(At, 0, 0); PG8_STAGE(PG8_SA(1, 1), a1 + hstepA, voffA);
;             PG8_WAIT_L(8); PG8_BAR; PG8_WAIT_L(0); PG8_MMA(0, 0, At, B0); PG8_BAR; PG8_SCHED;
;             PG8_LDB(B1, 0, 1); PG8_STAGE(PG8_SB(0, 0), b2, voffB);
;             PG8_BAR; PG8_WAIT_L(0); PG8_MMA(0, 1, At, B1); PG8_BAR;
;             PG8_LDA(At, 0, 1); PG8_STAGE(PG8_SA(0, 0), a2, voffA);
;             PG8_BAR; PG8_WAIT_L(0); PG8_MMA(1, 0, At, B0); PG8_BAR; PG8_SCHED;
;             PG8_STAGE(PG8_SB(0, 1), b2 + hstepB, voffB);
;             PG8_WAIT_V(6); PG8_BAR; PG8_MMA(1, 1, At, B1); PG8_BAR;
;             PG8_LDB(B0, 1, 0); PG8_SCHED; PG8_LDA(At, 1, 0); PG8_STAGE(PG8_SA(0, 1), a2 + hstepA, voffA);
;             PG8_WAIT_L(8); PG8_BAR; PG8_WAIT_L(0); PG8_MMA(0, 0, At, B0); PG8_BAR; PG8_SCHED;
;             PG8_LDB(B1, 1, 1); PG8_STAGE(PG8_SB(1, 0), b3, voffB);
;             PG8_BAR; PG8_WAIT_L(0); PG8_MMA(0, 1, At, B1); PG8_BAR;
;             PG8_LDA(At, 1, 1); PG8_STAGE(PG8_SA(1, 0), a3, voffA);
;             PG8_BAR; PG8_WAIT_L(0); PG8_MMA(1, 0, At, B0); PG8_BAR; PG8_SCHED;
;             PG8_STAGE(PG8_SB(1, 1), b3 + hstepB, voffB);
;             PG8_WAIT_V(6); PG8_BAR; PG8_MMA(1, 1, At, B1); PG8_BAR;
;             }
;         }
;         if constexpr (ALIGN_EPI) { if (wr == 0) PG8_BAR; }
	ds_read_b128 v[138:141], v135
	ds_read_b128 v[142:145], v135 offset:1024
	ds_read_b128 v[146:149], v135 offset:2048
	ds_read_b128 v[150:153], v135 offset:3072
	ds_read_b128 v[154:157], v136
	ds_read_b128 v[158:161], v136 offset:1024
	ds_read_b128 v[162:165], v136 offset:2048
	ds_read_b128 v[166:169], v136 offset:3072
	ds_read_b128 v[170:173], v134 offset:32768
	ds_read_b128 v[174:177], v134 offset:33792
	ds_read_b128 v[178:181], v134 offset:34816
	ds_read_b128 v[182:185], v134 offset:35840
	ds_read_b128 v[186:189], v134 offset:36864
	ds_read_b128 v[190:193], v134 offset:37888
	ds_read_b128 v[194:197], v134 offset:38912
	ds_read_b128 v[198:201], v134 offset:39936
	s_add_u32 s42, s50, 0x20000
	s_addc_u32 s43, s51, 0
	s_mov_b32 s6, m0
	s_mov_b32 m0, s64
	s_nop 0
	global_load_lds_dwordx4 v128, s[42:43]
	s_mov_b32 m0, s6
	s_nop 0
	s_mov_b32 s6, m0
	s_mov_b32 m0, s68
	s_nop 0
	global_load_lds_dwordx4 v130, s[42:43]
	s_mov_b32 m0, s6
	s_waitcnt vmcnt(8)
	s_waitcnt lgkmcnt(0)
	s_barrier
	s_waitcnt lgkmcnt(7)
	v_mfma_f32_16x16x32_f16 v[124:127], v[138:141], v[170:173], v[124:127]
	v_mfma_f32_16x16x32_f16 v[120:123], v[146:149], v[170:173], v[120:123]
	s_waitcnt lgkmcnt(5)
	v_mfma_f32_16x16x32_f16 v[116:119], v[138:141], v[178:181], v[116:119]
	v_mfma_f32_16x16x32_f16 v[112:115], v[146:149], v[178:181], v[112:115]
	s_waitcnt lgkmcnt(3)
	v_mfma_f32_16x16x32_f16 v[100:103], v[138:141], v[186:189], v[100:103]
	v_mfma_f32_16x16x32_f16 v[96:99], v[146:149], v[186:189], v[96:99]
	s_waitcnt lgkmcnt(1)
	v_mfma_f32_16x16x32_f16 v[84:87], v[138:141], v[194:197], v[84:87]
	v_mfma_f32_16x16x32_f16 v[80:83], v[146:149], v[194:197], v[80:83]
	v_mfma_f32_16x16x32_f16 v[124:127], v[142:145], v[174:177], v[124:127]
	v_mfma_f32_16x16x32_f16 v[120:123], v[150:153], v[174:177], v[120:123]
	v_mfma_f32_16x16x32_f16 v[116:119], v[142:145], v[182:185], v[116:119]
	v_mfma_f32_16x16x32_f16 v[112:115], v[150:153], v[182:185], v[112:115]
	v_mfma_f32_16x16x32_f16 v[100:103], v[142:145], v[190:193], v[100:103]
	v_mfma_f32_16x16x32_f16 v[96:99], v[150:153], v[190:193], v[96:99]
	s_waitcnt lgkmcnt(0)
	v_mfma_f32_16x16x32_f16 v[84:87], v[142:145], v[198:201], v[84:87]
	v_mfma_f32_16x16x32_f16 v[80:83], v[150:153], v[198:201], v[80:83]
	v_mfma_f32_16x16x32_f16 v[108:111], v[154:157], v[170:173], v[108:111]
	v_mfma_f32_16x16x32_f16 v[104:107], v[162:165], v[170:173], v[104:107]
	v_mfma_f32_16x16x32_f16 v[92:95], v[154:157], v[178:181], v[92:95]
	v_mfma_f32_16x16x32_f16 v[88:91], v[162:165], v[178:181], v[88:91]
	v_mfma_f32_16x16x32_f16 v[76:79], v[154:157], v[186:189], v[76:79]
	v_mfma_f32_16x16x32_f16 v[72:75], v[162:165], v[186:189], v[72:75]
	v_mfma_f32_16x16x32_f16 v[68:71], v[154:157], v[194:197], v[68:71]
	v_mfma_f32_16x16x32_f16 v[64:67], v[162:165], v[194:197], v[64:67]
	v_mfma_f32_16x16x32_f16 v[108:111], v[158:161], v[174:177], v[108:111]
	v_mfma_f32_16x16x32_f16 v[104:107], v[166:169], v[174:177], v[104:107]
	v_mfma_f32_16x16x32_f16 v[92:95], v[158:161], v[182:185], v[92:95]
	v_mfma_f32_16x16x32_f16 v[88:91], v[166:169], v[182:185], v[88:91]
	v_mfma_f32_16x16x32_f16 v[76:79], v[158:161], v[190:193], v[76:79]
	v_mfma_f32_16x16x32_f16 v[72:75], v[166:169], v[190:193], v[72:75]
	v_mfma_f32_16x16x32_f16 v[68:71], v[158:161], v[198:201], v[68:71]
	v_mfma_f32_16x16x32_f16 v[64:67], v[166:169], v[198:201], v[64:67]
	s_barrier
	ds_read_b128 v[170:173], v134 offset:49152
	ds_read_b128 v[174:177], v134 offset:50176
	ds_read_b128 v[178:181], v134 offset:51200
	ds_read_b128 v[182:185], v134 offset:52224
	ds_read_b128 v[186:189], v134 offset:53248
	ds_read_b128 v[190:193], v134 offset:54272
	ds_read_b128 v[194:197], v134 offset:55296
	ds_read_b128 v[198:201], v134 offset:56320
	s_add_u32 s42, s48, 0x80
	s_addc_u32 s43, s49, 0
	s_mov_b32 s6, m0
	s_mov_b32 m0, s73
	s_nop 0
	global_load_lds_dwordx4 v129, s[42:43]
	s_mov_b32 m0, s6
	s_nop 0
	s_mov_b32 s6, m0
	s_mov_b32 m0, s74
	s_nop 0
	global_load_lds_dwordx4 v131, s[42:43]
	s_mov_b32 m0, s6
	s_add_u32 s42, s48, 0x80080
	s_addc_u32 s43, s49, 0
	s_mov_b32 s6, m0
	s_mov_b32 m0, s77
	s_nop 0
	global_load_lds_dwordx4 v129, s[42:43]
	s_mov_b32 m0, s6
	s_nop 0
	s_mov_b32 s6, m0
	s_mov_b32 m0, s79
	s_nop 0
	global_load_lds_dwordx4 v131, s[42:43]
	s_mov_b32 m0, s6
	s_nop 0
	s_mov_b32 s6, m0
	s_mov_b32 m0, s75
	s_nop 0
	global_load_lds_dwordx4 v128, s[46:47]
	s_mov_b32 m0, s6
	s_nop 0
	s_mov_b32 s6, m0
	s_mov_b32 m0, s76
	s_nop 0
	global_load_lds_dwordx4 v130, s[46:47]
	s_mov_b32 m0, s6
	s_waitcnt vmcnt(8)
	s_waitcnt lgkmcnt(0)
	s_barrier
	s_waitcnt lgkmcnt(7)
	v_mfma_f32_16x16x32_f16 v[60:63], v[138:141], v[170:173], v[60:63]
	v_mfma_f32_16x16x32_f16 v[56:59], v[146:149], v[170:173], v[56:59]
	s_waitcnt lgkmcnt(5)
	v_mfma_f32_16x16x32_f16 v[52:55], v[138:141], v[178:181], v[52:55]
	v_mfma_f32_16x16x32_f16 v[48:51], v[146:149], v[178:181], v[48:51]
	s_waitcnt lgkmcnt(3)
	v_mfma_f32_16x16x32_f16 v[36:39], v[138:141], v[186:189], v[36:39]
	v_mfma_f32_16x16x32_f16 v[32:35], v[146:149], v[186:189], v[32:35]
	s_waitcnt lgkmcnt(1)
	v_mfma_f32_16x16x32_f16 v[20:23], v[138:141], v[194:197], v[20:23]
	v_mfma_f32_16x16x32_f16 v[16:19], v[146:149], v[194:197], v[16:19]
	v_mfma_f32_16x16x32_f16 v[60:63], v[142:145], v[174:177], v[60:63]
	v_mfma_f32_16x16x32_f16 v[56:59], v[150:153], v[174:177], v[56:59]
	v_mfma_f32_16x16x32_f16 v[52:55], v[142:145], v[182:185], v[52:55]
	v_mfma_f32_16x16x32_f16 v[48:51], v[150:153], v[182:185], v[48:51]
	v_mfma_f32_16x16x32_f16 v[36:39], v[142:145], v[190:193], v[36:39]
	v_mfma_f32_16x16x32_f16 v[32:35], v[150:153], v[190:193], v[32:35]
	s_waitcnt lgkmcnt(0)
	v_mfma_f32_16x16x32_f16 v[20:23], v[142:145], v[198:201], v[20:23]
	v_mfma_f32_16x16x32_f16 v[16:19], v[150:153], v[198:201], v[16:19]
	v_mfma_f32_16x16x32_f16 v[44:47], v[154:157], v[170:173], v[44:47]
	v_mfma_f32_16x16x32_f16 v[40:43], v[162:165], v[170:173], v[40:43]
	v_mfma_f32_16x16x32_f16 v[28:31], v[154:157], v[178:181], v[28:31]
	v_mfma_f32_16x16x32_f16 v[24:27], v[162:165], v[178:181], v[24:27]
	v_mfma_f32_16x16x32_f16 v[12:15], v[154:157], v[186:189], v[12:15]
	v_mfma_f32_16x16x32_f16 v[8:11], v[162:165], v[186:189], v[8:11]
	v_mfma_f32_16x16x32_f16 v[4:7], v[154:157], v[194:197], v[4:7]
	v_mfma_f32_16x16x32_f16 v[0:3], v[162:165], v[194:197], v[0:3]
	v_mfma_f32_16x16x32_f16 v[44:47], v[158:161], v[174:177], v[44:47]
	v_mfma_f32_16x16x32_f16 v[40:43], v[166:169], v[174:177], v[40:43]
	v_mfma_f32_16x16x32_f16 v[28:31], v[158:161], v[182:185], v[28:31]
	v_mfma_f32_16x16x32_f16 v[24:27], v[166:169], v[182:185], v[24:27]
	v_mfma_f32_16x16x32_f16 v[12:15], v[158:161], v[190:193], v[12:15]
	v_mfma_f32_16x16x32_f16 v[8:11], v[166:169], v[190:193], v[8:11]
	v_mfma_f32_16x16x32_f16 v[4:7], v[158:161], v[198:201], v[4:7]
	v_mfma_f32_16x16x32_f16 v[0:3], v[166:169], v[198:201], v[0:3]
	s_barrier
	s_add_i32 s29, s29, 2
	s_add_u32 s4, s4, 0x100
	s_addc_u32 s5, s5, 0
	s_cmp_gt_u32 s29, 5
	s_mov_b64 s[42:43], s[44:45]
	s_cbranch_scc0 .LBB0_225
	s_and_b64 vcc, exec, s[16:17]
	s_cbranch_vccz .LBB0_228
	s_barrier

; __device__ __forceinline__ int mk_lane() { int l; asm volatile("v_mbcnt_lo_u32_b32 %0, -1, 0\n\tv_mbcnt_hi_u32_b32 %0, -1, %0" : "=v"(l)); return l; }
; #define PG8_STAGE(bufoff, gbase, voff) do { _Pragma("unroll") for (int _i = 0; _i < 2; ++_i) glds16_s((gbase), (voff)[_i], ldsb + (unsigned)((bufoff) + _i * 8192)); } while (0)
; template <class Prob, class Epi, bool I8 = false, bool ALIGN_EPI = true, bool SP2 = true>
; __device__ __forceinline__ void gemm_phase(LAS unsigned char* lds, int wave, const Prob& P, const Epi& E) {
;     const int tid_ = wave * 64 + mk_lane();
;     const int tid = tid_, wid = __builtin_amdgcn_readfirstlane(tid >> 6), lane = tid & 63, wr = wid >> 2, wc = wid & 3, fr = lane & 15, fq = lane >> 4;
;     const int K = P.K, nt = K / BK;
;     unsigned voffA[2], voffB[2];
; #pragma unroll
;     for (int i = 0; i < 2; ++i) { int R, C; stage_rc(tid * 16 + i * 8192, R, C); const int Rb = (R & ~31) + perm32(R & 31);
;         voffA[i] = P.a_rowoff(R) + (unsigned)C * 2u; voffB[i] = P.b_rowoff(Rb) + (unsigned)C * 2u; }
;     const size_t kstep = (size_t)(BK * 2);
;     const size_t hstepA = P.a_hstep(), hstepB = P.b_hstep();
;     const unsigned ldsw = (unsigned)wid * 1024u;
;     const unsigned ldsb = (unsigned)(size_t)lds + ldsw;
;     const int aoff = lds_byte(wr * 64 + fr, fq * 8), boff = lds_byte(wc * 32 + fr, fq * 8);
;     ...
;     Unit cur, nxt; int ui = 0;
;     if (!P.next(0, cur)) return;
;     Acc acc;
; #pragma unroll
;     for (int a = 0; a < 2; ++a)
; #pragma unroll
;         for (int b = 0; b < 2; ++b)
; #pragma unroll
;             for (int m = 0; m < 4; ++m)
; #pragma unroll
;                 for (int n = 0; n < 2; ++n) acc[a][b][m][n] = (f32x4){0.f, 0.f, 0.f, 0.f};
;     h16x8 At[4][2], B0[2][2], B1[2][2];
;     const char* cA = P.a_tile(cur); const char* cB = P.b_tile(cur);
;     if constexpr (SP2) {
;         PG8_STAGE(PG8_SB(0, 0), cB, voffB); PG8_STAGE(PG8_SB(0, 1), cB + hstepB, voffB); PG8_STAGE(PG8_SA(0, 0), cA, voffA); PG8_STAGE(PG8_SA(0, 1), cA + hstepA, voffA);
;         if (wr == 1) PG8_BAR;
;     __device__ unsigned a_rowoff(int R) const { return (unsigned)R * 4096u * 2u; }
;     __device__ unsigned b_rowoff(int R) const { return (unsigned)R * (unsigned)BTP * 2u; }
;     __device__ size_t a_hstep() const { return (size_t)128 * 4096 * 2; }
;     __device__ size_t b_hstep() const { return (size_t)128 * BTP * 2; }
.LBB0_286:
	s_add_u32 s46, s30, 0x4200000
	s_addc_u32 s47, s31, 0
	v_readlane_b32 s0, v254, 42
	v_readlane_b32 s4, v254, 55
	s_waitcnt lgkmcnt(0)
	s_barrier
	s_add_u32 s42, s30, 0x45200000
	v_mbcnt_lo_u32_b32 v0, -1, 0
	v_mbcnt_hi_u32_b32 v0, -1, v0
	v_readlane_b32 s5, v254, 56
	v_add_u32_e32 v1, s0, v0
	s_addc_u32 s43, s31, 0
	v_readfirstlane_b32 s0, v1
	s_and_b64 vcc, exec, s[4:5]
	s_cbranch_vccz .LBB0_380
	v_ashrrev_i32_e32 v2, 31, v1
	v_lshrrev_b32_e32 v2, 26, v2
	v_lshlrev_b32_e32 v3, 4, v1
	v_add_u32_e32 v2, v1, v2
	v_bfe_i32 v1, v1, 27, 1
	v_lshrrev_b32_e32 v1, 22, v1
	v_add_u32_e32 v1, v3, v1
	v_and_b32_e32 v1, 0xfffffc00, v1
	v_sub_u32_e32 v1, v3, v1
	v_lshrrev_b32_e32 v4, 4, v1
	v_bitop3_b32 v1, v4, v1, 32 bitop3:0x6c
	v_ashrrev_i32_e32 v5, 31, v1
	v_ashrrev_i32_e32 v2, 6, v2
	v_lshrrev_b32_e32 v5, 26, v5
	v_lshlrev_b32_e32 v4, 3, v2
	v_add_u32_e32 v5, v1, v5
	v_and_b32_e32 v4, -16, v4
	v_ashrrev_i32_e32 v6, 6, v5
	v_and_b32_e32 v5, 0xc0, v5
	v_add_u32_e32 v4, v6, v4
	v_sub_u32_e32 v1, v1, v5
	v_mov_b32_e32 v8, 1
	v_lshlrev_b32_e32 v2, 5, v2
	v_ashrrev_i16_sdwa v1, v8, sext(v1) dst_sel:DWORD dst_unused:UNUSED_PAD src0_sel:DWORD src1_sel:BYTE_0
	v_lshlrev_b32_e32 v5, 1, v4
	v_lshrrev_b32_e32 v7, 2, v4
	v_and_b32_e32 v6, 3, v6
	s_mov_b32 s2, 0x1ffffe0
	v_and_b32_e32 v2, 32, v2
	v_bfe_i32 v1, v1, 0, 16
	v_and_b32_e32 v5, 24, v5
	v_and_b32_e32 v7, 4, v7
	v_and_or_b32 v6, v4, s2, v6
	v_or3_b32 v5, v6, v7, v5
	v_add_lshl_u32 v2, v2, v1, 1
	v_add_u32_e32 v1, 0x2000, v3
	v_lshl_add_u32 v148, v4, 13, v2
	v_mad_u64_u32 v[136:137], s[4:5], v5, s21, v[2:3]
	v_ashrrev_i32_e32 v2, 31, v1
	v_lshrrev_b32_e32 v2, 22, v2
	v_add_u32_e32 v2, v1, v2
	v_ashrrev_i32_e32 v2, 10, v2
	v_mul_i32_i24_e32 v3, 0x400, v2
	v_sub_u32_e32 v1, v1, v3
	v_lshrrev_b32_e32 v3, 4, v1
	v_bitop3_b32 v1, v3, v1, 32 bitop3:0x6c
	v_ashrrev_i32_e32 v4, 31, v1
	v_lshrrev_b32_e32 v4, 26, v4
	v_lshlrev_b32_e32 v3, 3, v2
	v_add_u32_e32 v4, v1, v4
	v_and_b32_e32 v3, -16, v3
	v_ashrrev_i32_e32 v5, 6, v4
	v_and_b32_e32 v4, 0xc0, v4
	v_add_u32_e32 v3, v5, v3
	v_sub_u32_e32 v1, v1, v4
	v_lshlrev_b32_e32 v2, 5, v2
	v_ashrrev_i16_sdwa v1, v8, sext(v1) dst_sel:DWORD dst_unused:UNUSED_PAD src0_sel:DWORD src1_sel:BYTE_0
	v_lshlrev_b32_e32 v4, 1, v3
	v_lshrrev_b32_e32 v6, 2, v3
	v_and_b32_e32 v5, 3, v5
	v_and_b32_e32 v2, 32, v2
	v_bfe_i32 v1, v1, 0, 16
	v_and_b32_e32 v4, 24, v4
	v_and_b32_e32 v6, 4, v6
	v_and_or_b32 v5, v3, s2, v5
	v_or3_b32 v4, v5, v6, v4
	v_add_lshl_u32 v2, v2, v1, 1
	v_mad_u64_u32 v[138:139], s[4:5], v4, s21, v[2:3]
	s_ashr_i32 s4, s0, 6
	s_lshl_b32 s2, s4, 10
	v_readlane_b32 s6, v254, 58
	s_ashr_i32 s1, s0, 8
	s_add_i32 s2, s2, 0
	s_mul_i32 s5, s6, 0x820000
	s_add_u32 s5, s26, s5
	s_mul_hi_i32 s6, s6, 0x820000
	v_readlane_b32 s7, v254, 57
	s_addc_u32 s6, s27, s6
	s_mul_i32 s7, s7, 0x208000
	s_add_u32 s38, s5, s7
	s_addc_u32 s39, s6, 0
	s_add_i32 s19, s2, 0x10000
	s_mov_b32 s5, m0
	s_mov_b32 m0, s19
	s_nop 0
	global_load_lds_dwordx4 v136, s[38:39]
	s_mov_b32 m0, s5
	s_add_i32 s60, s2, 0x12000
	s_mov_b32 s5, m0
	s_mov_b32 m0, s60
	s_nop 0
	global_load_lds_dwordx4 v138, s[38:39]
	s_mov_b32 m0, s5
	s_add_u32 s14, s38, 0x104000
	s_addc_u32 s15, s39, 0
	s_add_i32 s61, s2, 0x14000
	s_mov_b32 s5, m0
	s_mov_b32 m0, s61
	s_nop 0
	global_load_lds_dwordx4 v136, s[14:15]
	s_mov_b32 m0, s5
	s_add_i32 s62, s2, 0x16000
	s_mov_b32 s5, m0
	s_mov_b32 m0, s62
	s_nop 0
	global_load_lds_dwordx4 v138, s[14:15]
	s_mov_b32 m0, s5
	v_lshl_add_u32 v137, v3, 13, v2
	v_readlane_b32 s5, v252, 30
	s_add_u32 s14, s46, s5
	s_addc_u32 s15, s47, 0
	s_mov_b32 s5, m0
	s_mov_b32 m0, s2
	s_nop 0
	global_load_lds_dwordx4 v148, s[14:15]
	s_mov_b32 m0, s5
	s_add_i32 s63, s2, 0x2000
	s_mov_b32 s5, m0
	s_mov_b32 m0, s63
	s_nop 0
	global_load_lds_dwordx4 v137, s[14:15]
	s_mov_b32 m0, s5
	s_add_u32 s16, s14, 0x100000
	s_addc_u32 s17, s15, 0
	s_add_i32 s68, s2, 0x4000
	s_mov_b32 s5, m0
	s_mov_b32 m0, s68
	s_nop 0
	global_load_lds_dwordx4 v148, s[16:17]
	s_mov_b32 m0, s5
	s_add_i32 s69, s2, 0x6000
	s_mov_b32 s5, m0
	s_mov_b32 m0, s69
	s_nop 0
	global_load_lds_dwordx4 v137, s[16:17]
	s_mov_b32 m0, s5
	s_cmp_eq_u32 s1, 1
	s_cselect_b64 s[76:77], -1, 0
	s_cmp_lg_u32 s1, 1
	s_cbranch_scc1 .LBB0_289
	s_barrier
	s_setprio 1

; #define PG8_STAGE(bufoff, gbase, voff) do { _Pragma("unroll") for (int _i = 0; _i < 2; ++_i) glds16_s((gbase), (voff)[_i], ldsb + (unsigned)((bufoff) + _i * 8192)); } while (0)
; #define PG8_LDA(dst, b, h) do { _Pragma("unroll") for (int m = 0; m < 4; ++m) _Pragma("unroll") for (int k = 0; k < 2; ++k) dst[m][k] = *(const LAS h16x8*)(lds + PG8_SA(b, h) + aoff + m * 2048 + k * 1024); } while (0)
; #define PG8_LDB(dst, b, h) do { _Pragma("unroll") for (int n = 0; n < 2; ++n) _Pragma("unroll") for (int k = 0; k < 2; ++k) dst[n][k] = *(const LAS h16x8*)(lds + PG8_SB(b, h) + boff + n * 2048 + k * 1024); } while (0)
; #define PG8_MMA(ai, bj, At, Bt) do { __builtin_amdgcn_s_setprio(1); _Pragma("unroll") for (int m = 0; m < 4; ++m) _Pragma("unroll") for (int n = 0; n < 2; ++n) _Pragma("unroll") for (int k = 0; k < 2; ++k) \
;         acc[ai][bj][m][n] = mma_step<I8>(Bt[n][k], At[m][k], acc[ai][bj][m][n]); __builtin_amdgcn_s_setprio(0); } while (0)
; #define PG8_WAIT_V(n) asm volatile("s_waitcnt vmcnt(" #n ")" ::: "memory")
; #define PG8_WAIT_L(n) asm volatile("s_waitcnt lgkmcnt(" #n ")" ::: "memory")
; #define PG8_BAR __builtin_amdgcn_s_barrier()
; #define PG8_SCHED __builtin_amdgcn_sched_barrier(0)
; template <class Prob, class Epi, bool I8 = false, bool ALIGN_EPI = true, bool SP2 = true>
; __device__ __forceinline__ void gemm_phase(LAS unsigned char* lds, int wave, const Prob& P, const Epi& E) {
;     ...
;             PG8_LDB(B0, 0, 0); PG8_LDB(B1, 0, 1); PG8_SCHED; PG8_LDA(At, 0, 0); PG8_STAGE(PG8_SA(1, 1), a1 + hstepA, voffA);
;             PG8_WAIT_V(8); PG8_WAIT_L(0); PG8_BAR; PG8_MMA(0, 0, At, B0); PG8_MMA(0, 1, At, B1); PG8_BAR; PG8_SCHED;
;             PG8_LDA(At, 0, 1); PG8_STAGE(PG8_SB(0, 0), b2, voffB); PG8_STAGE(PG8_SB(0, 1), b2 + hstepB, voffB); PG8_STAGE(PG8_SA(0, 0), a2, voffA);
;             PG8_WAIT_V(8); PG8_WAIT_L(0); PG8_BAR; PG8_MMA(1, 0, At, B0); PG8_MMA(1, 1, At, B1); PG8_BAR; PG8_SCHED;
.LBB0_297:
	v_add_u32_e32 v144, 0x10000, v139
	v_add_u32_e32 v162, 0x14000, v139
	ds_read_b128 v[128:131], v144
	ds_read_b128 v[132:135], v144 offset:1024
	ds_read_b128 v[140:143], v144 offset:2048
	ds_read_b128 v[144:147], v144 offset:3072
	ds_read_b128 v[150:153], v162
	ds_read_b128 v[154:157], v162 offset:1024
	ds_read_b128 v[158:161], v162 offset:2048
	ds_read_b128 v[162:165], v162 offset:3072
	s_add_u32 s38, s14, 0x100
	s_addc_u32 s39, s15, 0
	s_cmp_eq_u32 s5, 28
	s_cselect_b32 s56, s1, s38
	s_cselect_b32 s57, s0, s39
	s_cselect_b32 s44, s48, s17
	s_cselect_b32 s45, s49, s4
	s_add_u32 s40, s56, 0x80
	s_addc_u32 s41, s57, 0
	ds_read_b128 v[166:169], v149
	ds_read_b128 v[170:173], v149 offset:1024
	ds_read_b128 v[174:177], v149 offset:2048
	ds_read_b128 v[178:181], v149 offset:3072
	ds_read_b128 v[182:185], v149 offset:4096
	ds_read_b128 v[186:189], v149 offset:5120
	ds_read_b128 v[190:193], v149 offset:6144
	ds_read_b128 v[194:197], v149 offset:7168
	s_add_u32 s14, s14, 0x100080
	s_addc_u32 s15, s15, 0
	s_mov_b32 s6, m0
	s_mov_b32 m0, s86
	s_nop 0
	global_load_lds_dwordx4 v148, s[14:15]
	s_mov_b32 m0, s6
	s_nop 0
	s_mov_b32 s6, m0
	s_mov_b32 m0, s87
	s_nop 0
	global_load_lds_dwordx4 v137, s[14:15]
	s_mov_b32 m0, s6
	s_waitcnt vmcnt(8)
	s_waitcnt lgkmcnt(0)
	s_barrier
	s_waitcnt lgkmcnt(7)
	v_mfma_f32_16x16x32_f16 v[124:127], v[128:131], v[166:169], v[124:127]
	v_mfma_f32_16x16x32_f16 v[120:123], v[140:143], v[166:169], v[120:123]
	s_waitcnt lgkmcnt(5)
	v_mfma_f32_16x16x32_f16 v[116:119], v[128:131], v[174:177], v[116:119]
	v_mfma_f32_16x16x32_f16 v[112:115], v[140:143], v[174:177], v[112:115]
	s_waitcnt lgkmcnt(3)
	v_mfma_f32_16x16x32_f16 v[108:111], v[128:131], v[182:185], v[108:111]
	v_mfma_f32_16x16x32_f16 v[104:107], v[140:143], v[182:185], v[104:107]
	s_waitcnt lgkmcnt(1)
	v_mfma_f32_16x16x32_f16 v[100:103], v[128:131], v[190:193], v[100:103]
	v_mfma_f32_16x16x32_f16 v[96:99], v[140:143], v[190:193], v[96:99]
	v_mfma_f32_16x16x32_f16 v[124:127], v[132:135], v[170:173], v[124:127]
	v_mfma_f32_16x16x32_f16 v[120:123], v[144:147], v[170:173], v[120:123]
	v_mfma_f32_16x16x32_f16 v[116:119], v[132:135], v[178:181], v[116:119]
	v_mfma_f32_16x16x32_f16 v[112:115], v[144:147], v[178:181], v[112:115]
	v_mfma_f32_16x16x32_f16 v[108:111], v[132:135], v[186:189], v[108:111]
	v_mfma_f32_16x16x32_f16 v[104:107], v[144:147], v[186:189], v[104:107]
	s_waitcnt lgkmcnt(0)
	v_mfma_f32_16x16x32_f16 v[100:103], v[132:135], v[194:197], v[100:103]
	v_mfma_f32_16x16x32_f16 v[96:99], v[144:147], v[194:197], v[96:99]
	v_mfma_f32_16x16x32_f16 v[92:95], v[150:153], v[166:169], v[92:95]
	v_mfma_f32_16x16x32_f16 v[88:91], v[158:161], v[166:169], v[88:91]
	v_mfma_f32_16x16x32_f16 v[84:87], v[150:153], v[174:177], v[84:87]
	v_mfma_f32_16x16x32_f16 v[80:83], v[158:161], v[174:177], v[80:83]
	v_mfma_f32_16x16x32_f16 v[76:79], v[150:153], v[182:185], v[76:79]
	v_mfma_f32_16x16x32_f16 v[72:75], v[158:161], v[182:185], v[72:75]
	v_mfma_f32_16x16x32_f16 v[68:71], v[150:153], v[190:193], v[68:71]
	v_mfma_f32_16x16x32_f16 v[64:67], v[158:161], v[190:193], v[64:67]
	v_mfma_f32_16x16x32_f16 v[92:95], v[154:157], v[170:173], v[92:95]
	v_mfma_f32_16x16x32_f16 v[88:91], v[162:165], v[170:173], v[88:91]
	v_mfma_f32_16x16x32_f16 v[84:87], v[154:157], v[178:181], v[84:87]
	v_mfma_f32_16x16x32_f16 v[80:83], v[162:165], v[178:181], v[80:83]
	v_mfma_f32_16x16x32_f16 v[76:79], v[154:157], v[186:189], v[76:79]
	v_mfma_f32_16x16x32_f16 v[72:75], v[162:165], v[186:189], v[72:75]
	v_mfma_f32_16x16x32_f16 v[68:71], v[154:157], v[194:197], v[68:71]
	v_mfma_f32_16x16x32_f16 v[64:67], v[162:165], v[194:197], v[64:67]
	s_barrier
	ds_read_b128 v[166:169], v149 offset:16384
	ds_read_b128 v[170:173], v149 offset:17408
	ds_read_b128 v[174:177], v149 offset:18432
	ds_read_b128 v[178:181], v149 offset:19456
	ds_read_b128 v[182:185], v149 offset:20480
	ds_read_b128 v[186:189], v149 offset:21504
	ds_read_b128 v[190:193], v149 offset:22528
	ds_read_b128 v[194:197], v149 offset:23552
	s_mov_b32 s6, m0
	s_mov_b32 m0, s19
	s_nop 0
	global_load_lds_dwordx4 v136, s[44:45]
	s_mov_b32 m0, s6
	s_add_u32 s14, s44, 0x104000
	s_mov_b32 s6, m0
	s_mov_b32 m0, s60
	s_nop 0
	global_load_lds_dwordx4 v138, s[44:45]
	s_mov_b32 m0, s6
	s_addc_u32 s15, s45, 0
	s_mov_b32 s6, m0
	s_mov_b32 m0, s61
	s_nop 0
	global_load_lds_dwordx4 v136, s[14:15]
	s_mov_b32 m0, s6
	s_nop 0
	s_mov_b32 s6, m0
	s_mov_b32 m0, s62
	s_nop 0
	global_load_lds_dwordx4 v138, s[14:15]
	s_mov_b32 m0, s6
	s_nop 0
	s_mov_b32 s6, m0
	s_mov_b32 m0, s2
	s_nop 0
	global_load_lds_dwordx4 v148, s[56:57]
	s_mov_b32 m0, s6
	s_nop 0
	s_mov_b32 s6, m0
	s_mov_b32 m0, s63
	s_nop 0
	global_load_lds_dwordx4 v137, s[56:57]
	s_mov_b32 m0, s6
	s_waitcnt vmcnt(8)
	s_waitcnt lgkmcnt(0)
	s_barrier
; #define PG8_STAGE(bufoff, gbase, voff) do { _Pragma("unroll") for (int _i = 0; _i < 2; ++_i) glds16_s((gbase), (voff)[_i], ldsb + (unsigned)((bufoff) + _i * 8192)); } while (0)
; #define PG8_LDA(dst, b, h) do { _Pragma("unroll") for (int m = 0; m < 4; ++m) _Pragma("unroll") for (int k = 0; k < 2; ++k) dst[m][k] = *(const LAS h16x8*)(lds + PG8_SA(b, h) + aoff + m * 2048 + k * 1024); } while (0)
; #define PG8_LDB(dst, b, h) do { _Pragma("unroll") for (int n = 0; n < 2; ++n) _Pragma("unroll") for (int k = 0; k < 2; ++k) dst[n][k] = *(const LAS h16x8*)(lds + PG8_SB(b, h) + boff + n * 2048 + k * 1024); } while (0)
; #define PG8_MMA(ai, bj, At, Bt) do { __builtin_amdgcn_s_setprio(1); _Pragma("unroll") for (int m = 0; m < 4; ++m) _Pragma("unroll") for (int n = 0; n < 2; ++n) _Pragma("unroll") for (int k = 0; k < 2; ++k) \
;         acc[ai][bj][m][n] = mma_step<I8>(Bt[n][k], At[m][k], acc[ai][bj][m][n]); __builtin_amdgcn_s_setprio(0); } while (0)
; #define PG8_WAIT_V(n) asm volatile("s_waitcnt vmcnt(" #n ")" ::: "memory")
; #define PG8_WAIT_L(n) asm volatile("s_waitcnt lgkmcnt(" #n ")" ::: "memory")
; #define PG8_BAR __builtin_amdgcn_s_barrier()
; #define PG8_SCHED __builtin_amdgcn_sched_barrier(0)
; template <class Prob, class Epi, bool I8 = false, bool ALIGN_EPI = true, bool SP2 = true>
; __device__ __forceinline__ void gemm_phase(LAS unsigned char* lds, int wave, const Prob& P, const Epi& E) {
;     ...
;             PG8_WAIT_V(8); PG8_WAIT_L(0); PG8_BAR; PG8_MMA(1, 0, At, B0); PG8_MMA(1, 1, At, B1); PG8_BAR; PG8_SCHED;
;             PG8_LDB(B0, 1, 0); PG8_LDB(B1, 1, 1); PG8_SCHED; PG8_LDA(At, 1, 0); PG8_STAGE(PG8_SA(0, 1), a2 + hstepA, voffA);
;             PG8_WAIT_V(8); PG8_WAIT_L(0); PG8_BAR; PG8_MMA(0, 0, At, B0); PG8_MMA(0, 1, At, B1); PG8_BAR; PG8_SCHED;
	s_waitcnt lgkmcnt(7)
	v_mfma_f32_16x16x32_f16 v[60:63], v[128:131], v[166:169], v[60:63]
	v_mfma_f32_16x16x32_f16 v[56:59], v[140:143], v[166:169], v[56:59]
	s_waitcnt lgkmcnt(5)
	v_mfma_f32_16x16x32_f16 v[52:55], v[128:131], v[174:177], v[52:55]
	v_mfma_f32_16x16x32_f16 v[48:51], v[140:143], v[174:177], v[48:51]
	s_waitcnt lgkmcnt(3)
	v_mfma_f32_16x16x32_f16 v[44:47], v[128:131], v[182:185], v[44:47]
	v_mfma_f32_16x16x32_f16 v[40:43], v[140:143], v[182:185], v[40:43]
	s_waitcnt lgkmcnt(1)
	v_mfma_f32_16x16x32_f16 v[36:39], v[128:131], v[190:193], v[36:39]
	v_mfma_f32_16x16x32_f16 v[32:35], v[140:143], v[190:193], v[32:35]
	v_mfma_f32_16x16x32_f16 v[60:63], v[132:135], v[170:173], v[60:63]
	v_mfma_f32_16x16x32_f16 v[56:59], v[144:147], v[170:173], v[56:59]
	v_mfma_f32_16x16x32_f16 v[52:55], v[132:135], v[178:181], v[52:55]
	v_mfma_f32_16x16x32_f16 v[48:51], v[144:147], v[178:181], v[48:51]
	v_mfma_f32_16x16x32_f16 v[44:47], v[132:135], v[186:189], v[44:47]
	v_mfma_f32_16x16x32_f16 v[40:43], v[144:147], v[186:189], v[40:43]
	s_waitcnt lgkmcnt(0)
	v_mfma_f32_16x16x32_f16 v[36:39], v[132:135], v[194:197], v[36:39]
	v_mfma_f32_16x16x32_f16 v[32:35], v[144:147], v[194:197], v[32:35]
	v_mfma_f32_16x16x32_f16 v[28:31], v[150:153], v[166:169], v[28:31]
	v_mfma_f32_16x16x32_f16 v[24:27], v[158:161], v[166:169], v[24:27]
	v_mfma_f32_16x16x32_f16 v[20:23], v[150:153], v[174:177], v[20:23]
	v_mfma_f32_16x16x32_f16 v[16:19], v[158:161], v[174:177], v[16:19]
	v_mfma_f32_16x16x32_f16 v[12:15], v[150:153], v[182:185], v[12:15]
	v_mfma_f32_16x16x32_f16 v[8:11], v[158:161], v[182:185], v[8:11]
	v_mfma_f32_16x16x32_f16 v[4:7], v[150:153], v[190:193], v[4:7]
	v_mfma_f32_16x16x32_f16 v[0:3], v[158:161], v[190:193], v[0:3]
	v_mfma_f32_16x16x32_f16 v[28:31], v[154:157], v[170:173], v[28:31]
	v_mfma_f32_16x16x32_f16 v[24:27], v[162:165], v[170:173], v[24:27]
	v_mfma_f32_16x16x32_f16 v[20:23], v[154:157], v[178:181], v[20:23]
	v_mfma_f32_16x16x32_f16 v[16:19], v[162:165], v[178:181], v[16:19]
	v_mfma_f32_16x16x32_f16 v[12:15], v[154:157], v[186:189], v[12:15]
	v_mfma_f32_16x16x32_f16 v[8:11], v[162:165], v[186:189], v[8:11]
	v_mfma_f32_16x16x32_f16 v[4:7], v[154:157], v[194:197], v[4:7]
	v_mfma_f32_16x16x32_f16 v[0:3], v[162:165], v[194:197], v[0:3]
	s_barrier
	v_add_u32_e32 v144, 0x18000, v139
	v_add_u32_e32 v162, 0x1c000, v139
	ds_read_b128 v[128:131], v144
	ds_read_b128 v[132:135], v144 offset:1024
	ds_read_b128 v[140:143], v144 offset:2048
	ds_read_b128 v[144:147], v144 offset:3072
	ds_read_b128 v[150:153], v162
	ds_read_b128 v[154:157], v162 offset:1024
	ds_read_b128 v[158:161], v162 offset:2048
	ds_read_b128 v[162:165], v162 offset:3072
	ds_read_b128 v[166:169], v149 offset:32768
	ds_read_b128 v[170:173], v149 offset:33792
	ds_read_b128 v[174:177], v149 offset:34816
	ds_read_b128 v[178:181], v149 offset:35840
	ds_read_b128 v[182:185], v149 offset:36864
	ds_read_b128 v[186:189], v149 offset:37888
	ds_read_b128 v[190:193], v149 offset:38912
	ds_read_b128 v[194:197], v149 offset:39936
	s_add_u32 s14, s56, 0x100000
	s_addc_u32 s15, s57, 0
	s_mov_b32 s6, m0
	s_mov_b32 m0, s68
	s_nop 0
	global_load_lds_dwordx4 v148, s[14:15]
	s_mov_b32 m0, s6
	s_nop 0
	s_mov_b32 s6, m0
	s_mov_b32 m0, s69
	s_nop 0
	global_load_lds_dwordx4 v137, s[14:15]
	s_mov_b32 m0, s6
	s_waitcnt vmcnt(8)
	s_waitcnt lgkmcnt(0)
	s_barrier
	s_waitcnt lgkmcnt(7)
	v_mfma_f32_16x16x32_f16 v[124:127], v[128:131], v[166:169], v[124:127]
	v_mfma_f32_16x16x32_f16 v[120:123], v[140:143], v[166:169], v[120:123]
	s_waitcnt lgkmcnt(5)
	v_mfma_f32_16x16x32_f16 v[116:119], v[128:131], v[174:177], v[116:119]
	v_mfma_f32_16x16x32_f16 v[112:115], v[140:143], v[174:177], v[112:115]
	s_waitcnt lgkmcnt(3)
	v_mfma_f32_16x16x32_f16 v[108:111], v[128:131], v[182:185], v[108:111]
	v_mfma_f32_16x16x32_f16 v[104:107], v[140:143], v[182:185], v[104:107]
	s_waitcnt lgkmcnt(1)
	v_mfma_f32_16x16x32_f16 v[100:103], v[128:131], v[190:193], v[100:103]
	v_mfma_f32_16x16x32_f16 v[96:99], v[140:143], v[190:193], v[96:99]
	v_mfma_f32_16x16x32_f16 v[124:127], v[132:135], v[170:173], v[124:127]
	v_mfma_f32_16x16x32_f16 v[120:123], v[144:147], v[170:173], v[120:123]
	v_mfma_f32_16x16x32_f16 v[116:119], v[132:135], v[178:181], v[116:119]
	v_mfma_f32_16x16x32_f16 v[112:115], v[144:147], v[178:181], v[112:115]
	v_mfma_f32_16x16x32_f16 v[108:111], v[132:135], v[186:189], v[108:111]
	v_mfma_f32_16x16x32_f16 v[104:107], v[144:147], v[186:189], v[104:107]
	s_waitcnt lgkmcnt(0)
	v_mfma_f32_16x16x32_f16 v[100:103], v[132:135], v[194:197], v[100:103]
	v_mfma_f32_16x16x32_f16 v[96:99], v[144:147], v[194:197], v[96:99]
	v_mfma_f32_16x16x32_f16 v[92:95], v[150:153], v[166:169], v[92:95]
	v_mfma_f32_16x16x32_f16 v[88:91], v[158:161], v[166:169], v[88:91]
	v_mfma_f32_16x16x32_f16 v[84:87], v[150:153], v[174:177], v[84:87]
	v_mfma_f32_16x16x32_f16 v[80:83], v[158:161], v[174:177], v[80:83]
	v_mfma_f32_16x16x32_f16 v[76:79], v[150:153], v[182:185], v[76:79]
	v_mfma_f32_16x16x32_f16 v[72:75], v[158:161], v[182:185], v[72:75]
	v_mfma_f32_16x16x32_f16 v[68:71], v[150:153], v[190:193], v[68:71]
	v_mfma_f32_16x16x32_f16 v[64:67], v[158:161], v[190:193], v[64:67]
	v_mfma_f32_16x16x32_f16 v[92:95], v[154:157], v[170:173], v[92:95]
	v_mfma_f32_16x16x32_f16 v[88:91], v[162:165], v[170:173], v[88:91]
	v_mfma_f32_16x16x32_f16 v[84:87], v[154:157], v[178:181], v[84:87]
	v_mfma_f32_16x16x32_f16 v[80:83], v[162:165], v[178:181], v[80:83]
	v_mfma_f32_16x16x32_f16 v[76:79], v[154:157], v[186:189], v[76:79]
	v_mfma_f32_16x16x32_f16 v[72:75], v[162:165], v[186:189], v[72:75]
	v_mfma_f32_16x16x32_f16 v[68:71], v[154:157], v[194:197], v[68:71]
	v_mfma_f32_16x16x32_f16 v[64:67], v[162:165], v[194:197], v[64:67]
	s_barrier
; #define PG8_STAGE(bufoff, gbase, voff) do { _Pragma("unroll") for (int _i = 0; _i < 2; ++_i) glds16_s((gbase), (voff)[_i], ldsb + (unsigned)((bufoff) + _i * 8192)); } while (0)
; #define PG8_LDA(dst, b, h) do { _Pragma("unroll") for (int m = 0; m < 4; ++m) _Pragma("unroll") for (int k = 0; k < 2; ++k) dst[m][k] = *(const LAS h16x8*)(lds + PG8_SA(b, h) + aoff + m * 2048 + k * 1024); } while (0)
; #define PG8_WAIT_V(n) asm volatile("s_waitcnt vmcnt(" #n ")" ::: "memory")
; #define PG8_WAIT_L(n) asm volatile("s_waitcnt lgkmcnt(" #n ")" ::: "memory")
; template <class Prob, class Epi, bool I8 = false, bool ALIGN_EPI = true, bool SP2 = true>
; __device__ __forceinline__ void gemm_phase(LAS unsigned char* lds, int wave, const Prob& P, const Epi& E) {
;     ...
;             PG8_LDA(At, 1, 1); PG8_STAGE(PG8_SB(1, 0), b3, voffB); PG8_STAGE(PG8_SB(1, 1), b3 + hstepB, voffB); PG8_STAGE(PG8_SA(1, 0), a3, voffA);
;             PG8_WAIT_V(8); PG8_WAIT_L(0); PG8_BAR; PG8_MMA(1, 0, At, B0); PG8_MMA(1, 1, At, B1); PG8_BAR; PG8_SCHED;
;             } else {
;             PG8_LDB(B0, 0, 0); PG8_SCHED; PG8_LDA(At, 0, 0); PG8_STAGE(PG8_SA(1, 1), a1 + hstepA, voffA);
;             PG8_WAIT_L(8); PG8_BAR; PG8_WAIT_L(0); PG8_MMA(0, 0, At, B0); PG8_BAR; PG8_SCHED;
;             PG8_LDB(B1, 0, 1); PG8_STAGE(PG8_SB(0, 0), b2, voffB);
;             PG8_BAR; PG8_WAIT_L(0); PG8_MMA(0, 1, At, B1); PG8_BAR;
;             PG8_LDA(At, 0, 1); PG8_STAGE(PG8_SA(0, 0), a2, voffA);
;             PG8_BAR; PG8_WAIT_L(0); PG8_MMA(1, 0, At, B0); PG8_BAR; PG8_SCHED;
;             PG8_STAGE(PG8_SB(0, 1), b2 + hstepB, voffB);
;             PG8_WAIT_V(6); PG8_BAR; PG8_MMA(1, 1, At, B1); PG8_BAR;
;             PG8_LDB(B0, 1, 0); PG8_SCHED; PG8_LDA(At, 1, 0); PG8_STAGE(PG8_SA(0, 1), a2 + hstepA, voffA);
;             PG8_WAIT_L(8); PG8_BAR; PG8_WAIT_L(0); PG8_MMA(0, 0, At, B0); PG8_BAR; PG8_SCHED;
;             PG8_LDB(B1, 1, 1); PG8_STAGE(PG8_SB(1, 0), b3, voffB);
;             PG8_BAR; PG8_WAIT_L(0); PG8_MMA(0, 1, At, B1); PG8_BAR;
;             PG8_LDA(At, 1, 1); PG8_STAGE(PG8_SA(1, 0), a3, voffA);
;             PG8_BAR; PG8_WAIT_L(0); PG8_MMA(1, 0, At, B0); PG8_BAR; PG8_SCHED;
;             PG8_STAGE(PG8_SB(1, 1), b3 + hstepB, voffB);
;             PG8_WAIT_V(6); PG8_BAR; PG8_MMA(1, 1, At, B1); PG8_BAR;
;             }
;         }
;         if constexpr (ALIGN_EPI) { if (wr == 0) PG8_BAR; }
	ds_read_b128 v[166:169], v149 offset:49152
	ds_read_b128 v[170:173], v149 offset:50176
	ds_read_b128 v[174:177], v149 offset:51200
	ds_read_b128 v[178:181], v149 offset:52224
	ds_read_b128 v[182:185], v149 offset:53248
	ds_read_b128 v[186:189], v149 offset:54272
	ds_read_b128 v[190:193], v149 offset:55296
	ds_read_b128 v[194:197], v149 offset:56320
	s_add_u32 s14, s44, 0x80
	s_addc_u32 s15, s45, 0
	s_mov_b32 s6, m0
	s_mov_b32 m0, s80
	s_nop 0
	global_load_lds_dwordx4 v136, s[14:15]
	s_mov_b32 m0, s6
	s_nop 0
	s_mov_b32 s6, m0
	s_mov_b32 m0, s81
	s_nop 0
	global_load_lds_dwordx4 v138, s[14:15]
	s_mov_b32 m0, s6
	s_add_u32 s14, s44, 0x104080
	s_addc_u32 s15, s45, 0
	s_mov_b32 s6, m0
	s_mov_b32 m0, s84
	s_nop 0
	global_load_lds_dwordx4 v136, s[14:15]
	s_mov_b32 m0, s6
	s_nop 0
	s_mov_b32 s6, m0
	s_mov_b32 m0, s85
	s_nop 0
	global_load_lds_dwordx4 v138, s[14:15]
	s_mov_b32 m0, s6
	s_nop 0
	s_mov_b32 s6, m0
	s_mov_b32 m0, s82
	s_nop 0
	global_load_lds_dwordx4 v148, s[40:41]
	s_mov_b32 m0, s6
	s_nop 0
	s_mov_b32 s6, m0
	s_mov_b32 m0, s83
	s_nop 0
	global_load_lds_dwordx4 v137, s[40:41]
	s_mov_b32 m0, s6
	s_waitcnt vmcnt(8)
	s_waitcnt lgkmcnt(0)
	s_barrier
	s_waitcnt lgkmcnt(7)
	v_mfma_f32_16x16x32_f16 v[60:63], v[128:131], v[166:169], v[60:63]
	v_mfma_f32_16x16x32_f16 v[56:59], v[140:143], v[166:169], v[56:59]
	s_waitcnt lgkmcnt(5)
	v_mfma_f32_16x16x32_f16 v[52:55], v[128:131], v[174:177], v[52:55]
	v_mfma_f32_16x16x32_f16 v[48:51], v[140:143], v[174:177], v[48:51]
	s_waitcnt lgkmcnt(3)
	v_mfma_f32_16x16x32_f16 v[44:47], v[128:131], v[182:185], v[44:47]
	v_mfma_f32_16x16x32_f16 v[40:43], v[140:143], v[182:185], v[40:43]
	s_waitcnt lgkmcnt(1)
	v_mfma_f32_16x16x32_f16 v[36:39], v[128:131], v[190:193], v[36:39]
	v_mfma_f32_16x16x32_f16 v[32:35], v[140:143], v[190:193], v[32:35]
	v_mfma_f32_16x16x32_f16 v[60:63], v[132:135], v[170:173], v[60:63]
	v_mfma_f32_16x16x32_f16 v[56:59], v[144:147], v[170:173], v[56:59]
	v_mfma_f32_16x16x32_f16 v[52:55], v[132:135], v[178:181], v[52:55]
	v_mfma_f32_16x16x32_f16 v[48:51], v[144:147], v[178:181], v[48:51]
	v_mfma_f32_16x16x32_f16 v[44:47], v[132:135], v[186:189], v[44:47]
	v_mfma_f32_16x16x32_f16 v[40:43], v[144:147], v[186:189], v[40:43]
	s_waitcnt lgkmcnt(0)
	v_mfma_f32_16x16x32_f16 v[36:39], v[132:135], v[194:197], v[36:39]
	v_mfma_f32_16x16x32_f16 v[32:35], v[144:147], v[194:197], v[32:35]
	v_mfma_f32_16x16x32_f16 v[28:31], v[150:153], v[166:169], v[28:31]
	v_mfma_f32_16x16x32_f16 v[24:27], v[158:161], v[166:169], v[24:27]
	v_mfma_f32_16x16x32_f16 v[20:23], v[150:153], v[174:177], v[20:23]
	v_mfma_f32_16x16x32_f16 v[16:19], v[158:161], v[174:177], v[16:19]
	v_mfma_f32_16x16x32_f16 v[12:15], v[150:153], v[182:185], v[12:15]
	v_mfma_f32_16x16x32_f16 v[8:11], v[158:161], v[182:185], v[8:11]
	v_mfma_f32_16x16x32_f16 v[4:7], v[150:153], v[190:193], v[4:7]
	v_mfma_f32_16x16x32_f16 v[0:3], v[158:161], v[190:193], v[0:3]
	v_mfma_f32_16x16x32_f16 v[28:31], v[154:157], v[170:173], v[28:31]
	v_mfma_f32_16x16x32_f16 v[24:27], v[162:165], v[170:173], v[24:27]
	v_mfma_f32_16x16x32_f16 v[20:23], v[154:157], v[178:181], v[20:23]
	v_mfma_f32_16x16x32_f16 v[16:19], v[162:165], v[178:181], v[16:19]
	v_mfma_f32_16x16x32_f16 v[12:15], v[154:157], v[186:189], v[12:15]
	v_mfma_f32_16x16x32_f16 v[8:11], v[162:165], v[186:189], v[8:11]
	v_mfma_f32_16x16x32_f16 v[4:7], v[154:157], v[194:197], v[4:7]
	v_mfma_f32_16x16x32_f16 v[0:3], v[162:165], v[194:197], v[0:3]
	s_barrier
	s_add_i32 s5, s5, 2
	s_add_u32 s17, s17, 0x100
	s_addc_u32 s4, s4, 0
	s_cmp_gt_u32 s5, 29
	s_mov_b64 s[14:15], s[38:39]
	s_cbranch_scc0 .LBB0_297
	s_and_b64 vcc, exec, s[28:29]
	s_cbranch_vccz .LBB0_300
	s_barrier

; __device__ __forceinline__ int mk_lane() { int l; asm volatile("v_mbcnt_lo_u32_b32 %0, -1, 0\n\tv_mbcnt_hi_u32_b32 %0, -1, %0" : "=v"(l)); return l; }
; #define PG8_STAGE(bufoff, gbase, voff) do { _Pragma("unroll") for (int _i = 0; _i < 2; ++_i) glds16_s((gbase), (voff)[_i], ldsb + (unsigned)((bufoff) + _i * 8192)); } while (0)
; #define PG8_BAR __builtin_amdgcn_s_barrier()
;     __device__ bool next(int i, Unit& u) const { return S.next(i, u); }
;     __device__ unsigned a_rowoff(int R) const { const int r = upmap ? (128 * (R >> 6) + 8 * (R & 15) + ((R >> 4) & 3)) : R; return (unsigned)r * (unsigned)lda * 2u; }
; template <class Prob, class Epi, bool I8 = false, bool ALIGN_EPI = true, bool SP2 = true>
; __device__ __forceinline__ void gemm_phase(LAS unsigned char* lds, int wave, const Prob& P, const Epi& E) {
;     const int tid_ = wave * 64 + mk_lane();
;     const int tid = tid_, wid = __builtin_amdgcn_readfirstlane(tid >> 6), lane = tid & 63, wr = wid >> 2, wc = wid & 3, fr = lane & 15, fq = lane >> 4;
;     const int K = P.K, nt = K / BK;
;     unsigned voffA[2], voffB[2];
; #pragma unroll
;     for (int i = 0; i < 2; ++i) { int R, C; stage_rc(tid * 16 + i * 8192, R, C); const int Rb = (R & ~31) + perm32(R & 31);
;         voffA[i] = P.a_rowoff(R) + (unsigned)C * 2u; voffB[i] = P.b_rowoff(Rb) + (unsigned)C * 2u; }
;     const size_t kstep = (size_t)(BK * 2);
;     const size_t hstepA = P.a_hstep(), hstepB = P.b_hstep();
;     const unsigned ldsw = (unsigned)wid * 1024u;
;     const unsigned ldsb = (unsigned)(size_t)lds + ldsw;
;     const int aoff = lds_byte(wr * 64 + fr, fq * 8), boff = lds_byte(wc * 32 + fr, fq * 8);
;     ...
;     Unit cur, nxt; int ui = 0;
;     if (!P.next(0, cur)) return;
;     Acc acc;
; #pragma unroll
;     for (int a = 0; a < 2; ++a)
; #pragma unroll
;         for (int b = 0; b < 2; ++b)
; #pragma unroll
;             for (int m = 0; m < 4; ++m)
; #pragma unroll
;                 for (int n = 0; n < 2; ++n) acc[a][b][m][n] = (f32x4){0.f, 0.f, 0.f, 0.f};
;     h16x8 At[4][2], B0[2][2], B1[2][2];
;     const char* cA = P.a_tile(cur); const char* cB = P.b_tile(cur);
;     if constexpr (SP2) {
;         PG8_STAGE(PG8_SB(0, 0), cB, voffB); PG8_STAGE(PG8_SB(0, 1), cB + hstepB, voffB); PG8_STAGE(PG8_SA(0, 0), cA, voffA); PG8_STAGE(PG8_SA(0, 1), cA + hstepA, voffA);
;         if (wr == 1) PG8_BAR;
.LBB0_455:
	v_readlane_b32 s0, v254, 42
	v_readlane_b32 s4, v254, 43
	s_waitcnt lgkmcnt(0)
	s_barrier
	v_mbcnt_lo_u32_b32 v0, -1, 0
	v_mbcnt_hi_u32_b32 v0, -1, v0
	v_readlane_b32 s5, v254, 44
	v_add_u32_e32 v1, s0, v0
	s_and_b64 vcc, exec, s[4:5]
	v_readfirstlane_b32 s0, v1
	s_cbranch_vccz .LBB0_471
	v_ashrrev_i32_e32 v3, 31, v1
	v_lshrrev_b32_e32 v3, 26, v3
	v_lshlrev_b32_e32 v2, 4, v1
	v_add_u32_e32 v3, v1, v3
	v_bfe_i32 v1, v1, 27, 1
	v_lshrrev_b32_e32 v1, 22, v1
	v_add_u32_e32 v1, v2, v1
	v_and_b32_e32 v1, 0xfffffc00, v1
	v_sub_u32_e32 v1, v2, v1
	v_lshrrev_b32_e32 v4, 4, v1
	v_bitop3_b32 v1, v4, v1, 32 bitop3:0x6c
	v_ashrrev_i32_e32 v5, 31, v1
	v_readlane_b32 s1, v253, 52
	v_ashrrev_i32_e32 v3, 6, v3
	v_lshrrev_b32_e32 v5, 26, v5
	s_add_u32 s1, s30, s1
	v_lshlrev_b32_e32 v4, 3, v3
	v_add_u32_e32 v5, v1, v5
	s_addc_u32 s4, s31, 0
	v_and_b32_e32 v4, -16, v4
	v_ashrrev_i32_e32 v6, 6, v5
	v_and_b32_e32 v5, 0xc0, v5
	s_add_u32 s2, s1, 0x9a00000
	v_add_u32_e32 v4, v6, v4
	v_sub_u32_e32 v1, v1, v5
	v_mov_b32_e32 v8, 1
	s_addc_u32 s19, s4, 0
	v_lshlrev_b32_e32 v3, 5, v3
	v_ashrrev_i16_sdwa v1, v8, sext(v1) dst_sel:DWORD dst_unused:UNUSED_PAD src0_sel:DWORD src1_sel:BYTE_0
	v_lshlrev_b32_e32 v5, 1, v4
	v_lshrrev_b32_e32 v7, 2, v4
	v_and_b32_e32 v6, 3, v6
	s_mov_b32 s4, 0xfffe0
	v_and_b32_e32 v3, 32, v3
	v_bfe_i32 v1, v1, 0, 16
	v_and_b32_e32 v5, 24, v5
	v_and_b32_e32 v7, 4, v7
	v_and_or_b32 v6, v4, s4, v6
	v_or3_b32 v5, v6, v7, v5
	v_add_lshl_u32 v1, v3, v1, 1
	v_lshl_add_u32 v142, v4, 12, v1
	v_lshl_add_u32 v143, v5, 12, v1
	v_add_u32_e32 v1, 0x2000, v2
	v_ashrrev_i32_e32 v2, 31, v1
	v_lshrrev_b32_e32 v2, 22, v2
	v_add_u32_e32 v2, v1, v2
	v_ashrrev_i32_e32 v2, 10, v2
	v_mul_i32_i24_e32 v3, 0x400, v2
	v_sub_u32_e32 v1, v1, v3
	v_lshrrev_b32_e32 v3, 4, v1
	v_bitop3_b32 v1, v3, v1, 32 bitop3:0x6c
	v_ashrrev_i32_e32 v4, 31, v1
	v_lshrrev_b32_e32 v4, 26, v4
	v_lshlrev_b32_e32 v3, 3, v2
	v_add_u32_e32 v4, v1, v4
	v_and_b32_e32 v3, -16, v3
	v_ashrrev_i32_e32 v5, 6, v4
	v_add_u32_e32 v3, v5, v3
	v_and_b32_e32 v5, 3, v5
	v_and_b32_e32 v4, 0xc0, v4
	v_and_or_b32 v5, v3, s4, v5
	s_ashr_i32 s4, s0, 6
	v_sub_u32_e32 v1, v1, v4
	s_lshl_b32 s5, s4, 10
	s_ashr_i32 s1, s0, 8
	v_lshlrev_b32_e32 v2, 5, v2
	v_ashrrev_i16_sdwa v1, v8, sext(v1) dst_sel:DWORD dst_unused:UNUSED_PAD src0_sel:DWORD src1_sel:BYTE_0
	v_lshlrev_b32_e32 v4, 1, v3
	v_lshrrev_b32_e32 v6, 2, v3
	s_add_i32 s50, s5, 0
	v_readlane_b32 s6, v252, 32
	v_and_b32_e32 v2, 32, v2
	v_bfe_i32 v1, v1, 0, 16
	v_and_b32_e32 v4, 24, v4
	v_and_b32_e32 v6, 4, v6
	v_readlane_b32 s7, v252, 33
	s_add_u32 s40, s2, s6
	v_or3_b32 v4, v5, v6, v4
	v_add_lshl_u32 v1, v2, v1, 1
	s_addc_u32 s41, s19, s7
	s_add_i32 s51, s50, 0x10000
	s_mov_b32 s5, m0
	s_mov_b32 m0, s51
	s_nop 0
	global_load_lds_dwordx4 v143, s[40:41]
	s_mov_b32 m0, s5
	s_add_i32 s56, s50, 0x12000
	v_lshl_add_u32 v145, v4, 12, v1
	s_mov_b32 s5, m0
	s_mov_b32 m0, s56
	s_nop 0
	global_load_lds_dwordx4 v145, s[40:41]
	s_mov_b32 m0, s5
	s_add_u32 s14, s40, 0x80000
	s_addc_u32 s15, s41, 0
	s_add_i32 s57, s50, 0x14000
	s_mov_b32 s5, m0
	s_mov_b32 m0, s57
	s_nop 0
	global_load_lds_dwordx4 v143, s[14:15]
	s_mov_b32 m0, s5
	s_add_i32 s60, s50, 0x16000
	v_readlane_b32 s6, v252, 38
	s_mov_b32 s5, m0
	s_mov_b32 m0, s60
	s_nop 0
	global_load_lds_dwordx4 v145, s[14:15]
	s_mov_b32 m0, s5
	v_readlane_b32 s7, v252, 39
	s_add_u32 s44, s42, s6
	s_addc_u32 s45, s43, s7
	s_mov_b32 s5, m0
	s_mov_b32 m0, s50
	s_nop 0
	global_load_lds_dwordx4 v142, s[44:45]
	s_mov_b32 m0, s5
	s_add_i32 s61, s50, 0x2000
	v_lshl_add_u32 v144, v3, 12, v1
	s_mov_b32 s5, m0
	s_mov_b32 m0, s61
	s_nop 0
	global_load_lds_dwordx4 v144, s[44:45]
	s_mov_b32 m0, s5
	s_add_u32 s14, s44, 0x80000
	s_addc_u32 s15, s45, 0
	s_add_i32 s62, s50, 0x4000
	s_mov_b32 s5, m0
	s_mov_b32 m0, s62
	s_nop 0
	global_load_lds_dwordx4 v142, s[14:15]
	s_mov_b32 m0, s5
	s_add_i32 s63, s50, 0x6000
	s_mov_b32 s5, m0
	s_mov_b32 m0, s63
	s_nop 0
	global_load_lds_dwordx4 v144, s[14:15]
	s_mov_b32 m0, s5
	s_cmp_eq_u32 s1, 1
	s_cselect_b64 s[14:15], -1, 0
	s_cmp_lg_u32 s1, 1
	s_cbranch_scc1 .LBB0_458
	s_barrier
	s_setprio 1

; #define PG8_STAGE(bufoff, gbase, voff) do { _Pragma("unroll") for (int _i = 0; _i < 2; ++_i) glds16_s((gbase), (voff)[_i], ldsb + (unsigned)((bufoff) + _i * 8192)); } while (0)
; #define PG8_LDA(dst, b, h) do { _Pragma("unroll") for (int m = 0; m < 4; ++m) _Pragma("unroll") for (int k = 0; k < 2; ++k) dst[m][k] = *(const LAS h16x8*)(lds + PG8_SA(b, h) + aoff + m * 2048 + k * 1024); } while (0)
; #define PG8_LDB(dst, b, h) do { _Pragma("unroll") for (int n = 0; n < 2; ++n) _Pragma("unroll") for (int k = 0; k < 2; ++k) dst[n][k] = *(const LAS h16x8*)(lds + PG8_SB(b, h) + boff + n * 2048 + k * 1024); } while (0)
; #define PG8_MMA(ai, bj, At, Bt) do { __builtin_amdgcn_s_setprio(1); _Pragma("unroll") for (int m = 0; m < 4; ++m) _Pragma("unroll") for (int n = 0; n < 2; ++n) _Pragma("unroll") for (int k = 0; k < 2; ++k) \
;         acc[ai][bj][m][n] = mma_step<I8>(Bt[n][k], At[m][k], acc[ai][bj][m][n]); __builtin_amdgcn_s_setprio(0); } while (0)
; #define PG8_WAIT_V(n) asm volatile("s_waitcnt vmcnt(" #n ")" ::: "memory")
; #define PG8_WAIT_L(n) asm volatile("s_waitcnt lgkmcnt(" #n ")" ::: "memory")
; #define PG8_BAR __builtin_amdgcn_s_barrier()
; #define PG8_SCHED __builtin_amdgcn_sched_barrier(0)
; template <class Prob, class Epi, bool I8 = false, bool ALIGN_EPI = true, bool SP2 = true>
; __device__ __forceinline__ void gemm_phase(LAS unsigned char* lds, int wave, const Prob& P, const Epi& E) {
;     ...
;             PG8_LDB(B0, 0, 0); PG8_LDB(B1, 0, 1); PG8_SCHED; PG8_LDA(At, 0, 0); PG8_STAGE(PG8_SA(1, 1), a1 + hstepA, voffA);
;             PG8_WAIT_V(8); PG8_WAIT_L(0); PG8_BAR; PG8_MMA(0, 0, At, B0); PG8_MMA(0, 1, At, B1); PG8_BAR; PG8_SCHED;
;             PG8_LDA(At, 0, 1); PG8_STAGE(PG8_SB(0, 0), b2, voffB); PG8_STAGE(PG8_SB(0, 1), b2 + hstepB, voffB); PG8_STAGE(PG8_SA(0, 0), a2, voffA);
;             PG8_WAIT_V(8); PG8_WAIT_L(0); PG8_BAR; PG8_MMA(1, 0, At, B0); PG8_MMA(1, 1, At, B1); PG8_BAR; PG8_SCHED;
.Lpeel_464:
	v_add_u32_e32 v140, 0x10000, v146
	ds_read_b128 v[128:131], v140
	ds_read_b128 v[132:135], v140 offset:1024
	ds_read_b128 v[136:139], v140 offset:2048
	ds_read_b128 v[148:151], v140 offset:3072
	v_add_u32_e32 v140, 0x14000, v146
	ds_read_b128 v[152:155], v140
	ds_read_b128 v[156:159], v140 offset:1024
	ds_read_b128 v[160:163], v140 offset:2048
	ds_read_b128 v[164:167], v140 offset:3072
	s_cmp_eq_u32 s1, 28
	s_cselect_b32 s48, s83, s85
	s_cselect_b32 s49, s27, s86
	s_cselect_b32 s46, s84, s87
	s_cselect_b32 s47, s23, s0
	s_add_u32 s44, s48, 0x80
	s_addc_u32 s45, s49, 0
	ds_read_b128 v[168:171], v147
	ds_read_b128 v[172:175], v147 offset:1024
	ds_read_b128 v[176:179], v147 offset:2048
	ds_read_b128 v[180:183], v147 offset:3072
	ds_read_b128 v[184:187], v147 offset:4096
	ds_read_b128 v[188:191], v147 offset:5120
	ds_read_b128 v[192:195], v147 offset:6144
	ds_read_b128 v[196:199], v147 offset:7168
	s_mov_b32 s4, m0
	s_mov_b32 m0, s77
	s_nop 0
	global_load_lds_dwordx4 v142, s[40:41]
	s_mov_b32 m0, s4
	s_nop 0
	s_mov_b32 s4, m0
	s_mov_b32 m0, s79
	s_nop 0
	global_load_lds_dwordx4 v144, s[40:41]
	s_mov_b32 m0, s4
	s_waitcnt vmcnt(8)
	s_waitcnt lgkmcnt(0)
	s_barrier
	s_waitcnt lgkmcnt(7)
	v_mfma_f32_16x16x32_f16 v[124:127], v[128:131], v[168:171], 0
	v_mfma_f32_16x16x32_f16 v[120:123], v[136:139], v[168:171], 0
	s_waitcnt lgkmcnt(5)
	v_mfma_f32_16x16x32_f16 v[116:119], v[128:131], v[176:179], 0
	v_mfma_f32_16x16x32_f16 v[112:115], v[136:139], v[176:179], 0
	s_waitcnt lgkmcnt(3)
	v_mfma_f32_16x16x32_f16 v[108:111], v[128:131], v[184:187], 0
	v_mfma_f32_16x16x32_f16 v[104:107], v[136:139], v[184:187], 0
	s_waitcnt lgkmcnt(1)
	v_mfma_f32_16x16x32_f16 v[100:103], v[128:131], v[192:195], 0
	v_mfma_f32_16x16x32_f16 v[96:99], v[136:139], v[192:195], 0
	v_mfma_f32_16x16x32_f16 v[124:127], v[132:135], v[172:175], v[124:127]
	v_mfma_f32_16x16x32_f16 v[120:123], v[148:151], v[172:175], v[120:123]
	v_mfma_f32_16x16x32_f16 v[116:119], v[132:135], v[180:183], v[116:119]
	v_mfma_f32_16x16x32_f16 v[112:115], v[148:151], v[180:183], v[112:115]
	v_mfma_f32_16x16x32_f16 v[108:111], v[132:135], v[188:191], v[108:111]
	v_mfma_f32_16x16x32_f16 v[104:107], v[148:151], v[188:191], v[104:107]
	s_waitcnt lgkmcnt(0)
	v_mfma_f32_16x16x32_f16 v[100:103], v[132:135], v[196:199], v[100:103]
	v_mfma_f32_16x16x32_f16 v[96:99], v[148:151], v[196:199], v[96:99]
	v_mfma_f32_16x16x32_f16 v[64:67], v[152:155], v[168:171], 0
	v_mfma_f32_16x16x32_f16 v[56:59], v[160:163], v[168:171], 0
	v_mfma_f32_16x16x32_f16 v[52:55], v[152:155], v[176:179], 0
	v_mfma_f32_16x16x32_f16 v[48:51], v[160:163], v[176:179], 0
	v_mfma_f32_16x16x32_f16 v[44:47], v[152:155], v[184:187], 0
	v_mfma_f32_16x16x32_f16 v[40:43], v[160:163], v[184:187], 0
	v_mfma_f32_16x16x32_f16 v[36:39], v[152:155], v[192:195], 0
	v_mfma_f32_16x16x32_f16 v[32:35], v[160:163], v[192:195], 0
	v_mfma_f32_16x16x32_f16 v[64:67], v[156:159], v[172:175], v[64:67]
	v_mfma_f32_16x16x32_f16 v[56:59], v[164:167], v[172:175], v[56:59]
	v_mfma_f32_16x16x32_f16 v[52:55], v[156:159], v[180:183], v[52:55]
	v_mfma_f32_16x16x32_f16 v[48:51], v[164:167], v[180:183], v[48:51]
	v_mfma_f32_16x16x32_f16 v[44:47], v[156:159], v[188:191], v[44:47]
	v_mfma_f32_16x16x32_f16 v[40:43], v[164:167], v[188:191], v[40:43]
	v_mfma_f32_16x16x32_f16 v[36:39], v[156:159], v[196:199], v[36:39]
	v_mfma_f32_16x16x32_f16 v[32:35], v[164:167], v[196:199], v[32:35]
	s_barrier
	ds_read_b128 v[168:171], v147 offset:16384
	ds_read_b128 v[172:175], v147 offset:17408
	ds_read_b128 v[176:179], v147 offset:18432
	ds_read_b128 v[180:183], v147 offset:19456
	ds_read_b128 v[184:187], v147 offset:20480
	ds_read_b128 v[188:191], v147 offset:21504
	ds_read_b128 v[192:195], v147 offset:22528
	ds_read_b128 v[196:199], v147 offset:23552
	s_mov_b32 s4, m0
	s_mov_b32 m0, s51
	s_nop 0
	global_load_lds_dwordx4 v143, s[46:47]
	s_mov_b32 m0, s4
	s_nop 0
	s_mov_b32 s4, m0
	s_mov_b32 m0, s56
	s_nop 0
	global_load_lds_dwordx4 v145, s[46:47]
	s_mov_b32 m0, s4
	s_add_u32 s4, s46, 0x80000
	s_addc_u32 s5, s47, 0
	s_mov_b32 s6, m0
	s_mov_b32 m0, s57
	s_nop 0
	global_load_lds_dwordx4 v143, s[4:5]
	s_mov_b32 m0, s6
	s_nop 0
	s_mov_b32 s6, m0
	s_mov_b32 m0, s60
	s_nop 0
	global_load_lds_dwordx4 v145, s[4:5]
	s_mov_b32 m0, s6
	s_mov_b32 s4, m0
	s_mov_b32 m0, s50
	s_nop 0
	global_load_lds_dwordx4 v142, s[48:49]
	s_mov_b32 m0, s4
	s_nop 0
	s_mov_b32 s4, m0
	s_mov_b32 m0, s61
	s_nop 0
	global_load_lds_dwordx4 v144, s[48:49]
	s_mov_b32 m0, s4
	s_waitcnt vmcnt(8)
	s_waitcnt lgkmcnt(0)
	s_barrier
	s_waitcnt lgkmcnt(7)
	v_mfma_f32_16x16x32_f16 v[92:95], v[128:131], v[168:171], 0
	v_mfma_f32_16x16x32_f16 v[88:91], v[136:139], v[168:171], 0
	s_waitcnt lgkmcnt(5)
	v_mfma_f32_16x16x32_f16 v[84:87], v[128:131], v[176:179], 0
	v_mfma_f32_16x16x32_f16 v[80:83], v[136:139], v[176:179], 0
	s_waitcnt lgkmcnt(3)
	v_mfma_f32_16x16x32_f16 v[76:79], v[128:131], v[184:187], 0
	v_mfma_f32_16x16x32_f16 v[72:75], v[136:139], v[184:187], 0
	s_waitcnt lgkmcnt(1)
	v_mfma_f32_16x16x32_f16 v[68:71], v[128:131], v[192:195], 0
	v_mfma_f32_16x16x32_f16 v[60:63], v[136:139], v[192:195], 0
	v_mfma_f32_16x16x32_f16 v[92:95], v[132:135], v[172:175], v[92:95]
	v_mfma_f32_16x16x32_f16 v[88:91], v[148:151], v[172:175], v[88:91]
	v_mfma_f32_16x16x32_f16 v[84:87], v[132:135], v[180:183], v[84:87]
	v_mfma_f32_16x16x32_f16 v[80:83], v[148:151], v[180:183], v[80:83]
	v_mfma_f32_16x16x32_f16 v[76:79], v[132:135], v[188:191], v[76:79]
	v_mfma_f32_16x16x32_f16 v[72:75], v[148:151], v[188:191], v[72:75]
	s_waitcnt lgkmcnt(0)
	v_mfma_f32_16x16x32_f16 v[68:71], v[132:135], v[196:199], v[68:71]
	v_mfma_f32_16x16x32_f16 v[60:63], v[148:151], v[196:199], v[60:63]
	v_mfma_f32_16x16x32_f16 v[28:31], v[152:155], v[168:171], 0
	v_mfma_f32_16x16x32_f16 v[24:27], v[160:163], v[168:171], 0
	v_mfma_f32_16x16x32_f16 v[20:23], v[152:155], v[176:179], 0
	v_mfma_f32_16x16x32_f16 v[16:19], v[160:163], v[176:179], 0
	v_mfma_f32_16x16x32_f16 v[12:15], v[152:155], v[184:187], 0
	v_mfma_f32_16x16x32_f16 v[8:11], v[160:163], v[184:187], 0
	v_mfma_f32_16x16x32_f16 v[4:7], v[152:155], v[192:195], 0
	v_mfma_f32_16x16x32_f16 v[0:3], v[160:163], v[192:195], 0
	v_mfma_f32_16x16x32_f16 v[28:31], v[156:159], v[172:175], v[28:31]
	v_mfma_f32_16x16x32_f16 v[24:27], v[164:167], v[172:175], v[24:27]
	v_mfma_f32_16x16x32_f16 v[20:23], v[156:159], v[180:183], v[20:23]
	v_mfma_f32_16x16x32_f16 v[16:19], v[164:167], v[180:183], v[16:19]
	v_mfma_f32_16x16x32_f16 v[12:15], v[156:159], v[188:191], v[12:15]
	v_mfma_f32_16x16x32_f16 v[8:11], v[164:167], v[188:191], v[8:11]
	v_mfma_f32_16x16x32_f16 v[4:7], v[156:159], v[196:199], v[4:7]
	v_mfma_f32_16x16x32_f16 v[0:3], v[164:167], v[196:199], v[0:3]
	s_barrier
; #define PG8_STAGE(bufoff, gbase, voff) do { _Pragma("unroll") for (int _i = 0; _i < 2; ++_i) glds16_s((gbase), (voff)[_i], ldsb + (unsigned)((bufoff) + _i * 8192)); } while (0)
; #define PG8_LDA(dst, b, h) do { _Pragma("unroll") for (int m = 0; m < 4; ++m) _Pragma("unroll") for (int k = 0; k < 2; ++k) dst[m][k] = *(const LAS h16x8*)(lds + PG8_SA(b, h) + aoff + m * 2048 + k * 1024); } while (0)
; #define PG8_LDB(dst, b, h) do { _Pragma("unroll") for (int n = 0; n < 2; ++n) _Pragma("unroll") for (int k = 0; k < 2; ++k) dst[n][k] = *(const LAS h16x8*)(lds + PG8_SB(b, h) + boff + n * 2048 + k * 1024); } while (0)
; #define PG8_MMA(ai, bj, At, Bt) do { __builtin_amdgcn_s_setprio(1); _Pragma("unroll") for (int m = 0; m < 4; ++m) _Pragma("unroll") for (int n = 0; n < 2; ++n) _Pragma("unroll") for (int k = 0; k < 2; ++k) \
;         acc[ai][bj][m][n] = mma_step<I8>(Bt[n][k], At[m][k], acc[ai][bj][m][n]); __builtin_amdgcn_s_setprio(0); } while (0)
; #define PG8_WAIT_V(n) asm volatile("s_waitcnt vmcnt(" #n ")" ::: "memory")
; #define PG8_WAIT_L(n) asm volatile("s_waitcnt lgkmcnt(" #n ")" ::: "memory")
; #define PG8_BAR __builtin_amdgcn_s_barrier()
; #define PG8_SCHED __builtin_amdgcn_sched_barrier(0)
; template <class Prob, class Epi, bool I8 = false, bool ALIGN_EPI = true, bool SP2 = true>
; __device__ __forceinline__ void gemm_phase(LAS unsigned char* lds, int wave, const Prob& P, const Epi& E) {
;     ...
;             PG8_LDB(B0, 1, 0); PG8_LDB(B1, 1, 1); PG8_SCHED; PG8_LDA(At, 1, 0); PG8_STAGE(PG8_SA(0, 1), a2 + hstepA, voffA);
;             PG8_WAIT_V(8); PG8_WAIT_L(0); PG8_BAR; PG8_MMA(0, 0, At, B0); PG8_MMA(0, 1, At, B1); PG8_BAR; PG8_SCHED;
;             PG8_LDA(At, 1, 1); PG8_STAGE(PG8_SB(1, 0), b3, voffB); PG8_STAGE(PG8_SB(1, 1), b3 + hstepB, voffB); PG8_STAGE(PG8_SA(1, 0), a3, voffA);
;             PG8_WAIT_V(8); PG8_WAIT_L(0); PG8_BAR; PG8_MMA(1, 0, At, B0); PG8_MMA(1, 1, At, B1); PG8_BAR; PG8_SCHED;
	v_add_u32_e32 v140, 0x18000, v146
	ds_read_b128 v[128:131], v140
	ds_read_b128 v[132:135], v140 offset:1024
	ds_read_b128 v[136:139], v140 offset:2048
	ds_read_b128 v[148:151], v140 offset:3072
	v_add_u32_e32 v140, 0x1c000, v146
	ds_read_b128 v[152:155], v140
	ds_read_b128 v[156:159], v140 offset:1024
	ds_read_b128 v[160:163], v140 offset:2048
	ds_read_b128 v[164:167], v140 offset:3072
	ds_read_b128 v[168:171], v147 offset:32768
	ds_read_b128 v[172:175], v147 offset:33792
	ds_read_b128 v[176:179], v147 offset:34816
	ds_read_b128 v[180:183], v147 offset:35840
	ds_read_b128 v[184:187], v147 offset:36864
	ds_read_b128 v[188:191], v147 offset:37888
	ds_read_b128 v[192:195], v147 offset:38912
	ds_read_b128 v[196:199], v147 offset:39936
	s_add_u32 s4, s48, 0x80000
	s_addc_u32 s5, s49, 0
	s_mov_b32 s6, m0
	s_mov_b32 m0, s62
	s_nop 0
	global_load_lds_dwordx4 v142, s[4:5]
	s_mov_b32 m0, s6
	s_nop 0
	s_mov_b32 s6, m0
	s_mov_b32 m0, s63
	s_nop 0
	global_load_lds_dwordx4 v144, s[4:5]
	s_mov_b32 m0, s6
	s_waitcnt vmcnt(8)
	s_waitcnt lgkmcnt(0)
	s_barrier
	s_waitcnt lgkmcnt(7)
	v_mfma_f32_16x16x32_f16 v[124:127], v[128:131], v[168:171], v[124:127]
	v_mfma_f32_16x16x32_f16 v[120:123], v[136:139], v[168:171], v[120:123]
	s_waitcnt lgkmcnt(5)
	v_mfma_f32_16x16x32_f16 v[116:119], v[128:131], v[176:179], v[116:119]
	v_mfma_f32_16x16x32_f16 v[112:115], v[136:139], v[176:179], v[112:115]
	s_waitcnt lgkmcnt(3)
	v_mfma_f32_16x16x32_f16 v[108:111], v[128:131], v[184:187], v[108:111]
	v_mfma_f32_16x16x32_f16 v[104:107], v[136:139], v[184:187], v[104:107]
	s_waitcnt lgkmcnt(1)
	v_mfma_f32_16x16x32_f16 v[100:103], v[128:131], v[192:195], v[100:103]
	v_mfma_f32_16x16x32_f16 v[96:99], v[136:139], v[192:195], v[96:99]
	v_mfma_f32_16x16x32_f16 v[124:127], v[132:135], v[172:175], v[124:127]
	v_mfma_f32_16x16x32_f16 v[120:123], v[148:151], v[172:175], v[120:123]
	v_mfma_f32_16x16x32_f16 v[116:119], v[132:135], v[180:183], v[116:119]
	v_mfma_f32_16x16x32_f16 v[112:115], v[148:151], v[180:183], v[112:115]
	v_mfma_f32_16x16x32_f16 v[108:111], v[132:135], v[188:191], v[108:111]
	v_mfma_f32_16x16x32_f16 v[104:107], v[148:151], v[188:191], v[104:107]
	s_waitcnt lgkmcnt(0)
	v_mfma_f32_16x16x32_f16 v[100:103], v[132:135], v[196:199], v[100:103]
	v_mfma_f32_16x16x32_f16 v[96:99], v[148:151], v[196:199], v[96:99]
	v_mfma_f32_16x16x32_f16 v[64:67], v[152:155], v[168:171], v[64:67]
	v_mfma_f32_16x16x32_f16 v[56:59], v[160:163], v[168:171], v[56:59]
	v_mfma_f32_16x16x32_f16 v[52:55], v[152:155], v[176:179], v[52:55]
	v_mfma_f32_16x16x32_f16 v[48:51], v[160:163], v[176:179], v[48:51]
	v_mfma_f32_16x16x32_f16 v[44:47], v[152:155], v[184:187], v[44:47]
	v_mfma_f32_16x16x32_f16 v[40:43], v[160:163], v[184:187], v[40:43]
	v_mfma_f32_16x16x32_f16 v[36:39], v[152:155], v[192:195], v[36:39]
	v_mfma_f32_16x16x32_f16 v[32:35], v[160:163], v[192:195], v[32:35]
	v_mfma_f32_16x16x32_f16 v[64:67], v[156:159], v[172:175], v[64:67]
	v_mfma_f32_16x16x32_f16 v[56:59], v[164:167], v[172:175], v[56:59]
	v_mfma_f32_16x16x32_f16 v[52:55], v[156:159], v[180:183], v[52:55]
	v_mfma_f32_16x16x32_f16 v[48:51], v[164:167], v[180:183], v[48:51]
	v_mfma_f32_16x16x32_f16 v[44:47], v[156:159], v[188:191], v[44:47]
	v_mfma_f32_16x16x32_f16 v[40:43], v[164:167], v[188:191], v[40:43]
	v_mfma_f32_16x16x32_f16 v[36:39], v[156:159], v[196:199], v[36:39]
	v_mfma_f32_16x16x32_f16 v[32:35], v[164:167], v[196:199], v[32:35]
	s_barrier
	ds_read_b128 v[168:171], v147 offset:49152
	ds_read_b128 v[172:175], v147 offset:50176
	ds_read_b128 v[176:179], v147 offset:51200
	ds_read_b128 v[180:183], v147 offset:52224
	ds_read_b128 v[184:187], v147 offset:53248
	ds_read_b128 v[188:191], v147 offset:54272
	ds_read_b128 v[192:195], v147 offset:55296
	ds_read_b128 v[196:199], v147 offset:56320
	s_add_u32 s4, s46, 0x80
	s_addc_u32 s5, s47, 0
	s_mov_b32 s6, m0
	s_mov_b32 m0, s69
	s_nop 0
	global_load_lds_dwordx4 v143, s[4:5]
	s_mov_b32 m0, s6
	s_nop 0
	s_mov_b32 s6, m0
	s_mov_b32 m0, s72
	s_nop 0
	global_load_lds_dwordx4 v145, s[4:5]
	s_mov_b32 m0, s6
	s_add_u32 s4, s46, 0x80080
	s_addc_u32 s5, s47, 0
	s_mov_b32 s6, m0
	s_mov_b32 m0, s75
	s_nop 0
	global_load_lds_dwordx4 v143, s[4:5]
	s_mov_b32 m0, s6
	s_nop 0
	s_mov_b32 s6, m0
	s_mov_b32 m0, s76
	s_nop 0
	global_load_lds_dwordx4 v145, s[4:5]
	s_mov_b32 m0, s6
	s_mov_b32 s4, m0
	s_mov_b32 m0, s73
	s_nop 0
	global_load_lds_dwordx4 v142, s[44:45]
	s_mov_b32 m0, s4
	s_nop 0
	s_mov_b32 s4, m0
	s_mov_b32 m0, s74
	s_nop 0
	global_load_lds_dwordx4 v144, s[44:45]
	s_mov_b32 m0, s4
	s_waitcnt vmcnt(8)
	s_waitcnt lgkmcnt(0)
	s_barrier
	s_waitcnt lgkmcnt(7)
	v_mfma_f32_16x16x32_f16 v[92:95], v[128:131], v[168:171], v[92:95]
	v_mfma_f32_16x16x32_f16 v[88:91], v[136:139], v[168:171], v[88:91]
	s_waitcnt lgkmcnt(5)
	v_mfma_f32_16x16x32_f16 v[84:87], v[128:131], v[176:179], v[84:87]
	v_mfma_f32_16x16x32_f16 v[80:83], v[136:139], v[176:179], v[80:83]
	s_waitcnt lgkmcnt(3)
	v_mfma_f32_16x16x32_f16 v[76:79], v[128:131], v[184:187], v[76:79]
	v_mfma_f32_16x16x32_f16 v[72:75], v[136:139], v[184:187], v[72:75]
	s_waitcnt lgkmcnt(1)
	v_mfma_f32_16x16x32_f16 v[68:71], v[128:131], v[192:195], v[68:71]
	v_mfma_f32_16x16x32_f16 v[60:63], v[136:139], v[192:195], v[60:63]
	v_mfma_f32_16x16x32_f16 v[92:95], v[132:135], v[172:175], v[92:95]
	v_mfma_f32_16x16x32_f16 v[88:91], v[148:151], v[172:175], v[88:91]
	v_mfma_f32_16x16x32_f16 v[84:87], v[132:135], v[180:183], v[84:87]
	v_mfma_f32_16x16x32_f16 v[80:83], v[148:151], v[180:183], v[80:83]
	v_mfma_f32_16x16x32_f16 v[76:79], v[132:135], v[188:191], v[76:79]
	v_mfma_f32_16x16x32_f16 v[72:75], v[148:151], v[188:191], v[72:75]
	s_waitcnt lgkmcnt(0)
	v_mfma_f32_16x16x32_f16 v[68:71], v[132:135], v[196:199], v[68:71]
	v_mfma_f32_16x16x32_f16 v[60:63], v[148:151], v[196:199], v[60:63]
	v_mfma_f32_16x16x32_f16 v[28:31], v[152:155], v[168:171], v[28:31]
	v_mfma_f32_16x16x32_f16 v[24:27], v[160:163], v[168:171], v[24:27]
	v_mfma_f32_16x16x32_f16 v[20:23], v[152:155], v[176:179], v[20:23]
	v_mfma_f32_16x16x32_f16 v[16:19], v[160:163], v[176:179], v[16:19]
	v_mfma_f32_16x16x32_f16 v[12:15], v[152:155], v[184:187], v[12:15]
	v_mfma_f32_16x16x32_f16 v[8:11], v[160:163], v[184:187], v[8:11]
	v_mfma_f32_16x16x32_f16 v[4:7], v[152:155], v[192:195], v[4:7]
	v_mfma_f32_16x16x32_f16 v[0:3], v[160:163], v[192:195], v[0:3]
	v_mfma_f32_16x16x32_f16 v[28:31], v[156:159], v[172:175], v[28:31]
	v_mfma_f32_16x16x32_f16 v[24:27], v[164:167], v[172:175], v[24:27]
	v_mfma_f32_16x16x32_f16 v[20:23], v[156:159], v[180:183], v[20:23]
	v_mfma_f32_16x16x32_f16 v[16:19], v[164:167], v[180:183], v[16:19]
	v_mfma_f32_16x16x32_f16 v[12:15], v[156:159], v[188:191], v[12:15]
	v_mfma_f32_16x16x32_f16 v[8:11], v[164:167], v[188:191], v[8:11]
	v_mfma_f32_16x16x32_f16 v[4:7], v[156:159], v[196:199], v[4:7]
	v_mfma_f32_16x16x32_f16 v[0:3], v[164:167], v[196:199], v[0:3]
	s_barrier
	s_add_i32 s1, s1, 2
	s_add_u32 s85, s85, 0x100
	s_addc_u32 s86, s86, 0
	s_add_u32 s87, s87, 0x100
	s_addc_u32 s0, s0, 0
	s_add_u32 s40, s40, 0x100
	s_addc_u32 s41, s41, 0
	s_cmp_gt_u32 s1, 29
; #define PG8_STAGE(bufoff, gbase, voff) do { _Pragma("unroll") for (int _i = 0; _i < 2; ++_i) glds16_s((gbase), (voff)[_i], ldsb + (unsigned)((bufoff) + _i * 8192)); } while (0)
; #define PG8_LDA(dst, b, h) do { _Pragma("unroll") for (int m = 0; m < 4; ++m) _Pragma("unroll") for (int k = 0; k < 2; ++k) dst[m][k] = *(const LAS h16x8*)(lds + PG8_SA(b, h) + aoff + m * 2048 + k * 1024); } while (0)
; #define PG8_LDB(dst, b, h) do { _Pragma("unroll") for (int n = 0; n < 2; ++n) _Pragma("unroll") for (int k = 0; k < 2; ++k) dst[n][k] = *(const LAS h16x8*)(lds + PG8_SB(b, h) + boff + n * 2048 + k * 1024); } while (0)
; #define PG8_MMA(ai, bj, At, Bt) do { __builtin_amdgcn_s_setprio(1); _Pragma("unroll") for (int m = 0; m < 4; ++m) _Pragma("unroll") for (int n = 0; n < 2; ++n) _Pragma("unroll") for (int k = 0; k < 2; ++k) \
;         acc[ai][bj][m][n] = mma_step<I8>(Bt[n][k], At[m][k], acc[ai][bj][m][n]); __builtin_amdgcn_s_setprio(0); } while (0)
; #define PG8_WAIT_V(n) asm volatile("s_waitcnt vmcnt(" #n ")" ::: "memory")
; #define PG8_WAIT_L(n) asm volatile("s_waitcnt lgkmcnt(" #n ")" ::: "memory")
; #define PG8_BAR __builtin_amdgcn_s_barrier()
; #define PG8_SCHED __builtin_amdgcn_sched_barrier(0)
; template <class Prob, class Epi, bool I8 = false, bool ALIGN_EPI = true, bool SP2 = true>
; __device__ __forceinline__ void gemm_phase(LAS unsigned char* lds, int wave, const Prob& P, const Epi& E) {
;     ...
;             PG8_LDB(B0, 0, 0); PG8_LDB(B1, 0, 1); PG8_SCHED; PG8_LDA(At, 0, 0); PG8_STAGE(PG8_SA(1, 1), a1 + hstepA, voffA);
;             PG8_WAIT_V(8); PG8_WAIT_L(0); PG8_BAR; PG8_MMA(0, 0, At, B0); PG8_MMA(0, 1, At, B1); PG8_BAR; PG8_SCHED;
;             PG8_LDA(At, 0, 1); PG8_STAGE(PG8_SB(0, 0), b2, voffB); PG8_STAGE(PG8_SB(0, 1), b2 + hstepB, voffB); PG8_STAGE(PG8_SA(0, 0), a2, voffA);
;             PG8_WAIT_V(8); PG8_WAIT_L(0); PG8_BAR; PG8_MMA(1, 0, At, B0); PG8_MMA(1, 1, At, B1); PG8_BAR; PG8_SCHED;
.LBB0_464:
	v_add_u32_e32 v140, 0x10000, v146
	ds_read_b128 v[128:131], v140
	ds_read_b128 v[132:135], v140 offset:1024
	ds_read_b128 v[136:139], v140 offset:2048
	ds_read_b128 v[148:151], v140 offset:3072
	v_add_u32_e32 v140, 0x14000, v146
	ds_read_b128 v[152:155], v140
	ds_read_b128 v[156:159], v140 offset:1024
	ds_read_b128 v[160:163], v140 offset:2048
	ds_read_b128 v[164:167], v140 offset:3072
	s_cmp_eq_u32 s1, 28
	s_cselect_b32 s48, s83, s85
	s_cselect_b32 s49, s27, s86
	s_cselect_b32 s46, s84, s87
	s_cselect_b32 s47, s23, s0
	s_add_u32 s44, s48, 0x80
	s_addc_u32 s45, s49, 0
	ds_read_b128 v[168:171], v147
	ds_read_b128 v[172:175], v147 offset:1024
	ds_read_b128 v[176:179], v147 offset:2048
	ds_read_b128 v[180:183], v147 offset:3072
	ds_read_b128 v[184:187], v147 offset:4096
	ds_read_b128 v[188:191], v147 offset:5120
	ds_read_b128 v[192:195], v147 offset:6144
	ds_read_b128 v[196:199], v147 offset:7168
	s_mov_b32 s4, m0
	s_mov_b32 m0, s77
	s_nop 0
	global_load_lds_dwordx4 v142, s[40:41]
	s_mov_b32 m0, s4
	s_nop 0
	s_mov_b32 s4, m0
	s_mov_b32 m0, s79
	s_nop 0
	global_load_lds_dwordx4 v144, s[40:41]
	s_mov_b32 m0, s4
	s_waitcnt vmcnt(8)
	s_waitcnt lgkmcnt(0)
	s_barrier
	s_waitcnt lgkmcnt(7)
	v_mfma_f32_16x16x32_f16 v[124:127], v[128:131], v[168:171], v[124:127]
	v_mfma_f32_16x16x32_f16 v[120:123], v[136:139], v[168:171], v[120:123]
	s_waitcnt lgkmcnt(5)
	v_mfma_f32_16x16x32_f16 v[116:119], v[128:131], v[176:179], v[116:119]
	v_mfma_f32_16x16x32_f16 v[112:115], v[136:139], v[176:179], v[112:115]
	s_waitcnt lgkmcnt(3)
	v_mfma_f32_16x16x32_f16 v[108:111], v[128:131], v[184:187], v[108:111]
	v_mfma_f32_16x16x32_f16 v[104:107], v[136:139], v[184:187], v[104:107]
	s_waitcnt lgkmcnt(1)
	v_mfma_f32_16x16x32_f16 v[100:103], v[128:131], v[192:195], v[100:103]
	v_mfma_f32_16x16x32_f16 v[96:99], v[136:139], v[192:195], v[96:99]
	v_mfma_f32_16x16x32_f16 v[124:127], v[132:135], v[172:175], v[124:127]
	v_mfma_f32_16x16x32_f16 v[120:123], v[148:151], v[172:175], v[120:123]
	v_mfma_f32_16x16x32_f16 v[116:119], v[132:135], v[180:183], v[116:119]
	v_mfma_f32_16x16x32_f16 v[112:115], v[148:151], v[180:183], v[112:115]
	v_mfma_f32_16x16x32_f16 v[108:111], v[132:135], v[188:191], v[108:111]
	v_mfma_f32_16x16x32_f16 v[104:107], v[148:151], v[188:191], v[104:107]
	s_waitcnt lgkmcnt(0)
	v_mfma_f32_16x16x32_f16 v[100:103], v[132:135], v[196:199], v[100:103]
	v_mfma_f32_16x16x32_f16 v[96:99], v[148:151], v[196:199], v[96:99]
	v_mfma_f32_16x16x32_f16 v[64:67], v[152:155], v[168:171], v[64:67]
	v_mfma_f32_16x16x32_f16 v[56:59], v[160:163], v[168:171], v[56:59]
	v_mfma_f32_16x16x32_f16 v[52:55], v[152:155], v[176:179], v[52:55]
	v_mfma_f32_16x16x32_f16 v[48:51], v[160:163], v[176:179], v[48:51]
	v_mfma_f32_16x16x32_f16 v[44:47], v[152:155], v[184:187], v[44:47]
	v_mfma_f32_16x16x32_f16 v[40:43], v[160:163], v[184:187], v[40:43]
	v_mfma_f32_16x16x32_f16 v[36:39], v[152:155], v[192:195], v[36:39]
	v_mfma_f32_16x16x32_f16 v[32:35], v[160:163], v[192:195], v[32:35]
	v_mfma_f32_16x16x32_f16 v[64:67], v[156:159], v[172:175], v[64:67]
	v_mfma_f32_16x16x32_f16 v[56:59], v[164:167], v[172:175], v[56:59]
	v_mfma_f32_16x16x32_f16 v[52:55], v[156:159], v[180:183], v[52:55]
	v_mfma_f32_16x16x32_f16 v[48:51], v[164:167], v[180:183], v[48:51]
	v_mfma_f32_16x16x32_f16 v[44:47], v[156:159], v[188:191], v[44:47]
	v_mfma_f32_16x16x32_f16 v[40:43], v[164:167], v[188:191], v[40:43]
	v_mfma_f32_16x16x32_f16 v[36:39], v[156:159], v[196:199], v[36:39]
	v_mfma_f32_16x16x32_f16 v[32:35], v[164:167], v[196:199], v[32:35]
	s_barrier
	ds_read_b128 v[168:171], v147 offset:16384
	ds_read_b128 v[172:175], v147 offset:17408
	ds_read_b128 v[176:179], v147 offset:18432
	ds_read_b128 v[180:183], v147 offset:19456
	ds_read_b128 v[184:187], v147 offset:20480
	ds_read_b128 v[188:191], v147 offset:21504
	ds_read_b128 v[192:195], v147 offset:22528
	ds_read_b128 v[196:199], v147 offset:23552
	s_mov_b32 s4, m0
	s_mov_b32 m0, s51
	s_nop 0
	global_load_lds_dwordx4 v143, s[46:47]
	s_mov_b32 m0, s4
	s_nop 0
	s_mov_b32 s4, m0
	s_mov_b32 m0, s56
	s_nop 0
	global_load_lds_dwordx4 v145, s[46:47]
	s_mov_b32 m0, s4
	s_add_u32 s4, s46, 0x80000
	s_addc_u32 s5, s47, 0
	s_mov_b32 s6, m0
	s_mov_b32 m0, s57
	s_nop 0
	global_load_lds_dwordx4 v143, s[4:5]
	s_mov_b32 m0, s6
	s_nop 0
	s_mov_b32 s6, m0
	s_mov_b32 m0, s60
	s_nop 0
	global_load_lds_dwordx4 v145, s[4:5]
	s_mov_b32 m0, s6
	s_mov_b32 s4, m0
	s_mov_b32 m0, s50
	s_nop 0
	global_load_lds_dwordx4 v142, s[48:49]
	s_mov_b32 m0, s4
	s_nop 0
	s_mov_b32 s4, m0
	s_mov_b32 m0, s61
	s_nop 0
	global_load_lds_dwordx4 v144, s[48:49]
	s_mov_b32 m0, s4
	s_waitcnt vmcnt(8)
	s_waitcnt lgkmcnt(0)
	s_barrier
; #define PG8_STAGE(bufoff, gbase, voff) do { _Pragma("unroll") for (int _i = 0; _i < 2; ++_i) glds16_s((gbase), (voff)[_i], ldsb + (unsigned)((bufoff) + _i * 8192)); } while (0)
; #define PG8_LDA(dst, b, h) do { _Pragma("unroll") for (int m = 0; m < 4; ++m) _Pragma("unroll") for (int k = 0; k < 2; ++k) dst[m][k] = *(const LAS h16x8*)(lds + PG8_SA(b, h) + aoff + m * 2048 + k * 1024); } while (0)
; #define PG8_LDB(dst, b, h) do { _Pragma("unroll") for (int n = 0; n < 2; ++n) _Pragma("unroll") for (int k = 0; k < 2; ++k) dst[n][k] = *(const LAS h16x8*)(lds + PG8_SB(b, h) + boff + n * 2048 + k * 1024); } while (0)
; #define PG8_MMA(ai, bj, At, Bt) do { __builtin_amdgcn_s_setprio(1); _Pragma("unroll") for (int m = 0; m < 4; ++m) _Pragma("unroll") for (int n = 0; n < 2; ++n) _Pragma("unroll") for (int k = 0; k < 2; ++k) \
;         acc[ai][bj][m][n] = mma_step<I8>(Bt[n][k], At[m][k], acc[ai][bj][m][n]); __builtin_amdgcn_s_setprio(0); } while (0)
; #define PG8_WAIT_V(n) asm volatile("s_waitcnt vmcnt(" #n ")" ::: "memory")
; #define PG8_WAIT_L(n) asm volatile("s_waitcnt lgkmcnt(" #n ")" ::: "memory")
; #define PG8_BAR __builtin_amdgcn_s_barrier()
; #define PG8_SCHED __builtin_amdgcn_sched_barrier(0)
; template <class Prob, class Epi, bool I8 = false, bool ALIGN_EPI = true, bool SP2 = true>
; __device__ __forceinline__ void gemm_phase(LAS unsigned char* lds, int wave, const Prob& P, const Epi& E) {
;     ...
;             PG8_WAIT_V(8); PG8_WAIT_L(0); PG8_BAR; PG8_MMA(1, 0, At, B0); PG8_MMA(1, 1, At, B1); PG8_BAR; PG8_SCHED;
;             PG8_LDB(B0, 1, 0); PG8_LDB(B1, 1, 1); PG8_SCHED; PG8_LDA(At, 1, 0); PG8_STAGE(PG8_SA(0, 1), a2 + hstepA, voffA);
;             PG8_WAIT_V(8); PG8_WAIT_L(0); PG8_BAR; PG8_MMA(0, 0, At, B0); PG8_MMA(0, 1, At, B1); PG8_BAR; PG8_SCHED;
	s_waitcnt lgkmcnt(7)
	v_mfma_f32_16x16x32_f16 v[92:95], v[128:131], v[168:171], v[92:95]
	v_mfma_f32_16x16x32_f16 v[88:91], v[136:139], v[168:171], v[88:91]
	s_waitcnt lgkmcnt(5)
	v_mfma_f32_16x16x32_f16 v[84:87], v[128:131], v[176:179], v[84:87]
	v_mfma_f32_16x16x32_f16 v[80:83], v[136:139], v[176:179], v[80:83]
	s_waitcnt lgkmcnt(3)
	v_mfma_f32_16x16x32_f16 v[76:79], v[128:131], v[184:187], v[76:79]
	v_mfma_f32_16x16x32_f16 v[72:75], v[136:139], v[184:187], v[72:75]
	s_waitcnt lgkmcnt(1)
	v_mfma_f32_16x16x32_f16 v[68:71], v[128:131], v[192:195], v[68:71]
	v_mfma_f32_16x16x32_f16 v[60:63], v[136:139], v[192:195], v[60:63]
	v_mfma_f32_16x16x32_f16 v[92:95], v[132:135], v[172:175], v[92:95]
	v_mfma_f32_16x16x32_f16 v[88:91], v[148:151], v[172:175], v[88:91]
	v_mfma_f32_16x16x32_f16 v[84:87], v[132:135], v[180:183], v[84:87]
	v_mfma_f32_16x16x32_f16 v[80:83], v[148:151], v[180:183], v[80:83]
	v_mfma_f32_16x16x32_f16 v[76:79], v[132:135], v[188:191], v[76:79]
	v_mfma_f32_16x16x32_f16 v[72:75], v[148:151], v[188:191], v[72:75]
	s_waitcnt lgkmcnt(0)
	v_mfma_f32_16x16x32_f16 v[68:71], v[132:135], v[196:199], v[68:71]
	v_mfma_f32_16x16x32_f16 v[60:63], v[148:151], v[196:199], v[60:63]
	v_mfma_f32_16x16x32_f16 v[28:31], v[152:155], v[168:171], v[28:31]
	v_mfma_f32_16x16x32_f16 v[24:27], v[160:163], v[168:171], v[24:27]
	v_mfma_f32_16x16x32_f16 v[20:23], v[152:155], v[176:179], v[20:23]
	v_mfma_f32_16x16x32_f16 v[16:19], v[160:163], v[176:179], v[16:19]
	v_mfma_f32_16x16x32_f16 v[12:15], v[152:155], v[184:187], v[12:15]
	v_mfma_f32_16x16x32_f16 v[8:11], v[160:163], v[184:187], v[8:11]
	v_mfma_f32_16x16x32_f16 v[4:7], v[152:155], v[192:195], v[4:7]
	v_mfma_f32_16x16x32_f16 v[0:3], v[160:163], v[192:195], v[0:3]
	v_mfma_f32_16x16x32_f16 v[28:31], v[156:159], v[172:175], v[28:31]
	v_mfma_f32_16x16x32_f16 v[24:27], v[164:167], v[172:175], v[24:27]
	v_mfma_f32_16x16x32_f16 v[20:23], v[156:159], v[180:183], v[20:23]
	v_mfma_f32_16x16x32_f16 v[16:19], v[164:167], v[180:183], v[16:19]
	v_mfma_f32_16x16x32_f16 v[12:15], v[156:159], v[188:191], v[12:15]
	v_mfma_f32_16x16x32_f16 v[8:11], v[164:167], v[188:191], v[8:11]
	v_mfma_f32_16x16x32_f16 v[4:7], v[156:159], v[196:199], v[4:7]
	v_mfma_f32_16x16x32_f16 v[0:3], v[164:167], v[196:199], v[0:3]
	s_barrier
	v_add_u32_e32 v140, 0x18000, v146
	ds_read_b128 v[128:131], v140
	ds_read_b128 v[132:135], v140 offset:1024
	ds_read_b128 v[136:139], v140 offset:2048
	ds_read_b128 v[148:151], v140 offset:3072
	v_add_u32_e32 v140, 0x1c000, v146
	ds_read_b128 v[152:155], v140
	ds_read_b128 v[156:159], v140 offset:1024
	ds_read_b128 v[160:163], v140 offset:2048
	ds_read_b128 v[164:167], v140 offset:3072
	ds_read_b128 v[168:171], v147 offset:32768
	ds_read_b128 v[172:175], v147 offset:33792
	ds_read_b128 v[176:179], v147 offset:34816
	ds_read_b128 v[180:183], v147 offset:35840
	ds_read_b128 v[184:187], v147 offset:36864
	ds_read_b128 v[188:191], v147 offset:37888
	ds_read_b128 v[192:195], v147 offset:38912
	ds_read_b128 v[196:199], v147 offset:39936
	s_add_u32 s4, s48, 0x80000
	s_addc_u32 s5, s49, 0
	s_mov_b32 s6, m0
	s_mov_b32 m0, s62
	s_nop 0
	global_load_lds_dwordx4 v142, s[4:5]
	s_mov_b32 m0, s6
	s_nop 0
	s_mov_b32 s6, m0
	s_mov_b32 m0, s63
	s_nop 0
	global_load_lds_dwordx4 v144, s[4:5]
	s_mov_b32 m0, s6
	s_waitcnt vmcnt(8)
	s_waitcnt lgkmcnt(0)
	s_barrier
	s_waitcnt lgkmcnt(7)
	v_mfma_f32_16x16x32_f16 v[124:127], v[128:131], v[168:171], v[124:127]
	v_mfma_f32_16x16x32_f16 v[120:123], v[136:139], v[168:171], v[120:123]
	s_waitcnt lgkmcnt(5)
	v_mfma_f32_16x16x32_f16 v[116:119], v[128:131], v[176:179], v[116:119]
	v_mfma_f32_16x16x32_f16 v[112:115], v[136:139], v[176:179], v[112:115]
	s_waitcnt lgkmcnt(3)
	v_mfma_f32_16x16x32_f16 v[108:111], v[128:131], v[184:187], v[108:111]
	v_mfma_f32_16x16x32_f16 v[104:107], v[136:139], v[184:187], v[104:107]
	s_waitcnt lgkmcnt(1)
	v_mfma_f32_16x16x32_f16 v[100:103], v[128:131], v[192:195], v[100:103]
	v_mfma_f32_16x16x32_f16 v[96:99], v[136:139], v[192:195], v[96:99]
	v_mfma_f32_16x16x32_f16 v[124:127], v[132:135], v[172:175], v[124:127]
	v_mfma_f32_16x16x32_f16 v[120:123], v[148:151], v[172:175], v[120:123]
	v_mfma_f32_16x16x32_f16 v[116:119], v[132:135], v[180:183], v[116:119]
	v_mfma_f32_16x16x32_f16 v[112:115], v[148:151], v[180:183], v[112:115]
	v_mfma_f32_16x16x32_f16 v[108:111], v[132:135], v[188:191], v[108:111]
	v_mfma_f32_16x16x32_f16 v[104:107], v[148:151], v[188:191], v[104:107]
	s_waitcnt lgkmcnt(0)
	v_mfma_f32_16x16x32_f16 v[100:103], v[132:135], v[196:199], v[100:103]
	v_mfma_f32_16x16x32_f16 v[96:99], v[148:151], v[196:199], v[96:99]
	v_mfma_f32_16x16x32_f16 v[64:67], v[152:155], v[168:171], v[64:67]
	v_mfma_f32_16x16x32_f16 v[56:59], v[160:163], v[168:171], v[56:59]
	v_mfma_f32_16x16x32_f16 v[52:55], v[152:155], v[176:179], v[52:55]
	v_mfma_f32_16x16x32_f16 v[48:51], v[160:163], v[176:179], v[48:51]
	v_mfma_f32_16x16x32_f16 v[44:47], v[152:155], v[184:187], v[44:47]
	v_mfma_f32_16x16x32_f16 v[40:43], v[160:163], v[184:187], v[40:43]
	v_mfma_f32_16x16x32_f16 v[36:39], v[152:155], v[192:195], v[36:39]
	v_mfma_f32_16x16x32_f16 v[32:35], v[160:163], v[192:195], v[32:35]
	v_mfma_f32_16x16x32_f16 v[64:67], v[156:159], v[172:175], v[64:67]
	v_mfma_f32_16x16x32_f16 v[56:59], v[164:167], v[172:175], v[56:59]
	v_mfma_f32_16x16x32_f16 v[52:55], v[156:159], v[180:183], v[52:55]
	v_mfma_f32_16x16x32_f16 v[48:51], v[164:167], v[180:183], v[48:51]
	v_mfma_f32_16x16x32_f16 v[44:47], v[156:159], v[188:191], v[44:47]
	v_mfma_f32_16x16x32_f16 v[40:43], v[164:167], v[188:191], v[40:43]
	v_mfma_f32_16x16x32_f16 v[36:39], v[156:159], v[196:199], v[36:39]
	v_mfma_f32_16x16x32_f16 v[32:35], v[164:167], v[196:199], v[32:35]
	s_barrier
; #define PG8_STAGE(bufoff, gbase, voff) do { _Pragma("unroll") for (int _i = 0; _i < 2; ++_i) glds16_s((gbase), (voff)[_i], ldsb + (unsigned)((bufoff) + _i * 8192)); } while (0)
; #define PG8_WAIT_V(n) asm volatile("s_waitcnt vmcnt(" #n ")" ::: "memory")
; template <class Prob, class Epi, bool I8 = false, bool ALIGN_EPI = true, bool SP2 = true>
; __device__ __forceinline__ void gemm_phase(LAS unsigned char* lds, int wave, const Prob& P, const Epi& E) {
;     ...
;             PG8_LDA(At, 1, 1); PG8_STAGE(PG8_SB(1, 0), b3, voffB); PG8_STAGE(PG8_SB(1, 1), b3 + hstepB, voffB); PG8_STAGE(PG8_SA(1, 0), a3, voffA);
;             PG8_WAIT_V(8); PG8_WAIT_L(0); PG8_BAR; PG8_MMA(1, 0, At, B0); PG8_MMA(1, 1, At, B1); PG8_BAR; PG8_SCHED;
;             } else {
;             PG8_LDB(B0, 0, 0); PG8_SCHED; PG8_LDA(At, 0, 0); PG8_STAGE(PG8_SA(1, 1), a1 + hstepA, voffA);
;             PG8_WAIT_L(8); PG8_BAR; PG8_WAIT_L(0); PG8_MMA(0, 0, At, B0); PG8_BAR; PG8_SCHED;
;             PG8_LDB(B1, 0, 1); PG8_STAGE(PG8_SB(0, 0), b2, voffB);
;             PG8_BAR; PG8_WAIT_L(0); PG8_MMA(0, 1, At, B1); PG8_BAR;
;             PG8_LDA(At, 0, 1); PG8_STAGE(PG8_SA(0, 0), a2, voffA);
;             PG8_BAR; PG8_WAIT_L(0); PG8_MMA(1, 0, At, B0); PG8_BAR; PG8_SCHED;
;             PG8_STAGE(PG8_SB(0, 1), b2 + hstepB, voffB);
;             PG8_WAIT_V(6); PG8_BAR; PG8_MMA(1, 1, At, B1); PG8_BAR;
;             PG8_LDB(B0, 1, 0); PG8_SCHED; PG8_LDA(At, 1, 0); PG8_STAGE(PG8_SA(0, 1), a2 + hstepA, voffA);
;             PG8_WAIT_L(8); PG8_BAR; PG8_WAIT_L(0); PG8_MMA(0, 0, At, B0); PG8_BAR; PG8_SCHED;
;             PG8_LDB(B1, 1, 1); PG8_STAGE(PG8_SB(1, 0), b3, voffB);
;             PG8_BAR; PG8_WAIT_L(0); PG8_MMA(0, 1, At, B1); PG8_BAR;
;             PG8_LDA(At, 1, 1); PG8_STAGE(PG8_SA(1, 0), a3, voffA);
;             PG8_BAR; PG8_WAIT_L(0); PG8_MMA(1, 0, At, B0); PG8_BAR; PG8_SCHED;
;             PG8_STAGE(PG8_SB(1, 1), b3 + hstepB, voffB);
;             PG8_WAIT_V(6); PG8_BAR; PG8_MMA(1, 1, At, B1); PG8_BAR;
;             }
;         }
;         if constexpr (ALIGN_EPI) { if (wr == 0) PG8_BAR; }
;     __device__ __forceinline__ void operator()(Acc& acc, const Unit& u, int wr, int wc, int fr, int fq, LAS unsigned char* lds, int tid) const {
;     ...
;                 for (int m = 0; m < 4; ++m) { const unsigned row = u.pm * 256 + ai * 128 + wr * 64 + m * 16 + fr; xv[m] = *(const h16x8*)(X + (size_t)row * D + colt);
	ds_read_b128 v[168:171], v147 offset:49152
	ds_read_b128 v[172:175], v147 offset:50176
	ds_read_b128 v[176:179], v147 offset:51200
	ds_read_b128 v[180:183], v147 offset:52224
	ds_read_b128 v[184:187], v147 offset:53248
	ds_read_b128 v[188:191], v147 offset:54272
	ds_read_b128 v[192:195], v147 offset:55296
	ds_read_b128 v[196:199], v147 offset:56320
	s_add_u32 s4, s46, 0x80
	s_addc_u32 s5, s47, 0
	s_mov_b32 s6, m0
	s_mov_b32 m0, s69
	s_nop 0
	global_load_lds_dwordx4 v143, s[4:5]
	s_mov_b32 m0, s6
	s_nop 0
	s_mov_b32 s6, m0
	s_mov_b32 m0, s72
	s_nop 0
	global_load_lds_dwordx4 v145, s[4:5]
	s_mov_b32 m0, s6
	s_add_u32 s4, s46, 0x80080
	s_addc_u32 s5, s47, 0
	s_mov_b32 s6, m0
	s_mov_b32 m0, s75
	s_nop 0
	global_load_lds_dwordx4 v143, s[4:5]
	s_mov_b32 m0, s6
	s_nop 0
	s_mov_b32 s6, m0
	s_mov_b32 m0, s76
	s_nop 0
	global_load_lds_dwordx4 v145, s[4:5]
	s_mov_b32 m0, s6
	s_mov_b32 s4, m0
	s_mov_b32 m0, s73
	s_nop 0
	global_load_lds_dwordx4 v142, s[44:45]
	s_mov_b32 m0, s4
	s_nop 0
	s_mov_b32 s4, m0
	s_mov_b32 m0, s74
	s_nop 0
	global_load_lds_dwordx4 v144, s[44:45]
	s_mov_b32 m0, s4
	s_waitcnt vmcnt(8)
	s_waitcnt lgkmcnt(0)
	s_barrier
	s_waitcnt lgkmcnt(7)
	v_mfma_f32_16x16x32_f16 v[92:95], v[128:131], v[168:171], v[92:95]
	v_mfma_f32_16x16x32_f16 v[88:91], v[136:139], v[168:171], v[88:91]
	s_waitcnt lgkmcnt(5)
	v_mfma_f32_16x16x32_f16 v[84:87], v[128:131], v[176:179], v[84:87]
	v_mfma_f32_16x16x32_f16 v[80:83], v[136:139], v[176:179], v[80:83]
	s_waitcnt lgkmcnt(3)
	v_mfma_f32_16x16x32_f16 v[76:79], v[128:131], v[184:187], v[76:79]
	v_mfma_f32_16x16x32_f16 v[72:75], v[136:139], v[184:187], v[72:75]
	s_waitcnt lgkmcnt(1)
	v_mfma_f32_16x16x32_f16 v[68:71], v[128:131], v[192:195], v[68:71]
	v_mfma_f32_16x16x32_f16 v[60:63], v[136:139], v[192:195], v[60:63]
	v_mfma_f32_16x16x32_f16 v[92:95], v[132:135], v[172:175], v[92:95]
	v_mfma_f32_16x16x32_f16 v[88:91], v[148:151], v[172:175], v[88:91]
	v_mfma_f32_16x16x32_f16 v[84:87], v[132:135], v[180:183], v[84:87]
	v_mfma_f32_16x16x32_f16 v[80:83], v[148:151], v[180:183], v[80:83]
	v_mfma_f32_16x16x32_f16 v[76:79], v[132:135], v[188:191], v[76:79]
	v_mfma_f32_16x16x32_f16 v[72:75], v[148:151], v[188:191], v[72:75]
	s_waitcnt lgkmcnt(0)
	v_mfma_f32_16x16x32_f16 v[68:71], v[132:135], v[196:199], v[68:71]
	v_mfma_f32_16x16x32_f16 v[60:63], v[148:151], v[196:199], v[60:63]
	v_mfma_f32_16x16x32_f16 v[28:31], v[152:155], v[168:171], v[28:31]
	v_mfma_f32_16x16x32_f16 v[24:27], v[160:163], v[168:171], v[24:27]
	v_mfma_f32_16x16x32_f16 v[20:23], v[152:155], v[176:179], v[20:23]
	v_mfma_f32_16x16x32_f16 v[16:19], v[160:163], v[176:179], v[16:19]
	v_mfma_f32_16x16x32_f16 v[12:15], v[152:155], v[184:187], v[12:15]
	v_mfma_f32_16x16x32_f16 v[8:11], v[160:163], v[184:187], v[8:11]
	v_mfma_f32_16x16x32_f16 v[4:7], v[152:155], v[192:195], v[4:7]
	v_mfma_f32_16x16x32_f16 v[0:3], v[160:163], v[192:195], v[0:3]
	v_mfma_f32_16x16x32_f16 v[28:31], v[156:159], v[172:175], v[28:31]
	v_mfma_f32_16x16x32_f16 v[24:27], v[164:167], v[172:175], v[24:27]
	v_mfma_f32_16x16x32_f16 v[20:23], v[156:159], v[180:183], v[20:23]
	v_mfma_f32_16x16x32_f16 v[16:19], v[164:167], v[180:183], v[16:19]
	v_mfma_f32_16x16x32_f16 v[12:15], v[156:159], v[188:191], v[12:15]
	v_mfma_f32_16x16x32_f16 v[8:11], v[164:167], v[188:191], v[8:11]
	v_mfma_f32_16x16x32_f16 v[4:7], v[156:159], v[196:199], v[4:7]
	v_mfma_f32_16x16x32_f16 v[0:3], v[164:167], v[196:199], v[0:3]
	s_barrier
	s_add_i32 s1, s1, 2
	s_add_u32 s85, s85, 0x100
	s_addc_u32 s86, s86, 0
	s_add_u32 s87, s87, 0x100
	s_addc_u32 s0, s0, 0
	s_add_u32 s40, s40, 0x100
	s_addc_u32 s41, s41, 0
	s_cmp_gt_u32 s1, 29
	s_cbranch_scc0 .LBB0_464
	v_mbcnt_lo_u32_b32 v128, -1, 0
	v_mbcnt_hi_u32_b32 v128, -1, v128
	s_lshl_b32 s0, s82, 8
	s_lshl_b32 s1, s81, 8
	v_lshrrev_b32_e32 v129, 1, v128
	s_add_i32 s1, s1, s64
	v_and_or_b32 v129, v129, 24, s0
	v_and_or_b32 v130, v128, 15, s1
	v_or_b32_e32 v129, s68, v129
	v_lshlrev_b32_e32 v130, 12, v130
	v_lshl_add_u32 v128, v129, 1, v130
	v_add_u32_e32 v129, 0x10000, v128
	v_add_u32_e32 v130, 0x20000, v128
	v_add_u32_e32 v131, 0x30000, v128
	v_add_u32_e32 v132, 0x80000, v128
	v_add_u32_e32 v133, 0x90000, v128
	v_add_u32_e32 v134, 0xa0000, v128
	v_add_u32_e32 v135, 0xb0000, v128
	global_load_dwordx4 v[148:151], v128, s[54:55]
	global_load_dwordx4 v[152:155], v129, s[54:55]
	global_load_dwordx4 v[156:159], v130, s[54:55]
	global_load_dwordx4 v[160:163], v131, s[54:55]
	global_load_dwordx4 v[164:167], v132, s[54:55]
	global_load_dwordx4 v[168:171], v133, s[54:55]
	global_load_dwordx4 v[172:175], v134, s[54:55]
	global_load_dwordx4 v[176:179], v135, s[54:55]
	global_load_dwordx4 v[180:183], v128, s[54:55] offset:256
	global_load_dwordx4 v[184:187], v129, s[54:55] offset:256
	global_load_dwordx4 v[188:191], v130, s[54:55] offset:256
	global_load_dwordx4 v[192:195], v131, s[54:55] offset:256
	global_load_dwordx4 v[196:199], v132, s[54:55] offset:256
	global_load_dwordx4 v[200:203], v133, s[54:55] offset:256
	global_load_dwordx4 v[204:207], v134, s[54:55] offset:256
	global_load_dwordx4 v[212:215], v135, s[54:55] offset:256
	s_and_b64 vcc, exec, s[16:17]
	s_cbranch_vccz .LBB0_467
	s_barrier

; __device__ __forceinline__ int mk_lane() { int l; asm volatile("v_mbcnt_lo_u32_b32 %0, -1, 0\n\tv_mbcnt_hi_u32_b32 %0, -1, %0" : "=v"(l)); return l; }
; #define PG8_STAGE(bufoff, gbase, voff) do { _Pragma("unroll") for (int _i = 0; _i < 2; ++_i) glds16_s((gbase), (voff)[_i], ldsb + (unsigned)((bufoff) + _i * 8192)); } while (0)
; #define PG8_BAR __builtin_amdgcn_s_barrier()
;     __device__ bool next(int i, Unit& u) const { return S.next(i, u); }
;     __device__ unsigned a_rowoff(int R) const { const int r = upmap ? (128 * (R >> 6) + 8 * (R & 15) + ((R >> 4) & 3)) : R; return (unsigned)r * (unsigned)lda * 2u; }
; template <class Prob, class Epi, bool I8 = false, bool ALIGN_EPI = true, bool SP2 = true>
; __device__ __forceinline__ void gemm_phase(LAS unsigned char* lds, int wave, const Prob& P, const Epi& E) {
;     const int tid_ = wave * 64 + mk_lane();
;     const int tid = tid_, wid = __builtin_amdgcn_readfirstlane(tid >> 6), lane = tid & 63, wr = wid >> 2, wc = wid & 3, fr = lane & 15, fq = lane >> 4;
;     const int K = P.K, nt = K / BK;
;     unsigned voffA[2], voffB[2];
; #pragma unroll
;     for (int i = 0; i < 2; ++i) { int R, C; stage_rc(tid * 16 + i * 8192, R, C); const int Rb = (R & ~31) + perm32(R & 31);
;         voffA[i] = P.a_rowoff(R) + (unsigned)C * 2u; voffB[i] = P.b_rowoff(Rb) + (unsigned)C * 2u; }
;     const size_t kstep = (size_t)(BK * 2);
;     const size_t hstepA = P.a_hstep(), hstepB = P.b_hstep();
;     const unsigned ldsw = (unsigned)wid * 1024u;
;     const unsigned ldsb = (unsigned)(size_t)lds + ldsw;
;     const int aoff = lds_byte(wr * 64 + fr, fq * 8), boff = lds_byte(wc * 32 + fr, fq * 8);
;     ...
;     Unit cur, nxt; int ui = 0;
;     if (!P.next(0, cur)) return;
;     Acc acc;
; #pragma unroll
;     for (int a = 0; a < 2; ++a)
; #pragma unroll
;         for (int b = 0; b < 2; ++b)
; #pragma unroll
;             for (int m = 0; m < 4; ++m)
; #pragma unroll
;                 for (int n = 0; n < 2; ++n) acc[a][b][m][n] = (f32x4){0.f, 0.f, 0.f, 0.f};
;     h16x8 At[4][2], B0[2][2], B1[2][2];
;     const char* cA = P.a_tile(cur); const char* cB = P.b_tile(cur);
;     if constexpr (SP2) {
;         PG8_STAGE(PG8_SB(0, 0), cB, voffB); PG8_STAGE(PG8_SB(0, 1), cB + hstepB, voffB); PG8_STAGE(PG8_SA(0, 0), cA, voffA); PG8_STAGE(PG8_SA(0, 1), cA + hstepA, voffA);
;         if (wr == 1) PG8_BAR;
.LBB0_526:
	s_and_b64 vcc, exec, s[14:15]
	s_cbranch_vccz .LBB0_925
	s_add_u32 s76, s30, 0x3f200000
	s_addc_u32 s77, s31, 0
	s_add_u32 s46, s30, 0x100000
	s_addc_u32 s47, s31, 0
	v_readlane_b32 s0, v254, 42
	v_readlane_b32 s4, v252, 1
	s_add_u32 s26, s30, 0x180000
	v_mbcnt_lo_u32_b32 v0, -1, 0
	v_mbcnt_hi_u32_b32 v0, -1, v0
	v_readlane_b32 s5, v252, 2
	v_add_u32_e32 v1, s0, v0
	s_addc_u32 s27, s31, 0
	v_readfirstlane_b32 s0, v1
	s_and_b64 vcc, exec, s[4:5]
	v_writelane_b32 v255, s93, 1
	s_cbranch_vccz .LBB0_607
	v_ashrrev_i32_e32 v3, 31, v1
	v_lshrrev_b32_e32 v3, 26, v3
	v_lshlrev_b32_e32 v2, 4, v1
	v_add_u32_e32 v3, v1, v3
	v_bfe_i32 v1, v1, 27, 1
	v_lshrrev_b32_e32 v1, 22, v1
	v_add_u32_e32 v1, v2, v1
	v_and_b32_e32 v1, 0xfffffc00, v1
	v_sub_u32_e32 v1, v2, v1
	v_lshrrev_b32_e32 v4, 4, v1
	v_bitop3_b32 v1, v4, v1, 32 bitop3:0x6c
	v_ashrrev_i32_e32 v5, 31, v1
	v_readlane_b32 s1, v253, 53
	v_ashrrev_i32_e32 v3, 6, v3
	v_lshrrev_b32_e32 v5, 26, v5
	s_add_u32 s1, s30, s1
	v_lshlrev_b32_e32 v4, 3, v3
	v_add_u32_e32 v5, v1, v5
	s_addc_u32 s2, s31, 0
	v_and_b32_e32 v4, -16, v4
	v_ashrrev_i32_e32 v6, 6, v5
	v_and_b32_e32 v5, 0xc0, v5
	s_add_u32 s19, s1, 0x5a00000
	v_add_u32_e32 v4, v6, v4
	v_sub_u32_e32 v1, v1, v5
	v_mov_b32_e32 v8, 1
	s_addc_u32 s62, s2, 0
	v_lshlrev_b32_e32 v3, 5, v3
	v_ashrrev_i16_sdwa v1, v8, sext(v1) dst_sel:DWORD dst_unused:UNUSED_PAD src0_sel:DWORD src1_sel:BYTE_0
	v_lshlrev_b32_e32 v5, 1, v4
	v_lshrrev_b32_e32 v7, 2, v4
	v_and_b32_e32 v6, 3, v6
	s_mov_b32 s2, 0xfffe0
	v_and_b32_e32 v3, 32, v3
	v_bfe_i32 v1, v1, 0, 16
	v_and_b32_e32 v5, 24, v5
	v_and_b32_e32 v7, 4, v7
	v_and_or_b32 v6, v4, s2, v6
	v_or3_b32 v5, v6, v7, v5
	v_add_lshl_u32 v1, v3, v1, 1
	v_lshl_add_u32 v132, v4, 12, v1
	v_lshl_add_u32 v133, v5, 12, v1
	v_add_u32_e32 v1, 0x2000, v2
	v_ashrrev_i32_e32 v2, 31, v1
	v_lshrrev_b32_e32 v2, 22, v2
	v_add_u32_e32 v2, v1, v2
	v_ashrrev_i32_e32 v2, 10, v2
	v_mul_i32_i24_e32 v3, 0x400, v2
	v_sub_u32_e32 v1, v1, v3
	v_lshrrev_b32_e32 v3, 4, v1
	v_bitop3_b32 v1, v3, v1, 32 bitop3:0x6c
	v_ashrrev_i32_e32 v4, 31, v1
	v_lshrrev_b32_e32 v4, 26, v4
	v_lshlrev_b32_e32 v3, 3, v2
	v_add_u32_e32 v4, v1, v4
	s_ashr_i32 s1, s0, 6
	v_and_b32_e32 v3, -16, v3
	v_ashrrev_i32_e32 v5, 6, v4
	v_and_b32_e32 v4, 0xc0, v4
	v_add_u32_e32 v3, v5, v3
	v_sub_u32_e32 v1, v1, v4
	v_and_b32_e32 v5, 3, v5
	s_lshl_b32 s63, s1, 10
	v_lshlrev_b32_e32 v2, 5, v2
	v_ashrrev_i16_sdwa v1, v8, sext(v1) dst_sel:DWORD dst_unused:UNUSED_PAD src0_sel:DWORD src1_sel:BYTE_0
	v_lshlrev_b32_e32 v4, 1, v3
	v_lshrrev_b32_e32 v6, 2, v3
	v_and_or_b32 v5, v3, s2, v5
	s_ashr_i32 s2, s0, 8
	s_add_i32 s63, s63, 0
	v_readlane_b32 s4, v252, 46
	v_and_b32_e32 v2, 32, v2
	v_bfe_i32 v1, v1, 0, 16
	v_and_b32_e32 v4, 24, v4
	v_and_b32_e32 v6, 4, v6
	v_readlane_b32 s5, v252, 47
	s_add_u32 s38, s19, s4
	v_or3_b32 v4, v5, v6, v4
	v_add_lshl_u32 v1, v2, v1, 1
	s_addc_u32 s39, s62, s5
	s_add_i32 s64, s63, 0x10000
	s_mov_b32 s4, m0
	s_mov_b32 m0, s64
	s_nop 0
	global_load_lds_dwordx4 v133, s[38:39]
	s_mov_b32 m0, s4
	v_lshl_add_u32 v135, v4, 12, v1
	s_add_i32 s68, s63, 0x12000
	s_mov_b32 s4, m0
	s_mov_b32 m0, s68
	s_nop 0
	global_load_lds_dwordx4 v135, s[38:39]
	s_mov_b32 m0, s4
	s_add_u32 s4, s38, 0x80000
	s_addc_u32 s5, s39, 0
	s_add_i32 s69, s63, 0x14000
	s_mov_b32 s6, m0
	s_mov_b32 m0, s69
	s_nop 0
	global_load_lds_dwordx4 v133, s[4:5]
	s_mov_b32 m0, s6
	s_add_i32 s79, s63, 0x16000
	s_mov_b32 s6, m0
	s_mov_b32 m0, s79
	s_nop 0
	global_load_lds_dwordx4 v135, s[4:5]
	s_mov_b32 m0, s6
	v_readlane_b32 s4, v252, 52
	v_readlane_b32 s5, v252, 53
	s_add_u32 s40, s54, s4
	s_addc_u32 s41, s55, s5
	s_mov_b32 s4, m0
	s_mov_b32 m0, s63
	s_nop 0
	global_load_lds_dwordx4 v132, s[40:41]
	s_mov_b32 m0, s4
	v_lshl_add_u32 v134, v3, 12, v1
	s_add_i32 s80, s63, 0x2000
	s_mov_b32 s4, m0
	s_mov_b32 m0, s80
	s_nop 0
	global_load_lds_dwordx4 v134, s[40:41]
	s_mov_b32 m0, s4
	s_add_u32 s4, s40, 0x80000
	s_addc_u32 s5, s41, 0
	s_add_i32 s81, s63, 0x4000
	s_mov_b32 s6, m0
	s_mov_b32 m0, s81
	s_nop 0
	global_load_lds_dwordx4 v132, s[4:5]
	s_mov_b32 m0, s6
	s_add_i32 s82, s63, 0x6000
	s_mov_b32 s6, m0
	s_mov_b32 m0, s82
	s_nop 0
	global_load_lds_dwordx4 v134, s[4:5]
	s_mov_b32 m0, s6
	s_cmp_eq_u32 s2, 1
	s_cselect_b64 s[16:17], -1, 0
	s_cmp_lg_u32 s2, 1
	s_cbranch_scc1 .LBB0_530
	s_barrier
	s_setprio 1

; #define PG8_STAGE(bufoff, gbase, voff) do { _Pragma("unroll") for (int _i = 0; _i < 2; ++_i) glds16_s((gbase), (voff)[_i], ldsb + (unsigned)((bufoff) + _i * 8192)); } while (0)
; #define PG8_LDA(dst, b, h) do { _Pragma("unroll") for (int m = 0; m < 4; ++m) _Pragma("unroll") for (int k = 0; k < 2; ++k) dst[m][k] = *(const LAS h16x8*)(lds + PG8_SA(b, h) + aoff + m * 2048 + k * 1024); } while (0)
; #define PG8_WAIT_V(n) asm volatile("s_waitcnt vmcnt(" #n ")" ::: "memory")
; #define PG8_WAIT_L(n) asm volatile("s_waitcnt lgkmcnt(" #n ")" ::: "memory")
; #define PG8_BAR __builtin_amdgcn_s_barrier()
; template <class Prob, class Epi, bool I8 = false, bool ALIGN_EPI = true, bool SP2 = true>
; __device__ __forceinline__ void gemm_phase(LAS unsigned char* lds, int wave, const Prob& P, const Epi& E) {
;     ...
;         const bool has_next = P.next(ui + 1, nxt);
;         const char* nA = has_next ? P.a_tile(nxt) : cA; const char* nB = has_next ? P.b_tile(nxt) : cB;
;         for (int t = 0; t < nt; t += 2) {
;             const bool last = (t == nt - 2);
;             const char* a1 = cA + (size_t)(t + 1) * kstep;
;             const char* a2 = last ? nA : cA + (size_t)(t + 2) * kstep; const char* b2 = last ? nB : cB + (size_t)(t + 2) * kstep;
;             const char* a3 = a2 + kstep; const char* b3 = b2 + kstep;
;             if constexpr (SP2) {
;             PG8_LDB(B0, 0, 0); PG8_LDB(B1, 0, 1); PG8_SCHED; PG8_LDA(At, 0, 0); PG8_STAGE(PG8_SA(1, 1), a1 + hstepA, voffA);
;             PG8_WAIT_V(8); PG8_WAIT_L(0); PG8_BAR; PG8_MMA(0, 0, At, B0); PG8_MMA(0, 1, At, B1); PG8_BAR; PG8_SCHED;
;             PG8_LDA(At, 0, 1); PG8_STAGE(PG8_SB(0, 0), b2, voffB); PG8_STAGE(PG8_SB(0, 1), b2 + hstepB, voffB); PG8_STAGE(PG8_SA(0, 0), a2, voffA);
;             PG8_WAIT_V(8); PG8_WAIT_L(0); PG8_BAR; PG8_MMA(1, 0, At, B0); PG8_MMA(1, 1, At, B1); PG8_BAR; PG8_SCHED;
;             PG8_LDB(B0, 1, 0); PG8_LDB(B1, 1, 1); PG8_SCHED; PG8_LDA(At, 1, 0); PG8_STAGE(PG8_SA(0, 1), a2 + hstepA, voffA);
;             PG8_WAIT_V(8); PG8_WAIT_L(0); PG8_BAR; PG8_MMA(0, 0, At, B0); PG8_MMA(0, 1, At, B1); PG8_BAR; PG8_SCHED;
;             PG8_LDA(At, 1, 1); PG8_STAGE(PG8_SB(1, 0), b3, voffB); PG8_STAGE(PG8_SB(1, 1), b3 + hstepB, voffB); PG8_STAGE(PG8_SA(1, 0), a3, voffA);
;             PG8_WAIT_V(8); PG8_WAIT_L(0); PG8_BAR; PG8_MMA(1, 0, At, B0); PG8_MMA(1, 1, At, B1); PG8_BAR; PG8_SCHED;
.Lpeel_536:
	v_add_u32_e32 v146, 0x10000, v136
	v_add_u32_e32 v162, 0x14000, v136
	ds_read_b128 v[128:131], v146
	ds_read_b128 v[138:141], v146 offset:1024
	ds_read_b128 v[142:145], v146 offset:2048
	ds_read_b128 v[146:149], v146 offset:3072
	ds_read_b128 v[150:153], v162
	ds_read_b128 v[154:157], v162 offset:1024
	ds_read_b128 v[158:161], v162 offset:2048
	ds_read_b128 v[162:165], v162 offset:3072
	s_cmp_eq_u32 s1, 28
	s_cselect_b32 s44, s57, s73
	s_cselect_b32 s45, s51, s74
	s_cselect_b32 s42, s72, s75
	s_cselect_b32 s43, s49, s0
	s_add_u32 s40, s44, 0x80
	s_addc_u32 s41, s45, 0
	ds_read_b128 v[166:169], v137
	ds_read_b128 v[170:173], v137 offset:1024
	ds_read_b128 v[174:177], v137 offset:2048
	ds_read_b128 v[178:181], v137 offset:3072
	ds_read_b128 v[182:185], v137 offset:4096
	ds_read_b128 v[186:189], v137 offset:5120
	ds_read_b128 v[190:193], v137 offset:6144
	ds_read_b128 v[194:197], v137 offset:7168
	s_mov_b32 s4, m0
	s_mov_b32 m0, s91
	s_nop 0
	global_load_lds_dwordx4 v132, s[38:39]
	s_mov_b32 m0, s4
	s_nop 0
	s_mov_b32 s4, m0
	s_mov_b32 m0, s94
	s_nop 0
	global_load_lds_dwordx4 v134, s[38:39]
	s_mov_b32 m0, s4
	s_waitcnt vmcnt(8)
	s_waitcnt lgkmcnt(0)
	s_barrier
	s_waitcnt lgkmcnt(7)
	v_mfma_f32_16x16x32_f16 v[124:127], v[128:131], v[166:169], 0
	v_mfma_f32_16x16x32_f16 v[120:123], v[142:145], v[166:169], 0
	s_waitcnt lgkmcnt(5)
	v_mfma_f32_16x16x32_f16 v[108:111], v[128:131], v[174:177], 0
	v_mfma_f32_16x16x32_f16 v[104:107], v[142:145], v[174:177], 0
	s_waitcnt lgkmcnt(3)
	v_mfma_f32_16x16x32_f16 v[92:95], v[128:131], v[182:185], 0
	v_mfma_f32_16x16x32_f16 v[88:91], v[142:145], v[182:185], 0
	s_waitcnt lgkmcnt(1)
	v_mfma_f32_16x16x32_f16 v[76:79], v[128:131], v[190:193], 0
	v_mfma_f32_16x16x32_f16 v[72:75], v[142:145], v[190:193], 0
	v_mfma_f32_16x16x32_f16 v[124:127], v[138:141], v[170:173], v[124:127]
	v_mfma_f32_16x16x32_f16 v[120:123], v[146:149], v[170:173], v[120:123]
	v_mfma_f32_16x16x32_f16 v[108:111], v[138:141], v[178:181], v[108:111]
	v_mfma_f32_16x16x32_f16 v[104:107], v[146:149], v[178:181], v[104:107]
	v_mfma_f32_16x16x32_f16 v[92:95], v[138:141], v[186:189], v[92:95]
	v_mfma_f32_16x16x32_f16 v[88:91], v[146:149], v[186:189], v[88:91]
	s_waitcnt lgkmcnt(0)
	v_mfma_f32_16x16x32_f16 v[76:79], v[138:141], v[194:197], v[76:79]
	v_mfma_f32_16x16x32_f16 v[72:75], v[146:149], v[194:197], v[72:75]
	v_mfma_f32_16x16x32_f16 v[116:119], v[150:153], v[166:169], 0
	v_mfma_f32_16x16x32_f16 v[112:115], v[158:161], v[166:169], 0
	v_mfma_f32_16x16x32_f16 v[100:103], v[150:153], v[174:177], 0
	v_mfma_f32_16x16x32_f16 v[96:99], v[158:161], v[174:177], 0
	v_mfma_f32_16x16x32_f16 v[84:87], v[150:153], v[182:185], 0
	v_mfma_f32_16x16x32_f16 v[80:83], v[158:161], v[182:185], 0
	v_mfma_f32_16x16x32_f16 v[68:71], v[150:153], v[190:193], 0
	v_mfma_f32_16x16x32_f16 v[64:67], v[158:161], v[190:193], 0
	v_mfma_f32_16x16x32_f16 v[116:119], v[154:157], v[170:173], v[116:119]
	v_mfma_f32_16x16x32_f16 v[112:115], v[162:165], v[170:173], v[112:115]
	v_mfma_f32_16x16x32_f16 v[100:103], v[154:157], v[178:181], v[100:103]
	v_mfma_f32_16x16x32_f16 v[96:99], v[162:165], v[178:181], v[96:99]
	v_mfma_f32_16x16x32_f16 v[84:87], v[154:157], v[186:189], v[84:87]
	v_mfma_f32_16x16x32_f16 v[80:83], v[162:165], v[186:189], v[80:83]
	v_mfma_f32_16x16x32_f16 v[68:71], v[154:157], v[194:197], v[68:71]
	v_mfma_f32_16x16x32_f16 v[64:67], v[162:165], v[194:197], v[64:67]
	s_barrier
	ds_read_b128 v[166:169], v137 offset:16384
	ds_read_b128 v[170:173], v137 offset:17408
	ds_read_b128 v[174:177], v137 offset:18432
	ds_read_b128 v[178:181], v137 offset:19456
	ds_read_b128 v[182:185], v137 offset:20480
	ds_read_b128 v[186:189], v137 offset:21504
	ds_read_b128 v[190:193], v137 offset:22528
	ds_read_b128 v[194:197], v137 offset:23552
	s_mov_b32 s4, m0
	s_mov_b32 m0, s64
	s_nop 0
	global_load_lds_dwordx4 v133, s[42:43]
	s_mov_b32 m0, s4
	s_nop 0
	s_mov_b32 s4, m0
	s_mov_b32 m0, s68
	s_nop 0
	global_load_lds_dwordx4 v135, s[42:43]
	s_mov_b32 m0, s4
	s_add_u32 s4, s42, 0x80000
	s_addc_u32 s5, s43, 0
	s_mov_b32 s6, m0
	s_mov_b32 m0, s69
	s_nop 0
	global_load_lds_dwordx4 v133, s[4:5]
	s_mov_b32 m0, s6
	s_nop 0
	s_mov_b32 s6, m0
	s_mov_b32 m0, s79
	s_nop 0
	global_load_lds_dwordx4 v135, s[4:5]
	s_mov_b32 m0, s6
	s_mov_b32 s4, m0
	s_mov_b32 m0, s63
	s_nop 0
	global_load_lds_dwordx4 v132, s[44:45]
	s_mov_b32 m0, s4
	s_nop 0
	s_mov_b32 s4, m0
	s_mov_b32 m0, s80
	s_nop 0
	global_load_lds_dwordx4 v134, s[44:45]
	s_mov_b32 m0, s4
	s_waitcnt vmcnt(8)
	s_waitcnt lgkmcnt(0)
	s_barrier
	s_waitcnt lgkmcnt(7)
	v_mfma_f32_16x16x32_f16 v[60:63], v[128:131], v[166:169], 0
	v_mfma_f32_16x16x32_f16 v[56:59], v[142:145], v[166:169], 0
	s_waitcnt lgkmcnt(5)
	v_mfma_f32_16x16x32_f16 v[44:47], v[128:131], v[174:177], 0
	v_mfma_f32_16x16x32_f16 v[40:43], v[142:145], v[174:177], 0
	s_waitcnt lgkmcnt(3)
	v_mfma_f32_16x16x32_f16 v[28:31], v[128:131], v[182:185], 0
	v_mfma_f32_16x16x32_f16 v[24:27], v[142:145], v[182:185], 0
	s_waitcnt lgkmcnt(1)
	v_mfma_f32_16x16x32_f16 v[12:15], v[128:131], v[190:193], 0
	v_mfma_f32_16x16x32_f16 v[8:11], v[142:145], v[190:193], 0
	v_mfma_f32_16x16x32_f16 v[60:63], v[138:141], v[170:173], v[60:63]
	v_mfma_f32_16x16x32_f16 v[56:59], v[146:149], v[170:173], v[56:59]
	v_mfma_f32_16x16x32_f16 v[44:47], v[138:141], v[178:181], v[44:47]
	v_mfma_f32_16x16x32_f16 v[40:43], v[146:149], v[178:181], v[40:43]
	v_mfma_f32_16x16x32_f16 v[28:31], v[138:141], v[186:189], v[28:31]
	v_mfma_f32_16x16x32_f16 v[24:27], v[146:149], v[186:189], v[24:27]
	s_waitcnt lgkmcnt(0)
	v_mfma_f32_16x16x32_f16 v[12:15], v[138:141], v[194:197], v[12:15]
	v_mfma_f32_16x16x32_f16 v[8:11], v[146:149], v[194:197], v[8:11]
	v_mfma_f32_16x16x32_f16 v[52:55], v[150:153], v[166:169], 0
	v_mfma_f32_16x16x32_f16 v[48:51], v[158:161], v[166:169], 0
	v_mfma_f32_16x16x32_f16 v[36:39], v[150:153], v[174:177], 0
	v_mfma_f32_16x16x32_f16 v[32:35], v[158:161], v[174:177], 0
	v_mfma_f32_16x16x32_f16 v[20:23], v[150:153], v[182:185], 0
	v_mfma_f32_16x16x32_f16 v[16:19], v[158:161], v[182:185], 0
	v_mfma_f32_16x16x32_f16 v[4:7], v[150:153], v[190:193], 0
	v_mfma_f32_16x16x32_f16 v[0:3], v[158:161], v[190:193], 0
	v_mfma_f32_16x16x32_f16 v[52:55], v[154:157], v[170:173], v[52:55]
	v_mfma_f32_16x16x32_f16 v[48:51], v[162:165], v[170:173], v[48:51]
	v_mfma_f32_16x16x32_f16 v[36:39], v[154:157], v[178:181], v[36:39]
	v_mfma_f32_16x16x32_f16 v[32:35], v[162:165], v[178:181], v[32:35]
	v_mfma_f32_16x16x32_f16 v[20:23], v[154:157], v[186:189], v[20:23]
	v_mfma_f32_16x16x32_f16 v[16:19], v[162:165], v[186:189], v[16:19]
	v_mfma_f32_16x16x32_f16 v[4:7], v[154:157], v[194:197], v[4:7]
	v_mfma_f32_16x16x32_f16 v[0:3], v[162:165], v[194:197], v[0:3]
	s_barrier
; #define PG8_STAGE(bufoff, gbase, voff) do { _Pragma("unroll") for (int _i = 0; _i < 2; ++_i) glds16_s((gbase), (voff)[_i], ldsb + (unsigned)((bufoff) + _i * 8192)); } while (0)
; #define PG8_LDA(dst, b, h) do { _Pragma("unroll") for (int m = 0; m < 4; ++m) _Pragma("unroll") for (int k = 0; k < 2; ++k) dst[m][k] = *(const LAS h16x8*)(lds + PG8_SA(b, h) + aoff + m * 2048 + k * 1024); } while (0)
; #define PG8_LDB(dst, b, h) do { _Pragma("unroll") for (int n = 0; n < 2; ++n) _Pragma("unroll") for (int k = 0; k < 2; ++k) dst[n][k] = *(const LAS h16x8*)(lds + PG8_SB(b, h) + boff + n * 2048 + k * 1024); } while (0)
; #define PG8_MMA(ai, bj, At, Bt) do { __builtin_amdgcn_s_setprio(1); _Pragma("unroll") for (int m = 0; m < 4; ++m) _Pragma("unroll") for (int n = 0; n < 2; ++n) _Pragma("unroll") for (int k = 0; k < 2; ++k) \
;         acc[ai][bj][m][n] = mma_step<I8>(Bt[n][k], At[m][k], acc[ai][bj][m][n]); __builtin_amdgcn_s_setprio(0); } while (0)
; #define PG8_WAIT_V(n) asm volatile("s_waitcnt vmcnt(" #n ")" ::: "memory")
; #define PG8_WAIT_L(n) asm volatile("s_waitcnt lgkmcnt(" #n ")" ::: "memory")
; #define PG8_BAR __builtin_amdgcn_s_barrier()
; #define PG8_SCHED __builtin_amdgcn_sched_barrier(0)
; template <class Prob, class Epi, bool I8 = false, bool ALIGN_EPI = true, bool SP2 = true>
; __device__ __forceinline__ void gemm_phase(LAS unsigned char* lds, int wave, const Prob& P, const Epi& E) {
;     ...
;             PG8_LDB(B0, 1, 0); PG8_LDB(B1, 1, 1); PG8_SCHED; PG8_LDA(At, 1, 0); PG8_STAGE(PG8_SA(0, 1), a2 + hstepA, voffA);
;             PG8_WAIT_V(8); PG8_WAIT_L(0); PG8_BAR; PG8_MMA(0, 0, At, B0); PG8_MMA(0, 1, At, B1); PG8_BAR; PG8_SCHED;
;             PG8_LDA(At, 1, 1); PG8_STAGE(PG8_SB(1, 0), b3, voffB); PG8_STAGE(PG8_SB(1, 1), b3 + hstepB, voffB); PG8_STAGE(PG8_SA(1, 0), a3, voffA);
;             PG8_WAIT_V(8); PG8_WAIT_L(0); PG8_BAR; PG8_MMA(1, 0, At, B0); PG8_MMA(1, 1, At, B1); PG8_BAR; PG8_SCHED;
	v_add_u32_e32 v146, 0x18000, v136
	v_add_u32_e32 v162, 0x1c000, v136
	ds_read_b128 v[128:131], v146
	ds_read_b128 v[138:141], v146 offset:1024
	ds_read_b128 v[142:145], v146 offset:2048
	ds_read_b128 v[146:149], v146 offset:3072
	ds_read_b128 v[150:153], v162
	ds_read_b128 v[154:157], v162 offset:1024
	ds_read_b128 v[158:161], v162 offset:2048
	ds_read_b128 v[162:165], v162 offset:3072
	ds_read_b128 v[166:169], v137 offset:32768
	ds_read_b128 v[170:173], v137 offset:33792
	ds_read_b128 v[174:177], v137 offset:34816
	ds_read_b128 v[178:181], v137 offset:35840
	ds_read_b128 v[182:185], v137 offset:36864
	ds_read_b128 v[186:189], v137 offset:37888
	ds_read_b128 v[190:193], v137 offset:38912
	ds_read_b128 v[194:197], v137 offset:39936
	s_add_u32 s4, s44, 0x80000
	s_addc_u32 s5, s45, 0
	s_mov_b32 s6, m0
	s_mov_b32 m0, s81
	s_nop 0
	global_load_lds_dwordx4 v132, s[4:5]
	s_mov_b32 m0, s6
	s_nop 0
	s_mov_b32 s6, m0
	s_mov_b32 m0, s82
	s_nop 0
	global_load_lds_dwordx4 v134, s[4:5]
	s_mov_b32 m0, s6
	s_waitcnt vmcnt(8)
	s_waitcnt lgkmcnt(0)
	s_barrier
	s_waitcnt lgkmcnt(7)
	v_mfma_f32_16x16x32_f16 v[124:127], v[128:131], v[166:169], v[124:127]
	v_mfma_f32_16x16x32_f16 v[120:123], v[142:145], v[166:169], v[120:123]
	s_waitcnt lgkmcnt(5)
	v_mfma_f32_16x16x32_f16 v[108:111], v[128:131], v[174:177], v[108:111]
	v_mfma_f32_16x16x32_f16 v[104:107], v[142:145], v[174:177], v[104:107]
	s_waitcnt lgkmcnt(3)
	v_mfma_f32_16x16x32_f16 v[92:95], v[128:131], v[182:185], v[92:95]
	v_mfma_f32_16x16x32_f16 v[88:91], v[142:145], v[182:185], v[88:91]
	s_waitcnt lgkmcnt(1)
	v_mfma_f32_16x16x32_f16 v[76:79], v[128:131], v[190:193], v[76:79]
	v_mfma_f32_16x16x32_f16 v[72:75], v[142:145], v[190:193], v[72:75]
	v_mfma_f32_16x16x32_f16 v[124:127], v[138:141], v[170:173], v[124:127]
	v_mfma_f32_16x16x32_f16 v[120:123], v[146:149], v[170:173], v[120:123]
	v_mfma_f32_16x16x32_f16 v[108:111], v[138:141], v[178:181], v[108:111]
	v_mfma_f32_16x16x32_f16 v[104:107], v[146:149], v[178:181], v[104:107]
	v_mfma_f32_16x16x32_f16 v[92:95], v[138:141], v[186:189], v[92:95]
	v_mfma_f32_16x16x32_f16 v[88:91], v[146:149], v[186:189], v[88:91]
	s_waitcnt lgkmcnt(0)
	v_mfma_f32_16x16x32_f16 v[76:79], v[138:141], v[194:197], v[76:79]
	v_mfma_f32_16x16x32_f16 v[72:75], v[146:149], v[194:197], v[72:75]
	v_mfma_f32_16x16x32_f16 v[116:119], v[150:153], v[166:169], v[116:119]
	v_mfma_f32_16x16x32_f16 v[112:115], v[158:161], v[166:169], v[112:115]
	v_mfma_f32_16x16x32_f16 v[100:103], v[150:153], v[174:177], v[100:103]
	v_mfma_f32_16x16x32_f16 v[96:99], v[158:161], v[174:177], v[96:99]
	v_mfma_f32_16x16x32_f16 v[84:87], v[150:153], v[182:185], v[84:87]
	v_mfma_f32_16x16x32_f16 v[80:83], v[158:161], v[182:185], v[80:83]
	v_mfma_f32_16x16x32_f16 v[68:71], v[150:153], v[190:193], v[68:71]
	v_mfma_f32_16x16x32_f16 v[64:67], v[158:161], v[190:193], v[64:67]
	v_mfma_f32_16x16x32_f16 v[116:119], v[154:157], v[170:173], v[116:119]
	v_mfma_f32_16x16x32_f16 v[112:115], v[162:165], v[170:173], v[112:115]
	v_mfma_f32_16x16x32_f16 v[100:103], v[154:157], v[178:181], v[100:103]
	v_mfma_f32_16x16x32_f16 v[96:99], v[162:165], v[178:181], v[96:99]
	v_mfma_f32_16x16x32_f16 v[84:87], v[154:157], v[186:189], v[84:87]
	v_mfma_f32_16x16x32_f16 v[80:83], v[162:165], v[186:189], v[80:83]
	v_mfma_f32_16x16x32_f16 v[68:71], v[154:157], v[194:197], v[68:71]
	v_mfma_f32_16x16x32_f16 v[64:67], v[162:165], v[194:197], v[64:67]
	s_barrier
	ds_read_b128 v[166:169], v137 offset:49152
	ds_read_b128 v[170:173], v137 offset:50176
	ds_read_b128 v[174:177], v137 offset:51200
	ds_read_b128 v[178:181], v137 offset:52224
	ds_read_b128 v[182:185], v137 offset:53248
	ds_read_b128 v[186:189], v137 offset:54272
	ds_read_b128 v[190:193], v137 offset:55296
	ds_read_b128 v[194:197], v137 offset:56320
	s_add_u32 s4, s42, 0x80
	s_addc_u32 s5, s43, 0
	s_mov_b32 s6, m0
	s_mov_b32 m0, s85
	s_nop 0
	global_load_lds_dwordx4 v133, s[4:5]
	s_mov_b32 m0, s6
	s_nop 0
	s_mov_b32 s6, m0
	s_mov_b32 m0, s86
	s_nop 0
	global_load_lds_dwordx4 v135, s[4:5]
	s_mov_b32 m0, s6
	s_add_u32 s4, s42, 0x80080
	s_addc_u32 s5, s43, 0
	s_mov_b32 s6, m0
	s_mov_b32 m0, s89
	s_nop 0
	global_load_lds_dwordx4 v133, s[4:5]
	s_mov_b32 m0, s6
	s_nop 0
	s_mov_b32 s6, m0
	s_mov_b32 m0, s90
	s_nop 0
	global_load_lds_dwordx4 v135, s[4:5]
	s_mov_b32 m0, s6
	s_mov_b32 s4, m0
	s_mov_b32 m0, s87
	s_nop 0
	global_load_lds_dwordx4 v132, s[40:41]
	s_mov_b32 m0, s4
	s_nop 0
	s_mov_b32 s4, m0
	s_mov_b32 m0, s88
	s_nop 0
	global_load_lds_dwordx4 v134, s[40:41]
	s_mov_b32 m0, s4
	s_waitcnt vmcnt(8)
	s_waitcnt lgkmcnt(0)
	s_barrier
	s_waitcnt lgkmcnt(7)
	v_mfma_f32_16x16x32_f16 v[60:63], v[128:131], v[166:169], v[60:63]
	v_mfma_f32_16x16x32_f16 v[56:59], v[142:145], v[166:169], v[56:59]
	s_waitcnt lgkmcnt(5)
	v_mfma_f32_16x16x32_f16 v[44:47], v[128:131], v[174:177], v[44:47]
	v_mfma_f32_16x16x32_f16 v[40:43], v[142:145], v[174:177], v[40:43]
	s_waitcnt lgkmcnt(3)
	v_mfma_f32_16x16x32_f16 v[28:31], v[128:131], v[182:185], v[28:31]
	v_mfma_f32_16x16x32_f16 v[24:27], v[142:145], v[182:185], v[24:27]
	s_waitcnt lgkmcnt(1)
	v_mfma_f32_16x16x32_f16 v[12:15], v[128:131], v[190:193], v[12:15]
	v_mfma_f32_16x16x32_f16 v[8:11], v[142:145], v[190:193], v[8:11]
	v_mfma_f32_16x16x32_f16 v[60:63], v[138:141], v[170:173], v[60:63]
	v_mfma_f32_16x16x32_f16 v[56:59], v[146:149], v[170:173], v[56:59]
	v_mfma_f32_16x16x32_f16 v[44:47], v[138:141], v[178:181], v[44:47]
	v_mfma_f32_16x16x32_f16 v[40:43], v[146:149], v[178:181], v[40:43]
	v_mfma_f32_16x16x32_f16 v[28:31], v[138:141], v[186:189], v[28:31]
	v_mfma_f32_16x16x32_f16 v[24:27], v[146:149], v[186:189], v[24:27]
	s_waitcnt lgkmcnt(0)
	v_mfma_f32_16x16x32_f16 v[12:15], v[138:141], v[194:197], v[12:15]
	v_mfma_f32_16x16x32_f16 v[8:11], v[146:149], v[194:197], v[8:11]
	v_mfma_f32_16x16x32_f16 v[52:55], v[150:153], v[166:169], v[52:55]
	v_mfma_f32_16x16x32_f16 v[48:51], v[158:161], v[166:169], v[48:51]
	v_mfma_f32_16x16x32_f16 v[36:39], v[150:153], v[174:177], v[36:39]
	v_mfma_f32_16x16x32_f16 v[32:35], v[158:161], v[174:177], v[32:35]
	v_mfma_f32_16x16x32_f16 v[20:23], v[150:153], v[182:185], v[20:23]
	v_mfma_f32_16x16x32_f16 v[16:19], v[158:161], v[182:185], v[16:19]
	v_mfma_f32_16x16x32_f16 v[4:7], v[150:153], v[190:193], v[4:7]
	v_mfma_f32_16x16x32_f16 v[0:3], v[158:161], v[190:193], v[0:3]
	v_mfma_f32_16x16x32_f16 v[52:55], v[154:157], v[170:173], v[52:55]
	v_mfma_f32_16x16x32_f16 v[48:51], v[162:165], v[170:173], v[48:51]
	v_mfma_f32_16x16x32_f16 v[36:39], v[154:157], v[178:181], v[36:39]
	v_mfma_f32_16x16x32_f16 v[32:35], v[162:165], v[178:181], v[32:35]
	v_mfma_f32_16x16x32_f16 v[20:23], v[154:157], v[186:189], v[20:23]
	v_mfma_f32_16x16x32_f16 v[16:19], v[162:165], v[186:189], v[16:19]
	v_mfma_f32_16x16x32_f16 v[4:7], v[154:157], v[194:197], v[4:7]
	v_mfma_f32_16x16x32_f16 v[0:3], v[162:165], v[194:197], v[0:3]
	s_barrier
	s_add_i32 s1, s1, 2
	s_add_u32 s73, s73, 0x100
	s_addc_u32 s74, s74, 0
	s_add_u32 s75, s75, 0x100
	s_addc_u32 s0, s0, 0
	s_add_u32 s38, s38, 0x100
	s_addc_u32 s39, s39, 0
	s_cmp_gt_u32 s1, 29
; #define PG8_STAGE(bufoff, gbase, voff) do { _Pragma("unroll") for (int _i = 0; _i < 2; ++_i) glds16_s((gbase), (voff)[_i], ldsb + (unsigned)((bufoff) + _i * 8192)); } while (0)
; #define PG8_LDA(dst, b, h) do { _Pragma("unroll") for (int m = 0; m < 4; ++m) _Pragma("unroll") for (int k = 0; k < 2; ++k) dst[m][k] = *(const LAS h16x8*)(lds + PG8_SA(b, h) + aoff + m * 2048 + k * 1024); } while (0)
; #define PG8_LDB(dst, b, h) do { _Pragma("unroll") for (int n = 0; n < 2; ++n) _Pragma("unroll") for (int k = 0; k < 2; ++k) dst[n][k] = *(const LAS h16x8*)(lds + PG8_SB(b, h) + boff + n * 2048 + k * 1024); } while (0)
; #define PG8_MMA(ai, bj, At, Bt) do { __builtin_amdgcn_s_setprio(1); _Pragma("unroll") for (int m = 0; m < 4; ++m) _Pragma("unroll") for (int n = 0; n < 2; ++n) _Pragma("unroll") for (int k = 0; k < 2; ++k) \
;         acc[ai][bj][m][n] = mma_step<I8>(Bt[n][k], At[m][k], acc[ai][bj][m][n]); __builtin_amdgcn_s_setprio(0); } while (0)
; #define PG8_WAIT_V(n) asm volatile("s_waitcnt vmcnt(" #n ")" ::: "memory")
; #define PG8_WAIT_L(n) asm volatile("s_waitcnt lgkmcnt(" #n ")" ::: "memory")
; #define PG8_BAR __builtin_amdgcn_s_barrier()
; #define PG8_SCHED __builtin_amdgcn_sched_barrier(0)
; template <class Prob, class Epi, bool I8 = false, bool ALIGN_EPI = true, bool SP2 = true>
; __device__ __forceinline__ void gemm_phase(LAS unsigned char* lds, int wave, const Prob& P, const Epi& E) {
;     ...
;         for (int t = 0; t < nt; t += 2) {
;             const bool last = (t == nt - 2);
;             const char* a1 = cA + (size_t)(t + 1) * kstep;
;             const char* a2 = last ? nA : cA + (size_t)(t + 2) * kstep; const char* b2 = last ? nB : cB + (size_t)(t + 2) * kstep;
;             const char* a3 = a2 + kstep; const char* b3 = b2 + kstep;
;             if constexpr (SP2) {
;             PG8_LDB(B0, 0, 0); PG8_LDB(B1, 0, 1); PG8_SCHED; PG8_LDA(At, 0, 0); PG8_STAGE(PG8_SA(1, 1), a1 + hstepA, voffA);
;             PG8_WAIT_V(8); PG8_WAIT_L(0); PG8_BAR; PG8_MMA(0, 0, At, B0); PG8_MMA(0, 1, At, B1); PG8_BAR; PG8_SCHED;
;             PG8_LDA(At, 0, 1); PG8_STAGE(PG8_SB(0, 0), b2, voffB); PG8_STAGE(PG8_SB(0, 1), b2 + hstepB, voffB); PG8_STAGE(PG8_SA(0, 0), a2, voffA);
;             PG8_WAIT_V(8); PG8_WAIT_L(0); PG8_BAR; PG8_MMA(1, 0, At, B0); PG8_MMA(1, 1, At, B1); PG8_BAR; PG8_SCHED;
.LBB0_536:
	v_add_u32_e32 v146, 0x10000, v136
	v_add_u32_e32 v162, 0x14000, v136
	ds_read_b128 v[128:131], v146
	ds_read_b128 v[138:141], v146 offset:1024
	ds_read_b128 v[142:145], v146 offset:2048
	ds_read_b128 v[146:149], v146 offset:3072
	ds_read_b128 v[150:153], v162
	ds_read_b128 v[154:157], v162 offset:1024
	ds_read_b128 v[158:161], v162 offset:2048
	ds_read_b128 v[162:165], v162 offset:3072
	s_cmp_eq_u32 s1, 28
	s_cselect_b32 s44, s57, s73
	s_cselect_b32 s45, s51, s74
	s_cselect_b32 s42, s72, s75
	s_cselect_b32 s43, s49, s0
	s_add_u32 s40, s44, 0x80
	s_addc_u32 s41, s45, 0
	ds_read_b128 v[166:169], v137
	ds_read_b128 v[170:173], v137 offset:1024
	ds_read_b128 v[174:177], v137 offset:2048
	ds_read_b128 v[178:181], v137 offset:3072
	ds_read_b128 v[182:185], v137 offset:4096
	ds_read_b128 v[186:189], v137 offset:5120
	ds_read_b128 v[190:193], v137 offset:6144
	ds_read_b128 v[194:197], v137 offset:7168
	s_mov_b32 s4, m0
	s_mov_b32 m0, s91
	s_nop 0
	global_load_lds_dwordx4 v132, s[38:39]
	s_mov_b32 m0, s4
	s_nop 0
	s_mov_b32 s4, m0
	s_mov_b32 m0, s94
	s_nop 0
	global_load_lds_dwordx4 v134, s[38:39]
	s_mov_b32 m0, s4
	s_waitcnt vmcnt(8)
	s_waitcnt lgkmcnt(0)
	s_barrier
	s_waitcnt lgkmcnt(7)
	v_mfma_f32_16x16x32_f16 v[124:127], v[128:131], v[166:169], v[124:127]
	v_mfma_f32_16x16x32_f16 v[120:123], v[142:145], v[166:169], v[120:123]
	s_waitcnt lgkmcnt(5)
	v_mfma_f32_16x16x32_f16 v[108:111], v[128:131], v[174:177], v[108:111]
	v_mfma_f32_16x16x32_f16 v[104:107], v[142:145], v[174:177], v[104:107]
	s_waitcnt lgkmcnt(3)
	v_mfma_f32_16x16x32_f16 v[92:95], v[128:131], v[182:185], v[92:95]
	v_mfma_f32_16x16x32_f16 v[88:91], v[142:145], v[182:185], v[88:91]
	s_waitcnt lgkmcnt(1)
	v_mfma_f32_16x16x32_f16 v[76:79], v[128:131], v[190:193], v[76:79]
	v_mfma_f32_16x16x32_f16 v[72:75], v[142:145], v[190:193], v[72:75]
	v_mfma_f32_16x16x32_f16 v[124:127], v[138:141], v[170:173], v[124:127]
	v_mfma_f32_16x16x32_f16 v[120:123], v[146:149], v[170:173], v[120:123]
	v_mfma_f32_16x16x32_f16 v[108:111], v[138:141], v[178:181], v[108:111]
	v_mfma_f32_16x16x32_f16 v[104:107], v[146:149], v[178:181], v[104:107]
	v_mfma_f32_16x16x32_f16 v[92:95], v[138:141], v[186:189], v[92:95]
	v_mfma_f32_16x16x32_f16 v[88:91], v[146:149], v[186:189], v[88:91]
	s_waitcnt lgkmcnt(0)
	v_mfma_f32_16x16x32_f16 v[76:79], v[138:141], v[194:197], v[76:79]
	v_mfma_f32_16x16x32_f16 v[72:75], v[146:149], v[194:197], v[72:75]
	v_mfma_f32_16x16x32_f16 v[116:119], v[150:153], v[166:169], v[116:119]
	v_mfma_f32_16x16x32_f16 v[112:115], v[158:161], v[166:169], v[112:115]
	v_mfma_f32_16x16x32_f16 v[100:103], v[150:153], v[174:177], v[100:103]
	v_mfma_f32_16x16x32_f16 v[96:99], v[158:161], v[174:177], v[96:99]
	v_mfma_f32_16x16x32_f16 v[84:87], v[150:153], v[182:185], v[84:87]
	v_mfma_f32_16x16x32_f16 v[80:83], v[158:161], v[182:185], v[80:83]
	v_mfma_f32_16x16x32_f16 v[68:71], v[150:153], v[190:193], v[68:71]
	v_mfma_f32_16x16x32_f16 v[64:67], v[158:161], v[190:193], v[64:67]
	v_mfma_f32_16x16x32_f16 v[116:119], v[154:157], v[170:173], v[116:119]
	v_mfma_f32_16x16x32_f16 v[112:115], v[162:165], v[170:173], v[112:115]
	v_mfma_f32_16x16x32_f16 v[100:103], v[154:157], v[178:181], v[100:103]
	v_mfma_f32_16x16x32_f16 v[96:99], v[162:165], v[178:181], v[96:99]
	v_mfma_f32_16x16x32_f16 v[84:87], v[154:157], v[186:189], v[84:87]
	v_mfma_f32_16x16x32_f16 v[80:83], v[162:165], v[186:189], v[80:83]
	v_mfma_f32_16x16x32_f16 v[68:71], v[154:157], v[194:197], v[68:71]
	v_mfma_f32_16x16x32_f16 v[64:67], v[162:165], v[194:197], v[64:67]
	s_barrier
	ds_read_b128 v[166:169], v137 offset:16384
	ds_read_b128 v[170:173], v137 offset:17408
	ds_read_b128 v[174:177], v137 offset:18432
	ds_read_b128 v[178:181], v137 offset:19456
	ds_read_b128 v[182:185], v137 offset:20480
	ds_read_b128 v[186:189], v137 offset:21504
	ds_read_b128 v[190:193], v137 offset:22528
	ds_read_b128 v[194:197], v137 offset:23552
	s_mov_b32 s4, m0
	s_mov_b32 m0, s64
	s_nop 0
	global_load_lds_dwordx4 v133, s[42:43]
	s_mov_b32 m0, s4
	s_nop 0
	s_mov_b32 s4, m0
	s_mov_b32 m0, s68
	s_nop 0
	global_load_lds_dwordx4 v135, s[42:43]
	s_mov_b32 m0, s4
	s_add_u32 s4, s42, 0x80000
	s_addc_u32 s5, s43, 0
	s_mov_b32 s6, m0
	s_mov_b32 m0, s69
	s_nop 0
	global_load_lds_dwordx4 v133, s[4:5]
	s_mov_b32 m0, s6
	s_nop 0
	s_mov_b32 s6, m0
	s_mov_b32 m0, s79
	s_nop 0
	global_load_lds_dwordx4 v135, s[4:5]
	s_mov_b32 m0, s6
	s_mov_b32 s4, m0
	s_mov_b32 m0, s63
	s_nop 0
	global_load_lds_dwordx4 v132, s[44:45]
	s_mov_b32 m0, s4
	s_nop 0
	s_mov_b32 s4, m0
	s_mov_b32 m0, s80
	s_nop 0
	global_load_lds_dwordx4 v134, s[44:45]
	s_mov_b32 m0, s4
	s_waitcnt vmcnt(8)
	s_waitcnt lgkmcnt(0)
	s_barrier
; #define PG8_STAGE(bufoff, gbase, voff) do { _Pragma("unroll") for (int _i = 0; _i < 2; ++_i) glds16_s((gbase), (voff)[_i], ldsb + (unsigned)((bufoff) + _i * 8192)); } while (0)
; #define PG8_LDA(dst, b, h) do { _Pragma("unroll") for (int m = 0; m < 4; ++m) _Pragma("unroll") for (int k = 0; k < 2; ++k) dst[m][k] = *(const LAS h16x8*)(lds + PG8_SA(b, h) + aoff + m * 2048 + k * 1024); } while (0)
; #define PG8_LDB(dst, b, h) do { _Pragma("unroll") for (int n = 0; n < 2; ++n) _Pragma("unroll") for (int k = 0; k < 2; ++k) dst[n][k] = *(const LAS h16x8*)(lds + PG8_SB(b, h) + boff + n * 2048 + k * 1024); } while (0)
; #define PG8_MMA(ai, bj, At, Bt) do { __builtin_amdgcn_s_setprio(1); _Pragma("unroll") for (int m = 0; m < 4; ++m) _Pragma("unroll") for (int n = 0; n < 2; ++n) _Pragma("unroll") for (int k = 0; k < 2; ++k) \
;         acc[ai][bj][m][n] = mma_step<I8>(Bt[n][k], At[m][k], acc[ai][bj][m][n]); __builtin_amdgcn_s_setprio(0); } while (0)
; #define PG8_WAIT_V(n) asm volatile("s_waitcnt vmcnt(" #n ")" ::: "memory")
; #define PG8_WAIT_L(n) asm volatile("s_waitcnt lgkmcnt(" #n ")" ::: "memory")
; #define PG8_BAR __builtin_amdgcn_s_barrier()
; #define PG8_SCHED __builtin_amdgcn_sched_barrier(0)
; template <class Prob, class Epi, bool I8 = false, bool ALIGN_EPI = true, bool SP2 = true>
; __device__ __forceinline__ void gemm_phase(LAS unsigned char* lds, int wave, const Prob& P, const Epi& E) {
;     ...
;             PG8_WAIT_V(8); PG8_WAIT_L(0); PG8_BAR; PG8_MMA(1, 0, At, B0); PG8_MMA(1, 1, At, B1); PG8_BAR; PG8_SCHED;
;             PG8_LDB(B0, 1, 0); PG8_LDB(B1, 1, 1); PG8_SCHED; PG8_LDA(At, 1, 0); PG8_STAGE(PG8_SA(0, 1), a2 + hstepA, voffA);
;             PG8_WAIT_V(8); PG8_WAIT_L(0); PG8_BAR; PG8_MMA(0, 0, At, B0); PG8_MMA(0, 1, At, B1); PG8_BAR; PG8_SCHED;
;             PG8_LDA(At, 1, 1); PG8_STAGE(PG8_SB(1, 0), b3, voffB); PG8_STAGE(PG8_SB(1, 1), b3 + hstepB, voffB); PG8_STAGE(PG8_SA(1, 0), a3, voffA);
	s_waitcnt lgkmcnt(7)
	v_mfma_f32_16x16x32_f16 v[60:63], v[128:131], v[166:169], v[60:63]
	v_mfma_f32_16x16x32_f16 v[56:59], v[142:145], v[166:169], v[56:59]
	s_waitcnt lgkmcnt(5)
	v_mfma_f32_16x16x32_f16 v[44:47], v[128:131], v[174:177], v[44:47]
	v_mfma_f32_16x16x32_f16 v[40:43], v[142:145], v[174:177], v[40:43]
	s_waitcnt lgkmcnt(3)
	v_mfma_f32_16x16x32_f16 v[28:31], v[128:131], v[182:185], v[28:31]
	v_mfma_f32_16x16x32_f16 v[24:27], v[142:145], v[182:185], v[24:27]
	s_waitcnt lgkmcnt(1)
	v_mfma_f32_16x16x32_f16 v[12:15], v[128:131], v[190:193], v[12:15]
	v_mfma_f32_16x16x32_f16 v[8:11], v[142:145], v[190:193], v[8:11]
	v_mfma_f32_16x16x32_f16 v[60:63], v[138:141], v[170:173], v[60:63]
	v_mfma_f32_16x16x32_f16 v[56:59], v[146:149], v[170:173], v[56:59]
	v_mfma_f32_16x16x32_f16 v[44:47], v[138:141], v[178:181], v[44:47]
	v_mfma_f32_16x16x32_f16 v[40:43], v[146:149], v[178:181], v[40:43]
	v_mfma_f32_16x16x32_f16 v[28:31], v[138:141], v[186:189], v[28:31]
	v_mfma_f32_16x16x32_f16 v[24:27], v[146:149], v[186:189], v[24:27]
	s_waitcnt lgkmcnt(0)
	v_mfma_f32_16x16x32_f16 v[12:15], v[138:141], v[194:197], v[12:15]
	v_mfma_f32_16x16x32_f16 v[8:11], v[146:149], v[194:197], v[8:11]
	v_mfma_f32_16x16x32_f16 v[52:55], v[150:153], v[166:169], v[52:55]
	v_mfma_f32_16x16x32_f16 v[48:51], v[158:161], v[166:169], v[48:51]
	v_mfma_f32_16x16x32_f16 v[36:39], v[150:153], v[174:177], v[36:39]
	v_mfma_f32_16x16x32_f16 v[32:35], v[158:161], v[174:177], v[32:35]
	v_mfma_f32_16x16x32_f16 v[20:23], v[150:153], v[182:185], v[20:23]
	v_mfma_f32_16x16x32_f16 v[16:19], v[158:161], v[182:185], v[16:19]
	v_mfma_f32_16x16x32_f16 v[4:7], v[150:153], v[190:193], v[4:7]
	v_mfma_f32_16x16x32_f16 v[0:3], v[158:161], v[190:193], v[0:3]
	v_mfma_f32_16x16x32_f16 v[52:55], v[154:157], v[170:173], v[52:55]
	v_mfma_f32_16x16x32_f16 v[48:51], v[162:165], v[170:173], v[48:51]
	v_mfma_f32_16x16x32_f16 v[36:39], v[154:157], v[178:181], v[36:39]
	v_mfma_f32_16x16x32_f16 v[32:35], v[162:165], v[178:181], v[32:35]
	v_mfma_f32_16x16x32_f16 v[20:23], v[154:157], v[186:189], v[20:23]
	v_mfma_f32_16x16x32_f16 v[16:19], v[162:165], v[186:189], v[16:19]
	v_mfma_f32_16x16x32_f16 v[4:7], v[154:157], v[194:197], v[4:7]
	v_mfma_f32_16x16x32_f16 v[0:3], v[162:165], v[194:197], v[0:3]
	s_barrier
	v_add_u32_e32 v146, 0x18000, v136
	v_add_u32_e32 v162, 0x1c000, v136
	ds_read_b128 v[128:131], v146
	ds_read_b128 v[138:141], v146 offset:1024
	ds_read_b128 v[142:145], v146 offset:2048
	ds_read_b128 v[146:149], v146 offset:3072
	ds_read_b128 v[150:153], v162
	ds_read_b128 v[154:157], v162 offset:1024
	ds_read_b128 v[158:161], v162 offset:2048
	ds_read_b128 v[162:165], v162 offset:3072
	ds_read_b128 v[166:169], v137 offset:32768
	ds_read_b128 v[170:173], v137 offset:33792
	ds_read_b128 v[174:177], v137 offset:34816
	ds_read_b128 v[178:181], v137 offset:35840
	ds_read_b128 v[182:185], v137 offset:36864
	ds_read_b128 v[186:189], v137 offset:37888
	ds_read_b128 v[190:193], v137 offset:38912
	ds_read_b128 v[194:197], v137 offset:39936
	s_add_u32 s4, s44, 0x80000
	s_addc_u32 s5, s45, 0
	s_mov_b32 s6, m0
	s_mov_b32 m0, s81
	s_nop 0
	global_load_lds_dwordx4 v132, s[4:5]
	s_mov_b32 m0, s6
	s_nop 0
	s_mov_b32 s6, m0
	s_mov_b32 m0, s82
	s_nop 0
	global_load_lds_dwordx4 v134, s[4:5]
	s_mov_b32 m0, s6
	s_waitcnt vmcnt(8)
	s_waitcnt lgkmcnt(0)
	s_barrier
	s_waitcnt lgkmcnt(7)
	v_mfma_f32_16x16x32_f16 v[124:127], v[128:131], v[166:169], v[124:127]
	v_mfma_f32_16x16x32_f16 v[120:123], v[142:145], v[166:169], v[120:123]
	s_waitcnt lgkmcnt(5)
	v_mfma_f32_16x16x32_f16 v[108:111], v[128:131], v[174:177], v[108:111]
	v_mfma_f32_16x16x32_f16 v[104:107], v[142:145], v[174:177], v[104:107]
	s_waitcnt lgkmcnt(3)
	v_mfma_f32_16x16x32_f16 v[92:95], v[128:131], v[182:185], v[92:95]
	v_mfma_f32_16x16x32_f16 v[88:91], v[142:145], v[182:185], v[88:91]
	s_waitcnt lgkmcnt(1)
	v_mfma_f32_16x16x32_f16 v[76:79], v[128:131], v[190:193], v[76:79]
	v_mfma_f32_16x16x32_f16 v[72:75], v[142:145], v[190:193], v[72:75]
	v_mfma_f32_16x16x32_f16 v[124:127], v[138:141], v[170:173], v[124:127]
	v_mfma_f32_16x16x32_f16 v[120:123], v[146:149], v[170:173], v[120:123]
	v_mfma_f32_16x16x32_f16 v[108:111], v[138:141], v[178:181], v[108:111]
	v_mfma_f32_16x16x32_f16 v[104:107], v[146:149], v[178:181], v[104:107]
	v_mfma_f32_16x16x32_f16 v[92:95], v[138:141], v[186:189], v[92:95]
	v_mfma_f32_16x16x32_f16 v[88:91], v[146:149], v[186:189], v[88:91]
	s_waitcnt lgkmcnt(0)
	v_mfma_f32_16x16x32_f16 v[76:79], v[138:141], v[194:197], v[76:79]
	v_mfma_f32_16x16x32_f16 v[72:75], v[146:149], v[194:197], v[72:75]
	v_mfma_f32_16x16x32_f16 v[116:119], v[150:153], v[166:169], v[116:119]
	v_mfma_f32_16x16x32_f16 v[112:115], v[158:161], v[166:169], v[112:115]
	v_mfma_f32_16x16x32_f16 v[100:103], v[150:153], v[174:177], v[100:103]
	v_mfma_f32_16x16x32_f16 v[96:99], v[158:161], v[174:177], v[96:99]
	v_mfma_f32_16x16x32_f16 v[84:87], v[150:153], v[182:185], v[84:87]
	v_mfma_f32_16x16x32_f16 v[80:83], v[158:161], v[182:185], v[80:83]
	v_mfma_f32_16x16x32_f16 v[68:71], v[150:153], v[190:193], v[68:71]
	v_mfma_f32_16x16x32_f16 v[64:67], v[158:161], v[190:193], v[64:67]
	v_mfma_f32_16x16x32_f16 v[116:119], v[154:157], v[170:173], v[116:119]
	v_mfma_f32_16x16x32_f16 v[112:115], v[162:165], v[170:173], v[112:115]
	v_mfma_f32_16x16x32_f16 v[100:103], v[154:157], v[178:181], v[100:103]
	v_mfma_f32_16x16x32_f16 v[96:99], v[162:165], v[178:181], v[96:99]
	v_mfma_f32_16x16x32_f16 v[84:87], v[154:157], v[186:189], v[84:87]
	v_mfma_f32_16x16x32_f16 v[80:83], v[162:165], v[186:189], v[80:83]
	v_mfma_f32_16x16x32_f16 v[68:71], v[154:157], v[194:197], v[68:71]
	v_mfma_f32_16x16x32_f16 v[64:67], v[162:165], v[194:197], v[64:67]
	s_barrier
; #define PG8_STAGE(bufoff, gbase, voff) do { _Pragma("unroll") for (int _i = 0; _i < 2; ++_i) glds16_s((gbase), (voff)[_i], ldsb + (unsigned)((bufoff) + _i * 8192)); } while (0)
; #define PG8_LDA(dst, b, h) do { _Pragma("unroll") for (int m = 0; m < 4; ++m) _Pragma("unroll") for (int k = 0; k < 2; ++k) dst[m][k] = *(const LAS h16x8*)(lds + PG8_SA(b, h) + aoff + m * 2048 + k * 1024); } while (0)
; #define PG8_LDB(dst, b, h) do { _Pragma("unroll") for (int n = 0; n < 2; ++n) _Pragma("unroll") for (int k = 0; k < 2; ++k) dst[n][k] = *(const LAS h16x8*)(lds + PG8_SB(b, h) + boff + n * 2048 + k * 1024); } while (0)
; #define PG8_WAIT_V(n) asm volatile("s_waitcnt vmcnt(" #n ")" ::: "memory")
; #define PG8_WAIT_L(n) asm volatile("s_waitcnt lgkmcnt(" #n ")" ::: "memory")
; template <class Prob, class Epi, bool I8 = false, bool ALIGN_EPI = true, bool SP2 = true>
; __device__ __forceinline__ void gemm_phase(LAS unsigned char* lds, int wave, const Prob& P, const Epi& E) {
;     ...
;         for (int t = 0; t < nt; t += 2) {
;             const bool last = (t == nt - 2);
;             const char* a1 = cA + (size_t)(t + 1) * kstep;
;             const char* a2 = last ? nA : cA + (size_t)(t + 2) * kstep; const char* b2 = last ? nB : cB + (size_t)(t + 2) * kstep;
;             const char* a3 = a2 + kstep; const char* b3 = b2 + kstep;
;             if constexpr (SP2) {
;             PG8_LDB(B0, 0, 0); PG8_LDB(B1, 0, 1); PG8_SCHED; PG8_LDA(At, 0, 0); PG8_STAGE(PG8_SA(1, 1), a1 + hstepA, voffA);
;             PG8_WAIT_V(8); PG8_WAIT_L(0); PG8_BAR; PG8_MMA(0, 0, At, B0); PG8_MMA(0, 1, At, B1); PG8_BAR; PG8_SCHED;
;             PG8_LDA(At, 0, 1); PG8_STAGE(PG8_SB(0, 0), b2, voffB); PG8_STAGE(PG8_SB(0, 1), b2 + hstepB, voffB); PG8_STAGE(PG8_SA(0, 0), a2, voffA);
;             PG8_WAIT_V(8); PG8_WAIT_L(0); PG8_BAR; PG8_MMA(1, 0, At, B0); PG8_MMA(1, 1, At, B1); PG8_BAR; PG8_SCHED;
;             PG8_LDB(B0, 1, 0); PG8_LDB(B1, 1, 1); PG8_SCHED; PG8_LDA(At, 1, 0); PG8_STAGE(PG8_SA(0, 1), a2 + hstepA, voffA);
;             PG8_WAIT_V(8); PG8_WAIT_L(0); PG8_BAR; PG8_MMA(0, 0, At, B0); PG8_MMA(0, 1, At, B1); PG8_BAR; PG8_SCHED;
;             PG8_LDA(At, 1, 1); PG8_STAGE(PG8_SB(1, 0), b3, voffB); PG8_STAGE(PG8_SB(1, 1), b3 + hstepB, voffB); PG8_STAGE(PG8_SA(1, 0), a3, voffA);
;             PG8_WAIT_V(8); PG8_WAIT_L(0); PG8_BAR; PG8_MMA(1, 0, At, B0); PG8_MMA(1, 1, At, B1); PG8_BAR; PG8_SCHED;
	ds_read_b128 v[166:169], v137 offset:49152
	ds_read_b128 v[170:173], v137 offset:50176
	ds_read_b128 v[174:177], v137 offset:51200
	ds_read_b128 v[178:181], v137 offset:52224
	ds_read_b128 v[182:185], v137 offset:53248
	ds_read_b128 v[186:189], v137 offset:54272
	ds_read_b128 v[190:193], v137 offset:55296
	ds_read_b128 v[194:197], v137 offset:56320
	s_add_u32 s4, s42, 0x80
	s_addc_u32 s5, s43, 0
	s_mov_b32 s6, m0
	s_mov_b32 m0, s85
	s_nop 0
	global_load_lds_dwordx4 v133, s[4:5]
	s_mov_b32 m0, s6
	s_nop 0
	s_mov_b32 s6, m0
	s_mov_b32 m0, s86
	s_nop 0
	global_load_lds_dwordx4 v135, s[4:5]
	s_mov_b32 m0, s6
	s_add_u32 s4, s42, 0x80080
	s_addc_u32 s5, s43, 0
	s_mov_b32 s6, m0
	s_mov_b32 m0, s89
	s_nop 0
	global_load_lds_dwordx4 v133, s[4:5]
	s_mov_b32 m0, s6
	s_nop 0
	s_mov_b32 s6, m0
	s_mov_b32 m0, s90
	s_nop 0
	global_load_lds_dwordx4 v135, s[4:5]
	s_mov_b32 m0, s6
	s_mov_b32 s4, m0
	s_mov_b32 m0, s87
	s_nop 0
	global_load_lds_dwordx4 v132, s[40:41]
	s_mov_b32 m0, s4
	s_nop 0
	s_mov_b32 s4, m0
	s_mov_b32 m0, s88
	s_nop 0
	global_load_lds_dwordx4 v134, s[40:41]
	s_mov_b32 m0, s4
	s_waitcnt vmcnt(8)
	s_waitcnt lgkmcnt(0)
	s_barrier
	s_waitcnt lgkmcnt(7)
	v_mfma_f32_16x16x32_f16 v[60:63], v[128:131], v[166:169], v[60:63]
	v_mfma_f32_16x16x32_f16 v[56:59], v[142:145], v[166:169], v[56:59]
	s_waitcnt lgkmcnt(5)
	v_mfma_f32_16x16x32_f16 v[44:47], v[128:131], v[174:177], v[44:47]
	v_mfma_f32_16x16x32_f16 v[40:43], v[142:145], v[174:177], v[40:43]
	s_waitcnt lgkmcnt(3)
	v_mfma_f32_16x16x32_f16 v[28:31], v[128:131], v[182:185], v[28:31]
	v_mfma_f32_16x16x32_f16 v[24:27], v[142:145], v[182:185], v[24:27]
	s_waitcnt lgkmcnt(1)
	v_mfma_f32_16x16x32_f16 v[12:15], v[128:131], v[190:193], v[12:15]
	v_mfma_f32_16x16x32_f16 v[8:11], v[142:145], v[190:193], v[8:11]
	v_mfma_f32_16x16x32_f16 v[60:63], v[138:141], v[170:173], v[60:63]
	v_mfma_f32_16x16x32_f16 v[56:59], v[146:149], v[170:173], v[56:59]
	v_mfma_f32_16x16x32_f16 v[44:47], v[138:141], v[178:181], v[44:47]
	v_mfma_f32_16x16x32_f16 v[40:43], v[146:149], v[178:181], v[40:43]
	v_mfma_f32_16x16x32_f16 v[28:31], v[138:141], v[186:189], v[28:31]
	v_mfma_f32_16x16x32_f16 v[24:27], v[146:149], v[186:189], v[24:27]
	s_waitcnt lgkmcnt(0)
	v_mfma_f32_16x16x32_f16 v[12:15], v[138:141], v[194:197], v[12:15]
	v_mfma_f32_16x16x32_f16 v[8:11], v[146:149], v[194:197], v[8:11]
	v_mfma_f32_16x16x32_f16 v[52:55], v[150:153], v[166:169], v[52:55]
	v_mfma_f32_16x16x32_f16 v[48:51], v[158:161], v[166:169], v[48:51]
	v_mfma_f32_16x16x32_f16 v[36:39], v[150:153], v[174:177], v[36:39]
	v_mfma_f32_16x16x32_f16 v[32:35], v[158:161], v[174:177], v[32:35]
	v_mfma_f32_16x16x32_f16 v[20:23], v[150:153], v[182:185], v[20:23]
	v_mfma_f32_16x16x32_f16 v[16:19], v[158:161], v[182:185], v[16:19]
	v_mfma_f32_16x16x32_f16 v[4:7], v[150:153], v[190:193], v[4:7]
	v_mfma_f32_16x16x32_f16 v[0:3], v[158:161], v[190:193], v[0:3]
	v_mfma_f32_16x16x32_f16 v[52:55], v[154:157], v[170:173], v[52:55]
	v_mfma_f32_16x16x32_f16 v[48:51], v[162:165], v[170:173], v[48:51]
	v_mfma_f32_16x16x32_f16 v[36:39], v[154:157], v[178:181], v[36:39]
	v_mfma_f32_16x16x32_f16 v[32:35], v[162:165], v[178:181], v[32:35]
	v_mfma_f32_16x16x32_f16 v[20:23], v[154:157], v[186:189], v[20:23]
	v_mfma_f32_16x16x32_f16 v[16:19], v[162:165], v[186:189], v[16:19]
	v_mfma_f32_16x16x32_f16 v[4:7], v[154:157], v[194:197], v[4:7]
	v_mfma_f32_16x16x32_f16 v[0:3], v[162:165], v[194:197], v[0:3]
	s_barrier
	s_add_i32 s1, s1, 2
	s_add_u32 s73, s73, 0x100
	s_addc_u32 s74, s74, 0
	s_add_u32 s75, s75, 0x100
	s_addc_u32 s0, s0, 0
	s_add_u32 s38, s38, 0x100
	s_addc_u32 s39, s39, 0
	s_cmp_gt_u32 s1, 29
	s_cbranch_scc0 .LBB0_536
	s_and_b64 vcc, exec, s[28:29]
	s_cbranch_vccz .LBB0_539
	s_barrier

; __device__ __forceinline__ int mk_lane() { int l; asm volatile("v_mbcnt_lo_u32_b32 %0, -1, 0\n\tv_mbcnt_hi_u32_b32 %0, -1, %0" : "=v"(l)); return l; }
; #define PG8_STAGE(bufoff, gbase, voff) do { _Pragma("unroll") for (int _i = 0; _i < 2; ++_i) glds16_s((gbase), (voff)[_i], ldsb + (unsigned)((bufoff) + _i * 8192)); } while (0)
; #define PG8_BAR __builtin_amdgcn_s_barrier()
;     __device__ bool next(int i, Unit& u) const { return S.next(i, u); }
;     __device__ unsigned a_rowoff(int R) const { const int r = upmap ? (128 * (R >> 6) + 8 * (R & 15) + ((R >> 4) & 3)) : R; return (unsigned)r * (unsigned)lda * 2u; }
; template <class Prob, class Epi, bool I8 = false, bool ALIGN_EPI = true, bool SP2 = true>
; __device__ __forceinline__ void gemm_phase(LAS unsigned char* lds, int wave, const Prob& P, const Epi& E) {
;     const int tid_ = wave * 64 + mk_lane();
;     const int tid = tid_, wid = __builtin_amdgcn_readfirstlane(tid >> 6), lane = tid & 63, wr = wid >> 2, wc = wid & 3, fr = lane & 15, fq = lane >> 4;
;     const int K = P.K, nt = K / BK;
;     unsigned voffA[2], voffB[2];
; #pragma unroll
;     for (int i = 0; i < 2; ++i) { int R, C; stage_rc(tid * 16 + i * 8192, R, C); const int Rb = (R & ~31) + perm32(R & 31);
;         voffA[i] = P.a_rowoff(R) + (unsigned)C * 2u; voffB[i] = P.b_rowoff(Rb) + (unsigned)C * 2u; }
;     const size_t kstep = (size_t)(BK * 2);
;     const size_t hstepA = P.a_hstep(), hstepB = P.b_hstep();
;     const unsigned ldsw = (unsigned)wid * 1024u;
;     const unsigned ldsb = (unsigned)(size_t)lds + ldsw;
;     const int aoff = lds_byte(wr * 64 + fr, fq * 8), boff = lds_byte(wc * 32 + fr, fq * 8);
;     ...
;     Unit cur, nxt; int ui = 0;
;     if (!P.next(0, cur)) return;
;     Acc acc;
; #pragma unroll
;     for (int a = 0; a < 2; ++a)
; #pragma unroll
;         for (int b = 0; b < 2; ++b)
; #pragma unroll
;             for (int m = 0; m < 4; ++m)
; #pragma unroll
;                 for (int n = 0; n < 2; ++n) acc[a][b][m][n] = (f32x4){0.f, 0.f, 0.f, 0.f};
;     h16x8 At[4][2], B0[2][2], B1[2][2];
;     const char* cA = P.a_tile(cur); const char* cB = P.b_tile(cur);
;     if constexpr (SP2) {
;         PG8_STAGE(PG8_SB(0, 0), cB, voffB); PG8_STAGE(PG8_SB(0, 1), cB + hstepB, voffB); PG8_STAGE(PG8_SA(0, 0), cA, voffA); PG8_STAGE(PG8_SA(0, 1), cA + hstepA, voffA);
;         if (wr == 1) PG8_BAR;
.LBB0_607:
	v_readlane_b32 s0, v254, 42
	s_waitcnt vmcnt(63) expcnt(7) lgkmcnt(15)
	s_barrier
	v_mbcnt_lo_u32_b32 v0, -1, 0
	v_mbcnt_hi_u32_b32 v0, -1, v0
	s_nop 0
	v_add_u32_e32 v1, s0, v0
	v_readlane_b32 s0, v252, 1
	v_readlane_b32 s1, v252, 2
	s_andn2_b64 vcc, exec, s[0:1]
	v_readfirstlane_b32 s1, v1
	s_cbranch_vccnz .LBB0_647
	v_ashrrev_i32_e32 v3, 31, v1
	v_lshrrev_b32_e32 v3, 26, v3
	v_lshlrev_b32_e32 v2, 4, v1
	v_add_u32_e32 v3, v1, v3
	v_bfe_i32 v1, v1, 27, 1
	v_lshrrev_b32_e32 v1, 22, v1
	v_add_u32_e32 v1, v2, v1
	v_and_b32_e32 v1, 0xfffffc00, v1
	v_sub_u32_e32 v1, v2, v1
	v_lshrrev_b32_e32 v4, 4, v1
	v_bitop3_b32 v1, v4, v1, 32 bitop3:0x6c
	v_ashrrev_i32_e32 v5, 31, v1
	v_ashrrev_i32_e32 v3, 6, v3
	v_lshrrev_b32_e32 v5, 26, v5
	v_lshlrev_b32_e32 v4, 3, v3
	v_add_u32_e32 v5, v1, v5
	v_and_b32_e32 v4, -16, v4
	v_ashrrev_i32_e32 v6, 6, v5
	v_and_b32_e32 v5, 0xc0, v5
	v_add_u32_e32 v4, v6, v4
	v_sub_u32_e32 v1, v1, v5
	v_mov_b32_e32 v8, 1
	v_lshlrev_b32_e32 v3, 5, v3
	v_ashrrev_i16_sdwa v1, v8, sext(v1) dst_sel:DWORD dst_unused:UNUSED_PAD src0_sel:DWORD src1_sel:BYTE_0
	v_lshlrev_b32_e32 v5, 1, v4
	v_lshrrev_b32_e32 v7, 2, v4
	v_and_b32_e32 v6, 3, v6
	s_mov_b32 s2, 0x1fffe0
	v_and_b32_e32 v3, 32, v3
	v_bfe_i32 v1, v1, 0, 16
	v_and_b32_e32 v5, 24, v5
	v_and_b32_e32 v7, 4, v7
	v_and_or_b32 v6, v4, s2, v6
	v_or3_b32 v5, v6, v7, v5
	v_add_lshl_u32 v1, v3, v1, 1
	v_lshl_add_u32 v148, v4, 11, v1
	v_lshl_add_u32 v149, v5, 11, v1
	v_add_u32_e32 v1, 0x2000, v2
	v_ashrrev_i32_e32 v2, 31, v1
	v_lshrrev_b32_e32 v2, 22, v2
	v_add_u32_e32 v2, v1, v2
	v_ashrrev_i32_e32 v2, 10, v2
	v_mul_i32_i24_e32 v3, 0x400, v2
	v_sub_u32_e32 v1, v1, v3
	v_lshrrev_b32_e32 v3, 4, v1
	v_bitop3_b32 v1, v3, v1, 32 bitop3:0x6c
	v_ashrrev_i32_e32 v4, 31, v1
	v_lshrrev_b32_e32 v4, 26, v4
	v_lshlrev_b32_e32 v3, 3, v2
	v_add_u32_e32 v4, v1, v4
	v_and_b32_e32 v3, -16, v3
	v_ashrrev_i32_e32 v5, 6, v4
	s_ashr_i32 s0, s1, 6
	v_add_u32_e32 v3, v5, v3
	v_and_b32_e32 v5, 3, v5
	v_and_or_b32 v5, v3, s2, v5
	s_lshl_b32 s2, s0, 10
	s_ashr_i32 s4, s1, 8
	s_add_i32 s2, s2, 0
	s_add_u32 s19, s30, 0x51200000
	s_addc_u32 s64, s31, 0
	v_readlane_b32 s5, v253, 54
	s_add_u32 s5, s30, s5
	s_addc_u32 s6, s31, 0
	v_and_b32_e32 v4, 0xc0, v4
	s_add_u32 s79, s5, 0xaa00000
	v_sub_u32_e32 v1, v1, v4
	s_addc_u32 s80, s6, 0
	s_ashr_i32 s61, s60, 31
	s_ashr_i32 s39, s38, 31
	v_lshlrev_b32_e32 v2, 5, v2
	v_ashrrev_i16_sdwa v1, v8, sext(v1) dst_sel:DWORD dst_unused:UNUSED_PAD src0_sel:DWORD src1_sel:BYTE_0
	v_lshlrev_b32_e32 v4, 1, v3
	v_lshrrev_b32_e32 v6, 2, v3
	s_lshl_b64 s[14:15], s[60:61], 19
	s_lshl_b64 s[16:17], s[38:39], 19
	v_and_b32_e32 v2, 32, v2
	v_bfe_i32 v1, v1, 0, 16
	v_and_b32_e32 v4, 24, v4
	v_and_b32_e32 v6, 4, v6
	s_add_u32 s44, s79, s16
	v_or3_b32 v4, v5, v6, v4
	v_add_lshl_u32 v1, v2, v1, 1
	s_addc_u32 s45, s80, s17
	s_add_i32 s81, s2, 0x10000
	s_mov_b32 s5, m0
	s_mov_b32 m0, s81
	s_nop 0
	global_load_lds_dwordx4 v149, s[44:45]
	s_mov_b32 m0, s5
	s_add_i32 s82, s2, 0x12000
	v_lshl_add_u32 v151, v4, 11, v1
	s_mov_b32 s5, m0
	s_mov_b32 m0, s82
	s_nop 0
	global_load_lds_dwordx4 v151, s[44:45]
	s_mov_b32 m0, s5
	s_add_u32 s16, s44, 0x40000
	s_addc_u32 s17, s45, 0
	s_add_i32 s83, s2, 0x14000
	s_mov_b32 s5, m0
	s_mov_b32 m0, s83
	s_nop 0
	global_load_lds_dwordx4 v149, s[16:17]
	s_mov_b32 m0, s5
	s_add_i32 s84, s2, 0x16000
	s_mov_b32 s5, m0
	s_mov_b32 m0, s84
	s_nop 0
	global_load_lds_dwordx4 v151, s[16:17]
	s_mov_b32 m0, s5
	s_add_u32 s56, s19, s14
	s_addc_u32 s57, s64, s15
	s_mov_b32 s5, m0
	s_mov_b32 m0, s2
	s_nop 0
	global_load_lds_dwordx4 v148, s[56:57]
	s_mov_b32 m0, s5
	s_add_i32 s85, s2, 0x2000
	v_lshl_add_u32 v150, v3, 11, v1
	s_mov_b32 s5, m0
	s_mov_b32 m0, s85
	s_nop 0
	global_load_lds_dwordx4 v150, s[56:57]
	s_mov_b32 m0, s5
	s_add_u32 s14, s56, 0x40000
	s_addc_u32 s15, s57, 0
	s_add_i32 s86, s2, 0x4000
	s_mov_b32 s5, m0
	s_mov_b32 m0, s86
	s_nop 0
	global_load_lds_dwordx4 v148, s[14:15]
	s_mov_b32 m0, s5
	s_add_i32 s87, s2, 0x6000
	s_mov_b32 s5, m0
	s_mov_b32 m0, s87
	s_nop 0
	global_load_lds_dwordx4 v150, s[14:15]
	s_mov_b32 m0, s5
	s_cmp_eq_u32 s4, 1
	s_cselect_b64 s[14:15], -1, 0
	s_cmp_lg_u32 s4, 1
	s_cbranch_scc1 .LBB0_610
	s_barrier
	s_setprio 1

; #define PG8_STAGE(bufoff, gbase, voff) do { _Pragma("unroll") for (int _i = 0; _i < 2; ++_i) glds16_s((gbase), (voff)[_i], ldsb + (unsigned)((bufoff) + _i * 8192)); } while (0)
; #define PG8_LDA(dst, b, h) do { _Pragma("unroll") for (int m = 0; m < 4; ++m) _Pragma("unroll") for (int k = 0; k < 2; ++k) dst[m][k] = *(const LAS h16x8*)(lds + PG8_SA(b, h) + aoff + m * 2048 + k * 1024); } while (0)
; #define PG8_WAIT_V(n) asm volatile("s_waitcnt vmcnt(" #n ")" ::: "memory")
; #define PG8_WAIT_L(n) asm volatile("s_waitcnt lgkmcnt(" #n ")" ::: "memory")
; #define PG8_BAR __builtin_amdgcn_s_barrier()
; template <class Prob, class Epi, bool I8 = false, bool ALIGN_EPI = true, bool SP2 = true>
; __device__ __forceinline__ void gemm_phase(LAS unsigned char* lds, int wave, const Prob& P, const Epi& E) {
;     ...
;         const bool has_next = P.next(ui + 1, nxt);
;         const char* nA = has_next ? P.a_tile(nxt) : cA; const char* nB = has_next ? P.b_tile(nxt) : cB;
;         for (int t = 0; t < nt; t += 2) {
;             const bool last = (t == nt - 2);
;             const char* a1 = cA + (size_t)(t + 1) * kstep;
;             const char* a2 = last ? nA : cA + (size_t)(t + 2) * kstep; const char* b2 = last ? nB : cB + (size_t)(t + 2) * kstep;
;             const char* a3 = a2 + kstep; const char* b3 = b2 + kstep;
;             if constexpr (SP2) {
;             PG8_LDB(B0, 0, 0); PG8_LDB(B1, 0, 1); PG8_SCHED; PG8_LDA(At, 0, 0); PG8_STAGE(PG8_SA(1, 1), a1 + hstepA, voffA);
;             PG8_WAIT_V(8); PG8_WAIT_L(0); PG8_BAR; PG8_MMA(0, 0, At, B0); PG8_MMA(0, 1, At, B1); PG8_BAR; PG8_SCHED;
;             PG8_LDA(At, 0, 1); PG8_STAGE(PG8_SB(0, 0), b2, voffB); PG8_STAGE(PG8_SB(0, 1), b2 + hstepB, voffB); PG8_STAGE(PG8_SA(0, 0), a2, voffA);
;             PG8_WAIT_V(8); PG8_WAIT_L(0); PG8_BAR; PG8_MMA(1, 0, At, B0); PG8_MMA(1, 1, At, B1); PG8_BAR; PG8_SCHED;
;             PG8_LDB(B0, 1, 0); PG8_LDB(B1, 1, 1); PG8_SCHED; PG8_LDA(At, 1, 0); PG8_STAGE(PG8_SA(0, 1), a2 + hstepA, voffA);
;             PG8_WAIT_V(8); PG8_WAIT_L(0); PG8_BAR; PG8_MMA(0, 0, At, B0); PG8_MMA(0, 1, At, B1); PG8_BAR; PG8_SCHED;
;             PG8_LDA(At, 1, 1); PG8_STAGE(PG8_SB(1, 0), b3, voffB); PG8_STAGE(PG8_SB(1, 1), b3 + hstepB, voffB); PG8_STAGE(PG8_SA(1, 0), a3, voffA);
;             PG8_WAIT_V(8); PG8_WAIT_L(0); PG8_BAR; PG8_MMA(1, 0, At, B0); PG8_MMA(1, 1, At, B1); PG8_BAR; PG8_SCHED;
.Lpeel_616:
	v_add_u32_e32 v140, 0x10000, v152
	v_add_u32_e32 v162, 0x14000, v152
	ds_read_b128 v[128:131], v140
	ds_read_b128 v[132:135], v140 offset:1024
	ds_read_b128 v[136:139], v140 offset:2048
	ds_read_b128 v[140:143], v140 offset:3072
	ds_read_b128 v[144:147], v162
	ds_read_b128 v[154:157], v162 offset:1024
	ds_read_b128 v[158:161], v162 offset:2048
	ds_read_b128 v[162:165], v162 offset:3072
	s_cmp_eq_u32 s1, 12
	s_cselect_b32 s62, s43, s73
	s_cselect_b32 s63, s39, vcc_lo
	s_cselect_b32 s68, s61, vcc_hi
	s_cselect_b32 s69, s41, s0
	s_add_u32 s56, s62, 0x80
	s_addc_u32 s57, s63, 0
	ds_read_b128 v[166:169], v153
	ds_read_b128 v[170:173], v153 offset:1024
	ds_read_b128 v[174:177], v153 offset:2048
	ds_read_b128 v[178:181], v153 offset:3072
	ds_read_b128 v[182:185], v153 offset:4096
	ds_read_b128 v[186:189], v153 offset:5120
	ds_read_b128 v[190:193], v153 offset:6144
	ds_read_b128 v[194:197], v153 offset:7168
	s_mov_b32 s4, m0
	s_mov_b32 m0, s96
	s_nop 0
	global_load_lds_dwordx4 v148, s[44:45]
	s_mov_b32 m0, s4
	s_nop 0
	s_mov_b32 s4, m0
	s_mov_b32 m0, s75
	s_nop 0
	global_load_lds_dwordx4 v150, s[44:45]
	s_mov_b32 m0, s4
	s_waitcnt vmcnt(8)
	s_waitcnt lgkmcnt(0)
	s_barrier
	s_waitcnt lgkmcnt(7)
	v_mfma_i32_16x16x64_i8 v[124:127], v[128:131], v[166:169], 0
	v_mfma_i32_16x16x64_i8 v[120:123], v[136:139], v[166:169], 0
	s_waitcnt lgkmcnt(5)
	v_mfma_i32_16x16x64_i8 v[108:111], v[128:131], v[174:177], 0
	v_mfma_i32_16x16x64_i8 v[104:107], v[136:139], v[174:177], 0
	s_waitcnt lgkmcnt(3)
	v_mfma_i32_16x16x64_i8 v[92:95], v[128:131], v[182:185], 0
	v_mfma_i32_16x16x64_i8 v[88:91], v[136:139], v[182:185], 0
	s_waitcnt lgkmcnt(1)
	v_mfma_i32_16x16x64_i8 v[76:79], v[128:131], v[190:193], 0
	v_mfma_i32_16x16x64_i8 v[72:75], v[136:139], v[190:193], 0
	v_mfma_i32_16x16x64_i8 v[124:127], v[132:135], v[170:173], v[124:127]
	v_mfma_i32_16x16x64_i8 v[120:123], v[140:143], v[170:173], v[120:123]
	v_mfma_i32_16x16x64_i8 v[108:111], v[132:135], v[178:181], v[108:111]
	v_mfma_i32_16x16x64_i8 v[104:107], v[140:143], v[178:181], v[104:107]
	v_mfma_i32_16x16x64_i8 v[92:95], v[132:135], v[186:189], v[92:95]
	v_mfma_i32_16x16x64_i8 v[88:91], v[140:143], v[186:189], v[88:91]
	s_waitcnt lgkmcnt(0)
	v_mfma_i32_16x16x64_i8 v[76:79], v[132:135], v[194:197], v[76:79]
	v_mfma_i32_16x16x64_i8 v[72:75], v[140:143], v[194:197], v[72:75]
	v_mfma_i32_16x16x64_i8 v[116:119], v[144:147], v[166:169], 0
	v_mfma_i32_16x16x64_i8 v[112:115], v[158:161], v[166:169], 0
	v_mfma_i32_16x16x64_i8 v[100:103], v[144:147], v[174:177], 0
	v_mfma_i32_16x16x64_i8 v[96:99], v[158:161], v[174:177], 0
	v_mfma_i32_16x16x64_i8 v[84:87], v[144:147], v[182:185], 0
	v_mfma_i32_16x16x64_i8 v[80:83], v[158:161], v[182:185], 0
	v_mfma_i32_16x16x64_i8 v[68:71], v[144:147], v[190:193], 0
	v_mfma_i32_16x16x64_i8 v[64:67], v[158:161], v[190:193], 0
	v_mfma_i32_16x16x64_i8 v[116:119], v[154:157], v[170:173], v[116:119]
	v_mfma_i32_16x16x64_i8 v[112:115], v[162:165], v[170:173], v[112:115]
	v_mfma_i32_16x16x64_i8 v[100:103], v[154:157], v[178:181], v[100:103]
	v_mfma_i32_16x16x64_i8 v[96:99], v[162:165], v[178:181], v[96:99]
	v_mfma_i32_16x16x64_i8 v[84:87], v[154:157], v[186:189], v[84:87]
	v_mfma_i32_16x16x64_i8 v[80:83], v[162:165], v[186:189], v[80:83]
	v_mfma_i32_16x16x64_i8 v[68:71], v[154:157], v[194:197], v[68:71]
	v_mfma_i32_16x16x64_i8 v[64:67], v[162:165], v[194:197], v[64:67]
	s_barrier
	ds_read_b128 v[166:169], v153 offset:16384
	ds_read_b128 v[170:173], v153 offset:17408
	ds_read_b128 v[174:177], v153 offset:18432
	ds_read_b128 v[178:181], v153 offset:19456
	ds_read_b128 v[182:185], v153 offset:20480
	ds_read_b128 v[186:189], v153 offset:21504
	ds_read_b128 v[190:193], v153 offset:22528
	ds_read_b128 v[194:197], v153 offset:23552
	s_mov_b32 s4, m0
	s_mov_b32 m0, s81
	s_nop 0
	global_load_lds_dwordx4 v149, s[68:69]
	s_mov_b32 m0, s4
	s_nop 0
	s_mov_b32 s4, m0
	s_mov_b32 m0, s82
	s_nop 0
	global_load_lds_dwordx4 v151, s[68:69]
	s_mov_b32 m0, s4
	s_add_u32 s4, s68, 0x40000
	s_addc_u32 s5, s69, 0
	s_mov_b32 s6, m0
	s_mov_b32 m0, s83
	s_nop 0
	global_load_lds_dwordx4 v149, s[4:5]
	s_mov_b32 m0, s6
	s_nop 0
	s_mov_b32 s6, m0
	s_mov_b32 m0, s84
	s_nop 0
	global_load_lds_dwordx4 v151, s[4:5]
	s_mov_b32 m0, s6
	s_mov_b32 s4, m0
	s_mov_b32 m0, s2
	s_nop 0
	global_load_lds_dwordx4 v148, s[62:63]
	s_mov_b32 m0, s4
	s_nop 0
	s_mov_b32 s4, m0
	s_mov_b32 m0, s85
	s_nop 0
	global_load_lds_dwordx4 v150, s[62:63]
	s_mov_b32 m0, s4
	s_waitcnt vmcnt(8)
	s_waitcnt lgkmcnt(0)
	s_barrier
	s_waitcnt lgkmcnt(7)
	v_mfma_i32_16x16x64_i8 v[60:63], v[128:131], v[166:169], 0
	v_mfma_i32_16x16x64_i8 v[56:59], v[136:139], v[166:169], 0
	s_waitcnt lgkmcnt(5)
	v_mfma_i32_16x16x64_i8 v[44:47], v[128:131], v[174:177], 0
	v_mfma_i32_16x16x64_i8 v[40:43], v[136:139], v[174:177], 0
	s_waitcnt lgkmcnt(3)
	v_mfma_i32_16x16x64_i8 v[28:31], v[128:131], v[182:185], 0
	v_mfma_i32_16x16x64_i8 v[24:27], v[136:139], v[182:185], 0
	s_waitcnt lgkmcnt(1)
	v_mfma_i32_16x16x64_i8 v[12:15], v[128:131], v[190:193], 0
	v_mfma_i32_16x16x64_i8 v[8:11], v[136:139], v[190:193], 0
	v_mfma_i32_16x16x64_i8 v[60:63], v[132:135], v[170:173], v[60:63]
	v_mfma_i32_16x16x64_i8 v[56:59], v[140:143], v[170:173], v[56:59]
	v_mfma_i32_16x16x64_i8 v[44:47], v[132:135], v[178:181], v[44:47]
	v_mfma_i32_16x16x64_i8 v[40:43], v[140:143], v[178:181], v[40:43]
	v_mfma_i32_16x16x64_i8 v[28:31], v[132:135], v[186:189], v[28:31]
	v_mfma_i32_16x16x64_i8 v[24:27], v[140:143], v[186:189], v[24:27]
	s_waitcnt lgkmcnt(0)
	v_mfma_i32_16x16x64_i8 v[12:15], v[132:135], v[194:197], v[12:15]
	v_mfma_i32_16x16x64_i8 v[8:11], v[140:143], v[194:197], v[8:11]
	v_mfma_i32_16x16x64_i8 v[52:55], v[144:147], v[166:169], 0
	v_mfma_i32_16x16x64_i8 v[48:51], v[158:161], v[166:169], 0
	v_mfma_i32_16x16x64_i8 v[36:39], v[144:147], v[174:177], 0
	v_mfma_i32_16x16x64_i8 v[32:35], v[158:161], v[174:177], 0
	v_mfma_i32_16x16x64_i8 v[20:23], v[144:147], v[182:185], 0
	v_mfma_i32_16x16x64_i8 v[16:19], v[158:161], v[182:185], 0
	v_mfma_i32_16x16x64_i8 v[4:7], v[144:147], v[190:193], 0
	v_mfma_i32_16x16x64_i8 v[0:3], v[158:161], v[190:193], 0
	v_mfma_i32_16x16x64_i8 v[52:55], v[154:157], v[170:173], v[52:55]
	v_mfma_i32_16x16x64_i8 v[48:51], v[162:165], v[170:173], v[48:51]
	v_mfma_i32_16x16x64_i8 v[36:39], v[154:157], v[178:181], v[36:39]
	v_mfma_i32_16x16x64_i8 v[32:35], v[162:165], v[178:181], v[32:35]
	v_mfma_i32_16x16x64_i8 v[20:23], v[154:157], v[186:189], v[20:23]
	v_mfma_i32_16x16x64_i8 v[16:19], v[162:165], v[186:189], v[16:19]
	v_mfma_i32_16x16x64_i8 v[4:7], v[154:157], v[194:197], v[4:7]
	v_mfma_i32_16x16x64_i8 v[0:3], v[162:165], v[194:197], v[0:3]
	s_barrier
; #define PG8_STAGE(bufoff, gbase, voff) do { _Pragma("unroll") for (int _i = 0; _i < 2; ++_i) glds16_s((gbase), (voff)[_i], ldsb + (unsigned)((bufoff) + _i * 8192)); } while (0)
; #define PG8_LDA(dst, b, h) do { _Pragma("unroll") for (int m = 0; m < 4; ++m) _Pragma("unroll") for (int k = 0; k < 2; ++k) dst[m][k] = *(const LAS h16x8*)(lds + PG8_SA(b, h) + aoff + m * 2048 + k * 1024); } while (0)
; #define PG8_LDB(dst, b, h) do { _Pragma("unroll") for (int n = 0; n < 2; ++n) _Pragma("unroll") for (int k = 0; k < 2; ++k) dst[n][k] = *(const LAS h16x8*)(lds + PG8_SB(b, h) + boff + n * 2048 + k * 1024); } while (0)
; #define PG8_MMA(ai, bj, At, Bt) do { __builtin_amdgcn_s_setprio(1); _Pragma("unroll") for (int m = 0; m < 4; ++m) _Pragma("unroll") for (int n = 0; n < 2; ++n) _Pragma("unroll") for (int k = 0; k < 2; ++k) \
;         acc[ai][bj][m][n] = mma_step<I8>(Bt[n][k], At[m][k], acc[ai][bj][m][n]); __builtin_amdgcn_s_setprio(0); } while (0)
; #define PG8_WAIT_V(n) asm volatile("s_waitcnt vmcnt(" #n ")" ::: "memory")
; #define PG8_WAIT_L(n) asm volatile("s_waitcnt lgkmcnt(" #n ")" ::: "memory")
; #define PG8_BAR __builtin_amdgcn_s_barrier()
; #define PG8_SCHED __builtin_amdgcn_sched_barrier(0)
; template <class Prob, class Epi, bool I8 = false, bool ALIGN_EPI = true, bool SP2 = true>
; __device__ __forceinline__ void gemm_phase(LAS unsigned char* lds, int wave, const Prob& P, const Epi& E) {
;     ...
;             PG8_LDB(B0, 1, 0); PG8_LDB(B1, 1, 1); PG8_SCHED; PG8_LDA(At, 1, 0); PG8_STAGE(PG8_SA(0, 1), a2 + hstepA, voffA);
;             PG8_WAIT_V(8); PG8_WAIT_L(0); PG8_BAR; PG8_MMA(0, 0, At, B0); PG8_MMA(0, 1, At, B1); PG8_BAR; PG8_SCHED;
;             PG8_LDA(At, 1, 1); PG8_STAGE(PG8_SB(1, 0), b3, voffB); PG8_STAGE(PG8_SB(1, 1), b3 + hstepB, voffB); PG8_STAGE(PG8_SA(1, 0), a3, voffA);
;             PG8_WAIT_V(8); PG8_WAIT_L(0); PG8_BAR; PG8_MMA(1, 0, At, B0); PG8_MMA(1, 1, At, B1); PG8_BAR; PG8_SCHED;
	v_add_u32_e32 v140, 0x18000, v152
	v_add_u32_e32 v162, 0x1c000, v152
	ds_read_b128 v[128:131], v140
	ds_read_b128 v[132:135], v140 offset:1024
	ds_read_b128 v[136:139], v140 offset:2048
	ds_read_b128 v[140:143], v140 offset:3072
	ds_read_b128 v[144:147], v162
	ds_read_b128 v[154:157], v162 offset:1024
	ds_read_b128 v[158:161], v162 offset:2048
	ds_read_b128 v[162:165], v162 offset:3072
	ds_read_b128 v[166:169], v153 offset:32768
	ds_read_b128 v[170:173], v153 offset:33792
	ds_read_b128 v[174:177], v153 offset:34816
	ds_read_b128 v[178:181], v153 offset:35840
	ds_read_b128 v[182:185], v153 offset:36864
	ds_read_b128 v[186:189], v153 offset:37888
	ds_read_b128 v[190:193], v153 offset:38912
	ds_read_b128 v[194:197], v153 offset:39936
	s_add_u32 s4, s62, 0x40000
	s_addc_u32 s5, s63, 0
	s_mov_b32 s6, m0
	s_mov_b32 m0, s86
	s_nop 0
	global_load_lds_dwordx4 v148, s[4:5]
	s_mov_b32 m0, s6
	s_nop 0
	s_mov_b32 s6, m0
	s_mov_b32 m0, s87
	s_nop 0
	global_load_lds_dwordx4 v150, s[4:5]
	s_mov_b32 m0, s6
	s_waitcnt vmcnt(8)
	s_waitcnt lgkmcnt(0)
	s_barrier
	s_waitcnt lgkmcnt(7)
	v_mfma_i32_16x16x64_i8 v[124:127], v[128:131], v[166:169], v[124:127]
	v_mfma_i32_16x16x64_i8 v[120:123], v[136:139], v[166:169], v[120:123]
	s_waitcnt lgkmcnt(5)
	v_mfma_i32_16x16x64_i8 v[108:111], v[128:131], v[174:177], v[108:111]
	v_mfma_i32_16x16x64_i8 v[104:107], v[136:139], v[174:177], v[104:107]
	s_waitcnt lgkmcnt(3)
	v_mfma_i32_16x16x64_i8 v[92:95], v[128:131], v[182:185], v[92:95]
	v_mfma_i32_16x16x64_i8 v[88:91], v[136:139], v[182:185], v[88:91]
	s_waitcnt lgkmcnt(1)
	v_mfma_i32_16x16x64_i8 v[76:79], v[128:131], v[190:193], v[76:79]
	v_mfma_i32_16x16x64_i8 v[72:75], v[136:139], v[190:193], v[72:75]
	v_mfma_i32_16x16x64_i8 v[124:127], v[132:135], v[170:173], v[124:127]
	v_mfma_i32_16x16x64_i8 v[120:123], v[140:143], v[170:173], v[120:123]
	v_mfma_i32_16x16x64_i8 v[108:111], v[132:135], v[178:181], v[108:111]
	v_mfma_i32_16x16x64_i8 v[104:107], v[140:143], v[178:181], v[104:107]
	v_mfma_i32_16x16x64_i8 v[92:95], v[132:135], v[186:189], v[92:95]
	v_mfma_i32_16x16x64_i8 v[88:91], v[140:143], v[186:189], v[88:91]
	s_waitcnt lgkmcnt(0)
	v_mfma_i32_16x16x64_i8 v[76:79], v[132:135], v[194:197], v[76:79]
	v_mfma_i32_16x16x64_i8 v[72:75], v[140:143], v[194:197], v[72:75]
	v_mfma_i32_16x16x64_i8 v[116:119], v[144:147], v[166:169], v[116:119]
	v_mfma_i32_16x16x64_i8 v[112:115], v[158:161], v[166:169], v[112:115]
	v_mfma_i32_16x16x64_i8 v[100:103], v[144:147], v[174:177], v[100:103]
	v_mfma_i32_16x16x64_i8 v[96:99], v[158:161], v[174:177], v[96:99]
	v_mfma_i32_16x16x64_i8 v[84:87], v[144:147], v[182:185], v[84:87]
	v_mfma_i32_16x16x64_i8 v[80:83], v[158:161], v[182:185], v[80:83]
	v_mfma_i32_16x16x64_i8 v[68:71], v[144:147], v[190:193], v[68:71]
	v_mfma_i32_16x16x64_i8 v[64:67], v[158:161], v[190:193], v[64:67]
	v_mfma_i32_16x16x64_i8 v[116:119], v[154:157], v[170:173], v[116:119]
	v_mfma_i32_16x16x64_i8 v[112:115], v[162:165], v[170:173], v[112:115]
	v_mfma_i32_16x16x64_i8 v[100:103], v[154:157], v[178:181], v[100:103]
	v_mfma_i32_16x16x64_i8 v[96:99], v[162:165], v[178:181], v[96:99]
	v_mfma_i32_16x16x64_i8 v[84:87], v[154:157], v[186:189], v[84:87]
	v_mfma_i32_16x16x64_i8 v[80:83], v[162:165], v[186:189], v[80:83]
	v_mfma_i32_16x16x64_i8 v[68:71], v[154:157], v[194:197], v[68:71]
	v_mfma_i32_16x16x64_i8 v[64:67], v[162:165], v[194:197], v[64:67]
	s_barrier
	ds_read_b128 v[166:169], v153 offset:49152
	ds_read_b128 v[170:173], v153 offset:50176
	ds_read_b128 v[174:177], v153 offset:51200
	ds_read_b128 v[178:181], v153 offset:52224
	ds_read_b128 v[182:185], v153 offset:53248
	ds_read_b128 v[186:189], v153 offset:54272
	ds_read_b128 v[190:193], v153 offset:55296
	ds_read_b128 v[194:197], v153 offset:56320
	s_add_u32 s4, s68, 0x80
	s_addc_u32 s5, s69, 0
	s_mov_b32 s6, m0
	s_mov_b32 m0, s90
	s_nop 0
	global_load_lds_dwordx4 v149, s[4:5]
	s_mov_b32 m0, s6
	s_nop 0
	s_mov_b32 s6, m0
	s_mov_b32 m0, s91
	s_nop 0
	global_load_lds_dwordx4 v151, s[4:5]
	s_mov_b32 m0, s6
	s_add_u32 s4, s68, 0x40080
	s_addc_u32 s5, s69, 0
	s_mov_b32 s6, m0
	s_mov_b32 m0, s94
	s_nop 0
	global_load_lds_dwordx4 v149, s[4:5]
	s_mov_b32 m0, s6
	s_nop 0
	s_mov_b32 s6, m0
	s_mov_b32 m0, s95
	s_nop 0
	global_load_lds_dwordx4 v151, s[4:5]
	s_mov_b32 m0, s6
	s_mov_b32 s4, m0
	s_mov_b32 m0, s92
	s_nop 0
	global_load_lds_dwordx4 v148, s[56:57]
	s_mov_b32 m0, s4
	s_nop 0
	s_mov_b32 s4, m0
	s_mov_b32 m0, s93
	s_nop 0
	global_load_lds_dwordx4 v150, s[56:57]
	s_mov_b32 m0, s4
	s_waitcnt vmcnt(8)
	s_waitcnt lgkmcnt(0)
	s_barrier
	s_waitcnt lgkmcnt(7)
	v_mfma_i32_16x16x64_i8 v[60:63], v[128:131], v[166:169], v[60:63]
	v_mfma_i32_16x16x64_i8 v[56:59], v[136:139], v[166:169], v[56:59]
	s_waitcnt lgkmcnt(5)
	v_mfma_i32_16x16x64_i8 v[44:47], v[128:131], v[174:177], v[44:47]
	v_mfma_i32_16x16x64_i8 v[40:43], v[136:139], v[174:177], v[40:43]
	s_waitcnt lgkmcnt(3)
	v_mfma_i32_16x16x64_i8 v[28:31], v[128:131], v[182:185], v[28:31]
	v_mfma_i32_16x16x64_i8 v[24:27], v[136:139], v[182:185], v[24:27]
	s_waitcnt lgkmcnt(1)
	v_mfma_i32_16x16x64_i8 v[12:15], v[128:131], v[190:193], v[12:15]
	v_mfma_i32_16x16x64_i8 v[8:11], v[136:139], v[190:193], v[8:11]
	v_mfma_i32_16x16x64_i8 v[60:63], v[132:135], v[170:173], v[60:63]
	v_mfma_i32_16x16x64_i8 v[56:59], v[140:143], v[170:173], v[56:59]
	v_mfma_i32_16x16x64_i8 v[44:47], v[132:135], v[178:181], v[44:47]
	v_mfma_i32_16x16x64_i8 v[40:43], v[140:143], v[178:181], v[40:43]
	v_mfma_i32_16x16x64_i8 v[28:31], v[132:135], v[186:189], v[28:31]
	v_mfma_i32_16x16x64_i8 v[24:27], v[140:143], v[186:189], v[24:27]
	s_waitcnt lgkmcnt(0)
	v_mfma_i32_16x16x64_i8 v[12:15], v[132:135], v[194:197], v[12:15]
	v_mfma_i32_16x16x64_i8 v[8:11], v[140:143], v[194:197], v[8:11]
	v_mfma_i32_16x16x64_i8 v[52:55], v[144:147], v[166:169], v[52:55]
	v_mfma_i32_16x16x64_i8 v[48:51], v[158:161], v[166:169], v[48:51]
	v_mfma_i32_16x16x64_i8 v[36:39], v[144:147], v[174:177], v[36:39]
	v_mfma_i32_16x16x64_i8 v[32:35], v[158:161], v[174:177], v[32:35]
	v_mfma_i32_16x16x64_i8 v[20:23], v[144:147], v[182:185], v[20:23]
	v_mfma_i32_16x16x64_i8 v[16:19], v[158:161], v[182:185], v[16:19]
	v_mfma_i32_16x16x64_i8 v[4:7], v[144:147], v[190:193], v[4:7]
	v_mfma_i32_16x16x64_i8 v[0:3], v[158:161], v[190:193], v[0:3]
	v_mfma_i32_16x16x64_i8 v[52:55], v[154:157], v[170:173], v[52:55]
	v_mfma_i32_16x16x64_i8 v[48:51], v[162:165], v[170:173], v[48:51]
	v_mfma_i32_16x16x64_i8 v[36:39], v[154:157], v[178:181], v[36:39]
	v_mfma_i32_16x16x64_i8 v[32:35], v[162:165], v[178:181], v[32:35]
	v_mfma_i32_16x16x64_i8 v[20:23], v[154:157], v[186:189], v[20:23]
	v_mfma_i32_16x16x64_i8 v[16:19], v[162:165], v[186:189], v[16:19]
	v_mfma_i32_16x16x64_i8 v[4:7], v[154:157], v[194:197], v[4:7]
	v_mfma_i32_16x16x64_i8 v[0:3], v[162:165], v[194:197], v[0:3]
	s_barrier
	s_add_i32 s1, s1, 2
	s_add_u32 s73, s73, 0x100
	s_addc_u32 vcc_lo, vcc_lo, 0
	s_add_u32 vcc_hi, vcc_hi, 0x100
	s_addc_u32 s0, s0, 0
	s_add_u32 s44, s44, 0x100
	s_addc_u32 s45, s45, 0
	s_cmp_gt_u32 s1, 13
; #define PG8_STAGE(bufoff, gbase, voff) do { _Pragma("unroll") for (int _i = 0; _i < 2; ++_i) glds16_s((gbase), (voff)[_i], ldsb + (unsigned)((bufoff) + _i * 8192)); } while (0)
; #define PG8_LDA(dst, b, h) do { _Pragma("unroll") for (int m = 0; m < 4; ++m) _Pragma("unroll") for (int k = 0; k < 2; ++k) dst[m][k] = *(const LAS h16x8*)(lds + PG8_SA(b, h) + aoff + m * 2048 + k * 1024); } while (0)
; #define PG8_LDB(dst, b, h) do { _Pragma("unroll") for (int n = 0; n < 2; ++n) _Pragma("unroll") for (int k = 0; k < 2; ++k) dst[n][k] = *(const LAS h16x8*)(lds + PG8_SB(b, h) + boff + n * 2048 + k * 1024); } while (0)
; #define PG8_MMA(ai, bj, At, Bt) do { __builtin_amdgcn_s_setprio(1); _Pragma("unroll") for (int m = 0; m < 4; ++m) _Pragma("unroll") for (int n = 0; n < 2; ++n) _Pragma("unroll") for (int k = 0; k < 2; ++k) \
;         acc[ai][bj][m][n] = mma_step<I8>(Bt[n][k], At[m][k], acc[ai][bj][m][n]); __builtin_amdgcn_s_setprio(0); } while (0)
; #define PG8_WAIT_V(n) asm volatile("s_waitcnt vmcnt(" #n ")" ::: "memory")
; #define PG8_WAIT_L(n) asm volatile("s_waitcnt lgkmcnt(" #n ")" ::: "memory")
; #define PG8_BAR __builtin_amdgcn_s_barrier()
; #define PG8_SCHED __builtin_amdgcn_sched_barrier(0)
; template <class Prob, class Epi, bool I8 = false, bool ALIGN_EPI = true, bool SP2 = true>
; __device__ __forceinline__ void gemm_phase(LAS unsigned char* lds, int wave, const Prob& P, const Epi& E) {
;     ...
;         for (int t = 0; t < nt; t += 2) {
;             const bool last = (t == nt - 2);
;             const char* a1 = cA + (size_t)(t + 1) * kstep;
;             const char* a2 = last ? nA : cA + (size_t)(t + 2) * kstep; const char* b2 = last ? nB : cB + (size_t)(t + 2) * kstep;
;             const char* a3 = a2 + kstep; const char* b3 = b2 + kstep;
;             if constexpr (SP2) {
;             PG8_LDB(B0, 0, 0); PG8_LDB(B1, 0, 1); PG8_SCHED; PG8_LDA(At, 0, 0); PG8_STAGE(PG8_SA(1, 1), a1 + hstepA, voffA);
;             PG8_WAIT_V(8); PG8_WAIT_L(0); PG8_BAR; PG8_MMA(0, 0, At, B0); PG8_MMA(0, 1, At, B1); PG8_BAR; PG8_SCHED;
;             PG8_LDA(At, 0, 1); PG8_STAGE(PG8_SB(0, 0), b2, voffB); PG8_STAGE(PG8_SB(0, 1), b2 + hstepB, voffB); PG8_STAGE(PG8_SA(0, 0), a2, voffA);
;             PG8_WAIT_V(8); PG8_WAIT_L(0); PG8_BAR; PG8_MMA(1, 0, At, B0); PG8_MMA(1, 1, At, B1); PG8_BAR; PG8_SCHED;
.LBB0_616:
	v_add_u32_e32 v140, 0x10000, v152
	v_add_u32_e32 v162, 0x14000, v152
	ds_read_b128 v[128:131], v140
	ds_read_b128 v[132:135], v140 offset:1024
	ds_read_b128 v[136:139], v140 offset:2048
	ds_read_b128 v[140:143], v140 offset:3072
	ds_read_b128 v[144:147], v162
	ds_read_b128 v[154:157], v162 offset:1024
	ds_read_b128 v[158:161], v162 offset:2048
	ds_read_b128 v[162:165], v162 offset:3072
	s_cmp_eq_u32 s1, 12
	s_cselect_b32 s62, s43, s73
	s_cselect_b32 s63, s39, vcc_lo
	s_cselect_b32 s68, s61, vcc_hi
	s_cselect_b32 s69, s41, s0
	s_add_u32 s56, s62, 0x80
	s_addc_u32 s57, s63, 0
	ds_read_b128 v[166:169], v153
	ds_read_b128 v[170:173], v153 offset:1024
	ds_read_b128 v[174:177], v153 offset:2048
	ds_read_b128 v[178:181], v153 offset:3072
	ds_read_b128 v[182:185], v153 offset:4096
	ds_read_b128 v[186:189], v153 offset:5120
	ds_read_b128 v[190:193], v153 offset:6144
	ds_read_b128 v[194:197], v153 offset:7168
	s_mov_b32 s4, m0
	s_mov_b32 m0, s96
	s_nop 0
	global_load_lds_dwordx4 v148, s[44:45]
	s_mov_b32 m0, s4
	s_nop 0
	s_mov_b32 s4, m0
	s_mov_b32 m0, s75
	s_nop 0
	global_load_lds_dwordx4 v150, s[44:45]
	s_mov_b32 m0, s4
	s_waitcnt vmcnt(8)
	s_waitcnt lgkmcnt(0)
	s_barrier
	s_waitcnt lgkmcnt(7)
	v_mfma_i32_16x16x64_i8 v[124:127], v[128:131], v[166:169], v[124:127]
	v_mfma_i32_16x16x64_i8 v[120:123], v[136:139], v[166:169], v[120:123]
	s_waitcnt lgkmcnt(5)
	v_mfma_i32_16x16x64_i8 v[108:111], v[128:131], v[174:177], v[108:111]
	v_mfma_i32_16x16x64_i8 v[104:107], v[136:139], v[174:177], v[104:107]
	s_waitcnt lgkmcnt(3)
	v_mfma_i32_16x16x64_i8 v[92:95], v[128:131], v[182:185], v[92:95]
	v_mfma_i32_16x16x64_i8 v[88:91], v[136:139], v[182:185], v[88:91]
	s_waitcnt lgkmcnt(1)
	v_mfma_i32_16x16x64_i8 v[76:79], v[128:131], v[190:193], v[76:79]
	v_mfma_i32_16x16x64_i8 v[72:75], v[136:139], v[190:193], v[72:75]
	v_mfma_i32_16x16x64_i8 v[124:127], v[132:135], v[170:173], v[124:127]
	v_mfma_i32_16x16x64_i8 v[120:123], v[140:143], v[170:173], v[120:123]
	v_mfma_i32_16x16x64_i8 v[108:111], v[132:135], v[178:181], v[108:111]
	v_mfma_i32_16x16x64_i8 v[104:107], v[140:143], v[178:181], v[104:107]
	v_mfma_i32_16x16x64_i8 v[92:95], v[132:135], v[186:189], v[92:95]
	v_mfma_i32_16x16x64_i8 v[88:91], v[140:143], v[186:189], v[88:91]
	s_waitcnt lgkmcnt(0)
	v_mfma_i32_16x16x64_i8 v[76:79], v[132:135], v[194:197], v[76:79]
	v_mfma_i32_16x16x64_i8 v[72:75], v[140:143], v[194:197], v[72:75]
	v_mfma_i32_16x16x64_i8 v[116:119], v[144:147], v[166:169], v[116:119]
	v_mfma_i32_16x16x64_i8 v[112:115], v[158:161], v[166:169], v[112:115]
	v_mfma_i32_16x16x64_i8 v[100:103], v[144:147], v[174:177], v[100:103]
	v_mfma_i32_16x16x64_i8 v[96:99], v[158:161], v[174:177], v[96:99]
	v_mfma_i32_16x16x64_i8 v[84:87], v[144:147], v[182:185], v[84:87]
	v_mfma_i32_16x16x64_i8 v[80:83], v[158:161], v[182:185], v[80:83]
	v_mfma_i32_16x16x64_i8 v[68:71], v[144:147], v[190:193], v[68:71]
	v_mfma_i32_16x16x64_i8 v[64:67], v[158:161], v[190:193], v[64:67]
	v_mfma_i32_16x16x64_i8 v[116:119], v[154:157], v[170:173], v[116:119]
	v_mfma_i32_16x16x64_i8 v[112:115], v[162:165], v[170:173], v[112:115]
	v_mfma_i32_16x16x64_i8 v[100:103], v[154:157], v[178:181], v[100:103]
	v_mfma_i32_16x16x64_i8 v[96:99], v[162:165], v[178:181], v[96:99]
	v_mfma_i32_16x16x64_i8 v[84:87], v[154:157], v[186:189], v[84:87]
	v_mfma_i32_16x16x64_i8 v[80:83], v[162:165], v[186:189], v[80:83]
	v_mfma_i32_16x16x64_i8 v[68:71], v[154:157], v[194:197], v[68:71]
	v_mfma_i32_16x16x64_i8 v[64:67], v[162:165], v[194:197], v[64:67]
	s_barrier
	ds_read_b128 v[166:169], v153 offset:16384
	ds_read_b128 v[170:173], v153 offset:17408
	ds_read_b128 v[174:177], v153 offset:18432
	ds_read_b128 v[178:181], v153 offset:19456
	ds_read_b128 v[182:185], v153 offset:20480
	ds_read_b128 v[186:189], v153 offset:21504
	ds_read_b128 v[190:193], v153 offset:22528
	ds_read_b128 v[194:197], v153 offset:23552
	s_mov_b32 s4, m0
	s_mov_b32 m0, s81
	s_nop 0
	global_load_lds_dwordx4 v149, s[68:69]
	s_mov_b32 m0, s4
	s_nop 0
	s_mov_b32 s4, m0
	s_mov_b32 m0, s82
	s_nop 0
	global_load_lds_dwordx4 v151, s[68:69]
	s_mov_b32 m0, s4
	s_add_u32 s4, s68, 0x40000
	s_addc_u32 s5, s69, 0
	s_mov_b32 s6, m0
	s_mov_b32 m0, s83
	s_nop 0
	global_load_lds_dwordx4 v149, s[4:5]
	s_mov_b32 m0, s6
	s_nop 0
	s_mov_b32 s6, m0
	s_mov_b32 m0, s84
	s_nop 0
	global_load_lds_dwordx4 v151, s[4:5]
	s_mov_b32 m0, s6
	s_mov_b32 s4, m0
	s_mov_b32 m0, s2
	s_nop 0
	global_load_lds_dwordx4 v148, s[62:63]
	s_mov_b32 m0, s4
	s_nop 0
	s_mov_b32 s4, m0
	s_mov_b32 m0, s85
	s_nop 0
	global_load_lds_dwordx4 v150, s[62:63]
	s_mov_b32 m0, s4
	s_waitcnt vmcnt(8)
	s_waitcnt lgkmcnt(0)
	s_barrier
; #define PG8_STAGE(bufoff, gbase, voff) do { _Pragma("unroll") for (int _i = 0; _i < 2; ++_i) glds16_s((gbase), (voff)[_i], ldsb + (unsigned)((bufoff) + _i * 8192)); } while (0)
; #define PG8_LDA(dst, b, h) do { _Pragma("unroll") for (int m = 0; m < 4; ++m) _Pragma("unroll") for (int k = 0; k < 2; ++k) dst[m][k] = *(const LAS h16x8*)(lds + PG8_SA(b, h) + aoff + m * 2048 + k * 1024); } while (0)
; #define PG8_LDB(dst, b, h) do { _Pragma("unroll") for (int n = 0; n < 2; ++n) _Pragma("unroll") for (int k = 0; k < 2; ++k) dst[n][k] = *(const LAS h16x8*)(lds + PG8_SB(b, h) + boff + n * 2048 + k * 1024); } while (0)
; #define PG8_MMA(ai, bj, At, Bt) do { __builtin_amdgcn_s_setprio(1); _Pragma("unroll") for (int m = 0; m < 4; ++m) _Pragma("unroll") for (int n = 0; n < 2; ++n) _Pragma("unroll") for (int k = 0; k < 2; ++k) \
;         acc[ai][bj][m][n] = mma_step<I8>(Bt[n][k], At[m][k], acc[ai][bj][m][n]); __builtin_amdgcn_s_setprio(0); } while (0)
; #define PG8_WAIT_V(n) asm volatile("s_waitcnt vmcnt(" #n ")" ::: "memory")
; #define PG8_WAIT_L(n) asm volatile("s_waitcnt lgkmcnt(" #n ")" ::: "memory")
; #define PG8_BAR __builtin_amdgcn_s_barrier()
; #define PG8_SCHED __builtin_amdgcn_sched_barrier(0)
; template <class Prob, class Epi, bool I8 = false, bool ALIGN_EPI = true, bool SP2 = true>
; __device__ __forceinline__ void gemm_phase(LAS unsigned char* lds, int wave, const Prob& P, const Epi& E) {
;     ...
;             PG8_WAIT_V(8); PG8_WAIT_L(0); PG8_BAR; PG8_MMA(1, 0, At, B0); PG8_MMA(1, 1, At, B1); PG8_BAR; PG8_SCHED;
;             PG8_LDB(B0, 1, 0); PG8_LDB(B1, 1, 1); PG8_SCHED; PG8_LDA(At, 1, 0); PG8_STAGE(PG8_SA(0, 1), a2 + hstepA, voffA);
;             PG8_WAIT_V(8); PG8_WAIT_L(0); PG8_BAR; PG8_MMA(0, 0, At, B0); PG8_MMA(0, 1, At, B1); PG8_BAR; PG8_SCHED;
;             PG8_LDA(At, 1, 1); PG8_STAGE(PG8_SB(1, 0), b3, voffB); PG8_STAGE(PG8_SB(1, 1), b3 + hstepB, voffB); PG8_STAGE(PG8_SA(1, 0), a3, voffA);
	s_waitcnt lgkmcnt(7)
	v_mfma_i32_16x16x64_i8 v[60:63], v[128:131], v[166:169], v[60:63]
	v_mfma_i32_16x16x64_i8 v[56:59], v[136:139], v[166:169], v[56:59]
	s_waitcnt lgkmcnt(5)
	v_mfma_i32_16x16x64_i8 v[44:47], v[128:131], v[174:177], v[44:47]
	v_mfma_i32_16x16x64_i8 v[40:43], v[136:139], v[174:177], v[40:43]
	s_waitcnt lgkmcnt(3)
	v_mfma_i32_16x16x64_i8 v[28:31], v[128:131], v[182:185], v[28:31]
	v_mfma_i32_16x16x64_i8 v[24:27], v[136:139], v[182:185], v[24:27]
	s_waitcnt lgkmcnt(1)
	v_mfma_i32_16x16x64_i8 v[12:15], v[128:131], v[190:193], v[12:15]
	v_mfma_i32_16x16x64_i8 v[8:11], v[136:139], v[190:193], v[8:11]
	v_mfma_i32_16x16x64_i8 v[60:63], v[132:135], v[170:173], v[60:63]
	v_mfma_i32_16x16x64_i8 v[56:59], v[140:143], v[170:173], v[56:59]
	v_mfma_i32_16x16x64_i8 v[44:47], v[132:135], v[178:181], v[44:47]
	v_mfma_i32_16x16x64_i8 v[40:43], v[140:143], v[178:181], v[40:43]
	v_mfma_i32_16x16x64_i8 v[28:31], v[132:135], v[186:189], v[28:31]
	v_mfma_i32_16x16x64_i8 v[24:27], v[140:143], v[186:189], v[24:27]
	s_waitcnt lgkmcnt(0)
	v_mfma_i32_16x16x64_i8 v[12:15], v[132:135], v[194:197], v[12:15]
	v_mfma_i32_16x16x64_i8 v[8:11], v[140:143], v[194:197], v[8:11]
	v_mfma_i32_16x16x64_i8 v[52:55], v[144:147], v[166:169], v[52:55]
	v_mfma_i32_16x16x64_i8 v[48:51], v[158:161], v[166:169], v[48:51]
	v_mfma_i32_16x16x64_i8 v[36:39], v[144:147], v[174:177], v[36:39]
	v_mfma_i32_16x16x64_i8 v[32:35], v[158:161], v[174:177], v[32:35]
	v_mfma_i32_16x16x64_i8 v[20:23], v[144:147], v[182:185], v[20:23]
	v_mfma_i32_16x16x64_i8 v[16:19], v[158:161], v[182:185], v[16:19]
	v_mfma_i32_16x16x64_i8 v[4:7], v[144:147], v[190:193], v[4:7]
	v_mfma_i32_16x16x64_i8 v[0:3], v[158:161], v[190:193], v[0:3]
	v_mfma_i32_16x16x64_i8 v[52:55], v[154:157], v[170:173], v[52:55]
	v_mfma_i32_16x16x64_i8 v[48:51], v[162:165], v[170:173], v[48:51]
	v_mfma_i32_16x16x64_i8 v[36:39], v[154:157], v[178:181], v[36:39]
	v_mfma_i32_16x16x64_i8 v[32:35], v[162:165], v[178:181], v[32:35]
	v_mfma_i32_16x16x64_i8 v[20:23], v[154:157], v[186:189], v[20:23]
	v_mfma_i32_16x16x64_i8 v[16:19], v[162:165], v[186:189], v[16:19]
	v_mfma_i32_16x16x64_i8 v[4:7], v[154:157], v[194:197], v[4:7]
	v_mfma_i32_16x16x64_i8 v[0:3], v[162:165], v[194:197], v[0:3]
	s_barrier
	v_add_u32_e32 v140, 0x18000, v152
	v_add_u32_e32 v162, 0x1c000, v152
	ds_read_b128 v[128:131], v140
	ds_read_b128 v[132:135], v140 offset:1024
	ds_read_b128 v[136:139], v140 offset:2048
	ds_read_b128 v[140:143], v140 offset:3072
	ds_read_b128 v[144:147], v162
	ds_read_b128 v[154:157], v162 offset:1024
	ds_read_b128 v[158:161], v162 offset:2048
	ds_read_b128 v[162:165], v162 offset:3072
	ds_read_b128 v[166:169], v153 offset:32768
	ds_read_b128 v[170:173], v153 offset:33792
	ds_read_b128 v[174:177], v153 offset:34816
	ds_read_b128 v[178:181], v153 offset:35840
	ds_read_b128 v[182:185], v153 offset:36864
	ds_read_b128 v[186:189], v153 offset:37888
	ds_read_b128 v[190:193], v153 offset:38912
	ds_read_b128 v[194:197], v153 offset:39936
	s_add_u32 s4, s62, 0x40000
	s_addc_u32 s5, s63, 0
	s_mov_b32 s6, m0
	s_mov_b32 m0, s86
	s_nop 0
	global_load_lds_dwordx4 v148, s[4:5]
	s_mov_b32 m0, s6
	s_nop 0
	s_mov_b32 s6, m0
	s_mov_b32 m0, s87
	s_nop 0
	global_load_lds_dwordx4 v150, s[4:5]
	s_mov_b32 m0, s6
	s_waitcnt vmcnt(8)
	s_waitcnt lgkmcnt(0)
	s_barrier
	s_waitcnt lgkmcnt(7)
	v_mfma_i32_16x16x64_i8 v[124:127], v[128:131], v[166:169], v[124:127]
	v_mfma_i32_16x16x64_i8 v[120:123], v[136:139], v[166:169], v[120:123]
	s_waitcnt lgkmcnt(5)
	v_mfma_i32_16x16x64_i8 v[108:111], v[128:131], v[174:177], v[108:111]
	v_mfma_i32_16x16x64_i8 v[104:107], v[136:139], v[174:177], v[104:107]
	s_waitcnt lgkmcnt(3)
	v_mfma_i32_16x16x64_i8 v[92:95], v[128:131], v[182:185], v[92:95]
	v_mfma_i32_16x16x64_i8 v[88:91], v[136:139], v[182:185], v[88:91]
	s_waitcnt lgkmcnt(1)
	v_mfma_i32_16x16x64_i8 v[76:79], v[128:131], v[190:193], v[76:79]
	v_mfma_i32_16x16x64_i8 v[72:75], v[136:139], v[190:193], v[72:75]
	v_mfma_i32_16x16x64_i8 v[124:127], v[132:135], v[170:173], v[124:127]
	v_mfma_i32_16x16x64_i8 v[120:123], v[140:143], v[170:173], v[120:123]
	v_mfma_i32_16x16x64_i8 v[108:111], v[132:135], v[178:181], v[108:111]
	v_mfma_i32_16x16x64_i8 v[104:107], v[140:143], v[178:181], v[104:107]
	v_mfma_i32_16x16x64_i8 v[92:95], v[132:135], v[186:189], v[92:95]
	v_mfma_i32_16x16x64_i8 v[88:91], v[140:143], v[186:189], v[88:91]
	s_waitcnt lgkmcnt(0)
	v_mfma_i32_16x16x64_i8 v[76:79], v[132:135], v[194:197], v[76:79]
	v_mfma_i32_16x16x64_i8 v[72:75], v[140:143], v[194:197], v[72:75]
	v_mfma_i32_16x16x64_i8 v[116:119], v[144:147], v[166:169], v[116:119]
	v_mfma_i32_16x16x64_i8 v[112:115], v[158:161], v[166:169], v[112:115]
	v_mfma_i32_16x16x64_i8 v[100:103], v[144:147], v[174:177], v[100:103]
	v_mfma_i32_16x16x64_i8 v[96:99], v[158:161], v[174:177], v[96:99]
	v_mfma_i32_16x16x64_i8 v[84:87], v[144:147], v[182:185], v[84:87]
	v_mfma_i32_16x16x64_i8 v[80:83], v[158:161], v[182:185], v[80:83]
	v_mfma_i32_16x16x64_i8 v[68:71], v[144:147], v[190:193], v[68:71]
	v_mfma_i32_16x16x64_i8 v[64:67], v[158:161], v[190:193], v[64:67]
	v_mfma_i32_16x16x64_i8 v[116:119], v[154:157], v[170:173], v[116:119]
	v_mfma_i32_16x16x64_i8 v[112:115], v[162:165], v[170:173], v[112:115]
	v_mfma_i32_16x16x64_i8 v[100:103], v[154:157], v[178:181], v[100:103]
	v_mfma_i32_16x16x64_i8 v[96:99], v[162:165], v[178:181], v[96:99]
	v_mfma_i32_16x16x64_i8 v[84:87], v[154:157], v[186:189], v[84:87]
	v_mfma_i32_16x16x64_i8 v[80:83], v[162:165], v[186:189], v[80:83]
	v_mfma_i32_16x16x64_i8 v[68:71], v[154:157], v[194:197], v[68:71]
	v_mfma_i32_16x16x64_i8 v[64:67], v[162:165], v[194:197], v[64:67]
	s_barrier
; #define PG8_STAGE(bufoff, gbase, voff) do { _Pragma("unroll") for (int _i = 0; _i < 2; ++_i) glds16_s((gbase), (voff)[_i], ldsb + (unsigned)((bufoff) + _i * 8192)); } while (0)
; #define PG8_LDA(dst, b, h) do { _Pragma("unroll") for (int m = 0; m < 4; ++m) _Pragma("unroll") for (int k = 0; k < 2; ++k) dst[m][k] = *(const LAS h16x8*)(lds + PG8_SA(b, h) + aoff + m * 2048 + k * 1024); } while (0)
; #define PG8_LDB(dst, b, h) do { _Pragma("unroll") for (int n = 0; n < 2; ++n) _Pragma("unroll") for (int k = 0; k < 2; ++k) dst[n][k] = *(const LAS h16x8*)(lds + PG8_SB(b, h) + boff + n * 2048 + k * 1024); } while (0)
; #define PG8_WAIT_V(n) asm volatile("s_waitcnt vmcnt(" #n ")" ::: "memory")
; #define PG8_WAIT_L(n) asm volatile("s_waitcnt lgkmcnt(" #n ")" ::: "memory")
; template <class Prob, class Epi, bool I8 = false, bool ALIGN_EPI = true, bool SP2 = true>
; __device__ __forceinline__ void gemm_phase(LAS unsigned char* lds, int wave, const Prob& P, const Epi& E) {
;     ...
;         for (int t = 0; t < nt; t += 2) {
;             const bool last = (t == nt - 2);
;             const char* a1 = cA + (size_t)(t + 1) * kstep;
;             const char* a2 = last ? nA : cA + (size_t)(t + 2) * kstep; const char* b2 = last ? nB : cB + (size_t)(t + 2) * kstep;
;             const char* a3 = a2 + kstep; const char* b3 = b2 + kstep;
;             if constexpr (SP2) {
;             PG8_LDB(B0, 0, 0); PG8_LDB(B1, 0, 1); PG8_SCHED; PG8_LDA(At, 0, 0); PG8_STAGE(PG8_SA(1, 1), a1 + hstepA, voffA);
;             PG8_WAIT_V(8); PG8_WAIT_L(0); PG8_BAR; PG8_MMA(0, 0, At, B0); PG8_MMA(0, 1, At, B1); PG8_BAR; PG8_SCHED;
;             PG8_LDA(At, 0, 1); PG8_STAGE(PG8_SB(0, 0), b2, voffB); PG8_STAGE(PG8_SB(0, 1), b2 + hstepB, voffB); PG8_STAGE(PG8_SA(0, 0), a2, voffA);
;             PG8_WAIT_V(8); PG8_WAIT_L(0); PG8_BAR; PG8_MMA(1, 0, At, B0); PG8_MMA(1, 1, At, B1); PG8_BAR; PG8_SCHED;
;             PG8_LDB(B0, 1, 0); PG8_LDB(B1, 1, 1); PG8_SCHED; PG8_LDA(At, 1, 0); PG8_STAGE(PG8_SA(0, 1), a2 + hstepA, voffA);
;             PG8_WAIT_V(8); PG8_WAIT_L(0); PG8_BAR; PG8_MMA(0, 0, At, B0); PG8_MMA(0, 1, At, B1); PG8_BAR; PG8_SCHED;
;             PG8_LDA(At, 1, 1); PG8_STAGE(PG8_SB(1, 0), b3, voffB); PG8_STAGE(PG8_SB(1, 1), b3 + hstepB, voffB); PG8_STAGE(PG8_SA(1, 0), a3, voffA);
;             PG8_WAIT_V(8); PG8_WAIT_L(0); PG8_BAR; PG8_MMA(1, 0, At, B0); PG8_MMA(1, 1, At, B1); PG8_BAR; PG8_SCHED;
	ds_read_b128 v[166:169], v153 offset:49152
	ds_read_b128 v[170:173], v153 offset:50176
	ds_read_b128 v[174:177], v153 offset:51200
	ds_read_b128 v[178:181], v153 offset:52224
	ds_read_b128 v[182:185], v153 offset:53248
	ds_read_b128 v[186:189], v153 offset:54272
	ds_read_b128 v[190:193], v153 offset:55296
	ds_read_b128 v[194:197], v153 offset:56320
	s_add_u32 s4, s68, 0x80
	s_addc_u32 s5, s69, 0
	s_mov_b32 s6, m0
	s_mov_b32 m0, s90
	s_nop 0
	global_load_lds_dwordx4 v149, s[4:5]
	s_mov_b32 m0, s6
	s_nop 0
	s_mov_b32 s6, m0
	s_mov_b32 m0, s91
	s_nop 0
	global_load_lds_dwordx4 v151, s[4:5]
	s_mov_b32 m0, s6
	s_add_u32 s4, s68, 0x40080
	s_addc_u32 s5, s69, 0
	s_mov_b32 s6, m0
	s_mov_b32 m0, s94
	s_nop 0
	global_load_lds_dwordx4 v149, s[4:5]
	s_mov_b32 m0, s6
	s_nop 0
	s_mov_b32 s6, m0
	s_mov_b32 m0, s95
	s_nop 0
	global_load_lds_dwordx4 v151, s[4:5]
	s_mov_b32 m0, s6
	s_mov_b32 s4, m0
	s_mov_b32 m0, s92
	s_nop 0
	global_load_lds_dwordx4 v148, s[56:57]
	s_mov_b32 m0, s4
	s_nop 0
	s_mov_b32 s4, m0
	s_mov_b32 m0, s93
	s_nop 0
	global_load_lds_dwordx4 v150, s[56:57]
	s_mov_b32 m0, s4
	s_waitcnt vmcnt(8)
	s_waitcnt lgkmcnt(0)
	s_barrier
	s_waitcnt lgkmcnt(7)
	v_mfma_i32_16x16x64_i8 v[60:63], v[128:131], v[166:169], v[60:63]
	v_mfma_i32_16x16x64_i8 v[56:59], v[136:139], v[166:169], v[56:59]
	s_waitcnt lgkmcnt(5)
	v_mfma_i32_16x16x64_i8 v[44:47], v[128:131], v[174:177], v[44:47]
	v_mfma_i32_16x16x64_i8 v[40:43], v[136:139], v[174:177], v[40:43]
	s_waitcnt lgkmcnt(3)
	v_mfma_i32_16x16x64_i8 v[28:31], v[128:131], v[182:185], v[28:31]
	v_mfma_i32_16x16x64_i8 v[24:27], v[136:139], v[182:185], v[24:27]
	s_waitcnt lgkmcnt(1)
	v_mfma_i32_16x16x64_i8 v[12:15], v[128:131], v[190:193], v[12:15]
	v_mfma_i32_16x16x64_i8 v[8:11], v[136:139], v[190:193], v[8:11]
	v_mfma_i32_16x16x64_i8 v[60:63], v[132:135], v[170:173], v[60:63]
	v_mfma_i32_16x16x64_i8 v[56:59], v[140:143], v[170:173], v[56:59]
	v_mfma_i32_16x16x64_i8 v[44:47], v[132:135], v[178:181], v[44:47]
	v_mfma_i32_16x16x64_i8 v[40:43], v[140:143], v[178:181], v[40:43]
	v_mfma_i32_16x16x64_i8 v[28:31], v[132:135], v[186:189], v[28:31]
	v_mfma_i32_16x16x64_i8 v[24:27], v[140:143], v[186:189], v[24:27]
	s_waitcnt lgkmcnt(0)
	v_mfma_i32_16x16x64_i8 v[12:15], v[132:135], v[194:197], v[12:15]
	v_mfma_i32_16x16x64_i8 v[8:11], v[140:143], v[194:197], v[8:11]
	v_mfma_i32_16x16x64_i8 v[52:55], v[144:147], v[166:169], v[52:55]
	v_mfma_i32_16x16x64_i8 v[48:51], v[158:161], v[166:169], v[48:51]
	v_mfma_i32_16x16x64_i8 v[36:39], v[144:147], v[174:177], v[36:39]
	v_mfma_i32_16x16x64_i8 v[32:35], v[158:161], v[174:177], v[32:35]
	v_mfma_i32_16x16x64_i8 v[20:23], v[144:147], v[182:185], v[20:23]
	v_mfma_i32_16x16x64_i8 v[16:19], v[158:161], v[182:185], v[16:19]
	v_mfma_i32_16x16x64_i8 v[4:7], v[144:147], v[190:193], v[4:7]
	v_mfma_i32_16x16x64_i8 v[0:3], v[158:161], v[190:193], v[0:3]
	v_mfma_i32_16x16x64_i8 v[52:55], v[154:157], v[170:173], v[52:55]
	v_mfma_i32_16x16x64_i8 v[48:51], v[162:165], v[170:173], v[48:51]
	v_mfma_i32_16x16x64_i8 v[36:39], v[154:157], v[178:181], v[36:39]
	v_mfma_i32_16x16x64_i8 v[32:35], v[162:165], v[178:181], v[32:35]
	v_mfma_i32_16x16x64_i8 v[20:23], v[154:157], v[186:189], v[20:23]
	v_mfma_i32_16x16x64_i8 v[16:19], v[162:165], v[186:189], v[16:19]
	v_mfma_i32_16x16x64_i8 v[4:7], v[154:157], v[194:197], v[4:7]
	v_mfma_i32_16x16x64_i8 v[0:3], v[162:165], v[194:197], v[0:3]
	s_barrier
	s_add_i32 s1, s1, 2
	s_add_u32 s73, s73, 0x100
	s_addc_u32 vcc_lo, vcc_lo, 0
	s_add_u32 vcc_hi, vcc_hi, 0x100
	s_addc_u32 s0, s0, 0
	s_add_u32 s44, s44, 0x100
	s_addc_u32 s45, s45, 0
	s_cmp_gt_u32 s1, 13
	s_cbranch_scc0 .LBB0_616
	s_and_b64 vcc, exec, s[28:29]
	s_cbranch_vccz .LBB0_619
	s_barrier

; __device__ __forceinline__ int mk_lane() { int l; asm volatile("v_mbcnt_lo_u32_b32 %0, -1, 0\n\tv_mbcnt_hi_u32_b32 %0, -1, %0" : "=v"(l)); return l; }
; #define PG8_STAGE(bufoff, gbase, voff) do { _Pragma("unroll") for (int _i = 0; _i < 2; ++_i) glds16_s((gbase), (voff)[_i], ldsb + (unsigned)((bufoff) + _i * 8192)); } while (0)
; #define PG8_BAR __builtin_amdgcn_s_barrier()
;     __device__ bool next(int i, Unit& u) const { return S.next(i, u); }
;     __device__ unsigned a_rowoff(int R) const { const int r = upmap ? (128 * (R >> 6) + 8 * (R & 15) + ((R >> 4) & 3)) : R; return (unsigned)r * (unsigned)lda * 2u; }
; template <class Prob, class Epi, bool I8 = false, bool ALIGN_EPI = true, bool SP2 = true>
; __device__ __forceinline__ void gemm_phase(LAS unsigned char* lds, int wave, const Prob& P, const Epi& E) {
;     const int tid_ = wave * 64 + mk_lane();
;     const int tid = tid_, wid = __builtin_amdgcn_readfirstlane(tid >> 6), lane = tid & 63, wr = wid >> 2, wc = wid & 3, fr = lane & 15, fq = lane >> 4;
;     const int K = P.K, nt = K / BK;
;     unsigned voffA[2], voffB[2];
; #pragma unroll
;     for (int i = 0; i < 2; ++i) { int R, C; stage_rc(tid * 16 + i * 8192, R, C); const int Rb = (R & ~31) + perm32(R & 31);
;         voffA[i] = P.a_rowoff(R) + (unsigned)C * 2u; voffB[i] = P.b_rowoff(Rb) + (unsigned)C * 2u; }
;     const size_t kstep = (size_t)(BK * 2);
;     const size_t hstepA = P.a_hstep(), hstepB = P.b_hstep();
;     const unsigned ldsw = (unsigned)wid * 1024u;
;     const unsigned ldsb = (unsigned)(size_t)lds + ldsw;
;     const int aoff = lds_byte(wr * 64 + fr, fq * 8), boff = lds_byte(wc * 32 + fr, fq * 8);
;     ...
;     Unit cur, nxt; int ui = 0;
;     if (!P.next(0, cur)) return;
;     Acc acc;
; #pragma unroll
;     for (int a = 0; a < 2; ++a)
; #pragma unroll
;         for (int b = 0; b < 2; ++b)
; #pragma unroll
;             for (int m = 0; m < 4; ++m)
; #pragma unroll
;                 for (int n = 0; n < 2; ++n) acc[a][b][m][n] = (f32x4){0.f, 0.f, 0.f, 0.f};
;     h16x8 At[4][2], B0[2][2], B1[2][2];
;     const char* cA = P.a_tile(cur); const char* cB = P.b_tile(cur);
;     if constexpr (SP2) {
;         PG8_STAGE(PG8_SB(0, 0), cB, voffB); PG8_STAGE(PG8_SB(0, 1), cB + hstepB, voffB); PG8_STAGE(PG8_SA(0, 0), cA, voffA); PG8_STAGE(PG8_SA(0, 1), cA + hstepA, voffA);
;         if (wr == 1) PG8_BAR;
.LBB0_854:
	v_readlane_b32 s0, v254, 42
	v_readlane_b32 s4, v254, 43
	s_waitcnt lgkmcnt(0)
	s_barrier
	v_mbcnt_lo_u32_b32 v0, -1, 0
	v_mbcnt_hi_u32_b32 v0, -1, v0
	v_readlane_b32 s5, v254, 44
	v_add_u32_e32 v1, s0, v0
	s_and_b64 vcc, exec, s[4:5]
	v_readfirstlane_b32 s0, v1
	s_cbranch_vccz .LBB0_870
	v_ashrrev_i32_e32 v3, 31, v1
	v_lshrrev_b32_e32 v3, 26, v3
	v_lshlrev_b32_e32 v2, 4, v1
	v_add_u32_e32 v3, v1, v3
	v_bfe_i32 v1, v1, 27, 1
	v_lshrrev_b32_e32 v1, 22, v1
	v_add_u32_e32 v1, v2, v1
	v_and_b32_e32 v1, 0xfffffc00, v1
	v_sub_u32_e32 v1, v2, v1
	v_lshrrev_b32_e32 v4, 4, v1
	v_bitop3_b32 v1, v4, v1, 32 bitop3:0x6c
	v_ashrrev_i32_e32 v5, 31, v1
	v_readlane_b32 s1, v253, 52
	v_ashrrev_i32_e32 v3, 6, v3
	v_lshrrev_b32_e32 v5, 26, v5
	s_add_u32 s1, s30, s1
	v_lshlrev_b32_e32 v4, 3, v3
	v_add_u32_e32 v5, v1, v5
	s_addc_u32 s4, s31, 0
	v_and_b32_e32 v4, -16, v4
	v_ashrrev_i32_e32 v6, 6, v5
	v_and_b32_e32 v5, 0xc0, v5
	s_add_u32 s2, s1, 0x8a00000
	v_add_u32_e32 v4, v6, v4
	v_sub_u32_e32 v1, v1, v5
	v_mov_b32_e32 v8, 1
	s_addc_u32 s19, s4, 0
	v_lshlrev_b32_e32 v3, 5, v3
	v_ashrrev_i16_sdwa v1, v8, sext(v1) dst_sel:DWORD dst_unused:UNUSED_PAD src0_sel:DWORD src1_sel:BYTE_0
	v_lshlrev_b32_e32 v5, 1, v4
	v_lshrrev_b32_e32 v7, 2, v4
	v_and_b32_e32 v6, 3, v6
	s_mov_b32 s4, 0xfffe0
	v_and_b32_e32 v3, 32, v3
	v_bfe_i32 v1, v1, 0, 16
	v_and_b32_e32 v5, 24, v5
	v_and_b32_e32 v7, 4, v7
	v_and_or_b32 v6, v4, s4, v6
	v_or3_b32 v5, v6, v7, v5
	v_add_lshl_u32 v1, v3, v1, 1
	v_lshl_add_u32 v142, v4, 12, v1
	v_lshl_add_u32 v143, v5, 12, v1
	v_add_u32_e32 v1, 0x2000, v2
	v_ashrrev_i32_e32 v2, 31, v1
	v_lshrrev_b32_e32 v2, 22, v2
	v_add_u32_e32 v2, v1, v2
	v_ashrrev_i32_e32 v2, 10, v2
	v_mul_i32_i24_e32 v3, 0x400, v2
	v_sub_u32_e32 v1, v1, v3
	v_lshrrev_b32_e32 v3, 4, v1
	v_bitop3_b32 v1, v3, v1, 32 bitop3:0x6c
	v_ashrrev_i32_e32 v4, 31, v1
	v_lshrrev_b32_e32 v4, 26, v4
	v_lshlrev_b32_e32 v3, 3, v2
	v_add_u32_e32 v4, v1, v4
	v_and_b32_e32 v3, -16, v3
	v_ashrrev_i32_e32 v5, 6, v4
	v_add_u32_e32 v3, v5, v3
	v_and_b32_e32 v5, 3, v5
	v_and_b32_e32 v4, 0xc0, v4
	v_and_or_b32 v5, v3, s4, v5
	s_ashr_i32 s4, s0, 6
	v_sub_u32_e32 v1, v1, v4
	s_lshl_b32 s5, s4, 10
	s_ashr_i32 s1, s0, 8
	v_lshlrev_b32_e32 v2, 5, v2
	v_ashrrev_i16_sdwa v1, v8, sext(v1) dst_sel:DWORD dst_unused:UNUSED_PAD src0_sel:DWORD src1_sel:BYTE_0
	v_lshlrev_b32_e32 v4, 1, v3
	v_lshrrev_b32_e32 v6, 2, v3
	s_add_i32 s48, s5, 0
	v_readlane_b32 s6, v252, 32
	v_and_b32_e32 v2, 32, v2
	v_bfe_i32 v1, v1, 0, 16
	v_and_b32_e32 v4, 24, v4
	v_and_b32_e32 v6, 4, v6
	v_readlane_b32 s7, v252, 33
	s_add_u32 s40, s2, s6
	v_or3_b32 v4, v5, v6, v4
	v_add_lshl_u32 v1, v2, v1, 1
	s_addc_u32 s41, s19, s7
	s_add_i32 s49, s48, 0x10000
	s_mov_b32 s5, m0
	s_mov_b32 m0, s49
	s_nop 0
	global_load_lds_dwordx4 v143, s[40:41]
	s_mov_b32 m0, s5
	s_add_i32 s50, s48, 0x12000
	v_lshl_add_u32 v145, v4, 12, v1
	s_mov_b32 s5, m0
	s_mov_b32 m0, s50
	s_nop 0
	global_load_lds_dwordx4 v145, s[40:41]
	s_mov_b32 m0, s5
	s_add_u32 s14, s40, 0x80000
	s_addc_u32 s15, s41, 0
	s_add_i32 s51, s48, 0x14000
	s_mov_b32 s5, m0
	s_mov_b32 m0, s51
	s_nop 0
	global_load_lds_dwordx4 v143, s[14:15]
	s_mov_b32 m0, s5
	s_add_i32 s56, s48, 0x16000
	v_readlane_b32 s6, v252, 38
	s_mov_b32 s5, m0
	s_mov_b32 m0, s56
	s_nop 0
	global_load_lds_dwordx4 v145, s[14:15]
	s_mov_b32 m0, s5
	v_readlane_b32 s7, v252, 39
	s_add_u32 s42, s76, s6
	s_addc_u32 s43, s77, s7
	s_mov_b32 s5, m0
	s_mov_b32 m0, s48
	s_nop 0
	global_load_lds_dwordx4 v142, s[42:43]
	s_mov_b32 m0, s5
	s_add_i32 s57, s48, 0x2000
	v_lshl_add_u32 v144, v3, 12, v1
	s_mov_b32 s5, m0
	s_mov_b32 m0, s57
	s_nop 0
	global_load_lds_dwordx4 v144, s[42:43]
	s_mov_b32 m0, s5
	s_add_u32 s14, s42, 0x80000
	s_addc_u32 s15, s43, 0
	s_add_i32 s60, s48, 0x4000
	s_mov_b32 s5, m0
	s_mov_b32 m0, s60
	s_nop 0
	global_load_lds_dwordx4 v142, s[14:15]
	s_mov_b32 m0, s5
	s_add_i32 s61, s48, 0x6000
	s_mov_b32 s5, m0
	s_mov_b32 m0, s61
	s_nop 0
	global_load_lds_dwordx4 v144, s[14:15]
	s_mov_b32 m0, s5
	s_cmp_eq_u32 s1, 1
	s_cselect_b64 s[14:15], -1, 0
	s_cmp_lg_u32 s1, 1
	s_cbranch_scc1 .LBB0_857
	s_barrier
	s_setprio 1

; #define PG8_STAGE(bufoff, gbase, voff) do { _Pragma("unroll") for (int _i = 0; _i < 2; ++_i) glds16_s((gbase), (voff)[_i], ldsb + (unsigned)((bufoff) + _i * 8192)); } while (0)
; #define PG8_LDA(dst, b, h) do { _Pragma("unroll") for (int m = 0; m < 4; ++m) _Pragma("unroll") for (int k = 0; k < 2; ++k) dst[m][k] = *(const LAS h16x8*)(lds + PG8_SA(b, h) + aoff + m * 2048 + k * 1024); } while (0)
; #define PG8_WAIT_V(n) asm volatile("s_waitcnt vmcnt(" #n ")" ::: "memory")
; #define PG8_WAIT_L(n) asm volatile("s_waitcnt lgkmcnt(" #n ")" ::: "memory")
; #define PG8_BAR __builtin_amdgcn_s_barrier()
; template <class Prob, class Epi, bool I8 = false, bool ALIGN_EPI = true, bool SP2 = true>
; __device__ __forceinline__ void gemm_phase(LAS unsigned char* lds, int wave, const Prob& P, const Epi& E) {
;     ...
;         const bool has_next = P.next(ui + 1, nxt);
;         const char* nA = has_next ? P.a_tile(nxt) : cA; const char* nB = has_next ? P.b_tile(nxt) : cB;
;         for (int t = 0; t < nt; t += 2) {
;             const bool last = (t == nt - 2);
;             const char* a1 = cA + (size_t)(t + 1) * kstep;
;             const char* a2 = last ? nA : cA + (size_t)(t + 2) * kstep; const char* b2 = last ? nB : cB + (size_t)(t + 2) * kstep;
;             const char* a3 = a2 + kstep; const char* b3 = b2 + kstep;
;             if constexpr (SP2) {
;             PG8_LDB(B0, 0, 0); PG8_LDB(B1, 0, 1); PG8_SCHED; PG8_LDA(At, 0, 0); PG8_STAGE(PG8_SA(1, 1), a1 + hstepA, voffA);
;             PG8_WAIT_V(8); PG8_WAIT_L(0); PG8_BAR; PG8_MMA(0, 0, At, B0); PG8_MMA(0, 1, At, B1); PG8_BAR; PG8_SCHED;
;             PG8_LDA(At, 0, 1); PG8_STAGE(PG8_SB(0, 0), b2, voffB); PG8_STAGE(PG8_SB(0, 1), b2 + hstepB, voffB); PG8_STAGE(PG8_SA(0, 0), a2, voffA);
;             PG8_WAIT_V(8); PG8_WAIT_L(0); PG8_BAR; PG8_MMA(1, 0, At, B0); PG8_MMA(1, 1, At, B1); PG8_BAR; PG8_SCHED;
;             PG8_LDB(B0, 1, 0); PG8_LDB(B1, 1, 1); PG8_SCHED; PG8_LDA(At, 1, 0); PG8_STAGE(PG8_SA(0, 1), a2 + hstepA, voffA);
;             PG8_WAIT_V(8); PG8_WAIT_L(0); PG8_BAR; PG8_MMA(0, 0, At, B0); PG8_MMA(0, 1, At, B1); PG8_BAR; PG8_SCHED;
;             PG8_LDA(At, 1, 1); PG8_STAGE(PG8_SB(1, 0), b3, voffB); PG8_STAGE(PG8_SB(1, 1), b3 + hstepB, voffB); PG8_STAGE(PG8_SA(1, 0), a3, voffA);
;             PG8_WAIT_V(8); PG8_WAIT_L(0); PG8_BAR; PG8_MMA(1, 0, At, B0); PG8_MMA(1, 1, At, B1); PG8_BAR; PG8_SCHED;
.Lpeel_863:
	v_add_u32_e32 v140, 0x10000, v146
	ds_read_b128 v[128:131], v140
	ds_read_b128 v[132:135], v140 offset:1024
	ds_read_b128 v[136:139], v140 offset:2048
	ds_read_b128 v[148:151], v140 offset:3072
	v_add_u32_e32 v140, 0x14000, v146
	ds_read_b128 v[152:155], v140
	ds_read_b128 v[156:159], v140 offset:1024
	ds_read_b128 v[160:163], v140 offset:2048
	ds_read_b128 v[164:167], v140 offset:3072
	s_cmp_eq_u32 s1, 28
	s_cselect_b32 s46, s83, s85
	s_cselect_b32 s47, s27, s86
	s_cselect_b32 s44, s84, s87
	s_cselect_b32 s45, s23, s0
	s_add_u32 s42, s46, 0x80
	s_addc_u32 s43, s47, 0
	ds_read_b128 v[168:171], v147
	ds_read_b128 v[172:175], v147 offset:1024
	ds_read_b128 v[176:179], v147 offset:2048
	ds_read_b128 v[180:183], v147 offset:3072
	ds_read_b128 v[184:187], v147 offset:4096
	ds_read_b128 v[188:191], v147 offset:5120
	ds_read_b128 v[192:195], v147 offset:6144
	ds_read_b128 v[196:199], v147 offset:7168
	s_mov_b32 s4, m0
	s_mov_b32 m0, s75
	s_nop 0
	global_load_lds_dwordx4 v142, s[40:41]
	s_mov_b32 m0, s4
	s_nop 0
	s_mov_b32 s4, m0
	s_mov_b32 m0, s79
	s_nop 0
	global_load_lds_dwordx4 v144, s[40:41]
	s_mov_b32 m0, s4
	s_waitcnt vmcnt(8)
	s_waitcnt lgkmcnt(0)
	s_barrier
	s_waitcnt lgkmcnt(7)
	v_mfma_f32_16x16x32_f16 v[124:127], v[128:131], v[168:171], 0
	v_mfma_f32_16x16x32_f16 v[120:123], v[136:139], v[168:171], 0
	s_waitcnt lgkmcnt(5)
	v_mfma_f32_16x16x32_f16 v[116:119], v[128:131], v[176:179], 0
	v_mfma_f32_16x16x32_f16 v[112:115], v[136:139], v[176:179], 0
	s_waitcnt lgkmcnt(3)
	v_mfma_f32_16x16x32_f16 v[108:111], v[128:131], v[184:187], 0
	v_mfma_f32_16x16x32_f16 v[104:107], v[136:139], v[184:187], 0
	s_waitcnt lgkmcnt(1)
	v_mfma_f32_16x16x32_f16 v[100:103], v[128:131], v[192:195], 0
	v_mfma_f32_16x16x32_f16 v[96:99], v[136:139], v[192:195], 0
	v_mfma_f32_16x16x32_f16 v[124:127], v[132:135], v[172:175], v[124:127]
	v_mfma_f32_16x16x32_f16 v[120:123], v[148:151], v[172:175], v[120:123]
	v_mfma_f32_16x16x32_f16 v[116:119], v[132:135], v[180:183], v[116:119]
	v_mfma_f32_16x16x32_f16 v[112:115], v[148:151], v[180:183], v[112:115]
	v_mfma_f32_16x16x32_f16 v[108:111], v[132:135], v[188:191], v[108:111]
	v_mfma_f32_16x16x32_f16 v[104:107], v[148:151], v[188:191], v[104:107]
	s_waitcnt lgkmcnt(0)
	v_mfma_f32_16x16x32_f16 v[100:103], v[132:135], v[196:199], v[100:103]
	v_mfma_f32_16x16x32_f16 v[96:99], v[148:151], v[196:199], v[96:99]
	v_mfma_f32_16x16x32_f16 v[64:67], v[152:155], v[168:171], 0
	v_mfma_f32_16x16x32_f16 v[56:59], v[160:163], v[168:171], 0
	v_mfma_f32_16x16x32_f16 v[52:55], v[152:155], v[176:179], 0
	v_mfma_f32_16x16x32_f16 v[48:51], v[160:163], v[176:179], 0
	v_mfma_f32_16x16x32_f16 v[44:47], v[152:155], v[184:187], 0
	v_mfma_f32_16x16x32_f16 v[40:43], v[160:163], v[184:187], 0
	v_mfma_f32_16x16x32_f16 v[36:39], v[152:155], v[192:195], 0
	v_mfma_f32_16x16x32_f16 v[32:35], v[160:163], v[192:195], 0
	v_mfma_f32_16x16x32_f16 v[64:67], v[156:159], v[172:175], v[64:67]
	v_mfma_f32_16x16x32_f16 v[56:59], v[164:167], v[172:175], v[56:59]
	v_mfma_f32_16x16x32_f16 v[52:55], v[156:159], v[180:183], v[52:55]
	v_mfma_f32_16x16x32_f16 v[48:51], v[164:167], v[180:183], v[48:51]
	v_mfma_f32_16x16x32_f16 v[44:47], v[156:159], v[188:191], v[44:47]
	v_mfma_f32_16x16x32_f16 v[40:43], v[164:167], v[188:191], v[40:43]
	v_mfma_f32_16x16x32_f16 v[36:39], v[156:159], v[196:199], v[36:39]
	v_mfma_f32_16x16x32_f16 v[32:35], v[164:167], v[196:199], v[32:35]
	s_barrier
	ds_read_b128 v[168:171], v147 offset:16384
	ds_read_b128 v[172:175], v147 offset:17408
	ds_read_b128 v[176:179], v147 offset:18432
	ds_read_b128 v[180:183], v147 offset:19456
	ds_read_b128 v[184:187], v147 offset:20480
	ds_read_b128 v[188:191], v147 offset:21504
	ds_read_b128 v[192:195], v147 offset:22528
	ds_read_b128 v[196:199], v147 offset:23552
	s_mov_b32 s4, m0
	s_mov_b32 m0, s49
	s_nop 0
	global_load_lds_dwordx4 v143, s[44:45]
	s_mov_b32 m0, s4
	s_nop 0
	s_mov_b32 s4, m0
	s_mov_b32 m0, s50
	s_nop 0
	global_load_lds_dwordx4 v145, s[44:45]
	s_mov_b32 m0, s4
	s_add_u32 s4, s44, 0x80000
	s_addc_u32 s5, s45, 0
	s_mov_b32 s6, m0
	s_mov_b32 m0, s51
	s_nop 0
	global_load_lds_dwordx4 v143, s[4:5]
	s_mov_b32 m0, s6
	s_nop 0
	s_mov_b32 s6, m0
	s_mov_b32 m0, s56
	s_nop 0
	global_load_lds_dwordx4 v145, s[4:5]
	s_mov_b32 m0, s6
	s_mov_b32 s4, m0
	s_mov_b32 m0, s48
	s_nop 0
	global_load_lds_dwordx4 v142, s[46:47]
	s_mov_b32 m0, s4
	s_nop 0
	s_mov_b32 s4, m0
	s_mov_b32 m0, s57
	s_nop 0
	global_load_lds_dwordx4 v144, s[46:47]
	s_mov_b32 m0, s4
	s_waitcnt vmcnt(8)
	s_waitcnt lgkmcnt(0)
	s_barrier
	s_waitcnt lgkmcnt(7)
	v_mfma_f32_16x16x32_f16 v[92:95], v[128:131], v[168:171], 0
	v_mfma_f32_16x16x32_f16 v[88:91], v[136:139], v[168:171], 0
	s_waitcnt lgkmcnt(5)
	v_mfma_f32_16x16x32_f16 v[84:87], v[128:131], v[176:179], 0
	v_mfma_f32_16x16x32_f16 v[80:83], v[136:139], v[176:179], 0
	s_waitcnt lgkmcnt(3)
	v_mfma_f32_16x16x32_f16 v[76:79], v[128:131], v[184:187], 0
	v_mfma_f32_16x16x32_f16 v[72:75], v[136:139], v[184:187], 0
	s_waitcnt lgkmcnt(1)
	v_mfma_f32_16x16x32_f16 v[68:71], v[128:131], v[192:195], 0
	v_mfma_f32_16x16x32_f16 v[60:63], v[136:139], v[192:195], 0
	v_mfma_f32_16x16x32_f16 v[92:95], v[132:135], v[172:175], v[92:95]
	v_mfma_f32_16x16x32_f16 v[88:91], v[148:151], v[172:175], v[88:91]
	v_mfma_f32_16x16x32_f16 v[84:87], v[132:135], v[180:183], v[84:87]
	v_mfma_f32_16x16x32_f16 v[80:83], v[148:151], v[180:183], v[80:83]
	v_mfma_f32_16x16x32_f16 v[76:79], v[132:135], v[188:191], v[76:79]
	v_mfma_f32_16x16x32_f16 v[72:75], v[148:151], v[188:191], v[72:75]
	s_waitcnt lgkmcnt(0)
	v_mfma_f32_16x16x32_f16 v[68:71], v[132:135], v[196:199], v[68:71]
	v_mfma_f32_16x16x32_f16 v[60:63], v[148:151], v[196:199], v[60:63]
	v_mfma_f32_16x16x32_f16 v[28:31], v[152:155], v[168:171], 0
	v_mfma_f32_16x16x32_f16 v[24:27], v[160:163], v[168:171], 0
	v_mfma_f32_16x16x32_f16 v[20:23], v[152:155], v[176:179], 0
	v_mfma_f32_16x16x32_f16 v[16:19], v[160:163], v[176:179], 0
	v_mfma_f32_16x16x32_f16 v[12:15], v[152:155], v[184:187], 0
	v_mfma_f32_16x16x32_f16 v[8:11], v[160:163], v[184:187], 0
	v_mfma_f32_16x16x32_f16 v[4:7], v[152:155], v[192:195], 0
	v_mfma_f32_16x16x32_f16 v[0:3], v[160:163], v[192:195], 0
	v_mfma_f32_16x16x32_f16 v[28:31], v[156:159], v[172:175], v[28:31]
	v_mfma_f32_16x16x32_f16 v[24:27], v[164:167], v[172:175], v[24:27]
	v_mfma_f32_16x16x32_f16 v[20:23], v[156:159], v[180:183], v[20:23]
	v_mfma_f32_16x16x32_f16 v[16:19], v[164:167], v[180:183], v[16:19]
	v_mfma_f32_16x16x32_f16 v[12:15], v[156:159], v[188:191], v[12:15]
	v_mfma_f32_16x16x32_f16 v[8:11], v[164:167], v[188:191], v[8:11]
	v_mfma_f32_16x16x32_f16 v[4:7], v[156:159], v[196:199], v[4:7]
	v_mfma_f32_16x16x32_f16 v[0:3], v[164:167], v[196:199], v[0:3]
	s_barrier
; #define PG8_STAGE(bufoff, gbase, voff) do { _Pragma("unroll") for (int _i = 0; _i < 2; ++_i) glds16_s((gbase), (voff)[_i], ldsb + (unsigned)((bufoff) + _i * 8192)); } while (0)
; #define PG8_LDA(dst, b, h) do { _Pragma("unroll") for (int m = 0; m < 4; ++m) _Pragma("unroll") for (int k = 0; k < 2; ++k) dst[m][k] = *(const LAS h16x8*)(lds + PG8_SA(b, h) + aoff + m * 2048 + k * 1024); } while (0)
; #define PG8_LDB(dst, b, h) do { _Pragma("unroll") for (int n = 0; n < 2; ++n) _Pragma("unroll") for (int k = 0; k < 2; ++k) dst[n][k] = *(const LAS h16x8*)(lds + PG8_SB(b, h) + boff + n * 2048 + k * 1024); } while (0)
; #define PG8_MMA(ai, bj, At, Bt) do { __builtin_amdgcn_s_setprio(1); _Pragma("unroll") for (int m = 0; m < 4; ++m) _Pragma("unroll") for (int n = 0; n < 2; ++n) _Pragma("unroll") for (int k = 0; k < 2; ++k) \
;         acc[ai][bj][m][n] = mma_step<I8>(Bt[n][k], At[m][k], acc[ai][bj][m][n]); __builtin_amdgcn_s_setprio(0); } while (0)
; #define PG8_WAIT_V(n) asm volatile("s_waitcnt vmcnt(" #n ")" ::: "memory")
; #define PG8_WAIT_L(n) asm volatile("s_waitcnt lgkmcnt(" #n ")" ::: "memory")
; #define PG8_BAR __builtin_amdgcn_s_barrier()
; #define PG8_SCHED __builtin_amdgcn_sched_barrier(0)
; template <class Prob, class Epi, bool I8 = false, bool ALIGN_EPI = true, bool SP2 = true>
; __device__ __forceinline__ void gemm_phase(LAS unsigned char* lds, int wave, const Prob& P, const Epi& E) {
;     ...
;             PG8_LDB(B0, 1, 0); PG8_LDB(B1, 1, 1); PG8_SCHED; PG8_LDA(At, 1, 0); PG8_STAGE(PG8_SA(0, 1), a2 + hstepA, voffA);
;             PG8_WAIT_V(8); PG8_WAIT_L(0); PG8_BAR; PG8_MMA(0, 0, At, B0); PG8_MMA(0, 1, At, B1); PG8_BAR; PG8_SCHED;
;             PG8_LDA(At, 1, 1); PG8_STAGE(PG8_SB(1, 0), b3, voffB); PG8_STAGE(PG8_SB(1, 1), b3 + hstepB, voffB); PG8_STAGE(PG8_SA(1, 0), a3, voffA);
;             PG8_WAIT_V(8); PG8_WAIT_L(0); PG8_BAR; PG8_MMA(1, 0, At, B0); PG8_MMA(1, 1, At, B1); PG8_BAR; PG8_SCHED;
	v_add_u32_e32 v140, 0x18000, v146
	ds_read_b128 v[128:131], v140
	ds_read_b128 v[132:135], v140 offset:1024
	ds_read_b128 v[136:139], v140 offset:2048
	ds_read_b128 v[148:151], v140 offset:3072
	v_add_u32_e32 v140, 0x1c000, v146
	ds_read_b128 v[152:155], v140
	ds_read_b128 v[156:159], v140 offset:1024
	ds_read_b128 v[160:163], v140 offset:2048
	ds_read_b128 v[164:167], v140 offset:3072
	ds_read_b128 v[168:171], v147 offset:32768
	ds_read_b128 v[172:175], v147 offset:33792
	ds_read_b128 v[176:179], v147 offset:34816
	ds_read_b128 v[180:183], v147 offset:35840
	ds_read_b128 v[184:187], v147 offset:36864
	ds_read_b128 v[188:191], v147 offset:37888
	ds_read_b128 v[192:195], v147 offset:38912
	ds_read_b128 v[196:199], v147 offset:39936
	s_add_u32 s4, s46, 0x80000
	s_addc_u32 s5, s47, 0
	s_mov_b32 s6, m0
	s_mov_b32 m0, s60
	s_nop 0
	global_load_lds_dwordx4 v142, s[4:5]
	s_mov_b32 m0, s6
	s_nop 0
	s_mov_b32 s6, m0
	s_mov_b32 m0, s61
	s_nop 0
	global_load_lds_dwordx4 v144, s[4:5]
	s_mov_b32 m0, s6
	s_waitcnt vmcnt(8)
	s_waitcnt lgkmcnt(0)
	s_barrier
	s_waitcnt lgkmcnt(7)
	v_mfma_f32_16x16x32_f16 v[124:127], v[128:131], v[168:171], v[124:127]
	v_mfma_f32_16x16x32_f16 v[120:123], v[136:139], v[168:171], v[120:123]
	s_waitcnt lgkmcnt(5)
	v_mfma_f32_16x16x32_f16 v[116:119], v[128:131], v[176:179], v[116:119]
	v_mfma_f32_16x16x32_f16 v[112:115], v[136:139], v[176:179], v[112:115]
	s_waitcnt lgkmcnt(3)
	v_mfma_f32_16x16x32_f16 v[108:111], v[128:131], v[184:187], v[108:111]
	v_mfma_f32_16x16x32_f16 v[104:107], v[136:139], v[184:187], v[104:107]
	s_waitcnt lgkmcnt(1)
	v_mfma_f32_16x16x32_f16 v[100:103], v[128:131], v[192:195], v[100:103]
	v_mfma_f32_16x16x32_f16 v[96:99], v[136:139], v[192:195], v[96:99]
	v_mfma_f32_16x16x32_f16 v[124:127], v[132:135], v[172:175], v[124:127]
	v_mfma_f32_16x16x32_f16 v[120:123], v[148:151], v[172:175], v[120:123]
	v_mfma_f32_16x16x32_f16 v[116:119], v[132:135], v[180:183], v[116:119]
	v_mfma_f32_16x16x32_f16 v[112:115], v[148:151], v[180:183], v[112:115]
	v_mfma_f32_16x16x32_f16 v[108:111], v[132:135], v[188:191], v[108:111]
	v_mfma_f32_16x16x32_f16 v[104:107], v[148:151], v[188:191], v[104:107]
	s_waitcnt lgkmcnt(0)
	v_mfma_f32_16x16x32_f16 v[100:103], v[132:135], v[196:199], v[100:103]
	v_mfma_f32_16x16x32_f16 v[96:99], v[148:151], v[196:199], v[96:99]
	v_mfma_f32_16x16x32_f16 v[64:67], v[152:155], v[168:171], v[64:67]
	v_mfma_f32_16x16x32_f16 v[56:59], v[160:163], v[168:171], v[56:59]
	v_mfma_f32_16x16x32_f16 v[52:55], v[152:155], v[176:179], v[52:55]
	v_mfma_f32_16x16x32_f16 v[48:51], v[160:163], v[176:179], v[48:51]
	v_mfma_f32_16x16x32_f16 v[44:47], v[152:155], v[184:187], v[44:47]
	v_mfma_f32_16x16x32_f16 v[40:43], v[160:163], v[184:187], v[40:43]
	v_mfma_f32_16x16x32_f16 v[36:39], v[152:155], v[192:195], v[36:39]
	v_mfma_f32_16x16x32_f16 v[32:35], v[160:163], v[192:195], v[32:35]
	v_mfma_f32_16x16x32_f16 v[64:67], v[156:159], v[172:175], v[64:67]
	v_mfma_f32_16x16x32_f16 v[56:59], v[164:167], v[172:175], v[56:59]
	v_mfma_f32_16x16x32_f16 v[52:55], v[156:159], v[180:183], v[52:55]
	v_mfma_f32_16x16x32_f16 v[48:51], v[164:167], v[180:183], v[48:51]
	v_mfma_f32_16x16x32_f16 v[44:47], v[156:159], v[188:191], v[44:47]
	v_mfma_f32_16x16x32_f16 v[40:43], v[164:167], v[188:191], v[40:43]
	v_mfma_f32_16x16x32_f16 v[36:39], v[156:159], v[196:199], v[36:39]
	v_mfma_f32_16x16x32_f16 v[32:35], v[164:167], v[196:199], v[32:35]
	s_barrier
	ds_read_b128 v[168:171], v147 offset:49152
	ds_read_b128 v[172:175], v147 offset:50176
	ds_read_b128 v[176:179], v147 offset:51200
	ds_read_b128 v[180:183], v147 offset:52224
	ds_read_b128 v[184:187], v147 offset:53248
	ds_read_b128 v[188:191], v147 offset:54272
	ds_read_b128 v[192:195], v147 offset:55296
	ds_read_b128 v[196:199], v147 offset:56320
	s_add_u32 s4, s44, 0x80
	s_addc_u32 s5, s45, 0
	s_mov_b32 s6, m0
	s_mov_b32 m0, s64
	s_nop 0
	global_load_lds_dwordx4 v143, s[4:5]
	s_mov_b32 m0, s6
	s_nop 0
	s_mov_b32 s6, m0
	s_mov_b32 m0, s68
	s_nop 0
	global_load_lds_dwordx4 v145, s[4:5]
	s_mov_b32 m0, s6
	s_add_u32 s4, s44, 0x80080
	s_addc_u32 s5, s45, 0
	s_mov_b32 s6, m0
	s_mov_b32 m0, s73
	s_nop 0
	global_load_lds_dwordx4 v143, s[4:5]
	s_mov_b32 m0, s6
	s_nop 0
	s_mov_b32 s6, m0
	s_mov_b32 m0, s74
	s_nop 0
	global_load_lds_dwordx4 v145, s[4:5]
	s_mov_b32 m0, s6
	s_mov_b32 s4, m0
	s_mov_b32 m0, s69
	s_nop 0
	global_load_lds_dwordx4 v142, s[42:43]
	s_mov_b32 m0, s4
	s_nop 0
	s_mov_b32 s4, m0
	s_mov_b32 m0, s72
	s_nop 0
	global_load_lds_dwordx4 v144, s[42:43]
	s_mov_b32 m0, s4
	s_waitcnt vmcnt(8)
	s_waitcnt lgkmcnt(0)
	s_barrier
	s_waitcnt lgkmcnt(7)
	v_mfma_f32_16x16x32_f16 v[92:95], v[128:131], v[168:171], v[92:95]
	v_mfma_f32_16x16x32_f16 v[88:91], v[136:139], v[168:171], v[88:91]
	s_waitcnt lgkmcnt(5)
	v_mfma_f32_16x16x32_f16 v[84:87], v[128:131], v[176:179], v[84:87]
	v_mfma_f32_16x16x32_f16 v[80:83], v[136:139], v[176:179], v[80:83]
	s_waitcnt lgkmcnt(3)
	v_mfma_f32_16x16x32_f16 v[76:79], v[128:131], v[184:187], v[76:79]
	v_mfma_f32_16x16x32_f16 v[72:75], v[136:139], v[184:187], v[72:75]
	s_waitcnt lgkmcnt(1)
	v_mfma_f32_16x16x32_f16 v[68:71], v[128:131], v[192:195], v[68:71]
	v_mfma_f32_16x16x32_f16 v[60:63], v[136:139], v[192:195], v[60:63]
	v_mfma_f32_16x16x32_f16 v[92:95], v[132:135], v[172:175], v[92:95]
	v_mfma_f32_16x16x32_f16 v[88:91], v[148:151], v[172:175], v[88:91]
	v_mfma_f32_16x16x32_f16 v[84:87], v[132:135], v[180:183], v[84:87]
	v_mfma_f32_16x16x32_f16 v[80:83], v[148:151], v[180:183], v[80:83]
	v_mfma_f32_16x16x32_f16 v[76:79], v[132:135], v[188:191], v[76:79]
	v_mfma_f32_16x16x32_f16 v[72:75], v[148:151], v[188:191], v[72:75]
	s_waitcnt lgkmcnt(0)
	v_mfma_f32_16x16x32_f16 v[68:71], v[132:135], v[196:199], v[68:71]
	v_mfma_f32_16x16x32_f16 v[60:63], v[148:151], v[196:199], v[60:63]
	v_mfma_f32_16x16x32_f16 v[28:31], v[152:155], v[168:171], v[28:31]
	v_mfma_f32_16x16x32_f16 v[24:27], v[160:163], v[168:171], v[24:27]
	v_mfma_f32_16x16x32_f16 v[20:23], v[152:155], v[176:179], v[20:23]
	v_mfma_f32_16x16x32_f16 v[16:19], v[160:163], v[176:179], v[16:19]
	v_mfma_f32_16x16x32_f16 v[12:15], v[152:155], v[184:187], v[12:15]
	v_mfma_f32_16x16x32_f16 v[8:11], v[160:163], v[184:187], v[8:11]
	v_mfma_f32_16x16x32_f16 v[4:7], v[152:155], v[192:195], v[4:7]
	v_mfma_f32_16x16x32_f16 v[0:3], v[160:163], v[192:195], v[0:3]
	v_mfma_f32_16x16x32_f16 v[28:31], v[156:159], v[172:175], v[28:31]
	v_mfma_f32_16x16x32_f16 v[24:27], v[164:167], v[172:175], v[24:27]
	v_mfma_f32_16x16x32_f16 v[20:23], v[156:159], v[180:183], v[20:23]
	v_mfma_f32_16x16x32_f16 v[16:19], v[164:167], v[180:183], v[16:19]
	v_mfma_f32_16x16x32_f16 v[12:15], v[156:159], v[188:191], v[12:15]
	v_mfma_f32_16x16x32_f16 v[8:11], v[164:167], v[188:191], v[8:11]
	v_mfma_f32_16x16x32_f16 v[4:7], v[156:159], v[196:199], v[4:7]
	v_mfma_f32_16x16x32_f16 v[0:3], v[164:167], v[196:199], v[0:3]
	s_barrier
	s_add_i32 s1, s1, 2
	s_add_u32 s85, s85, 0x100
	s_addc_u32 s86, s86, 0
	s_add_u32 s87, s87, 0x100
	s_addc_u32 s0, s0, 0
	s_add_u32 s40, s40, 0x100
	s_addc_u32 s41, s41, 0
	s_cmp_gt_u32 s1, 29
; #define PG8_STAGE(bufoff, gbase, voff) do { _Pragma("unroll") for (int _i = 0; _i < 2; ++_i) glds16_s((gbase), (voff)[_i], ldsb + (unsigned)((bufoff) + _i * 8192)); } while (0)
; #define PG8_LDA(dst, b, h) do { _Pragma("unroll") for (int m = 0; m < 4; ++m) _Pragma("unroll") for (int k = 0; k < 2; ++k) dst[m][k] = *(const LAS h16x8*)(lds + PG8_SA(b, h) + aoff + m * 2048 + k * 1024); } while (0)
; #define PG8_LDB(dst, b, h) do { _Pragma("unroll") for (int n = 0; n < 2; ++n) _Pragma("unroll") for (int k = 0; k < 2; ++k) dst[n][k] = *(const LAS h16x8*)(lds + PG8_SB(b, h) + boff + n * 2048 + k * 1024); } while (0)
; #define PG8_MMA(ai, bj, At, Bt) do { __builtin_amdgcn_s_setprio(1); _Pragma("unroll") for (int m = 0; m < 4; ++m) _Pragma("unroll") for (int n = 0; n < 2; ++n) _Pragma("unroll") for (int k = 0; k < 2; ++k) \
;         acc[ai][bj][m][n] = mma_step<I8>(Bt[n][k], At[m][k], acc[ai][bj][m][n]); __builtin_amdgcn_s_setprio(0); } while (0)
; #define PG8_WAIT_V(n) asm volatile("s_waitcnt vmcnt(" #n ")" ::: "memory")
; #define PG8_WAIT_L(n) asm volatile("s_waitcnt lgkmcnt(" #n ")" ::: "memory")
; #define PG8_BAR __builtin_amdgcn_s_barrier()
; #define PG8_SCHED __builtin_amdgcn_sched_barrier(0)
; template <class Prob, class Epi, bool I8 = false, bool ALIGN_EPI = true, bool SP2 = true>
; __device__ __forceinline__ void gemm_phase(LAS unsigned char* lds, int wave, const Prob& P, const Epi& E) {
;     ...
;         for (int t = 0; t < nt; t += 2) {
;             const bool last = (t == nt - 2);
;             const char* a1 = cA + (size_t)(t + 1) * kstep;
;             const char* a2 = last ? nA : cA + (size_t)(t + 2) * kstep; const char* b2 = last ? nB : cB + (size_t)(t + 2) * kstep;
;             const char* a3 = a2 + kstep; const char* b3 = b2 + kstep;
;             if constexpr (SP2) {
;             PG8_LDB(B0, 0, 0); PG8_LDB(B1, 0, 1); PG8_SCHED; PG8_LDA(At, 0, 0); PG8_STAGE(PG8_SA(1, 1), a1 + hstepA, voffA);
;             PG8_WAIT_V(8); PG8_WAIT_L(0); PG8_BAR; PG8_MMA(0, 0, At, B0); PG8_MMA(0, 1, At, B1); PG8_BAR; PG8_SCHED;
;             PG8_LDA(At, 0, 1); PG8_STAGE(PG8_SB(0, 0), b2, voffB); PG8_STAGE(PG8_SB(0, 1), b2 + hstepB, voffB); PG8_STAGE(PG8_SA(0, 0), a2, voffA);
;             PG8_WAIT_V(8); PG8_WAIT_L(0); PG8_BAR; PG8_MMA(1, 0, At, B0); PG8_MMA(1, 1, At, B1); PG8_BAR; PG8_SCHED;
.LBB0_863:
	v_add_u32_e32 v140, 0x10000, v146
	ds_read_b128 v[128:131], v140
	ds_read_b128 v[132:135], v140 offset:1024
	ds_read_b128 v[136:139], v140 offset:2048
	ds_read_b128 v[148:151], v140 offset:3072
	v_add_u32_e32 v140, 0x14000, v146
	ds_read_b128 v[152:155], v140
	ds_read_b128 v[156:159], v140 offset:1024
	ds_read_b128 v[160:163], v140 offset:2048
	ds_read_b128 v[164:167], v140 offset:3072
	s_cmp_eq_u32 s1, 28
	s_cselect_b32 s46, s83, s85
	s_cselect_b32 s47, s27, s86
	s_cselect_b32 s44, s84, s87
	s_cselect_b32 s45, s23, s0
	s_add_u32 s42, s46, 0x80
	s_addc_u32 s43, s47, 0
	ds_read_b128 v[168:171], v147
	ds_read_b128 v[172:175], v147 offset:1024
	ds_read_b128 v[176:179], v147 offset:2048
	ds_read_b128 v[180:183], v147 offset:3072
	ds_read_b128 v[184:187], v147 offset:4096
	ds_read_b128 v[188:191], v147 offset:5120
	ds_read_b128 v[192:195], v147 offset:6144
	ds_read_b128 v[196:199], v147 offset:7168
	s_mov_b32 s4, m0
	s_mov_b32 m0, s75
	s_nop 0
	global_load_lds_dwordx4 v142, s[40:41]
	s_mov_b32 m0, s4
	s_nop 0
	s_mov_b32 s4, m0
	s_mov_b32 m0, s79
	s_nop 0
	global_load_lds_dwordx4 v144, s[40:41]
	s_mov_b32 m0, s4
	s_waitcnt vmcnt(8)
	s_waitcnt lgkmcnt(0)
	s_barrier
	s_waitcnt lgkmcnt(7)
	v_mfma_f32_16x16x32_f16 v[124:127], v[128:131], v[168:171], v[124:127]
	v_mfma_f32_16x16x32_f16 v[120:123], v[136:139], v[168:171], v[120:123]
	s_waitcnt lgkmcnt(5)
	v_mfma_f32_16x16x32_f16 v[116:119], v[128:131], v[176:179], v[116:119]
	v_mfma_f32_16x16x32_f16 v[112:115], v[136:139], v[176:179], v[112:115]
	s_waitcnt lgkmcnt(3)
	v_mfma_f32_16x16x32_f16 v[108:111], v[128:131], v[184:187], v[108:111]
	v_mfma_f32_16x16x32_f16 v[104:107], v[136:139], v[184:187], v[104:107]
	s_waitcnt lgkmcnt(1)
	v_mfma_f32_16x16x32_f16 v[100:103], v[128:131], v[192:195], v[100:103]
	v_mfma_f32_16x16x32_f16 v[96:99], v[136:139], v[192:195], v[96:99]
	v_mfma_f32_16x16x32_f16 v[124:127], v[132:135], v[172:175], v[124:127]
	v_mfma_f32_16x16x32_f16 v[120:123], v[148:151], v[172:175], v[120:123]
	v_mfma_f32_16x16x32_f16 v[116:119], v[132:135], v[180:183], v[116:119]
	v_mfma_f32_16x16x32_f16 v[112:115], v[148:151], v[180:183], v[112:115]
	v_mfma_f32_16x16x32_f16 v[108:111], v[132:135], v[188:191], v[108:111]
	v_mfma_f32_16x16x32_f16 v[104:107], v[148:151], v[188:191], v[104:107]
	s_waitcnt lgkmcnt(0)
	v_mfma_f32_16x16x32_f16 v[100:103], v[132:135], v[196:199], v[100:103]
	v_mfma_f32_16x16x32_f16 v[96:99], v[148:151], v[196:199], v[96:99]
	v_mfma_f32_16x16x32_f16 v[64:67], v[152:155], v[168:171], v[64:67]
	v_mfma_f32_16x16x32_f16 v[56:59], v[160:163], v[168:171], v[56:59]
	v_mfma_f32_16x16x32_f16 v[52:55], v[152:155], v[176:179], v[52:55]
	v_mfma_f32_16x16x32_f16 v[48:51], v[160:163], v[176:179], v[48:51]
	v_mfma_f32_16x16x32_f16 v[44:47], v[152:155], v[184:187], v[44:47]
	v_mfma_f32_16x16x32_f16 v[40:43], v[160:163], v[184:187], v[40:43]
	v_mfma_f32_16x16x32_f16 v[36:39], v[152:155], v[192:195], v[36:39]
	v_mfma_f32_16x16x32_f16 v[32:35], v[160:163], v[192:195], v[32:35]
	v_mfma_f32_16x16x32_f16 v[64:67], v[156:159], v[172:175], v[64:67]
	v_mfma_f32_16x16x32_f16 v[56:59], v[164:167], v[172:175], v[56:59]
	v_mfma_f32_16x16x32_f16 v[52:55], v[156:159], v[180:183], v[52:55]
	v_mfma_f32_16x16x32_f16 v[48:51], v[164:167], v[180:183], v[48:51]
	v_mfma_f32_16x16x32_f16 v[44:47], v[156:159], v[188:191], v[44:47]
	v_mfma_f32_16x16x32_f16 v[40:43], v[164:167], v[188:191], v[40:43]
	v_mfma_f32_16x16x32_f16 v[36:39], v[156:159], v[196:199], v[36:39]
	v_mfma_f32_16x16x32_f16 v[32:35], v[164:167], v[196:199], v[32:35]
	s_barrier
	ds_read_b128 v[168:171], v147 offset:16384
	ds_read_b128 v[172:175], v147 offset:17408
	ds_read_b128 v[176:179], v147 offset:18432
	ds_read_b128 v[180:183], v147 offset:19456
	ds_read_b128 v[184:187], v147 offset:20480
	ds_read_b128 v[188:191], v147 offset:21504
	ds_read_b128 v[192:195], v147 offset:22528
	ds_read_b128 v[196:199], v147 offset:23552
	s_mov_b32 s4, m0
	s_mov_b32 m0, s49
	s_nop 0
	global_load_lds_dwordx4 v143, s[44:45]
	s_mov_b32 m0, s4
	s_nop 0
	s_mov_b32 s4, m0
	s_mov_b32 m0, s50
	s_nop 0
	global_load_lds_dwordx4 v145, s[44:45]
	s_mov_b32 m0, s4
	s_add_u32 s4, s44, 0x80000
	s_addc_u32 s5, s45, 0
	s_mov_b32 s6, m0
	s_mov_b32 m0, s51
	s_nop 0
	global_load_lds_dwordx4 v143, s[4:5]
	s_mov_b32 m0, s6
	s_nop 0
	s_mov_b32 s6, m0
	s_mov_b32 m0, s56
	s_nop 0
	global_load_lds_dwordx4 v145, s[4:5]
	s_mov_b32 m0, s6
	s_mov_b32 s4, m0
	s_mov_b32 m0, s48
	s_nop 0
	global_load_lds_dwordx4 v142, s[46:47]
	s_mov_b32 m0, s4
	s_nop 0
	s_mov_b32 s4, m0
	s_mov_b32 m0, s57
	s_nop 0
	global_load_lds_dwordx4 v144, s[46:47]
	s_mov_b32 m0, s4
	s_waitcnt vmcnt(8)
	s_waitcnt lgkmcnt(0)
	s_barrier
; #define PG8_STAGE(bufoff, gbase, voff) do { _Pragma("unroll") for (int _i = 0; _i < 2; ++_i) glds16_s((gbase), (voff)[_i], ldsb + (unsigned)((bufoff) + _i * 8192)); } while (0)
; #define PG8_LDA(dst, b, h) do { _Pragma("unroll") for (int m = 0; m < 4; ++m) _Pragma("unroll") for (int k = 0; k < 2; ++k) dst[m][k] = *(const LAS h16x8*)(lds + PG8_SA(b, h) + aoff + m * 2048 + k * 1024); } while (0)
; #define PG8_LDB(dst, b, h) do { _Pragma("unroll") for (int n = 0; n < 2; ++n) _Pragma("unroll") for (int k = 0; k < 2; ++k) dst[n][k] = *(const LAS h16x8*)(lds + PG8_SB(b, h) + boff + n * 2048 + k * 1024); } while (0)
; #define PG8_MMA(ai, bj, At, Bt) do { __builtin_amdgcn_s_setprio(1); _Pragma("unroll") for (int m = 0; m < 4; ++m) _Pragma("unroll") for (int n = 0; n < 2; ++n) _Pragma("unroll") for (int k = 0; k < 2; ++k) \
;         acc[ai][bj][m][n] = mma_step<I8>(Bt[n][k], At[m][k], acc[ai][bj][m][n]); __builtin_amdgcn_s_setprio(0); } while (0)
; #define PG8_WAIT_V(n) asm volatile("s_waitcnt vmcnt(" #n ")" ::: "memory")
; #define PG8_WAIT_L(n) asm volatile("s_waitcnt lgkmcnt(" #n ")" ::: "memory")
; #define PG8_BAR __builtin_amdgcn_s_barrier()
; #define PG8_SCHED __builtin_amdgcn_sched_barrier(0)
; template <class Prob, class Epi, bool I8 = false, bool ALIGN_EPI = true, bool SP2 = true>
; __device__ __forceinline__ void gemm_phase(LAS unsigned char* lds, int wave, const Prob& P, const Epi& E) {
;     ...
;             PG8_WAIT_V(8); PG8_WAIT_L(0); PG8_BAR; PG8_MMA(1, 0, At, B0); PG8_MMA(1, 1, At, B1); PG8_BAR; PG8_SCHED;
;             PG8_LDB(B0, 1, 0); PG8_LDB(B1, 1, 1); PG8_SCHED; PG8_LDA(At, 1, 0); PG8_STAGE(PG8_SA(0, 1), a2 + hstepA, voffA);
;             PG8_WAIT_V(8); PG8_WAIT_L(0); PG8_BAR; PG8_MMA(0, 0, At, B0); PG8_MMA(0, 1, At, B1); PG8_BAR; PG8_SCHED;
;             PG8_LDA(At, 1, 1); PG8_STAGE(PG8_SB(1, 0), b3, voffB); PG8_STAGE(PG8_SB(1, 1), b3 + hstepB, voffB); PG8_STAGE(PG8_SA(1, 0), a3, voffA);
	s_waitcnt lgkmcnt(7)
	v_mfma_f32_16x16x32_f16 v[92:95], v[128:131], v[168:171], v[92:95]
	v_mfma_f32_16x16x32_f16 v[88:91], v[136:139], v[168:171], v[88:91]
	s_waitcnt lgkmcnt(5)
	v_mfma_f32_16x16x32_f16 v[84:87], v[128:131], v[176:179], v[84:87]
	v_mfma_f32_16x16x32_f16 v[80:83], v[136:139], v[176:179], v[80:83]
	s_waitcnt lgkmcnt(3)
	v_mfma_f32_16x16x32_f16 v[76:79], v[128:131], v[184:187], v[76:79]
	v_mfma_f32_16x16x32_f16 v[72:75], v[136:139], v[184:187], v[72:75]
	s_waitcnt lgkmcnt(1)
	v_mfma_f32_16x16x32_f16 v[68:71], v[128:131], v[192:195], v[68:71]
	v_mfma_f32_16x16x32_f16 v[60:63], v[136:139], v[192:195], v[60:63]
	v_mfma_f32_16x16x32_f16 v[92:95], v[132:135], v[172:175], v[92:95]
	v_mfma_f32_16x16x32_f16 v[88:91], v[148:151], v[172:175], v[88:91]
	v_mfma_f32_16x16x32_f16 v[84:87], v[132:135], v[180:183], v[84:87]
	v_mfma_f32_16x16x32_f16 v[80:83], v[148:151], v[180:183], v[80:83]
	v_mfma_f32_16x16x32_f16 v[76:79], v[132:135], v[188:191], v[76:79]
	v_mfma_f32_16x16x32_f16 v[72:75], v[148:151], v[188:191], v[72:75]
	s_waitcnt lgkmcnt(0)
	v_mfma_f32_16x16x32_f16 v[68:71], v[132:135], v[196:199], v[68:71]
	v_mfma_f32_16x16x32_f16 v[60:63], v[148:151], v[196:199], v[60:63]
	v_mfma_f32_16x16x32_f16 v[28:31], v[152:155], v[168:171], v[28:31]
	v_mfma_f32_16x16x32_f16 v[24:27], v[160:163], v[168:171], v[24:27]
	v_mfma_f32_16x16x32_f16 v[20:23], v[152:155], v[176:179], v[20:23]
	v_mfma_f32_16x16x32_f16 v[16:19], v[160:163], v[176:179], v[16:19]
	v_mfma_f32_16x16x32_f16 v[12:15], v[152:155], v[184:187], v[12:15]
	v_mfma_f32_16x16x32_f16 v[8:11], v[160:163], v[184:187], v[8:11]
	v_mfma_f32_16x16x32_f16 v[4:7], v[152:155], v[192:195], v[4:7]
	v_mfma_f32_16x16x32_f16 v[0:3], v[160:163], v[192:195], v[0:3]
	v_mfma_f32_16x16x32_f16 v[28:31], v[156:159], v[172:175], v[28:31]
	v_mfma_f32_16x16x32_f16 v[24:27], v[164:167], v[172:175], v[24:27]
	v_mfma_f32_16x16x32_f16 v[20:23], v[156:159], v[180:183], v[20:23]
	v_mfma_f32_16x16x32_f16 v[16:19], v[164:167], v[180:183], v[16:19]
	v_mfma_f32_16x16x32_f16 v[12:15], v[156:159], v[188:191], v[12:15]
	v_mfma_f32_16x16x32_f16 v[8:11], v[164:167], v[188:191], v[8:11]
	v_mfma_f32_16x16x32_f16 v[4:7], v[156:159], v[196:199], v[4:7]
	v_mfma_f32_16x16x32_f16 v[0:3], v[164:167], v[196:199], v[0:3]
	s_barrier
	v_add_u32_e32 v140, 0x18000, v146
	ds_read_b128 v[128:131], v140
	ds_read_b128 v[132:135], v140 offset:1024
	ds_read_b128 v[136:139], v140 offset:2048
	ds_read_b128 v[148:151], v140 offset:3072
	v_add_u32_e32 v140, 0x1c000, v146
	ds_read_b128 v[152:155], v140
	ds_read_b128 v[156:159], v140 offset:1024
	ds_read_b128 v[160:163], v140 offset:2048
	ds_read_b128 v[164:167], v140 offset:3072
	ds_read_b128 v[168:171], v147 offset:32768
	ds_read_b128 v[172:175], v147 offset:33792
	ds_read_b128 v[176:179], v147 offset:34816
	ds_read_b128 v[180:183], v147 offset:35840
	ds_read_b128 v[184:187], v147 offset:36864
	ds_read_b128 v[188:191], v147 offset:37888
	ds_read_b128 v[192:195], v147 offset:38912
	ds_read_b128 v[196:199], v147 offset:39936
	s_add_u32 s4, s46, 0x80000
	s_addc_u32 s5, s47, 0
	s_mov_b32 s6, m0
	s_mov_b32 m0, s60
	s_nop 0
	global_load_lds_dwordx4 v142, s[4:5]
	s_mov_b32 m0, s6
	s_nop 0
	s_mov_b32 s6, m0
	s_mov_b32 m0, s61
	s_nop 0
	global_load_lds_dwordx4 v144, s[4:5]
	s_mov_b32 m0, s6
	s_waitcnt vmcnt(8)
	s_waitcnt lgkmcnt(0)
	s_barrier
	s_waitcnt lgkmcnt(7)
	v_mfma_f32_16x16x32_f16 v[124:127], v[128:131], v[168:171], v[124:127]
	v_mfma_f32_16x16x32_f16 v[120:123], v[136:139], v[168:171], v[120:123]
	s_waitcnt lgkmcnt(5)
	v_mfma_f32_16x16x32_f16 v[116:119], v[128:131], v[176:179], v[116:119]
	v_mfma_f32_16x16x32_f16 v[112:115], v[136:139], v[176:179], v[112:115]
	s_waitcnt lgkmcnt(3)
	v_mfma_f32_16x16x32_f16 v[108:111], v[128:131], v[184:187], v[108:111]
	v_mfma_f32_16x16x32_f16 v[104:107], v[136:139], v[184:187], v[104:107]
	s_waitcnt lgkmcnt(1)
	v_mfma_f32_16x16x32_f16 v[100:103], v[128:131], v[192:195], v[100:103]
	v_mfma_f32_16x16x32_f16 v[96:99], v[136:139], v[192:195], v[96:99]
	v_mfma_f32_16x16x32_f16 v[124:127], v[132:135], v[172:175], v[124:127]
	v_mfma_f32_16x16x32_f16 v[120:123], v[148:151], v[172:175], v[120:123]
	v_mfma_f32_16x16x32_f16 v[116:119], v[132:135], v[180:183], v[116:119]
	v_mfma_f32_16x16x32_f16 v[112:115], v[148:151], v[180:183], v[112:115]
	v_mfma_f32_16x16x32_f16 v[108:111], v[132:135], v[188:191], v[108:111]
	v_mfma_f32_16x16x32_f16 v[104:107], v[148:151], v[188:191], v[104:107]
	s_waitcnt lgkmcnt(0)
	v_mfma_f32_16x16x32_f16 v[100:103], v[132:135], v[196:199], v[100:103]
	v_mfma_f32_16x16x32_f16 v[96:99], v[148:151], v[196:199], v[96:99]
	v_mfma_f32_16x16x32_f16 v[64:67], v[152:155], v[168:171], v[64:67]
	v_mfma_f32_16x16x32_f16 v[56:59], v[160:163], v[168:171], v[56:59]
	v_mfma_f32_16x16x32_f16 v[52:55], v[152:155], v[176:179], v[52:55]
	v_mfma_f32_16x16x32_f16 v[48:51], v[160:163], v[176:179], v[48:51]
	v_mfma_f32_16x16x32_f16 v[44:47], v[152:155], v[184:187], v[44:47]
	v_mfma_f32_16x16x32_f16 v[40:43], v[160:163], v[184:187], v[40:43]
	v_mfma_f32_16x16x32_f16 v[36:39], v[152:155], v[192:195], v[36:39]
	v_mfma_f32_16x16x32_f16 v[32:35], v[160:163], v[192:195], v[32:35]
	v_mfma_f32_16x16x32_f16 v[64:67], v[156:159], v[172:175], v[64:67]
	v_mfma_f32_16x16x32_f16 v[56:59], v[164:167], v[172:175], v[56:59]
	v_mfma_f32_16x16x32_f16 v[52:55], v[156:159], v[180:183], v[52:55]
	v_mfma_f32_16x16x32_f16 v[48:51], v[164:167], v[180:183], v[48:51]
	v_mfma_f32_16x16x32_f16 v[44:47], v[156:159], v[188:191], v[44:47]
	v_mfma_f32_16x16x32_f16 v[40:43], v[164:167], v[188:191], v[40:43]
	v_mfma_f32_16x16x32_f16 v[36:39], v[156:159], v[196:199], v[36:39]
	v_mfma_f32_16x16x32_f16 v[32:35], v[164:167], v[196:199], v[32:35]
	s_barrier
; #define PG8_STAGE(bufoff, gbase, voff) do { _Pragma("unroll") for (int _i = 0; _i < 2; ++_i) glds16_s((gbase), (voff)[_i], ldsb + (unsigned)((bufoff) + _i * 8192)); } while (0)
; #define PG8_LDA(dst, b, h) do { _Pragma("unroll") for (int m = 0; m < 4; ++m) _Pragma("unroll") for (int k = 0; k < 2; ++k) dst[m][k] = *(const LAS h16x8*)(lds + PG8_SA(b, h) + aoff + m * 2048 + k * 1024); } while (0)
; #define PG8_MMA(ai, bj, At, Bt) do { __builtin_amdgcn_s_setprio(1); _Pragma("unroll") for (int m = 0; m < 4; ++m) _Pragma("unroll") for (int n = 0; n < 2; ++n) _Pragma("unroll") for (int k = 0; k < 2; ++k) \
;         acc[ai][bj][m][n] = mma_step<I8>(Bt[n][k], At[m][k], acc[ai][bj][m][n]); __builtin_amdgcn_s_setprio(0); } while (0)
; #define PG8_WAIT_V(n) asm volatile("s_waitcnt vmcnt(" #n ")" ::: "memory")
; #define PG8_WAIT_L(n) asm volatile("s_waitcnt lgkmcnt(" #n ")" ::: "memory")
; #define PG8_BAR __builtin_amdgcn_s_barrier()
; #define PG8_SCHED __builtin_amdgcn_sched_barrier(0)
; template <class Prob, class Epi, bool I8 = false, bool ALIGN_EPI = true, bool SP2 = true>
; __device__ __forceinline__ void gemm_phase(LAS unsigned char* lds, int wave, const Prob& P, const Epi& E) {
;     ...
;             PG8_LDA(At, 1, 1); PG8_STAGE(PG8_SB(1, 0), b3, voffB); PG8_STAGE(PG8_SB(1, 1), b3 + hstepB, voffB); PG8_STAGE(PG8_SA(1, 0), a3, voffA);
;             PG8_WAIT_V(8); PG8_WAIT_L(0); PG8_BAR; PG8_MMA(1, 0, At, B0); PG8_MMA(1, 1, At, B1); PG8_BAR; PG8_SCHED;
;     __device__ __forceinline__ void operator()(Acc& acc, const Unit& u, int wr, int wc, int fr, int fq, LAS unsigned char* lds, int tid) const {
;     ...
;                 for (int m = 0; m < 4; ++m) { const unsigned row = u.pm * 256 + ai * 128 + wr * 64 + m * 16 + fr; xv[m] = *(const h16x8*)(X + (size_t)row * D + colt);
;                     if constexpr (LNX) st[m] = *(const f32x2*)((const char*)stats + (row << 3));
;                     if constexpr (I8) rs[m] = *(const float*)((const char*)sa + (row << 2)); }
	ds_read_b128 v[168:171], v147 offset:49152
	ds_read_b128 v[172:175], v147 offset:50176
	ds_read_b128 v[176:179], v147 offset:51200
	ds_read_b128 v[180:183], v147 offset:52224
	ds_read_b128 v[184:187], v147 offset:53248
	ds_read_b128 v[188:191], v147 offset:54272
	ds_read_b128 v[192:195], v147 offset:55296
	ds_read_b128 v[196:199], v147 offset:56320
	s_add_u32 s4, s44, 0x80
	s_addc_u32 s5, s45, 0
	s_mov_b32 s6, m0
	s_mov_b32 m0, s64
	s_nop 0
	global_load_lds_dwordx4 v143, s[4:5]
	s_mov_b32 m0, s6
	s_nop 0
	s_mov_b32 s6, m0
	s_mov_b32 m0, s68
	s_nop 0
	global_load_lds_dwordx4 v145, s[4:5]
	s_mov_b32 m0, s6
	s_add_u32 s4, s44, 0x80080
	s_addc_u32 s5, s45, 0
	s_mov_b32 s6, m0
	s_mov_b32 m0, s73
	s_nop 0
	global_load_lds_dwordx4 v143, s[4:5]
	s_mov_b32 m0, s6
	s_nop 0
	s_mov_b32 s6, m0
	s_mov_b32 m0, s74
	s_nop 0
	global_load_lds_dwordx4 v145, s[4:5]
	s_mov_b32 m0, s6
	s_mov_b32 s4, m0
	s_mov_b32 m0, s69
	s_nop 0
	global_load_lds_dwordx4 v142, s[42:43]
	s_mov_b32 m0, s4
	s_nop 0
	s_mov_b32 s4, m0
	s_mov_b32 m0, s72
	s_nop 0
	global_load_lds_dwordx4 v144, s[42:43]
	s_mov_b32 m0, s4
	s_waitcnt vmcnt(8)
	s_waitcnt lgkmcnt(0)
	s_barrier
	s_waitcnt lgkmcnt(7)
	v_mfma_f32_16x16x32_f16 v[92:95], v[128:131], v[168:171], v[92:95]
	v_mfma_f32_16x16x32_f16 v[88:91], v[136:139], v[168:171], v[88:91]
	s_waitcnt lgkmcnt(5)
	v_mfma_f32_16x16x32_f16 v[84:87], v[128:131], v[176:179], v[84:87]
	v_mfma_f32_16x16x32_f16 v[80:83], v[136:139], v[176:179], v[80:83]
	s_waitcnt lgkmcnt(3)
	v_mfma_f32_16x16x32_f16 v[76:79], v[128:131], v[184:187], v[76:79]
	v_mfma_f32_16x16x32_f16 v[72:75], v[136:139], v[184:187], v[72:75]
	s_waitcnt lgkmcnt(1)
	v_mfma_f32_16x16x32_f16 v[68:71], v[128:131], v[192:195], v[68:71]
	v_mfma_f32_16x16x32_f16 v[60:63], v[136:139], v[192:195], v[60:63]
	v_mfma_f32_16x16x32_f16 v[92:95], v[132:135], v[172:175], v[92:95]
	v_mfma_f32_16x16x32_f16 v[88:91], v[148:151], v[172:175], v[88:91]
	v_mfma_f32_16x16x32_f16 v[84:87], v[132:135], v[180:183], v[84:87]
	v_mfma_f32_16x16x32_f16 v[80:83], v[148:151], v[180:183], v[80:83]
	v_mfma_f32_16x16x32_f16 v[76:79], v[132:135], v[188:191], v[76:79]
	v_mfma_f32_16x16x32_f16 v[72:75], v[148:151], v[188:191], v[72:75]
	s_waitcnt lgkmcnt(0)
	v_mfma_f32_16x16x32_f16 v[68:71], v[132:135], v[196:199], v[68:71]
	v_mfma_f32_16x16x32_f16 v[60:63], v[148:151], v[196:199], v[60:63]
	v_mfma_f32_16x16x32_f16 v[28:31], v[152:155], v[168:171], v[28:31]
	v_mfma_f32_16x16x32_f16 v[24:27], v[160:163], v[168:171], v[24:27]
	v_mfma_f32_16x16x32_f16 v[20:23], v[152:155], v[176:179], v[20:23]
	v_mfma_f32_16x16x32_f16 v[16:19], v[160:163], v[176:179], v[16:19]
	v_mfma_f32_16x16x32_f16 v[12:15], v[152:155], v[184:187], v[12:15]
	v_mfma_f32_16x16x32_f16 v[8:11], v[160:163], v[184:187], v[8:11]
	v_mfma_f32_16x16x32_f16 v[4:7], v[152:155], v[192:195], v[4:7]
	v_mfma_f32_16x16x32_f16 v[0:3], v[160:163], v[192:195], v[0:3]
	v_mfma_f32_16x16x32_f16 v[28:31], v[156:159], v[172:175], v[28:31]
	v_mfma_f32_16x16x32_f16 v[24:27], v[164:167], v[172:175], v[24:27]
	v_mfma_f32_16x16x32_f16 v[20:23], v[156:159], v[180:183], v[20:23]
	v_mfma_f32_16x16x32_f16 v[16:19], v[164:167], v[180:183], v[16:19]
	v_mfma_f32_16x16x32_f16 v[12:15], v[156:159], v[188:191], v[12:15]
	v_mfma_f32_16x16x32_f16 v[8:11], v[164:167], v[188:191], v[8:11]
	v_mfma_f32_16x16x32_f16 v[4:7], v[156:159], v[196:199], v[4:7]
	v_mfma_f32_16x16x32_f16 v[0:3], v[164:167], v[196:199], v[0:3]
	s_barrier
	s_add_i32 s1, s1, 2
	s_add_u32 s85, s85, 0x100
	s_addc_u32 s86, s86, 0
	s_add_u32 s87, s87, 0x100
	s_addc_u32 s0, s0, 0
	s_add_u32 s40, s40, 0x100
	s_addc_u32 s41, s41, 0
	s_cmp_gt_u32 s1, 29
	s_cbranch_scc0 .LBB0_863
	v_mbcnt_lo_u32_b32 v128, -1, 0
	v_mbcnt_hi_u32_b32 v128, -1, v128
	s_lshl_b32 s0, s82, 8
	s_lshl_b32 s1, s81, 8
	v_lshrrev_b32_e32 v129, 1, v128
	s_add_i32 s1, s1, s62
	v_and_or_b32 v129, v129, 24, s0
	v_and_or_b32 v130, v128, 15, s1
	v_or_b32_e32 v129, s63, v129
	v_lshlrev_b32_e32 v130, 12, v130
	v_lshl_add_u32 v128, v129, 1, v130
	v_add_u32_e32 v129, 0x10000, v128
	v_add_u32_e32 v130, 0x20000, v128
	v_add_u32_e32 v131, 0x30000, v128
	v_add_u32_e32 v132, 0x80000, v128
	v_add_u32_e32 v133, 0x90000, v128
	v_add_u32_e32 v134, 0xa0000, v128
	v_add_u32_e32 v135, 0xb0000, v128
	global_load_dwordx4 v[148:151], v128, s[54:55]
	global_load_dwordx4 v[152:155], v129, s[54:55]
	global_load_dwordx4 v[156:159], v130, s[54:55]
	global_load_dwordx4 v[160:163], v131, s[54:55]
	global_load_dwordx4 v[164:167], v132, s[54:55]
	global_load_dwordx4 v[168:171], v133, s[54:55]
	global_load_dwordx4 v[172:175], v134, s[54:55]
	global_load_dwordx4 v[176:179], v135, s[54:55]
	global_load_dwordx4 v[180:183], v128, s[54:55] offset:256
	global_load_dwordx4 v[184:187], v129, s[54:55] offset:256
	global_load_dwordx4 v[188:191], v130, s[54:55] offset:256
	global_load_dwordx4 v[192:195], v131, s[54:55] offset:256
	global_load_dwordx4 v[196:199], v132, s[54:55] offset:256
	global_load_dwordx4 v[200:203], v133, s[54:55] offset:256
	global_load_dwordx4 v[204:207], v134, s[54:55] offset:256
	global_load_dwordx4 v[212:215], v135, s[54:55] offset:256
	s_and_b64 vcc, exec, s[16:17]
	s_cbranch_vccz .LBB0_866
	s_barrier

; __device__ __forceinline__ int mk_lane() { int l; asm volatile("v_mbcnt_lo_u32_b32 %0, -1, 0\n\tv_mbcnt_hi_u32_b32 %0, -1, %0" : "=v"(l)); return l; }
; #define PG8_STAGE(bufoff, gbase, voff) do { _Pragma("unroll") for (int _i = 0; _i < 2; ++_i) glds16_s((gbase), (voff)[_i], ldsb + (unsigned)((bufoff) + _i * 8192)); } while (0)
; #define PG8_BAR __builtin_amdgcn_s_barrier()
; template <class Prob, class Epi, bool I8 = false, bool ALIGN_EPI = true, bool SP2 = true>
; __device__ __forceinline__ void gemm_phase(LAS unsigned char* lds, int wave, const Prob& P, const Epi& E) {
;     const int tid_ = wave * 64 + mk_lane();
;     const int tid = tid_, wid = __builtin_amdgcn_readfirstlane(tid >> 6), lane = tid & 63, wr = wid >> 2, wc = wid & 3, fr = lane & 15, fq = lane >> 4;
;     const int K = P.K, nt = K / BK;
;     unsigned voffA[2], voffB[2];
; #pragma unroll
;     for (int i = 0; i < 2; ++i) { int R, C; stage_rc(tid * 16 + i * 8192, R, C); const int Rb = (R & ~31) + perm32(R & 31);
;         voffA[i] = P.a_rowoff(R) + (unsigned)C * 2u; voffB[i] = P.b_rowoff(Rb) + (unsigned)C * 2u; }
;     const size_t kstep = (size_t)(BK * 2);
;     const size_t hstepA = P.a_hstep(), hstepB = P.b_hstep();
;     const unsigned ldsw = (unsigned)wid * 1024u;
;     const unsigned ldsb = (unsigned)(size_t)lds + ldsw;
;     const int aoff = lds_byte(wr * 64 + fr, fq * 8), boff = lds_byte(wc * 32 + fr, fq * 8);
;     ...
;     Unit cur, nxt; int ui = 0;
;     if (!P.next(0, cur)) return;
;     Acc acc;
; #pragma unroll
;     for (int a = 0; a < 2; ++a)
; #pragma unroll
;         for (int b = 0; b < 2; ++b)
; #pragma unroll
;             for (int m = 0; m < 4; ++m)
; #pragma unroll
;                 for (int n = 0; n < 2; ++n) acc[a][b][m][n] = (f32x4){0.f, 0.f, 0.f, 0.f};
;     h16x8 At[4][2], B0[2][2], B1[2][2];
;     const char* cA = P.a_tile(cur); const char* cB = P.b_tile(cur);
;     if constexpr (SP2) {
;         PG8_STAGE(PG8_SB(0, 0), cB, voffB); PG8_STAGE(PG8_SB(0, 1), cB + hstepB, voffB); PG8_STAGE(PG8_SA(0, 0), cA, voffA); PG8_STAGE(PG8_SA(0, 1), cA + hstepA, voffA);
;         if (wr == 1) PG8_BAR;
;     __device__ unsigned a_rowoff(int R) const { return (unsigned)(64 * R + 65 * (R & 1)) * (unsigned)lda * 2u; }
;     __device__ unsigned b_rowoff(int R) const { return (unsigned)R * (unsigned)ldb * 2u; }
;     __device__ size_t a_hstep() const { return (size_t)64 * 128 * lda * 2; }
.LBB0_986:
	s_add_u32 s26, s30, 0x240000
	v_readlane_b32 s0, v255, 1
	s_addc_u32 s27, s31, 0
	s_mul_i32 s0, s0, 0x1600000
	s_add_u32 s0, s30, s0
	s_addc_u32 s1, s31, 0
	s_add_u32 s79, s0, 0x57200000
	s_addc_u32 s40, s1, 0
	s_add_u32 s41, s30, 0x51200000
	s_addc_u32 s19, s31, 0
	v_readlane_b32 s0, v254, 42
	v_readlane_b32 s4, v252, 13
	s_waitcnt lgkmcnt(0)
	s_barrier
	s_add_u32 s38, s30, 0x2000000
	v_mbcnt_lo_u32_b32 v0, -1, 0
	v_mbcnt_hi_u32_b32 v0, -1, v0
	v_readlane_b32 s5, v252, 14
	v_add_u32_e32 v1, s0, v0
	s_addc_u32 s39, s31, 0
	v_readfirstlane_b32 s0, v1
	s_and_b64 vcc, exec, s[4:5]
	s_cbranch_vccz .LBB0_1002
	v_ashrrev_i32_e32 v3, 31, v1
	v_lshrrev_b32_e32 v3, 26, v3
	v_lshlrev_b32_e32 v2, 4, v1
	v_add_u32_e32 v3, v1, v3
	v_bfe_i32 v1, v1, 27, 1
	v_lshrrev_b32_e32 v1, 22, v1
	v_add_u32_e32 v1, v2, v1
	v_and_b32_e32 v1, 0xfffffc00, v1
	v_sub_u32_e32 v1, v2, v1
	v_lshrrev_b32_e32 v4, 4, v1
	v_bitop3_b32 v1, v4, v1, 32 bitop3:0x6c
	v_ashrrev_i32_e32 v5, 31, v1
	v_ashrrev_i32_e32 v3, 6, v3
	v_lshrrev_b32_e32 v5, 26, v5
	v_lshlrev_b32_e32 v4, 3, v3
	v_add_u32_e32 v5, v1, v5
	v_and_b32_e32 v4, -16, v4
	v_ashrrev_i32_e32 v6, 6, v5
	v_add_u32_e32 v4, v6, v4
	v_and_b32_e32 v5, 0xc0, v5
	v_sub_u32_e32 v1, v1, v5
	v_mov_b32_e32 v9, 1
	v_lshlrev_b32_e32 v5, 1, v4
	v_lshrrev_b32_e32 v7, 2, v4
	v_and_b32_e32 v8, 3, v6
	s_mov_b32 s2, 0x1fffe0
	v_lshlrev_b32_e32 v3, 5, v3
	v_ashrrev_i16_sdwa v1, v9, sext(v1) dst_sel:DWORD dst_unused:UNUSED_PAD src0_sel:DWORD src1_sel:BYTE_0
	v_and_b32_e32 v5, 24, v5
	v_and_b32_e32 v7, 4, v7
	v_and_or_b32 v8, v4, s2, v8
	v_and_b32_e32 v6, 1, v6
	v_and_b32_e32 v3, 32, v3
	v_bfe_i32 v1, v1, 0, 16
	v_or3_b32 v5, v8, v7, v5
	v_cmp_eq_u32_e32 vcc, 1, v6
	v_mov_b32_e32 v8, 0x20800
	v_lshlrev_b32_e32 v4, 17, v4
	v_cndmask_b32_e32 v6, 0, v8, vcc
	v_add_lshl_u32 v1, v3, v1, 1
	v_add3_u32 v129, v4, v6, v1
	v_lshl_add_u32 v130, v5, 11, v1
	v_add_u32_e32 v1, 0x2000, v2
	v_ashrrev_i32_e32 v2, 31, v1
	v_lshrrev_b32_e32 v2, 22, v2
	v_add_u32_e32 v2, v1, v2
	v_ashrrev_i32_e32 v2, 10, v2
	v_mul_i32_i24_e32 v3, 0x400, v2
	v_sub_u32_e32 v1, v1, v3
	v_readlane_b32 s4, v252, 21
	v_lshrrev_b32_e32 v3, 4, v1
	v_readlane_b32 s5, v252, 22
	s_add_u32 s44, s79, s4
	v_bitop3_b32 v1, v3, v1, 32 bitop3:0x6c
	s_addc_u32 s45, s40, s5
	v_readlane_b32 s4, v252, 17
	v_ashrrev_i32_e32 v4, 31, v1
	v_readlane_b32 s5, v252, 18
	s_add_u32 s4, s41, s4
	v_lshrrev_b32_e32 v4, 26, v4
	s_addc_u32 s5, s19, s5
	v_lshlrev_b32_e32 v3, 3, v2
	v_add_u32_e32 v4, v1, v4
	s_add_u32 s50, s4, 0xfffff800
	v_and_b32_e32 v3, -16, v3
	v_ashrrev_i32_e32 v5, 6, v4
	s_addc_u32 s51, s5, -1
	v_add_u32_e32 v3, v5, v3
	v_and_b32_e32 v7, 3, v5
	s_ashr_i32 s16, s0, 6
	v_and_or_b32 v7, v3, s2, v7
	s_lshl_b32 s2, s16, 10
	s_ashr_i32 s1, s0, 8
	v_and_b32_e32 v4, 0xc0, v4
	s_add_i32 s2, s2, 0
	v_sub_u32_e32 v1, v1, v4
	s_add_u32 s14, s4, 0xfff800
	v_lshlrev_b32_e32 v2, 5, v2
	v_ashrrev_i16_sdwa v1, v9, sext(v1) dst_sel:DWORD dst_unused:UNUSED_PAD src0_sel:DWORD src1_sel:BYTE_0
	v_lshlrev_b32_e32 v4, 1, v3
	v_lshrrev_b32_e32 v6, 2, v3
	s_addc_u32 s15, s5, 0
	v_and_b32_e32 v2, 32, v2
	v_bfe_i32 v1, v1, 0, 16
	v_and_b32_e32 v4, 24, v4
	v_and_b32_e32 v6, 4, v6
	s_add_u32 s22, s44, 0x40000
	v_or3_b32 v4, v7, v6, v4
	v_add_lshl_u32 v1, v2, v1, 1
	s_addc_u32 s23, s45, 0
	s_add_i32 s62, s2, 0x10000
	s_mov_b32 s6, m0
	s_mov_b32 m0, s62
	s_nop 0
	global_load_lds_dwordx4 v130, s[44:45]
	s_mov_b32 m0, s6
	v_lshl_add_u32 v132, v4, 11, v1
	s_add_i32 s63, s2, 0x12000
	s_mov_b32 s6, m0
	s_mov_b32 m0, s63
	s_nop 0
	global_load_lds_dwordx4 v132, s[44:45]
	s_mov_b32 m0, s6
	v_and_b32_e32 v5, 1, v5
	s_add_i32 s64, s2, 0x14000
	s_mov_b32 s6, m0
	s_mov_b32 m0, s64
	s_nop 0
	global_load_lds_dwordx4 v130, s[22:23]
	s_mov_b32 m0, s6
	v_cmp_eq_u32_e32 vcc, 1, v5
	s_add_i32 s68, s2, 0x16000
	s_mov_b32 s6, m0
	s_mov_b32 m0, s68
	s_nop 0
	global_load_lds_dwordx4 v132, s[22:23]
	s_mov_b32 m0, s6
	v_lshlrev_b32_e32 v3, 17, v3
	v_cndmask_b32_e32 v5, 0, v8, vcc
	s_mov_b32 s6, m0
	s_mov_b32 m0, s2
	s_nop 0
	global_load_lds_dwordx4 v129, s[50:51]
	s_mov_b32 m0, s6
	v_add3_u32 v131, v3, v5, v1
	s_add_i32 s69, s2, 0x2000
	s_mov_b32 s6, m0
	s_mov_b32 m0, s69
	s_nop 0
	global_load_lds_dwordx4 v131, s[50:51]
	s_mov_b32 m0, s6
	s_add_i32 s72, s2, 0x4000
	s_mov_b32 s6, m0
	s_mov_b32 m0, s72
	s_nop 0
	global_load_lds_dwordx4 v129, s[14:15]
	s_mov_b32 m0, s6
	s_add_i32 s73, s2, 0x6000
	s_mov_b32 s6, m0
	s_mov_b32 m0, s73
	s_nop 0
	global_load_lds_dwordx4 v131, s[14:15]
	s_mov_b32 m0, s6
	s_cmp_eq_u32 s1, 1
	s_cselect_b64 s[14:15], -1, 0
	s_cmp_lg_u32 s1, 1
	s_cbranch_scc1 .LBB0_989
	s_barrier
	s_setprio 1

; #define PG8_STAGE(bufoff, gbase, voff) do { _Pragma("unroll") for (int _i = 0; _i < 2; ++_i) glds16_s((gbase), (voff)[_i], ldsb + (unsigned)((bufoff) + _i * 8192)); } while (0)
; #define PG8_LDA(dst, b, h) do { _Pragma("unroll") for (int m = 0; m < 4; ++m) _Pragma("unroll") for (int k = 0; k < 2; ++k) dst[m][k] = *(const LAS h16x8*)(lds + PG8_SA(b, h) + aoff + m * 2048 + k * 1024); } while (0)
; #define PG8_WAIT_V(n) asm volatile("s_waitcnt vmcnt(" #n ")" ::: "memory")
; #define PG8_WAIT_L(n) asm volatile("s_waitcnt lgkmcnt(" #n ")" ::: "memory")
; #define PG8_BAR __builtin_amdgcn_s_barrier()
; template <class Prob, class Epi, bool I8 = false, bool ALIGN_EPI = true, bool SP2 = true>
; __device__ __forceinline__ void gemm_phase(LAS unsigned char* lds, int wave, const Prob& P, const Epi& E) {
;     ...
;         const bool has_next = P.next(ui + 1, nxt);
;         const char* nA = has_next ? P.a_tile(nxt) : cA; const char* nB = has_next ? P.b_tile(nxt) : cB;
;         for (int t = 0; t < nt; t += 2) {
;             const bool last = (t == nt - 2);
;             const char* a1 = cA + (size_t)(t + 1) * kstep;
;             const char* a2 = last ? nA : cA + (size_t)(t + 2) * kstep; const char* b2 = last ? nB : cB + (size_t)(t + 2) * kstep;
;             const char* a3 = a2 + kstep; const char* b3 = b2 + kstep;
;             if constexpr (SP2) {
;             PG8_LDB(B0, 0, 0); PG8_LDB(B1, 0, 1); PG8_SCHED; PG8_LDA(At, 0, 0); PG8_STAGE(PG8_SA(1, 1), a1 + hstepA, voffA);
;             PG8_WAIT_V(8); PG8_WAIT_L(0); PG8_BAR; PG8_MMA(0, 0, At, B0); PG8_MMA(0, 1, At, B1); PG8_BAR; PG8_SCHED;
;             PG8_LDA(At, 0, 1); PG8_STAGE(PG8_SB(0, 0), b2, voffB); PG8_STAGE(PG8_SB(0, 1), b2 + hstepB, voffB); PG8_STAGE(PG8_SA(0, 0), a2, voffA);
;             PG8_WAIT_V(8); PG8_WAIT_L(0); PG8_BAR; PG8_MMA(1, 0, At, B0); PG8_MMA(1, 1, At, B1); PG8_BAR; PG8_SCHED;
;             PG8_LDB(B0, 1, 0); PG8_LDB(B1, 1, 1); PG8_SCHED; PG8_LDA(At, 1, 0); PG8_STAGE(PG8_SA(0, 1), a2 + hstepA, voffA);
;             PG8_WAIT_V(8); PG8_WAIT_L(0); PG8_BAR; PG8_MMA(0, 0, At, B0); PG8_MMA(0, 1, At, B1); PG8_BAR; PG8_SCHED;
;             PG8_LDA(At, 1, 1); PG8_STAGE(PG8_SB(1, 0), b3, voffB); PG8_STAGE(PG8_SB(1, 1), b3 + hstepB, voffB); PG8_STAGE(PG8_SA(1, 0), a3, voffA);
;             PG8_WAIT_V(8); PG8_WAIT_L(0); PG8_BAR; PG8_MMA(1, 0, At, B0); PG8_MMA(1, 1, At, B1); PG8_BAR; PG8_SCHED;
.Lpeel_995:
	v_add_u32_e32 v128, 0x10000, v133
	ds_read_b128 v[136:139], v128
	ds_read_b128 v[140:143], v128 offset:1024
	ds_read_b128 v[144:147], v128 offset:2048
	ds_read_b128 v[148:151], v128 offset:3072
	v_add_u32_e32 v128, 0x14000, v133
	ds_read_b128 v[152:155], v128
	ds_read_b128 v[156:159], v128 offset:1024
	ds_read_b128 v[160:163], v128 offset:2048
	ds_read_b128 v[164:167], v128 offset:3072
	s_cmp_eq_u32 s1, 12
	s_cselect_b32 s60, s89, s91
	s_cselect_b32 s61, s29, s92
	s_cselect_b32 s56, s90, s93
	s_cselect_b32 s57, s23, s0
	s_add_u32 s50, s60, 0x80
	s_addc_u32 s51, s61, 0
	ds_read_b128 v[168:171], v134
	ds_read_b128 v[172:175], v134 offset:1024
	ds_read_b128 v[176:179], v134 offset:2048
	ds_read_b128 v[180:183], v134 offset:3072
	ds_read_b128 v[184:187], v134 offset:4096
	ds_read_b128 v[188:191], v134 offset:5120
	ds_read_b128 v[192:195], v134 offset:6144
	ds_read_b128 v[196:199], v134 offset:7168
	s_mov_b32 s4, m0
	s_mov_b32 m0, s84
	s_nop 0
	global_load_lds_dwordx4 v129, s[44:45]
	s_mov_b32 m0, s4
	s_nop 0
	s_mov_b32 s4, m0
	s_mov_b32 m0, s85
	s_nop 0
	global_load_lds_dwordx4 v131, s[44:45]
	s_mov_b32 m0, s4
	s_waitcnt vmcnt(8)
	s_waitcnt lgkmcnt(0)
	s_barrier
	s_waitcnt lgkmcnt(7)
	v_mfma_i32_16x16x64_i8 v[16:19], v[136:139], v[168:171], 0
	v_mfma_i32_16x16x64_i8 v[20:23], v[144:147], v[168:171], 0
	s_waitcnt lgkmcnt(5)
	v_mfma_i32_16x16x64_i8 v[48:51], v[136:139], v[176:179], 0
	v_mfma_i32_16x16x64_i8 v[52:55], v[144:147], v[176:179], 0
	s_waitcnt lgkmcnt(3)
	v_mfma_i32_16x16x64_i8 v[72:75], v[136:139], v[184:187], 0
	v_mfma_i32_16x16x64_i8 v[76:79], v[144:147], v[184:187], 0
	s_waitcnt lgkmcnt(1)
	v_mfma_i32_16x16x64_i8 v[96:99], v[136:139], v[192:195], 0
	v_mfma_i32_16x16x64_i8 v[100:103], v[144:147], v[192:195], 0
	v_mfma_i32_16x16x64_i8 v[16:19], v[140:143], v[172:175], v[16:19]
	v_mfma_i32_16x16x64_i8 v[20:23], v[148:151], v[172:175], v[20:23]
	v_mfma_i32_16x16x64_i8 v[48:51], v[140:143], v[180:183], v[48:51]
	v_mfma_i32_16x16x64_i8 v[52:55], v[148:151], v[180:183], v[52:55]
	v_mfma_i32_16x16x64_i8 v[72:75], v[140:143], v[188:191], v[72:75]
	v_mfma_i32_16x16x64_i8 v[76:79], v[148:151], v[188:191], v[76:79]
	s_waitcnt lgkmcnt(0)
	v_mfma_i32_16x16x64_i8 v[96:99], v[140:143], v[196:199], v[96:99]
	v_mfma_i32_16x16x64_i8 v[100:103], v[148:151], v[196:199], v[100:103]
	v_mfma_i32_16x16x64_i8 v[24:27], v[152:155], v[168:171], 0
	v_mfma_i32_16x16x64_i8 v[28:31], v[160:163], v[168:171], 0
	v_mfma_i32_16x16x64_i8 v[56:59], v[152:155], v[176:179], 0
	v_mfma_i32_16x16x64_i8 v[60:63], v[160:163], v[176:179], 0
	v_mfma_i32_16x16x64_i8 v[80:83], v[152:155], v[184:187], 0
	v_mfma_i32_16x16x64_i8 v[84:87], v[160:163], v[184:187], 0
	v_mfma_i32_16x16x64_i8 v[104:107], v[152:155], v[192:195], 0
	v_mfma_i32_16x16x64_i8 v[108:111], v[160:163], v[192:195], 0
	v_mfma_i32_16x16x64_i8 v[24:27], v[156:159], v[172:175], v[24:27]
	v_mfma_i32_16x16x64_i8 v[28:31], v[164:167], v[172:175], v[28:31]
	v_mfma_i32_16x16x64_i8 v[56:59], v[156:159], v[180:183], v[56:59]
	v_mfma_i32_16x16x64_i8 v[60:63], v[164:167], v[180:183], v[60:63]
	v_mfma_i32_16x16x64_i8 v[80:83], v[156:159], v[188:191], v[80:83]
	v_mfma_i32_16x16x64_i8 v[84:87], v[164:167], v[188:191], v[84:87]
	v_mfma_i32_16x16x64_i8 v[104:107], v[156:159], v[196:199], v[104:107]
	v_mfma_i32_16x16x64_i8 v[108:111], v[164:167], v[196:199], v[108:111]
	s_barrier
	ds_read_b128 v[168:171], v134 offset:16384
	ds_read_b128 v[172:175], v134 offset:17408
	ds_read_b128 v[176:179], v134 offset:18432
	ds_read_b128 v[180:183], v134 offset:19456
	ds_read_b128 v[184:187], v134 offset:20480
	ds_read_b128 v[188:191], v134 offset:21504
	ds_read_b128 v[192:195], v134 offset:22528
	ds_read_b128 v[196:199], v134 offset:23552
	s_mov_b32 s4, m0
	s_mov_b32 m0, s62
	s_nop 0
	global_load_lds_dwordx4 v130, s[56:57]
	s_mov_b32 m0, s4
	s_nop 0
	s_mov_b32 s4, m0
	s_mov_b32 m0, s63
	s_nop 0
	global_load_lds_dwordx4 v132, s[56:57]
	s_mov_b32 m0, s4
	s_add_u32 s4, s56, 0x40000
	s_addc_u32 s5, s57, 0
	s_mov_b32 s6, m0
	s_mov_b32 m0, s64
	s_nop 0
	global_load_lds_dwordx4 v130, s[4:5]
	s_mov_b32 m0, s6
	s_nop 0
	s_mov_b32 s6, m0
	s_mov_b32 m0, s68
	s_nop 0
	global_load_lds_dwordx4 v132, s[4:5]
	s_mov_b32 m0, s6
	s_mov_b32 s4, m0
	s_mov_b32 m0, s2
	s_nop 0
	global_load_lds_dwordx4 v129, s[60:61]
	s_mov_b32 m0, s4
	s_nop 0
	s_mov_b32 s4, m0
	s_mov_b32 m0, s69
	s_nop 0
	global_load_lds_dwordx4 v131, s[60:61]
	s_mov_b32 m0, s4
	s_waitcnt vmcnt(8)
	s_waitcnt lgkmcnt(0)
	s_barrier
	s_waitcnt lgkmcnt(7)
	v_mfma_i32_16x16x64_i8 v[124:127], v[136:139], v[168:171], 0
	v_mfma_i32_16x16x64_i8 v[120:123], v[144:147], v[168:171], 0
	s_waitcnt lgkmcnt(5)
	v_mfma_i32_16x16x64_i8 v[92:95], v[136:139], v[176:179], 0
	v_mfma_i32_16x16x64_i8 v[88:91], v[144:147], v[176:179], 0
	s_waitcnt lgkmcnt(3)
	v_mfma_i32_16x16x64_i8 v[44:47], v[136:139], v[184:187], 0
	v_mfma_i32_16x16x64_i8 v[40:43], v[144:147], v[184:187], 0
	s_waitcnt lgkmcnt(1)
	v_mfma_i32_16x16x64_i8 v[12:15], v[136:139], v[192:195], 0
	v_mfma_i32_16x16x64_i8 v[8:11], v[144:147], v[192:195], 0
	v_mfma_i32_16x16x64_i8 v[124:127], v[140:143], v[172:175], v[124:127]
	v_mfma_i32_16x16x64_i8 v[120:123], v[148:151], v[172:175], v[120:123]
	v_mfma_i32_16x16x64_i8 v[92:95], v[140:143], v[180:183], v[92:95]
	v_mfma_i32_16x16x64_i8 v[88:91], v[148:151], v[180:183], v[88:91]
	v_mfma_i32_16x16x64_i8 v[44:47], v[140:143], v[188:191], v[44:47]
	v_mfma_i32_16x16x64_i8 v[40:43], v[148:151], v[188:191], v[40:43]
	s_waitcnt lgkmcnt(0)
	v_mfma_i32_16x16x64_i8 v[12:15], v[140:143], v[196:199], v[12:15]
	v_mfma_i32_16x16x64_i8 v[8:11], v[148:151], v[196:199], v[8:11]
	v_mfma_i32_16x16x64_i8 v[116:119], v[152:155], v[168:171], 0
	v_mfma_i32_16x16x64_i8 v[112:115], v[160:163], v[168:171], 0
	v_mfma_i32_16x16x64_i8 v[68:71], v[152:155], v[176:179], 0
	v_mfma_i32_16x16x64_i8 v[64:67], v[160:163], v[176:179], 0
	v_mfma_i32_16x16x64_i8 v[36:39], v[152:155], v[184:187], 0
	v_mfma_i32_16x16x64_i8 v[32:35], v[160:163], v[184:187], 0
	v_mfma_i32_16x16x64_i8 v[4:7], v[152:155], v[192:195], 0
	v_mfma_i32_16x16x64_i8 v[0:3], v[160:163], v[192:195], 0
	v_mfma_i32_16x16x64_i8 v[116:119], v[156:159], v[172:175], v[116:119]
	v_mfma_i32_16x16x64_i8 v[112:115], v[164:167], v[172:175], v[112:115]
	v_mfma_i32_16x16x64_i8 v[68:71], v[156:159], v[180:183], v[68:71]
	v_mfma_i32_16x16x64_i8 v[64:67], v[164:167], v[180:183], v[64:67]
	v_mfma_i32_16x16x64_i8 v[36:39], v[156:159], v[188:191], v[36:39]
	v_mfma_i32_16x16x64_i8 v[32:35], v[164:167], v[188:191], v[32:35]
	v_mfma_i32_16x16x64_i8 v[4:7], v[156:159], v[196:199], v[4:7]
	v_mfma_i32_16x16x64_i8 v[0:3], v[164:167], v[196:199], v[0:3]
	s_barrier
; #define PG8_STAGE(bufoff, gbase, voff) do { _Pragma("unroll") for (int _i = 0; _i < 2; ++_i) glds16_s((gbase), (voff)[_i], ldsb + (unsigned)((bufoff) + _i * 8192)); } while (0)
; #define PG8_LDA(dst, b, h) do { _Pragma("unroll") for (int m = 0; m < 4; ++m) _Pragma("unroll") for (int k = 0; k < 2; ++k) dst[m][k] = *(const LAS h16x8*)(lds + PG8_SA(b, h) + aoff + m * 2048 + k * 1024); } while (0)
; #define PG8_LDB(dst, b, h) do { _Pragma("unroll") for (int n = 0; n < 2; ++n) _Pragma("unroll") for (int k = 0; k < 2; ++k) dst[n][k] = *(const LAS h16x8*)(lds + PG8_SB(b, h) + boff + n * 2048 + k * 1024); } while (0)
; #define PG8_MMA(ai, bj, At, Bt) do { __builtin_amdgcn_s_setprio(1); _Pragma("unroll") for (int m = 0; m < 4; ++m) _Pragma("unroll") for (int n = 0; n < 2; ++n) _Pragma("unroll") for (int k = 0; k < 2; ++k) \
;         acc[ai][bj][m][n] = mma_step<I8>(Bt[n][k], At[m][k], acc[ai][bj][m][n]); __builtin_amdgcn_s_setprio(0); } while (0)
; #define PG8_WAIT_V(n) asm volatile("s_waitcnt vmcnt(" #n ")" ::: "memory")
; #define PG8_WAIT_L(n) asm volatile("s_waitcnt lgkmcnt(" #n ")" ::: "memory")
; #define PG8_BAR __builtin_amdgcn_s_barrier()
; #define PG8_SCHED __builtin_amdgcn_sched_barrier(0)
; template <class Prob, class Epi, bool I8 = false, bool ALIGN_EPI = true, bool SP2 = true>
; __device__ __forceinline__ void gemm_phase(LAS unsigned char* lds, int wave, const Prob& P, const Epi& E) {
;     ...
;             PG8_LDB(B0, 1, 0); PG8_LDB(B1, 1, 1); PG8_SCHED; PG8_LDA(At, 1, 0); PG8_STAGE(PG8_SA(0, 1), a2 + hstepA, voffA);
;             PG8_WAIT_V(8); PG8_WAIT_L(0); PG8_BAR; PG8_MMA(0, 0, At, B0); PG8_MMA(0, 1, At, B1); PG8_BAR; PG8_SCHED;
;             PG8_LDA(At, 1, 1); PG8_STAGE(PG8_SB(1, 0), b3, voffB); PG8_STAGE(PG8_SB(1, 1), b3 + hstepB, voffB); PG8_STAGE(PG8_SA(1, 0), a3, voffA);
;             PG8_WAIT_V(8); PG8_WAIT_L(0); PG8_BAR; PG8_MMA(1, 0, At, B0); PG8_MMA(1, 1, At, B1); PG8_BAR; PG8_SCHED;
	v_add_u32_e32 v128, 0x18000, v133
	ds_read_b128 v[136:139], v128
	ds_read_b128 v[140:143], v128 offset:1024
	ds_read_b128 v[144:147], v128 offset:2048
	ds_read_b128 v[148:151], v128 offset:3072
	v_add_u32_e32 v128, 0x1c000, v133
	ds_read_b128 v[152:155], v128
	ds_read_b128 v[156:159], v128 offset:1024
	ds_read_b128 v[160:163], v128 offset:2048
	ds_read_b128 v[164:167], v128 offset:3072
	ds_read_b128 v[168:171], v134 offset:32768
	ds_read_b128 v[172:175], v134 offset:33792
	ds_read_b128 v[176:179], v134 offset:34816
	ds_read_b128 v[180:183], v134 offset:35840
	ds_read_b128 v[184:187], v134 offset:36864
	ds_read_b128 v[188:191], v134 offset:37888
	ds_read_b128 v[192:195], v134 offset:38912
	ds_read_b128 v[196:199], v134 offset:39936
	s_add_u32 s4, s60, 0x1000000
	s_addc_u32 s5, s61, 0
	s_mov_b32 s6, m0
	s_mov_b32 m0, s72
	s_nop 0
	global_load_lds_dwordx4 v129, s[4:5]
	s_mov_b32 m0, s6
	s_nop 0
	s_mov_b32 s6, m0
	s_mov_b32 m0, s73
	s_nop 0
	global_load_lds_dwordx4 v131, s[4:5]
	s_mov_b32 m0, s6
	s_waitcnt vmcnt(8)
	s_waitcnt lgkmcnt(0)
	s_barrier
	s_waitcnt lgkmcnt(7)
	v_mfma_i32_16x16x64_i8 v[16:19], v[136:139], v[168:171], v[16:19]
	v_mfma_i32_16x16x64_i8 v[20:23], v[144:147], v[168:171], v[20:23]
	s_waitcnt lgkmcnt(5)
	v_mfma_i32_16x16x64_i8 v[48:51], v[136:139], v[176:179], v[48:51]
	v_mfma_i32_16x16x64_i8 v[52:55], v[144:147], v[176:179], v[52:55]
	s_waitcnt lgkmcnt(3)
	v_mfma_i32_16x16x64_i8 v[72:75], v[136:139], v[184:187], v[72:75]
	v_mfma_i32_16x16x64_i8 v[76:79], v[144:147], v[184:187], v[76:79]
	s_waitcnt lgkmcnt(1)
	v_mfma_i32_16x16x64_i8 v[96:99], v[136:139], v[192:195], v[96:99]
	v_mfma_i32_16x16x64_i8 v[100:103], v[144:147], v[192:195], v[100:103]
	v_mfma_i32_16x16x64_i8 v[16:19], v[140:143], v[172:175], v[16:19]
	v_mfma_i32_16x16x64_i8 v[20:23], v[148:151], v[172:175], v[20:23]
	v_mfma_i32_16x16x64_i8 v[48:51], v[140:143], v[180:183], v[48:51]
	v_mfma_i32_16x16x64_i8 v[52:55], v[148:151], v[180:183], v[52:55]
	v_mfma_i32_16x16x64_i8 v[72:75], v[140:143], v[188:191], v[72:75]
	v_mfma_i32_16x16x64_i8 v[76:79], v[148:151], v[188:191], v[76:79]
	s_waitcnt lgkmcnt(0)
	v_mfma_i32_16x16x64_i8 v[96:99], v[140:143], v[196:199], v[96:99]
	v_mfma_i32_16x16x64_i8 v[100:103], v[148:151], v[196:199], v[100:103]
	v_mfma_i32_16x16x64_i8 v[24:27], v[152:155], v[168:171], v[24:27]
	v_mfma_i32_16x16x64_i8 v[28:31], v[160:163], v[168:171], v[28:31]
	v_mfma_i32_16x16x64_i8 v[56:59], v[152:155], v[176:179], v[56:59]
	v_mfma_i32_16x16x64_i8 v[60:63], v[160:163], v[176:179], v[60:63]
	v_mfma_i32_16x16x64_i8 v[80:83], v[152:155], v[184:187], v[80:83]
	v_mfma_i32_16x16x64_i8 v[84:87], v[160:163], v[184:187], v[84:87]
	v_mfma_i32_16x16x64_i8 v[104:107], v[152:155], v[192:195], v[104:107]
	v_mfma_i32_16x16x64_i8 v[108:111], v[160:163], v[192:195], v[108:111]
	v_mfma_i32_16x16x64_i8 v[24:27], v[156:159], v[172:175], v[24:27]
	v_mfma_i32_16x16x64_i8 v[28:31], v[164:167], v[172:175], v[28:31]
	v_mfma_i32_16x16x64_i8 v[56:59], v[156:159], v[180:183], v[56:59]
	v_mfma_i32_16x16x64_i8 v[60:63], v[164:167], v[180:183], v[60:63]
	v_mfma_i32_16x16x64_i8 v[80:83], v[156:159], v[188:191], v[80:83]
	v_mfma_i32_16x16x64_i8 v[84:87], v[164:167], v[188:191], v[84:87]
	v_mfma_i32_16x16x64_i8 v[104:107], v[156:159], v[196:199], v[104:107]
	v_mfma_i32_16x16x64_i8 v[108:111], v[164:167], v[196:199], v[108:111]
	s_barrier
	ds_read_b128 v[168:171], v134 offset:49152
	ds_read_b128 v[172:175], v134 offset:50176
	ds_read_b128 v[176:179], v134 offset:51200
	ds_read_b128 v[180:183], v134 offset:52224
	ds_read_b128 v[184:187], v134 offset:53248
	ds_read_b128 v[188:191], v134 offset:54272
	ds_read_b128 v[192:195], v134 offset:55296
	ds_read_b128 v[196:199], v134 offset:56320
	s_add_u32 s4, s56, 0x80
	s_addc_u32 s5, s57, 0
	s_mov_b32 s6, m0
	s_mov_b32 m0, s76
	s_nop 0
	global_load_lds_dwordx4 v130, s[4:5]
	s_mov_b32 m0, s6
	s_nop 0
	s_mov_b32 s6, m0
	s_mov_b32 m0, s77
	s_nop 0
	global_load_lds_dwordx4 v132, s[4:5]
	s_mov_b32 m0, s6
	s_add_u32 s4, s56, 0x40080
	s_addc_u32 s5, s57, 0
	s_mov_b32 s6, m0
	s_mov_b32 m0, s82
	s_nop 0
	global_load_lds_dwordx4 v130, s[4:5]
	s_mov_b32 m0, s6
	s_nop 0
	s_mov_b32 s6, m0
	s_mov_b32 m0, s83
	s_nop 0
	global_load_lds_dwordx4 v132, s[4:5]
	s_mov_b32 m0, s6
	s_mov_b32 s4, m0
	s_mov_b32 m0, s80
	s_nop 0
	global_load_lds_dwordx4 v129, s[50:51]
	s_mov_b32 m0, s4
	s_nop 0
	s_mov_b32 s4, m0
	s_mov_b32 m0, s81
	s_nop 0
	global_load_lds_dwordx4 v131, s[50:51]
	s_mov_b32 m0, s4
	s_waitcnt vmcnt(8)
	s_waitcnt lgkmcnt(0)
	s_barrier
	s_waitcnt lgkmcnt(7)
	v_mfma_i32_16x16x64_i8 v[124:127], v[136:139], v[168:171], v[124:127]
	v_mfma_i32_16x16x64_i8 v[120:123], v[144:147], v[168:171], v[120:123]
	s_waitcnt lgkmcnt(5)
	v_mfma_i32_16x16x64_i8 v[92:95], v[136:139], v[176:179], v[92:95]
	v_mfma_i32_16x16x64_i8 v[88:91], v[144:147], v[176:179], v[88:91]
	s_waitcnt lgkmcnt(3)
	v_mfma_i32_16x16x64_i8 v[44:47], v[136:139], v[184:187], v[44:47]
	v_mfma_i32_16x16x64_i8 v[40:43], v[144:147], v[184:187], v[40:43]
	s_waitcnt lgkmcnt(1)
	v_mfma_i32_16x16x64_i8 v[12:15], v[136:139], v[192:195], v[12:15]
	v_mfma_i32_16x16x64_i8 v[8:11], v[144:147], v[192:195], v[8:11]
	v_mfma_i32_16x16x64_i8 v[124:127], v[140:143], v[172:175], v[124:127]
	v_mfma_i32_16x16x64_i8 v[120:123], v[148:151], v[172:175], v[120:123]
	v_mfma_i32_16x16x64_i8 v[92:95], v[140:143], v[180:183], v[92:95]
	v_mfma_i32_16x16x64_i8 v[88:91], v[148:151], v[180:183], v[88:91]
	v_mfma_i32_16x16x64_i8 v[44:47], v[140:143], v[188:191], v[44:47]
	v_mfma_i32_16x16x64_i8 v[40:43], v[148:151], v[188:191], v[40:43]
	s_waitcnt lgkmcnt(0)
	v_mfma_i32_16x16x64_i8 v[12:15], v[140:143], v[196:199], v[12:15]
	v_mfma_i32_16x16x64_i8 v[8:11], v[148:151], v[196:199], v[8:11]
	v_mfma_i32_16x16x64_i8 v[116:119], v[152:155], v[168:171], v[116:119]
	v_mfma_i32_16x16x64_i8 v[112:115], v[160:163], v[168:171], v[112:115]
	v_mfma_i32_16x16x64_i8 v[68:71], v[152:155], v[176:179], v[68:71]
	v_mfma_i32_16x16x64_i8 v[64:67], v[160:163], v[176:179], v[64:67]
	v_mfma_i32_16x16x64_i8 v[36:39], v[152:155], v[184:187], v[36:39]
	v_mfma_i32_16x16x64_i8 v[32:35], v[160:163], v[184:187], v[32:35]
	v_mfma_i32_16x16x64_i8 v[4:7], v[152:155], v[192:195], v[4:7]
	v_mfma_i32_16x16x64_i8 v[0:3], v[160:163], v[192:195], v[0:3]
	v_mfma_i32_16x16x64_i8 v[116:119], v[156:159], v[172:175], v[116:119]
	v_mfma_i32_16x16x64_i8 v[112:115], v[164:167], v[172:175], v[112:115]
	v_mfma_i32_16x16x64_i8 v[68:71], v[156:159], v[180:183], v[68:71]
	v_mfma_i32_16x16x64_i8 v[64:67], v[164:167], v[180:183], v[64:67]
	v_mfma_i32_16x16x64_i8 v[36:39], v[156:159], v[188:191], v[36:39]
	v_mfma_i32_16x16x64_i8 v[32:35], v[164:167], v[188:191], v[32:35]
	v_mfma_i32_16x16x64_i8 v[4:7], v[156:159], v[196:199], v[4:7]
	v_mfma_i32_16x16x64_i8 v[0:3], v[164:167], v[196:199], v[0:3]
	s_barrier
	s_add_i32 s1, s1, 2
	s_add_u32 s91, s91, 0x100
	s_addc_u32 s92, s92, 0
	s_add_u32 s93, s93, 0x100
	s_addc_u32 s0, s0, 0
	s_add_u32 s44, s44, 0x100
	s_addc_u32 s45, s45, 0
	s_cmp_gt_u32 s1, 13
; #define PG8_STAGE(bufoff, gbase, voff) do { _Pragma("unroll") for (int _i = 0; _i < 2; ++_i) glds16_s((gbase), (voff)[_i], ldsb + (unsigned)((bufoff) + _i * 8192)); } while (0)
; #define PG8_LDA(dst, b, h) do { _Pragma("unroll") for (int m = 0; m < 4; ++m) _Pragma("unroll") for (int k = 0; k < 2; ++k) dst[m][k] = *(const LAS h16x8*)(lds + PG8_SA(b, h) + aoff + m * 2048 + k * 1024); } while (0)
; #define PG8_LDB(dst, b, h) do { _Pragma("unroll") for (int n = 0; n < 2; ++n) _Pragma("unroll") for (int k = 0; k < 2; ++k) dst[n][k] = *(const LAS h16x8*)(lds + PG8_SB(b, h) + boff + n * 2048 + k * 1024); } while (0)
; #define PG8_MMA(ai, bj, At, Bt) do { __builtin_amdgcn_s_setprio(1); _Pragma("unroll") for (int m = 0; m < 4; ++m) _Pragma("unroll") for (int n = 0; n < 2; ++n) _Pragma("unroll") for (int k = 0; k < 2; ++k) \
;         acc[ai][bj][m][n] = mma_step<I8>(Bt[n][k], At[m][k], acc[ai][bj][m][n]); __builtin_amdgcn_s_setprio(0); } while (0)
; #define PG8_WAIT_V(n) asm volatile("s_waitcnt vmcnt(" #n ")" ::: "memory")
; #define PG8_WAIT_L(n) asm volatile("s_waitcnt lgkmcnt(" #n ")" ::: "memory")
; #define PG8_BAR __builtin_amdgcn_s_barrier()
; #define PG8_SCHED __builtin_amdgcn_sched_barrier(0)
; template <class Prob, class Epi, bool I8 = false, bool ALIGN_EPI = true, bool SP2 = true>
; __device__ __forceinline__ void gemm_phase(LAS unsigned char* lds, int wave, const Prob& P, const Epi& E) {
;     ...
;         for (int t = 0; t < nt; t += 2) {
;             const bool last = (t == nt - 2);
;             const char* a1 = cA + (size_t)(t + 1) * kstep;
;             const char* a2 = last ? nA : cA + (size_t)(t + 2) * kstep; const char* b2 = last ? nB : cB + (size_t)(t + 2) * kstep;
;             const char* a3 = a2 + kstep; const char* b3 = b2 + kstep;
;             if constexpr (SP2) {
;             PG8_LDB(B0, 0, 0); PG8_LDB(B1, 0, 1); PG8_SCHED; PG8_LDA(At, 0, 0); PG8_STAGE(PG8_SA(1, 1), a1 + hstepA, voffA);
;             PG8_WAIT_V(8); PG8_WAIT_L(0); PG8_BAR; PG8_MMA(0, 0, At, B0); PG8_MMA(0, 1, At, B1); PG8_BAR; PG8_SCHED;
;             PG8_LDA(At, 0, 1); PG8_STAGE(PG8_SB(0, 0), b2, voffB); PG8_STAGE(PG8_SB(0, 1), b2 + hstepB, voffB); PG8_STAGE(PG8_SA(0, 0), a2, voffA);
;             PG8_WAIT_V(8); PG8_WAIT_L(0); PG8_BAR; PG8_MMA(1, 0, At, B0); PG8_MMA(1, 1, At, B1); PG8_BAR; PG8_SCHED;
.LBB0_995:
	v_add_u32_e32 v128, 0x10000, v133
	ds_read_b128 v[136:139], v128
	ds_read_b128 v[140:143], v128 offset:1024
	ds_read_b128 v[144:147], v128 offset:2048
	ds_read_b128 v[148:151], v128 offset:3072
	v_add_u32_e32 v128, 0x14000, v133
	ds_read_b128 v[152:155], v128
	ds_read_b128 v[156:159], v128 offset:1024
	ds_read_b128 v[160:163], v128 offset:2048
	ds_read_b128 v[164:167], v128 offset:3072
	s_cmp_eq_u32 s1, 12
	s_cselect_b32 s60, s89, s91
	s_cselect_b32 s61, s29, s92
	s_cselect_b32 s56, s90, s93
	s_cselect_b32 s57, s23, s0
	s_add_u32 s50, s60, 0x80
	s_addc_u32 s51, s61, 0
	ds_read_b128 v[168:171], v134
	ds_read_b128 v[172:175], v134 offset:1024
	ds_read_b128 v[176:179], v134 offset:2048
	ds_read_b128 v[180:183], v134 offset:3072
	ds_read_b128 v[184:187], v134 offset:4096
	ds_read_b128 v[188:191], v134 offset:5120
	ds_read_b128 v[192:195], v134 offset:6144
	ds_read_b128 v[196:199], v134 offset:7168
	s_mov_b32 s4, m0
	s_mov_b32 m0, s84
	s_nop 0
	global_load_lds_dwordx4 v129, s[44:45]
	s_mov_b32 m0, s4
	s_nop 0
	s_mov_b32 s4, m0
	s_mov_b32 m0, s85
	s_nop 0
	global_load_lds_dwordx4 v131, s[44:45]
	s_mov_b32 m0, s4
	s_waitcnt vmcnt(8)
	s_waitcnt lgkmcnt(0)
	s_barrier
	s_waitcnt lgkmcnt(7)
	v_mfma_i32_16x16x64_i8 v[16:19], v[136:139], v[168:171], v[16:19]
	v_mfma_i32_16x16x64_i8 v[20:23], v[144:147], v[168:171], v[20:23]
	s_waitcnt lgkmcnt(5)
	v_mfma_i32_16x16x64_i8 v[48:51], v[136:139], v[176:179], v[48:51]
	v_mfma_i32_16x16x64_i8 v[52:55], v[144:147], v[176:179], v[52:55]
	s_waitcnt lgkmcnt(3)
	v_mfma_i32_16x16x64_i8 v[72:75], v[136:139], v[184:187], v[72:75]
	v_mfma_i32_16x16x64_i8 v[76:79], v[144:147], v[184:187], v[76:79]
	s_waitcnt lgkmcnt(1)
	v_mfma_i32_16x16x64_i8 v[96:99], v[136:139], v[192:195], v[96:99]
	v_mfma_i32_16x16x64_i8 v[100:103], v[144:147], v[192:195], v[100:103]
	v_mfma_i32_16x16x64_i8 v[16:19], v[140:143], v[172:175], v[16:19]
	v_mfma_i32_16x16x64_i8 v[20:23], v[148:151], v[172:175], v[20:23]
	v_mfma_i32_16x16x64_i8 v[48:51], v[140:143], v[180:183], v[48:51]
	v_mfma_i32_16x16x64_i8 v[52:55], v[148:151], v[180:183], v[52:55]
	v_mfma_i32_16x16x64_i8 v[72:75], v[140:143], v[188:191], v[72:75]
	v_mfma_i32_16x16x64_i8 v[76:79], v[148:151], v[188:191], v[76:79]
	s_waitcnt lgkmcnt(0)
	v_mfma_i32_16x16x64_i8 v[96:99], v[140:143], v[196:199], v[96:99]
	v_mfma_i32_16x16x64_i8 v[100:103], v[148:151], v[196:199], v[100:103]
	v_mfma_i32_16x16x64_i8 v[24:27], v[152:155], v[168:171], v[24:27]
	v_mfma_i32_16x16x64_i8 v[28:31], v[160:163], v[168:171], v[28:31]
	v_mfma_i32_16x16x64_i8 v[56:59], v[152:155], v[176:179], v[56:59]
	v_mfma_i32_16x16x64_i8 v[60:63], v[160:163], v[176:179], v[60:63]
	v_mfma_i32_16x16x64_i8 v[80:83], v[152:155], v[184:187], v[80:83]
	v_mfma_i32_16x16x64_i8 v[84:87], v[160:163], v[184:187], v[84:87]
	v_mfma_i32_16x16x64_i8 v[104:107], v[152:155], v[192:195], v[104:107]
	v_mfma_i32_16x16x64_i8 v[108:111], v[160:163], v[192:195], v[108:111]
	v_mfma_i32_16x16x64_i8 v[24:27], v[156:159], v[172:175], v[24:27]
	v_mfma_i32_16x16x64_i8 v[28:31], v[164:167], v[172:175], v[28:31]
	v_mfma_i32_16x16x64_i8 v[56:59], v[156:159], v[180:183], v[56:59]
	v_mfma_i32_16x16x64_i8 v[60:63], v[164:167], v[180:183], v[60:63]
	v_mfma_i32_16x16x64_i8 v[80:83], v[156:159], v[188:191], v[80:83]
	v_mfma_i32_16x16x64_i8 v[84:87], v[164:167], v[188:191], v[84:87]
	v_mfma_i32_16x16x64_i8 v[104:107], v[156:159], v[196:199], v[104:107]
	v_mfma_i32_16x16x64_i8 v[108:111], v[164:167], v[196:199], v[108:111]
	s_barrier
	ds_read_b128 v[168:171], v134 offset:16384
	ds_read_b128 v[172:175], v134 offset:17408
	ds_read_b128 v[176:179], v134 offset:18432
	ds_read_b128 v[180:183], v134 offset:19456
	ds_read_b128 v[184:187], v134 offset:20480
	ds_read_b128 v[188:191], v134 offset:21504
	ds_read_b128 v[192:195], v134 offset:22528
	ds_read_b128 v[196:199], v134 offset:23552
	s_mov_b32 s4, m0
	s_mov_b32 m0, s62
	s_nop 0
	global_load_lds_dwordx4 v130, s[56:57]
	s_mov_b32 m0, s4
	s_nop 0
	s_mov_b32 s4, m0
	s_mov_b32 m0, s63
	s_nop 0
	global_load_lds_dwordx4 v132, s[56:57]
	s_mov_b32 m0, s4
	s_add_u32 s4, s56, 0x40000
	s_addc_u32 s5, s57, 0
	s_mov_b32 s6, m0
	s_mov_b32 m0, s64
	s_nop 0
	global_load_lds_dwordx4 v130, s[4:5]
	s_mov_b32 m0, s6
	s_nop 0
	s_mov_b32 s6, m0
	s_mov_b32 m0, s68
	s_nop 0
	global_load_lds_dwordx4 v132, s[4:5]
	s_mov_b32 m0, s6
	s_mov_b32 s4, m0
	s_mov_b32 m0, s2
	s_nop 0
	global_load_lds_dwordx4 v129, s[60:61]
	s_mov_b32 m0, s4
	s_nop 0
	s_mov_b32 s4, m0
	s_mov_b32 m0, s69
	s_nop 0
	global_load_lds_dwordx4 v131, s[60:61]
	s_mov_b32 m0, s4
	s_waitcnt vmcnt(8)
	s_waitcnt lgkmcnt(0)
	s_barrier
; #define PG8_STAGE(bufoff, gbase, voff) do { _Pragma("unroll") for (int _i = 0; _i < 2; ++_i) glds16_s((gbase), (voff)[_i], ldsb + (unsigned)((bufoff) + _i * 8192)); } while (0)
; #define PG8_LDA(dst, b, h) do { _Pragma("unroll") for (int m = 0; m < 4; ++m) _Pragma("unroll") for (int k = 0; k < 2; ++k) dst[m][k] = *(const LAS h16x8*)(lds + PG8_SA(b, h) + aoff + m * 2048 + k * 1024); } while (0)
; #define PG8_LDB(dst, b, h) do { _Pragma("unroll") for (int n = 0; n < 2; ++n) _Pragma("unroll") for (int k = 0; k < 2; ++k) dst[n][k] = *(const LAS h16x8*)(lds + PG8_SB(b, h) + boff + n * 2048 + k * 1024); } while (0)
; #define PG8_MMA(ai, bj, At, Bt) do { __builtin_amdgcn_s_setprio(1); _Pragma("unroll") for (int m = 0; m < 4; ++m) _Pragma("unroll") for (int n = 0; n < 2; ++n) _Pragma("unroll") for (int k = 0; k < 2; ++k) \
;         acc[ai][bj][m][n] = mma_step<I8>(Bt[n][k], At[m][k], acc[ai][bj][m][n]); __builtin_amdgcn_s_setprio(0); } while (0)
; #define PG8_WAIT_V(n) asm volatile("s_waitcnt vmcnt(" #n ")" ::: "memory")
; #define PG8_WAIT_L(n) asm volatile("s_waitcnt lgkmcnt(" #n ")" ::: "memory")
; #define PG8_BAR __builtin_amdgcn_s_barrier()
; #define PG8_SCHED __builtin_amdgcn_sched_barrier(0)
; template <class Prob, class Epi, bool I8 = false, bool ALIGN_EPI = true, bool SP2 = true>
; __device__ __forceinline__ void gemm_phase(LAS unsigned char* lds, int wave, const Prob& P, const Epi& E) {
;     ...
;             PG8_WAIT_V(8); PG8_WAIT_L(0); PG8_BAR; PG8_MMA(1, 0, At, B0); PG8_MMA(1, 1, At, B1); PG8_BAR; PG8_SCHED;
;             PG8_LDB(B0, 1, 0); PG8_LDB(B1, 1, 1); PG8_SCHED; PG8_LDA(At, 1, 0); PG8_STAGE(PG8_SA(0, 1), a2 + hstepA, voffA);
;             PG8_WAIT_V(8); PG8_WAIT_L(0); PG8_BAR; PG8_MMA(0, 0, At, B0); PG8_MMA(0, 1, At, B1); PG8_BAR; PG8_SCHED;
;             PG8_LDA(At, 1, 1); PG8_STAGE(PG8_SB(1, 0), b3, voffB); PG8_STAGE(PG8_SB(1, 1), b3 + hstepB, voffB); PG8_STAGE(PG8_SA(1, 0), a3, voffA);
	s_waitcnt lgkmcnt(7)
	v_mfma_i32_16x16x64_i8 v[124:127], v[136:139], v[168:171], v[124:127]
	v_mfma_i32_16x16x64_i8 v[120:123], v[144:147], v[168:171], v[120:123]
	s_waitcnt lgkmcnt(5)
	v_mfma_i32_16x16x64_i8 v[92:95], v[136:139], v[176:179], v[92:95]
	v_mfma_i32_16x16x64_i8 v[88:91], v[144:147], v[176:179], v[88:91]
	s_waitcnt lgkmcnt(3)
	v_mfma_i32_16x16x64_i8 v[44:47], v[136:139], v[184:187], v[44:47]
	v_mfma_i32_16x16x64_i8 v[40:43], v[144:147], v[184:187], v[40:43]
	s_waitcnt lgkmcnt(1)
	v_mfma_i32_16x16x64_i8 v[12:15], v[136:139], v[192:195], v[12:15]
	v_mfma_i32_16x16x64_i8 v[8:11], v[144:147], v[192:195], v[8:11]
	v_mfma_i32_16x16x64_i8 v[124:127], v[140:143], v[172:175], v[124:127]
	v_mfma_i32_16x16x64_i8 v[120:123], v[148:151], v[172:175], v[120:123]
	v_mfma_i32_16x16x64_i8 v[92:95], v[140:143], v[180:183], v[92:95]
	v_mfma_i32_16x16x64_i8 v[88:91], v[148:151], v[180:183], v[88:91]
	v_mfma_i32_16x16x64_i8 v[44:47], v[140:143], v[188:191], v[44:47]
	v_mfma_i32_16x16x64_i8 v[40:43], v[148:151], v[188:191], v[40:43]
	s_waitcnt lgkmcnt(0)
	v_mfma_i32_16x16x64_i8 v[12:15], v[140:143], v[196:199], v[12:15]
	v_mfma_i32_16x16x64_i8 v[8:11], v[148:151], v[196:199], v[8:11]
	v_mfma_i32_16x16x64_i8 v[116:119], v[152:155], v[168:171], v[116:119]
	v_mfma_i32_16x16x64_i8 v[112:115], v[160:163], v[168:171], v[112:115]
	v_mfma_i32_16x16x64_i8 v[68:71], v[152:155], v[176:179], v[68:71]
	v_mfma_i32_16x16x64_i8 v[64:67], v[160:163], v[176:179], v[64:67]
	v_mfma_i32_16x16x64_i8 v[36:39], v[152:155], v[184:187], v[36:39]
	v_mfma_i32_16x16x64_i8 v[32:35], v[160:163], v[184:187], v[32:35]
	v_mfma_i32_16x16x64_i8 v[4:7], v[152:155], v[192:195], v[4:7]
	v_mfma_i32_16x16x64_i8 v[0:3], v[160:163], v[192:195], v[0:3]
	v_mfma_i32_16x16x64_i8 v[116:119], v[156:159], v[172:175], v[116:119]
	v_mfma_i32_16x16x64_i8 v[112:115], v[164:167], v[172:175], v[112:115]
	v_mfma_i32_16x16x64_i8 v[68:71], v[156:159], v[180:183], v[68:71]
	v_mfma_i32_16x16x64_i8 v[64:67], v[164:167], v[180:183], v[64:67]
	v_mfma_i32_16x16x64_i8 v[36:39], v[156:159], v[188:191], v[36:39]
	v_mfma_i32_16x16x64_i8 v[32:35], v[164:167], v[188:191], v[32:35]
	v_mfma_i32_16x16x64_i8 v[4:7], v[156:159], v[196:199], v[4:7]
	v_mfma_i32_16x16x64_i8 v[0:3], v[164:167], v[196:199], v[0:3]
	s_barrier
	v_add_u32_e32 v128, 0x18000, v133
	ds_read_b128 v[136:139], v128
	ds_read_b128 v[140:143], v128 offset:1024
	ds_read_b128 v[144:147], v128 offset:2048
	ds_read_b128 v[148:151], v128 offset:3072
	v_add_u32_e32 v128, 0x1c000, v133
	ds_read_b128 v[152:155], v128
	ds_read_b128 v[156:159], v128 offset:1024
	ds_read_b128 v[160:163], v128 offset:2048
	ds_read_b128 v[164:167], v128 offset:3072
	ds_read_b128 v[168:171], v134 offset:32768
	ds_read_b128 v[172:175], v134 offset:33792
	ds_read_b128 v[176:179], v134 offset:34816
	ds_read_b128 v[180:183], v134 offset:35840
	ds_read_b128 v[184:187], v134 offset:36864
	ds_read_b128 v[188:191], v134 offset:37888
	ds_read_b128 v[192:195], v134 offset:38912
	ds_read_b128 v[196:199], v134 offset:39936
	s_add_u32 s4, s60, 0x1000000
	s_addc_u32 s5, s61, 0
	s_mov_b32 s6, m0
	s_mov_b32 m0, s72
	s_nop 0
	global_load_lds_dwordx4 v129, s[4:5]
	s_mov_b32 m0, s6
	s_nop 0
	s_mov_b32 s6, m0
	s_mov_b32 m0, s73
	s_nop 0
	global_load_lds_dwordx4 v131, s[4:5]
	s_mov_b32 m0, s6
	s_waitcnt vmcnt(8)
	s_waitcnt lgkmcnt(0)
	s_barrier
	s_waitcnt lgkmcnt(7)
	v_mfma_i32_16x16x64_i8 v[16:19], v[136:139], v[168:171], v[16:19]
	v_mfma_i32_16x16x64_i8 v[20:23], v[144:147], v[168:171], v[20:23]
	s_waitcnt lgkmcnt(5)
	v_mfma_i32_16x16x64_i8 v[48:51], v[136:139], v[176:179], v[48:51]
	v_mfma_i32_16x16x64_i8 v[52:55], v[144:147], v[176:179], v[52:55]
	s_waitcnt lgkmcnt(3)
	v_mfma_i32_16x16x64_i8 v[72:75], v[136:139], v[184:187], v[72:75]
	v_mfma_i32_16x16x64_i8 v[76:79], v[144:147], v[184:187], v[76:79]
	s_waitcnt lgkmcnt(1)
	v_mfma_i32_16x16x64_i8 v[96:99], v[136:139], v[192:195], v[96:99]
	v_mfma_i32_16x16x64_i8 v[100:103], v[144:147], v[192:195], v[100:103]
	v_mfma_i32_16x16x64_i8 v[16:19], v[140:143], v[172:175], v[16:19]
	v_mfma_i32_16x16x64_i8 v[20:23], v[148:151], v[172:175], v[20:23]
	v_mfma_i32_16x16x64_i8 v[48:51], v[140:143], v[180:183], v[48:51]
	v_mfma_i32_16x16x64_i8 v[52:55], v[148:151], v[180:183], v[52:55]
	v_mfma_i32_16x16x64_i8 v[72:75], v[140:143], v[188:191], v[72:75]
	v_mfma_i32_16x16x64_i8 v[76:79], v[148:151], v[188:191], v[76:79]
	s_waitcnt lgkmcnt(0)
	v_mfma_i32_16x16x64_i8 v[96:99], v[140:143], v[196:199], v[96:99]
	v_mfma_i32_16x16x64_i8 v[100:103], v[148:151], v[196:199], v[100:103]
	v_mfma_i32_16x16x64_i8 v[24:27], v[152:155], v[168:171], v[24:27]
	v_mfma_i32_16x16x64_i8 v[28:31], v[160:163], v[168:171], v[28:31]
	v_mfma_i32_16x16x64_i8 v[56:59], v[152:155], v[176:179], v[56:59]
	v_mfma_i32_16x16x64_i8 v[60:63], v[160:163], v[176:179], v[60:63]
	v_mfma_i32_16x16x64_i8 v[80:83], v[152:155], v[184:187], v[80:83]
	v_mfma_i32_16x16x64_i8 v[84:87], v[160:163], v[184:187], v[84:87]
	v_mfma_i32_16x16x64_i8 v[104:107], v[152:155], v[192:195], v[104:107]
	v_mfma_i32_16x16x64_i8 v[108:111], v[160:163], v[192:195], v[108:111]
	v_mfma_i32_16x16x64_i8 v[24:27], v[156:159], v[172:175], v[24:27]
	v_mfma_i32_16x16x64_i8 v[28:31], v[164:167], v[172:175], v[28:31]
	v_mfma_i32_16x16x64_i8 v[56:59], v[156:159], v[180:183], v[56:59]
	v_mfma_i32_16x16x64_i8 v[60:63], v[164:167], v[180:183], v[60:63]
	v_mfma_i32_16x16x64_i8 v[80:83], v[156:159], v[188:191], v[80:83]
	v_mfma_i32_16x16x64_i8 v[84:87], v[164:167], v[188:191], v[84:87]
	v_mfma_i32_16x16x64_i8 v[104:107], v[156:159], v[196:199], v[104:107]
	v_mfma_i32_16x16x64_i8 v[108:111], v[164:167], v[196:199], v[108:111]
	s_barrier
; #define PG8_STAGE(bufoff, gbase, voff) do { _Pragma("unroll") for (int _i = 0; _i < 2; ++_i) glds16_s((gbase), (voff)[_i], ldsb + (unsigned)((bufoff) + _i * 8192)); } while (0)
; #define PG8_WAIT_V(n) asm volatile("s_waitcnt vmcnt(" #n ")" ::: "memory")
; #define PG8_BAR __builtin_amdgcn_s_barrier()
; template <class Prob, class Epi, bool I8 = false, bool ALIGN_EPI = true, bool SP2 = true>
; __device__ __forceinline__ void gemm_phase(LAS unsigned char* lds, int wave, const Prob& P, const Epi& E) {
;     ...
;             PG8_LDB(B0, 1, 0); PG8_LDB(B1, 1, 1); PG8_SCHED; PG8_LDA(At, 1, 0); PG8_STAGE(PG8_SA(0, 1), a2 + hstepA, voffA);
;             PG8_WAIT_V(8); PG8_WAIT_L(0); PG8_BAR; PG8_MMA(0, 0, At, B0); PG8_MMA(0, 1, At, B1); PG8_BAR; PG8_SCHED;
;             PG8_LDA(At, 1, 1); PG8_STAGE(PG8_SB(1, 0), b3, voffB); PG8_STAGE(PG8_SB(1, 1), b3 + hstepB, voffB); PG8_STAGE(PG8_SA(1, 0), a3, voffA);
;             PG8_WAIT_V(8); PG8_WAIT_L(0); PG8_BAR; PG8_MMA(1, 0, At, B0); PG8_MMA(1, 1, At, B1); PG8_BAR; PG8_SCHED;
;             } else {
;             PG8_LDB(B0, 0, 0); PG8_SCHED; PG8_LDA(At, 0, 0); PG8_STAGE(PG8_SA(1, 1), a1 + hstepA, voffA);
;             PG8_WAIT_L(8); PG8_BAR; PG8_WAIT_L(0); PG8_MMA(0, 0, At, B0); PG8_BAR; PG8_SCHED;
;             PG8_LDB(B1, 0, 1); PG8_STAGE(PG8_SB(0, 0), b2, voffB);
;             PG8_BAR; PG8_WAIT_L(0); PG8_MMA(0, 1, At, B1); PG8_BAR;
;             PG8_LDA(At, 0, 1); PG8_STAGE(PG8_SA(0, 0), a2, voffA);
;             PG8_BAR; PG8_WAIT_L(0); PG8_MMA(1, 0, At, B0); PG8_BAR; PG8_SCHED;
;             PG8_STAGE(PG8_SB(0, 1), b2 + hstepB, voffB);
;             PG8_WAIT_V(6); PG8_BAR; PG8_MMA(1, 1, At, B1); PG8_BAR;
;             PG8_LDB(B0, 1, 0); PG8_SCHED; PG8_LDA(At, 1, 0); PG8_STAGE(PG8_SA(0, 1), a2 + hstepA, voffA);
;             PG8_WAIT_L(8); PG8_BAR; PG8_WAIT_L(0); PG8_MMA(0, 0, At, B0); PG8_BAR; PG8_SCHED;
;             PG8_LDB(B1, 1, 1); PG8_STAGE(PG8_SB(1, 0), b3, voffB);
;             PG8_BAR; PG8_WAIT_L(0); PG8_MMA(0, 1, At, B1); PG8_BAR;
;             PG8_LDA(At, 1, 1); PG8_STAGE(PG8_SA(1, 0), a3, voffA);
;             PG8_BAR; PG8_WAIT_L(0); PG8_MMA(1, 0, At, B0); PG8_BAR; PG8_SCHED;
;             PG8_STAGE(PG8_SB(1, 1), b3 + hstepB, voffB);
;             PG8_WAIT_V(6); PG8_BAR; PG8_MMA(1, 1, At, B1); PG8_BAR;
;             }
;         }
;         if constexpr (ALIGN_EPI) { if (wr == 0) PG8_BAR; }
	ds_read_b128 v[168:171], v134 offset:49152
	ds_read_b128 v[172:175], v134 offset:50176
	ds_read_b128 v[176:179], v134 offset:51200
	ds_read_b128 v[180:183], v134 offset:52224
	ds_read_b128 v[184:187], v134 offset:53248
	ds_read_b128 v[188:191], v134 offset:54272
	ds_read_b128 v[192:195], v134 offset:55296
	ds_read_b128 v[196:199], v134 offset:56320
	s_add_u32 s4, s56, 0x80
	s_addc_u32 s5, s57, 0
	s_mov_b32 s6, m0
	s_mov_b32 m0, s76
	s_nop 0
	global_load_lds_dwordx4 v130, s[4:5]
	s_mov_b32 m0, s6
	s_nop 0
	s_mov_b32 s6, m0
	s_mov_b32 m0, s77
	s_nop 0
	global_load_lds_dwordx4 v132, s[4:5]
	s_mov_b32 m0, s6
	s_add_u32 s4, s56, 0x40080
	s_addc_u32 s5, s57, 0
	s_mov_b32 s6, m0
	s_mov_b32 m0, s82
	s_nop 0
	global_load_lds_dwordx4 v130, s[4:5]
	s_mov_b32 m0, s6
	s_nop 0
	s_mov_b32 s6, m0
	s_mov_b32 m0, s83
	s_nop 0
	global_load_lds_dwordx4 v132, s[4:5]
	s_mov_b32 m0, s6
	s_mov_b32 s4, m0
	s_mov_b32 m0, s80
	s_nop 0
	global_load_lds_dwordx4 v129, s[50:51]
	s_mov_b32 m0, s4
	s_nop 0
	s_mov_b32 s4, m0
	s_mov_b32 m0, s81
	s_nop 0
	global_load_lds_dwordx4 v131, s[50:51]
	s_mov_b32 m0, s4
	s_waitcnt vmcnt(8)
	s_waitcnt lgkmcnt(0)
	s_barrier
	s_waitcnt lgkmcnt(7)
	v_mfma_i32_16x16x64_i8 v[124:127], v[136:139], v[168:171], v[124:127]
	v_mfma_i32_16x16x64_i8 v[120:123], v[144:147], v[168:171], v[120:123]
	s_waitcnt lgkmcnt(5)
	v_mfma_i32_16x16x64_i8 v[92:95], v[136:139], v[176:179], v[92:95]
	v_mfma_i32_16x16x64_i8 v[88:91], v[144:147], v[176:179], v[88:91]
	s_waitcnt lgkmcnt(3)
	v_mfma_i32_16x16x64_i8 v[44:47], v[136:139], v[184:187], v[44:47]
	v_mfma_i32_16x16x64_i8 v[40:43], v[144:147], v[184:187], v[40:43]
	s_waitcnt lgkmcnt(1)
	v_mfma_i32_16x16x64_i8 v[12:15], v[136:139], v[192:195], v[12:15]
	v_mfma_i32_16x16x64_i8 v[8:11], v[144:147], v[192:195], v[8:11]
	v_mfma_i32_16x16x64_i8 v[124:127], v[140:143], v[172:175], v[124:127]
	v_mfma_i32_16x16x64_i8 v[120:123], v[148:151], v[172:175], v[120:123]
	v_mfma_i32_16x16x64_i8 v[92:95], v[140:143], v[180:183], v[92:95]
	v_mfma_i32_16x16x64_i8 v[88:91], v[148:151], v[180:183], v[88:91]
	v_mfma_i32_16x16x64_i8 v[44:47], v[140:143], v[188:191], v[44:47]
	v_mfma_i32_16x16x64_i8 v[40:43], v[148:151], v[188:191], v[40:43]
	s_waitcnt lgkmcnt(0)
	v_mfma_i32_16x16x64_i8 v[12:15], v[140:143], v[196:199], v[12:15]
	v_mfma_i32_16x16x64_i8 v[8:11], v[148:151], v[196:199], v[8:11]
	v_mfma_i32_16x16x64_i8 v[116:119], v[152:155], v[168:171], v[116:119]
	v_mfma_i32_16x16x64_i8 v[112:115], v[160:163], v[168:171], v[112:115]
	v_mfma_i32_16x16x64_i8 v[68:71], v[152:155], v[176:179], v[68:71]
	v_mfma_i32_16x16x64_i8 v[64:67], v[160:163], v[176:179], v[64:67]
	v_mfma_i32_16x16x64_i8 v[36:39], v[152:155], v[184:187], v[36:39]
	v_mfma_i32_16x16x64_i8 v[32:35], v[160:163], v[184:187], v[32:35]
	v_mfma_i32_16x16x64_i8 v[4:7], v[152:155], v[192:195], v[4:7]
	v_mfma_i32_16x16x64_i8 v[0:3], v[160:163], v[192:195], v[0:3]
	v_mfma_i32_16x16x64_i8 v[116:119], v[156:159], v[172:175], v[116:119]
	v_mfma_i32_16x16x64_i8 v[112:115], v[164:167], v[172:175], v[112:115]
	v_mfma_i32_16x16x64_i8 v[68:71], v[156:159], v[180:183], v[68:71]
	v_mfma_i32_16x16x64_i8 v[64:67], v[164:167], v[180:183], v[64:67]
	v_mfma_i32_16x16x64_i8 v[36:39], v[156:159], v[188:191], v[36:39]
	v_mfma_i32_16x16x64_i8 v[32:35], v[164:167], v[188:191], v[32:35]
	v_mfma_i32_16x16x64_i8 v[4:7], v[156:159], v[196:199], v[4:7]
	v_mfma_i32_16x16x64_i8 v[0:3], v[164:167], v[196:199], v[0:3]
	s_barrier
	s_add_i32 s1, s1, 2
	s_add_u32 s91, s91, 0x100
	s_addc_u32 s92, s92, 0
	s_add_u32 s93, s93, 0x100
	s_addc_u32 s0, s0, 0
	s_add_u32 s44, s44, 0x100
	s_addc_u32 s45, s45, 0
	s_cmp_gt_u32 s1, 13
	s_cbranch_scc0 .LBB0_995
	s_and_b64 vcc, exec, s[16:17]
	s_cbranch_vccz .LBB0_998
	s_barrier

; __device__ __forceinline__ int mk_lane() { int l; asm volatile("v_mbcnt_lo_u32_b32 %0, -1, 0\n\tv_mbcnt_hi_u32_b32 %0, -1, %0" : "=v"(l)); return l; }
; #define PG8_STAGE(bufoff, gbase, voff) do { _Pragma("unroll") for (int _i = 0; _i < 2; ++_i) glds16_s((gbase), (voff)[_i], ldsb + (unsigned)((bufoff) + _i * 8192)); } while (0)
; #define PG8_WAIT_V(n) asm volatile("s_waitcnt vmcnt(" #n ")" ::: "memory")
; template <class Prob, class Epi, bool I8 = false, bool ALIGN_EPI = true, bool SP2 = true>
; __device__ __forceinline__ void gemm_phase(LAS unsigned char* lds, int wave, const Prob& P, const Epi& E) {
;     const int tid_ = wave * 64 + mk_lane();
;     const int tid = tid_, wid = __builtin_amdgcn_readfirstlane(tid >> 6), lane = tid & 63, wr = wid >> 2, wc = wid & 3, fr = lane & 15, fq = lane >> 4;
;     const int K = P.K, nt = K / BK;
;     unsigned voffA[2], voffB[2];
; #pragma unroll
;     for (int i = 0; i < 2; ++i) { int R, C; stage_rc(tid * 16 + i * 8192, R, C); const int Rb = (R & ~31) + perm32(R & 31);
;         voffA[i] = P.a_rowoff(R) + (unsigned)C * 2u; voffB[i] = P.b_rowoff(Rb) + (unsigned)C * 2u; }
;     const size_t kstep = (size_t)(BK * 2);
;     const size_t hstepA = P.a_hstep(), hstepB = P.b_hstep();
;     const unsigned ldsw = (unsigned)wid * 1024u;
;     const unsigned ldsb = (unsigned)(size_t)lds + ldsw;
;     const int aoff = lds_byte(wr * 64 + fr, fq * 8), boff = lds_byte(wc * 32 + fr, fq * 8);
;     ...
;     Unit cur, nxt; int ui = 0;
;     if (!P.next(0, cur)) return;
;     Acc acc;
; #pragma unroll
;     for (int a = 0; a < 2; ++a)
; #pragma unroll
;         for (int b = 0; b < 2; ++b)
; #pragma unroll
;             for (int m = 0; m < 4; ++m)
; #pragma unroll
;                 for (int n = 0; n < 2; ++n) acc[a][b][m][n] = (f32x4){0.f, 0.f, 0.f, 0.f};
;     h16x8 At[4][2], B0[2][2], B1[2][2];
;     const char* cA = P.a_tile(cur); const char* cB = P.b_tile(cur);
;     if constexpr (SP2) {
;         PG8_STAGE(PG8_SB(0, 0), cB, voffB); PG8_STAGE(PG8_SB(0, 1), cB + hstepB, voffB); PG8_STAGE(PG8_SA(0, 0), cA, voffA); PG8_STAGE(PG8_SA(0, 1), cA + hstepA, voffA);
;         if (wr == 1) PG8_BAR;
;         PG8_WAIT_V(2); PG8_BAR;
;         PG8_STAGE(PG8_SB(1, 0), cB + kstep, voffB); PG8_STAGE(PG8_SA(1, 0), cA + kstep, voffA); PG8_STAGE(PG8_SB(1, 1), cB + hstepB + kstep, voffB);
;         PG8_WAIT_V(6); PG8_BAR;
.LBB0_1056:
	v_readlane_b32 s0, v254, 42
	v_readlane_b32 s4, v252, 23
	s_waitcnt lgkmcnt(0)
	s_barrier
	s_add_u32 s14, s30, 0x2d200000
	v_mbcnt_lo_u32_b32 v0, -1, 0
	v_mbcnt_hi_u32_b32 v0, -1, v0
	v_readlane_b32 s5, v252, 24
	v_add_u32_e32 v1, s0, v0
	s_addc_u32 s15, s31, 0
	v_readfirstlane_b32 s0, v1
	s_and_b64 vcc, exec, s[4:5]
	s_cbranch_vccz .LBB0_1088
	v_ashrrev_i32_e32 v3, 31, v1
	v_lshrrev_b32_e32 v3, 26, v3
	v_lshlrev_b32_e32 v2, 4, v1
	v_add_u32_e32 v3, v1, v3
	v_bfe_i32 v1, v1, 27, 1
	v_lshrrev_b32_e32 v1, 22, v1
	v_add_u32_e32 v1, v2, v1
	v_and_b32_e32 v1, 0xfffffc00, v1
	v_sub_u32_e32 v1, v2, v1
	v_lshrrev_b32_e32 v4, 4, v1
	v_bitop3_b32 v1, v4, v1, 32 bitop3:0x6c
	v_ashrrev_i32_e32 v5, 31, v1
	v_ashrrev_i32_e32 v3, 6, v3
	v_lshrrev_b32_e32 v5, 26, v5
	v_lshlrev_b32_e32 v4, 3, v3
	v_add_u32_e32 v5, v1, v5
	v_and_b32_e32 v4, -16, v4
	v_ashrrev_i32_e32 v6, 6, v5
	v_add_u32_e32 v4, v6, v4
	v_and_b32_e32 v5, 0xc0, v5
	v_sub_u32_e32 v1, v1, v5
	v_lshlrev_b32_e32 v5, 1, v4
	v_lshrrev_b32_e32 v8, 2, v4
	v_and_b32_e32 v6, 3, v6
	s_mov_b32 s1, 0x1fffe0
	v_mov_b32_e32 v9, 1
	v_and_b32_e32 v7, 24, v5
	v_and_b32_e32 v8, 4, v8
	v_and_or_b32 v6, v4, s1, v6
	v_lshlrev_b32_e32 v3, 5, v3
	v_ashrrev_i16_sdwa v1, v9, sext(v1) dst_sel:DWORD dst_unused:UNUSED_PAD src0_sel:DWORD src1_sel:BYTE_0
	v_or3_b32 v6, v6, v8, v7
	v_lshlrev_b32_e32 v7, 3, v4
	v_and_b32_e32 v3, 32, v3
	v_bfe_i32 v1, v1, 0, 16
	v_and_b32_e32 v5, 0x1fff80, v5
	v_and_b32_e32 v7, 0x78, v7
	v_bfe_u32 v4, v4, 4, 2
	v_or3_b32 v4, v5, v7, v4
	v_add_lshl_u32 v1, v3, v1, 1
	v_lshl_add_u32 v250, v4, 11, v1
	v_lshl_add_u32 v217, v6, 11, v1
	v_add_u32_e32 v1, 0x2000, v2
	v_ashrrev_i32_e32 v2, 31, v1
	v_lshrrev_b32_e32 v2, 22, v2
	v_add_u32_e32 v2, v1, v2
	v_ashrrev_i32_e32 v2, 10, v2
	v_mul_i32_i24_e32 v3, 0x400, v2
	v_sub_u32_e32 v1, v1, v3
	v_lshrrev_b32_e32 v3, 4, v1
	v_bitop3_b32 v1, v3, v1, 32 bitop3:0x6c
	v_ashrrev_i32_e32 v4, 31, v1
	v_lshrrev_b32_e32 v4, 26, v4
	v_lshlrev_b32_e32 v3, 3, v2
	v_add_u32_e32 v4, v1, v4
	v_and_b32_e32 v3, -16, v3
	v_ashrrev_i32_e32 v5, 6, v4
	v_add_u32_e32 v3, v5, v3
	v_and_b32_e32 v5, 3, v5
	v_and_b32_e32 v4, 0xc0, v4
	v_and_or_b32 v5, v3, s1, v5
	s_ashr_i32 s1, s0, 6
	v_sub_u32_e32 v1, v1, v4
	s_lshl_b32 s2, s1, 10
	s_ashr_i32 s64, s0, 8
	v_lshlrev_b32_e32 v2, 5, v2
	v_ashrrev_i16_sdwa v1, v9, sext(v1) dst_sel:DWORD dst_unused:UNUSED_PAD src0_sel:DWORD src1_sel:BYTE_0
	v_lshlrev_b32_e32 v4, 1, v3
	v_lshrrev_b32_e32 v7, 2, v3
	s_add_i32 s72, s2, 0
	v_readlane_b32 s4, v252, 48
	v_and_b32_e32 v2, 32, v2
	v_bfe_i32 v1, v1, 0, 16
	v_and_b32_e32 v6, 24, v4
	v_and_b32_e32 v7, 4, v7
	v_readlane_b32 s5, v252, 49
	s_add_u32 s44, s79, s4
	v_or3_b32 v5, v5, v7, v6
	v_add_lshl_u32 v1, v2, v1, 1
	s_addc_u32 s45, s40, s5
	s_add_i32 s73, s72, 0x10000
	s_mov_b32 s2, m0
	s_mov_b32 m0, s73
	s_nop 0
	global_load_lds_dwordx4 v217, s[44:45]
	s_mov_b32 m0, s2
	s_add_i32 s74, s72, 0x12000
	v_lshl_add_u32 v248, v5, 11, v1
	s_mov_b32 s2, m0
	s_mov_b32 m0, s74
	s_nop 0
	global_load_lds_dwordx4 v248, s[44:45]
	s_mov_b32 m0, s2
	s_add_u32 s4, s44, 0x40000
	s_addc_u32 s5, s45, 0
	s_add_i32 s75, s72, 0x14000
	s_mov_b32 s2, m0
	s_mov_b32 m0, s75
	s_nop 0
	global_load_lds_dwordx4 v217, s[4:5]
	s_mov_b32 m0, s2
	v_lshlrev_b32_e32 v6, 3, v3
	s_add_i32 s80, s72, 0x16000
	s_mov_b32 s2, m0
	s_mov_b32 m0, s80
	s_nop 0
	global_load_lds_dwordx4 v248, s[4:5]
	s_mov_b32 m0, s2
	v_readlane_b32 s4, v252, 56
	v_and_b32_e32 v4, 0x1fff80, v4
	v_and_b32_e32 v6, 0x78, v6
	v_bfe_u32 v3, v3, 4, 2
	v_readlane_b32 s5, v252, 57
	s_add_u32 s60, s41, s4
	v_or3_b32 v3, v4, v6, v3
	s_addc_u32 s61, s19, s5
	s_mov_b32 s2, m0
	s_mov_b32 m0, s72
	s_nop 0
	global_load_lds_dwordx4 v250, s[60:61]
	s_mov_b32 m0, s2
	s_add_i32 s81, s72, 0x2000
	v_lshl_add_u32 v247, v3, 11, v1
	s_mov_b32 s2, m0
	s_mov_b32 m0, s81
	s_nop 0
	global_load_lds_dwordx4 v247, s[60:61]
	s_mov_b32 m0, s2
	s_add_u32 s4, s60, 0x2000
	s_addc_u32 s5, s61, 0
	s_add_i32 s82, s72, 0x4000
	s_mov_b32 s2, m0
	s_mov_b32 m0, s82
	s_nop 0
	global_load_lds_dwordx4 v250, s[4:5]
	s_mov_b32 m0, s2
	s_add_i32 s83, s72, 0x6000
	s_mov_b32 s2, m0
	s_mov_b32 m0, s83
	s_nop 0
	global_load_lds_dwordx4 v247, s[4:5]
	s_mov_b32 m0, s2
	s_cmp_eq_u32 s64, 1
	s_cselect_b64 s[16:17], -1, 0
	s_cmp_lg_u32 s64, 1
	s_cbranch_scc1 .LBB0_1059
	s_barrier
	s_setprio 1

; #define PG8_STAGE(bufoff, gbase, voff) do { _Pragma("unroll") for (int _i = 0; _i < 2; ++_i) glds16_s((gbase), (voff)[_i], ldsb + (unsigned)((bufoff) + _i * 8192)); } while (0)
; #define PG8_LDA(dst, b, h) do { _Pragma("unroll") for (int m = 0; m < 4; ++m) _Pragma("unroll") for (int k = 0; k < 2; ++k) dst[m][k] = *(const LAS h16x8*)(lds + PG8_SA(b, h) + aoff + m * 2048 + k * 1024); } while (0)
; #define PG8_LDB(dst, b, h) do { _Pragma("unroll") for (int n = 0; n < 2; ++n) _Pragma("unroll") for (int k = 0; k < 2; ++k) dst[n][k] = *(const LAS h16x8*)(lds + PG8_SB(b, h) + boff + n * 2048 + k * 1024); } while (0)
; #define PG8_MMA(ai, bj, At, Bt) do { __builtin_amdgcn_s_setprio(1); _Pragma("unroll") for (int m = 0; m < 4; ++m) _Pragma("unroll") for (int n = 0; n < 2; ++n) _Pragma("unroll") for (int k = 0; k < 2; ++k) \
;         acc[ai][bj][m][n] = mma_step<I8>(Bt[n][k], At[m][k], acc[ai][bj][m][n]); __builtin_amdgcn_s_setprio(0); } while (0)
; #define PG8_WAIT_V(n) asm volatile("s_waitcnt vmcnt(" #n ")" ::: "memory")
; #define PG8_WAIT_L(n) asm volatile("s_waitcnt lgkmcnt(" #n ")" ::: "memory")
; #define PG8_BAR __builtin_amdgcn_s_barrier()
; #define PG8_SCHED __builtin_amdgcn_sched_barrier(0)
; template <class Prob, class Epi, bool I8 = false, bool ALIGN_EPI = true, bool SP2 = true>
; __device__ __forceinline__ void gemm_phase(LAS unsigned char* lds, int wave, const Prob& P, const Epi& E) {
;     ...
;             PG8_LDB(B0, 0, 0); PG8_LDB(B1, 0, 1); PG8_SCHED; PG8_LDA(At, 0, 0); PG8_STAGE(PG8_SA(1, 1), a1 + hstepA, voffA);
;             PG8_WAIT_V(8); PG8_WAIT_L(0); PG8_BAR; PG8_MMA(0, 0, At, B0); PG8_MMA(0, 1, At, B1); PG8_BAR; PG8_SCHED;
;             PG8_LDA(At, 0, 1); PG8_STAGE(PG8_SB(0, 0), b2, voffB); PG8_STAGE(PG8_SB(0, 1), b2 + hstepB, voffB); PG8_STAGE(PG8_SA(0, 0), a2, voffA);
;             PG8_WAIT_V(8); PG8_WAIT_L(0); PG8_BAR; PG8_MMA(1, 0, At, B0); PG8_MMA(1, 1, At, B1); PG8_BAR; PG8_SCHED;
.Lpeel_1065:
	v_add_u32_e32 v124, 0x10000, v210
	v_add_u32_e32 v140, 0x14000, v210
	ds_read_b128 v[104:107], v124
	ds_read_b128 v[112:115], v124 offset:1024
	ds_read_b128 v[120:123], v124 offset:2048
	ds_read_b128 v[124:127], v124 offset:3072
	ds_read_b128 v[128:131], v140
	ds_read_b128 v[132:135], v140 offset:1024
	ds_read_b128 v[136:139], v140 offset:2048
	ds_read_b128 v[140:143], v140 offset:3072
	s_cmp_eq_u32 s4, 12
	s_cselect_b32 s62, s96, vcc_lo
	s_cselect_b32 s63, s51, vcc_hi
	s_cselect_b32 s68, s97, s0
	s_cselect_b32 s69, s49, s1
	s_add_u32 s60, s62, 0x80
	s_addc_u32 s61, s63, 0
	ds_read_b128 v[144:147], v211
	ds_read_b128 v[164:167], v211 offset:1024
	ds_read_b128 v[168:171], v211 offset:2048
	ds_read_b128 v[172:175], v211 offset:3072
	ds_read_b128 v[176:179], v211 offset:4096
	ds_read_b128 v[180:183], v211 offset:5120
	ds_read_b128 v[184:187], v211 offset:6144
	ds_read_b128 v[188:191], v211 offset:7168
	s_mov_b32 s5, m0
	s_mov_b32 m0, s90
	s_nop 0
	global_load_lds_dwordx4 v250, s[44:45]
	s_mov_b32 m0, s5
	s_nop 0
	s_mov_b32 s5, m0
	s_mov_b32 m0, s92
	s_nop 0
	global_load_lds_dwordx4 v247, s[44:45]
	s_mov_b32 m0, s5
	s_waitcnt vmcnt(8)
	s_waitcnt lgkmcnt(0)
	s_barrier
	s_waitcnt lgkmcnt(7)
	v_mfma_i32_16x16x64_i8 v[160:163], v[104:107], v[144:147], 0
	v_mfma_i32_16x16x64_i8 v[152:155], v[120:123], v[144:147], 0
	s_waitcnt lgkmcnt(5)
	v_mfma_i32_16x16x64_i8 v[52:55], v[104:107], v[168:171], 0
	v_mfma_i32_16x16x64_i8 v[80:83], v[120:123], v[168:171], 0
	s_waitcnt lgkmcnt(3)
	v_mfma_i32_16x16x64_i8 v[48:51], v[104:107], v[176:179], 0
	v_mfma_i32_16x16x64_i8 v[72:75], v[120:123], v[176:179], 0
	s_waitcnt lgkmcnt(1)
	v_mfma_i32_16x16x64_i8 v[44:47], v[104:107], v[184:187], 0
	v_mfma_i32_16x16x64_i8 v[68:71], v[120:123], v[184:187], 0
	v_mfma_i32_16x16x64_i8 v[160:163], v[112:115], v[164:167], v[160:163]
	v_mfma_i32_16x16x64_i8 v[152:155], v[124:127], v[164:167], v[152:155]
	v_mfma_i32_16x16x64_i8 v[52:55], v[112:115], v[172:175], v[52:55]
	v_mfma_i32_16x16x64_i8 v[80:83], v[124:127], v[172:175], v[80:83]
	v_mfma_i32_16x16x64_i8 v[48:51], v[112:115], v[180:183], v[48:51]
	v_mfma_i32_16x16x64_i8 v[72:75], v[124:127], v[180:183], v[72:75]
	s_waitcnt lgkmcnt(0)
	v_mfma_i32_16x16x64_i8 v[44:47], v[112:115], v[188:191], v[44:47]
	v_mfma_i32_16x16x64_i8 v[68:71], v[124:127], v[188:191], v[68:71]
	v_mfma_i32_16x16x64_i8 v[116:119], v[128:131], v[144:147], 0
	v_mfma_i32_16x16x64_i8 v[28:31], v[136:139], v[144:147], 0
	v_mfma_i32_16x16x64_i8 v[100:103], v[128:131], v[168:171], 0
	v_mfma_i32_16x16x64_i8 v[24:27], v[136:139], v[168:171], 0
	v_mfma_i32_16x16x64_i8 v[96:99], v[128:131], v[176:179], 0
	v_mfma_i32_16x16x64_i8 v[20:23], v[136:139], v[176:179], 0
	v_mfma_i32_16x16x64_i8 v[92:95], v[128:131], v[184:187], 0
	v_mfma_i32_16x16x64_i8 v[16:19], v[136:139], v[184:187], 0
	v_mfma_i32_16x16x64_i8 v[116:119], v[132:135], v[164:167], v[116:119]
	v_mfma_i32_16x16x64_i8 v[28:31], v[140:143], v[164:167], v[28:31]
	v_mfma_i32_16x16x64_i8 v[100:103], v[132:135], v[172:175], v[100:103]
	v_mfma_i32_16x16x64_i8 v[24:27], v[140:143], v[172:175], v[24:27]
	v_mfma_i32_16x16x64_i8 v[96:99], v[132:135], v[180:183], v[96:99]
	v_mfma_i32_16x16x64_i8 v[20:23], v[140:143], v[180:183], v[20:23]
	v_mfma_i32_16x16x64_i8 v[92:95], v[132:135], v[188:191], v[92:95]
	v_mfma_i32_16x16x64_i8 v[16:19], v[140:143], v[188:191], v[16:19]
	s_barrier
	ds_read_b128 v[144:147], v211 offset:16384
	ds_read_b128 v[164:167], v211 offset:17408
	ds_read_b128 v[168:171], v211 offset:18432
	ds_read_b128 v[172:175], v211 offset:19456
	ds_read_b128 v[176:179], v211 offset:20480
	ds_read_b128 v[180:183], v211 offset:21504
	ds_read_b128 v[184:187], v211 offset:22528
	ds_read_b128 v[188:191], v211 offset:23552
	s_mov_b32 s5, m0
	s_mov_b32 m0, s73
	s_nop 0
	global_load_lds_dwordx4 v217, s[68:69]
	s_mov_b32 m0, s5
	s_add_u32 s6, s68, 0x40000
	s_mov_b32 s5, m0
	s_mov_b32 m0, s74
	s_nop 0
	global_load_lds_dwordx4 v248, s[68:69]
	s_mov_b32 m0, s5
	s_addc_u32 s7, s69, 0
	s_mov_b32 s5, m0
	s_mov_b32 m0, s75
	s_nop 0
	global_load_lds_dwordx4 v217, s[6:7]
	s_mov_b32 m0, s5
	s_nop 0
	s_mov_b32 s5, m0
	s_mov_b32 m0, s80
	s_nop 0
	global_load_lds_dwordx4 v248, s[6:7]
	s_mov_b32 m0, s5
	s_nop 0
	s_mov_b32 s5, m0
	s_mov_b32 m0, s72
	s_nop 0
	global_load_lds_dwordx4 v250, s[62:63]
	s_mov_b32 m0, s5
	s_nop 0
	s_mov_b32 s5, m0
	s_mov_b32 m0, s81
	s_nop 0
	global_load_lds_dwordx4 v247, s[62:63]
	s_mov_b32 m0, s5
	s_waitcnt vmcnt(8)
	s_waitcnt lgkmcnt(0)
	s_barrier
	s_waitcnt lgkmcnt(7)
	v_mfma_i32_16x16x64_i8 v[40:43], v[104:107], v[144:147], 0
	v_mfma_i32_16x16x64_i8 v[64:67], v[120:123], v[144:147], 0
	s_waitcnt lgkmcnt(5)
	v_mfma_i32_16x16x64_i8 v[36:39], v[104:107], v[168:171], 0
	v_mfma_i32_16x16x64_i8 v[60:63], v[120:123], v[168:171], 0
	s_waitcnt lgkmcnt(3)
	v_mfma_i32_16x16x64_i8 v[32:35], v[104:107], v[176:179], 0
	v_mfma_i32_16x16x64_i8 v[56:59], v[120:123], v[176:179], 0
	s_waitcnt lgkmcnt(1)
	v_mfma_i32_16x16x64_i8 v[104:107], v[104:107], v[184:187], 0
	v_mfma_i32_16x16x64_i8 v[40:43], v[112:115], v[164:167], v[40:43]
	v_mfma_i32_16x16x64_i8 v[64:67], v[124:127], v[164:167], v[64:67]
	v_mfma_i32_16x16x64_i8 v[36:39], v[112:115], v[172:175], v[36:39]
	v_mfma_i32_16x16x64_i8 v[60:63], v[124:127], v[172:175], v[60:63]
	v_mfma_i32_16x16x64_i8 v[32:35], v[112:115], v[180:183], v[32:35]
	v_mfma_i32_16x16x64_i8 v[56:59], v[124:127], v[180:183], v[56:59]
	s_waitcnt lgkmcnt(0)
	v_mfma_i32_16x16x64_i8 v[104:107], v[112:115], v[188:191], v[104:107]
	v_mfma_i32_16x16x64_i8 v[112:115], v[120:123], v[184:187], 0
	v_mfma_i32_16x16x64_i8 v[112:115], v[124:127], v[188:191], v[112:115]
	v_mfma_i32_16x16x64_i8 v[88:91], v[128:131], v[144:147], 0
	v_mfma_i32_16x16x64_i8 v[12:15], v[136:139], v[144:147], 0
	v_mfma_i32_16x16x64_i8 v[84:87], v[128:131], v[168:171], 0
	v_mfma_i32_16x16x64_i8 v[8:11], v[136:139], v[168:171], 0
	v_mfma_i32_16x16x64_i8 v[76:79], v[128:131], v[176:179], 0
	v_mfma_i32_16x16x64_i8 v[4:7], v[136:139], v[176:179], 0
	v_mfma_i32_16x16x64_i8 v[108:111], v[128:131], v[184:187], 0
	v_mfma_i32_16x16x64_i8 v[0:3], v[136:139], v[184:187], 0
	v_mfma_i32_16x16x64_i8 v[88:91], v[132:135], v[164:167], v[88:91]
	v_mfma_i32_16x16x64_i8 v[12:15], v[140:143], v[164:167], v[12:15]
	v_mfma_i32_16x16x64_i8 v[84:87], v[132:135], v[172:175], v[84:87]
	v_mfma_i32_16x16x64_i8 v[8:11], v[140:143], v[172:175], v[8:11]
	v_mfma_i32_16x16x64_i8 v[76:79], v[132:135], v[180:183], v[76:79]
	v_mfma_i32_16x16x64_i8 v[4:7], v[140:143], v[180:183], v[4:7]
	v_mfma_i32_16x16x64_i8 v[108:111], v[132:135], v[188:191], v[108:111]
	v_mfma_i32_16x16x64_i8 v[0:3], v[140:143], v[188:191], v[0:3]
	s_barrier
; #define PG8_STAGE(bufoff, gbase, voff) do { _Pragma("unroll") for (int _i = 0; _i < 2; ++_i) glds16_s((gbase), (voff)[_i], ldsb + (unsigned)((bufoff) + _i * 8192)); } while (0)
; #define PG8_LDA(dst, b, h) do { _Pragma("unroll") for (int m = 0; m < 4; ++m) _Pragma("unroll") for (int k = 0; k < 2; ++k) dst[m][k] = *(const LAS h16x8*)(lds + PG8_SA(b, h) + aoff + m * 2048 + k * 1024); } while (0)
; #define PG8_LDB(dst, b, h) do { _Pragma("unroll") for (int n = 0; n < 2; ++n) _Pragma("unroll") for (int k = 0; k < 2; ++k) dst[n][k] = *(const LAS h16x8*)(lds + PG8_SB(b, h) + boff + n * 2048 + k * 1024); } while (0)
; #define PG8_MMA(ai, bj, At, Bt) do { __builtin_amdgcn_s_setprio(1); _Pragma("unroll") for (int m = 0; m < 4; ++m) _Pragma("unroll") for (int n = 0; n < 2; ++n) _Pragma("unroll") for (int k = 0; k < 2; ++k) \
;         acc[ai][bj][m][n] = mma_step<I8>(Bt[n][k], At[m][k], acc[ai][bj][m][n]); __builtin_amdgcn_s_setprio(0); } while (0)
; #define PG8_WAIT_V(n) asm volatile("s_waitcnt vmcnt(" #n ")" ::: "memory")
; #define PG8_WAIT_L(n) asm volatile("s_waitcnt lgkmcnt(" #n ")" ::: "memory")
; #define PG8_BAR __builtin_amdgcn_s_barrier()
; #define PG8_SCHED __builtin_amdgcn_sched_barrier(0)
; template <class Prob, class Epi, bool I8 = false, bool ALIGN_EPI = true, bool SP2 = true>
; __device__ __forceinline__ void gemm_phase(LAS unsigned char* lds, int wave, const Prob& P, const Epi& E) {
;     ...
;             PG8_LDB(B0, 1, 0); PG8_LDB(B1, 1, 1); PG8_SCHED; PG8_LDA(At, 1, 0); PG8_STAGE(PG8_SA(0, 1), a2 + hstepA, voffA);
;             PG8_WAIT_V(8); PG8_WAIT_L(0); PG8_BAR; PG8_MMA(0, 0, At, B0); PG8_MMA(0, 1, At, B1); PG8_BAR; PG8_SCHED;
;             PG8_LDA(At, 1, 1); PG8_STAGE(PG8_SB(1, 0), b3, voffB); PG8_STAGE(PG8_SB(1, 1), b3 + hstepB, voffB); PG8_STAGE(PG8_SA(1, 0), a3, voffA);
;             PG8_WAIT_V(8); PG8_WAIT_L(0); PG8_BAR; PG8_MMA(1, 0, At, B0); PG8_MMA(1, 1, At, B1); PG8_BAR; PG8_SCHED;
	v_add_u32_e32 v132, 0x18000, v210
	v_add_u32_e32 v148, 0x1c000, v210
	ds_read_b128 v[120:123], v132
	ds_read_b128 v[124:127], v132 offset:1024
	ds_read_b128 v[128:131], v132 offset:2048
	ds_read_b128 v[132:135], v132 offset:3072
	ds_read_b128 v[136:139], v148
	ds_read_b128 v[140:143], v148 offset:1024
	ds_read_b128 v[144:147], v148 offset:2048
	ds_read_b128 v[164:167], v148 offset:3072
	ds_read_b128 v[148:151], v211 offset:32768
	ds_read_b128 v[156:159], v211 offset:33792
	ds_read_b128 v[168:171], v211 offset:34816
	ds_read_b128 v[172:175], v211 offset:35840
	ds_read_b128 v[176:179], v211 offset:36864
	ds_read_b128 v[180:183], v211 offset:37888
	ds_read_b128 v[184:187], v211 offset:38912
	ds_read_b128 v[188:191], v211 offset:39936
	s_add_u32 s6, s62, 0x2000
	s_addc_u32 s7, s63, 0
	s_mov_b32 s5, m0
	s_mov_b32 m0, s82
	s_nop 0
	global_load_lds_dwordx4 v250, s[6:7]
	s_mov_b32 m0, s5
	s_nop 0
	s_mov_b32 s5, m0
	s_mov_b32 m0, s83
	s_nop 0
	global_load_lds_dwordx4 v247, s[6:7]
	s_mov_b32 m0, s5
	s_waitcnt vmcnt(8)
	s_waitcnt lgkmcnt(0)
	s_barrier
	s_waitcnt lgkmcnt(7)
	v_mfma_i32_16x16x64_i8 v[160:163], v[120:123], v[148:151], v[160:163]
	v_mfma_i32_16x16x64_i8 v[152:155], v[128:131], v[148:151], v[152:155]
	s_waitcnt lgkmcnt(5)
	v_mfma_i32_16x16x64_i8 v[52:55], v[120:123], v[168:171], v[52:55]
	v_mfma_i32_16x16x64_i8 v[80:83], v[128:131], v[168:171], v[80:83]
	s_waitcnt lgkmcnt(3)
	v_mfma_i32_16x16x64_i8 v[48:51], v[120:123], v[176:179], v[48:51]
	v_mfma_i32_16x16x64_i8 v[72:75], v[128:131], v[176:179], v[72:75]
	s_waitcnt lgkmcnt(1)
	v_mfma_i32_16x16x64_i8 v[44:47], v[120:123], v[184:187], v[44:47]
	v_mfma_i32_16x16x64_i8 v[68:71], v[128:131], v[184:187], v[68:71]
	v_mfma_i32_16x16x64_i8 v[160:163], v[124:127], v[156:159], v[160:163]
	v_mfma_i32_16x16x64_i8 v[152:155], v[132:135], v[156:159], v[152:155]
	v_mfma_i32_16x16x64_i8 v[52:55], v[124:127], v[172:175], v[52:55]
	v_mfma_i32_16x16x64_i8 v[80:83], v[132:135], v[172:175], v[80:83]
	v_mfma_i32_16x16x64_i8 v[48:51], v[124:127], v[180:183], v[48:51]
	v_mfma_i32_16x16x64_i8 v[72:75], v[132:135], v[180:183], v[72:75]
	s_waitcnt lgkmcnt(0)
	v_mfma_i32_16x16x64_i8 v[44:47], v[124:127], v[188:191], v[44:47]
	v_mfma_i32_16x16x64_i8 v[68:71], v[132:135], v[188:191], v[68:71]
	v_mfma_i32_16x16x64_i8 v[116:119], v[136:139], v[148:151], v[116:119]
	v_mfma_i32_16x16x64_i8 v[28:31], v[144:147], v[148:151], v[28:31]
	v_mfma_i32_16x16x64_i8 v[100:103], v[136:139], v[168:171], v[100:103]
	v_mfma_i32_16x16x64_i8 v[24:27], v[144:147], v[168:171], v[24:27]
	v_mfma_i32_16x16x64_i8 v[96:99], v[136:139], v[176:179], v[96:99]
	v_mfma_i32_16x16x64_i8 v[20:23], v[144:147], v[176:179], v[20:23]
	v_mfma_i32_16x16x64_i8 v[92:95], v[136:139], v[184:187], v[92:95]
	v_mfma_i32_16x16x64_i8 v[16:19], v[144:147], v[184:187], v[16:19]
	v_mfma_i32_16x16x64_i8 v[116:119], v[140:143], v[156:159], v[116:119]
	v_mfma_i32_16x16x64_i8 v[28:31], v[164:167], v[156:159], v[28:31]
	v_mfma_i32_16x16x64_i8 v[100:103], v[140:143], v[172:175], v[100:103]
	v_mfma_i32_16x16x64_i8 v[24:27], v[164:167], v[172:175], v[24:27]
	v_mfma_i32_16x16x64_i8 v[96:99], v[140:143], v[180:183], v[96:99]
	v_mfma_i32_16x16x64_i8 v[20:23], v[164:167], v[180:183], v[20:23]
	v_mfma_i32_16x16x64_i8 v[92:95], v[140:143], v[188:191], v[92:95]
	v_mfma_i32_16x16x64_i8 v[16:19], v[164:167], v[188:191], v[16:19]
	s_barrier
	ds_read_b128 v[168:171], v211 offset:49152
	ds_read_b128 v[172:175], v211 offset:50176
	ds_read_b128 v[176:179], v211 offset:51200
	ds_read_b128 v[180:183], v211 offset:52224
	ds_read_b128 v[184:187], v211 offset:53248
	ds_read_b128 v[188:191], v211 offset:54272
	ds_read_b128 v[192:195], v211 offset:55296
	ds_read_b128 v[196:199], v211 offset:56320
	s_add_u32 s6, s68, 0x80
	s_addc_u32 s7, s69, 0
	s_mov_b32 s5, m0
	s_mov_b32 m0, s2
	s_nop 0
	global_load_lds_dwordx4 v217, s[6:7]
	s_mov_b32 m0, s5
	s_nop 0
	s_mov_b32 s5, m0
	s_mov_b32 m0, s85
	s_nop 0
	global_load_lds_dwordx4 v248, s[6:7]
	s_mov_b32 m0, s5
	s_add_u32 s6, s68, 0x40080
	s_addc_u32 s7, s69, 0
	s_mov_b32 s5, m0
	s_mov_b32 m0, s88
	s_nop 0
	global_load_lds_dwordx4 v217, s[6:7]
	s_mov_b32 m0, s5
	s_nop 0
	s_mov_b32 s5, m0
	s_mov_b32 m0, s89
	s_nop 0
	global_load_lds_dwordx4 v248, s[6:7]
	s_mov_b32 m0, s5
	s_nop 0
	s_mov_b32 s5, m0
	s_mov_b32 m0, s86
	s_nop 0
	global_load_lds_dwordx4 v250, s[60:61]
	s_mov_b32 m0, s5
	s_nop 0
	s_mov_b32 s5, m0
	s_mov_b32 m0, s87
	s_nop 0
	global_load_lds_dwordx4 v247, s[60:61]
	s_mov_b32 m0, s5
	s_waitcnt vmcnt(8)
	s_waitcnt lgkmcnt(0)
	s_barrier
	s_waitcnt lgkmcnt(1)
	v_mfma_i32_16x16x64_i8 v[104:107], v[120:123], v[192:195], v[104:107]
	v_mfma_i32_16x16x64_i8 v[40:43], v[120:123], v[168:171], v[40:43]
	v_mfma_i32_16x16x64_i8 v[64:67], v[128:131], v[168:171], v[64:67]
	v_mfma_i32_16x16x64_i8 v[36:39], v[120:123], v[176:179], v[36:39]
	v_mfma_i32_16x16x64_i8 v[60:63], v[128:131], v[176:179], v[60:63]
	v_mfma_i32_16x16x64_i8 v[32:35], v[120:123], v[184:187], v[32:35]
	v_mfma_i32_16x16x64_i8 v[56:59], v[128:131], v[184:187], v[56:59]
	s_waitcnt lgkmcnt(0)
	v_mfma_i32_16x16x64_i8 v[156:159], v[124:127], v[196:199], v[104:107]
	v_mfma_i32_16x16x64_i8 v[104:107], v[128:131], v[192:195], v[112:115]
	v_mfma_i32_16x16x64_i8 v[40:43], v[124:127], v[172:175], v[40:43]
	v_mfma_i32_16x16x64_i8 v[64:67], v[132:135], v[172:175], v[64:67]
	v_mfma_i32_16x16x64_i8 v[36:39], v[124:127], v[180:183], v[36:39]
	v_mfma_i32_16x16x64_i8 v[60:63], v[132:135], v[180:183], v[60:63]
	v_mfma_i32_16x16x64_i8 v[32:35], v[124:127], v[188:191], v[32:35]
	v_mfma_i32_16x16x64_i8 v[56:59], v[132:135], v[188:191], v[56:59]
	v_mfma_i32_16x16x64_i8 v[148:151], v[132:135], v[196:199], v[104:107]
	v_mfma_i32_16x16x64_i8 v[88:91], v[136:139], v[168:171], v[88:91]
	v_mfma_i32_16x16x64_i8 v[12:15], v[144:147], v[168:171], v[12:15]
	v_mfma_i32_16x16x64_i8 v[84:87], v[136:139], v[176:179], v[84:87]
	v_mfma_i32_16x16x64_i8 v[8:11], v[144:147], v[176:179], v[8:11]
	v_mfma_i32_16x16x64_i8 v[76:79], v[136:139], v[184:187], v[76:79]
	v_mfma_i32_16x16x64_i8 v[4:7], v[144:147], v[184:187], v[4:7]
	v_mfma_i32_16x16x64_i8 v[104:107], v[136:139], v[192:195], v[108:111]
	v_mfma_i32_16x16x64_i8 v[0:3], v[144:147], v[192:195], v[0:3]
	v_mfma_i32_16x16x64_i8 v[88:91], v[140:143], v[172:175], v[88:91]
	v_mfma_i32_16x16x64_i8 v[12:15], v[164:167], v[172:175], v[12:15]
	v_mfma_i32_16x16x64_i8 v[84:87], v[140:143], v[180:183], v[84:87]
	v_mfma_i32_16x16x64_i8 v[8:11], v[164:167], v[180:183], v[8:11]
	v_mfma_i32_16x16x64_i8 v[76:79], v[140:143], v[188:191], v[76:79]
	v_mfma_i32_16x16x64_i8 v[4:7], v[164:167], v[188:191], v[4:7]
	v_mfma_i32_16x16x64_i8 v[108:111], v[140:143], v[196:199], v[104:107]
	v_mfma_i32_16x16x64_i8 v[0:3], v[164:167], v[196:199], v[0:3]
	s_barrier
	s_add_i32 s4, s4, 2
	s_add_u32 vcc_lo, vcc_lo, 0x100
	s_addc_u32 vcc_hi, vcc_hi, 0
	s_add_u32 s0, s0, 0x100
	s_addc_u32 s1, s1, 0
	s_add_u32 s44, s44, 0x100
	s_addc_u32 s45, s45, 0
	s_cmp_gt_u32 s4, 13
; #define PG8_STAGE(bufoff, gbase, voff) do { _Pragma("unroll") for (int _i = 0; _i < 2; ++_i) glds16_s((gbase), (voff)[_i], ldsb + (unsigned)((bufoff) + _i * 8192)); } while (0)
; #define PG8_LDA(dst, b, h) do { _Pragma("unroll") for (int m = 0; m < 4; ++m) _Pragma("unroll") for (int k = 0; k < 2; ++k) dst[m][k] = *(const LAS h16x8*)(lds + PG8_SA(b, h) + aoff + m * 2048 + k * 1024); } while (0)
; #define PG8_LDB(dst, b, h) do { _Pragma("unroll") for (int n = 0; n < 2; ++n) _Pragma("unroll") for (int k = 0; k < 2; ++k) dst[n][k] = *(const LAS h16x8*)(lds + PG8_SB(b, h) + boff + n * 2048 + k * 1024); } while (0)
; #define PG8_MMA(ai, bj, At, Bt) do { __builtin_amdgcn_s_setprio(1); _Pragma("unroll") for (int m = 0; m < 4; ++m) _Pragma("unroll") for (int n = 0; n < 2; ++n) _Pragma("unroll") for (int k = 0; k < 2; ++k) \
;         acc[ai][bj][m][n] = mma_step<I8>(Bt[n][k], At[m][k], acc[ai][bj][m][n]); __builtin_amdgcn_s_setprio(0); } while (0)
; #define PG8_WAIT_V(n) asm volatile("s_waitcnt vmcnt(" #n ")" ::: "memory")
; #define PG8_WAIT_L(n) asm volatile("s_waitcnt lgkmcnt(" #n ")" ::: "memory")
; #define PG8_BAR __builtin_amdgcn_s_barrier()
; #define PG8_SCHED __builtin_amdgcn_sched_barrier(0)
; template <class Prob, class Epi, bool I8 = false, bool ALIGN_EPI = true, bool SP2 = true>
; __device__ __forceinline__ void gemm_phase(LAS unsigned char* lds, int wave, const Prob& P, const Epi& E) {
;     ...
;             PG8_LDB(B0, 0, 0); PG8_LDB(B1, 0, 1); PG8_SCHED; PG8_LDA(At, 0, 0); PG8_STAGE(PG8_SA(1, 1), a1 + hstepA, voffA);
;             PG8_WAIT_V(8); PG8_WAIT_L(0); PG8_BAR; PG8_MMA(0, 0, At, B0); PG8_MMA(0, 1, At, B1); PG8_BAR; PG8_SCHED;
;             PG8_LDA(At, 0, 1); PG8_STAGE(PG8_SB(0, 0), b2, voffB); PG8_STAGE(PG8_SB(0, 1), b2 + hstepB, voffB); PG8_STAGE(PG8_SA(0, 0), a2, voffA);
;             PG8_WAIT_V(8); PG8_WAIT_L(0); PG8_BAR; PG8_MMA(1, 0, At, B0); PG8_MMA(1, 1, At, B1); PG8_BAR; PG8_SCHED;
.LBB0_1065:
	v_add_u32_e32 v124, 0x10000, v210
	v_add_u32_e32 v140, 0x14000, v210
	ds_read_b128 v[104:107], v124
	ds_read_b128 v[112:115], v124 offset:1024
	ds_read_b128 v[120:123], v124 offset:2048
	ds_read_b128 v[124:127], v124 offset:3072
	ds_read_b128 v[128:131], v140
	ds_read_b128 v[132:135], v140 offset:1024
	ds_read_b128 v[136:139], v140 offset:2048
	ds_read_b128 v[140:143], v140 offset:3072
	s_cmp_eq_u32 s4, 12
	s_cselect_b32 s62, s96, vcc_lo
	s_cselect_b32 s63, s51, vcc_hi
	s_cselect_b32 s68, s97, s0
	s_cselect_b32 s69, s49, s1
	s_add_u32 s60, s62, 0x80
	s_addc_u32 s61, s63, 0
	ds_read_b128 v[144:147], v211
	ds_read_b128 v[164:167], v211 offset:1024
	ds_read_b128 v[168:171], v211 offset:2048
	ds_read_b128 v[172:175], v211 offset:3072
	ds_read_b128 v[176:179], v211 offset:4096
	ds_read_b128 v[180:183], v211 offset:5120
	ds_read_b128 v[184:187], v211 offset:6144
	ds_read_b128 v[188:191], v211 offset:7168
	s_mov_b32 s5, m0
	s_mov_b32 m0, s90
	s_nop 0
	global_load_lds_dwordx4 v250, s[44:45]
	s_mov_b32 m0, s5
	s_nop 0
	s_mov_b32 s5, m0
	s_mov_b32 m0, s92
	s_nop 0
	global_load_lds_dwordx4 v247, s[44:45]
	s_mov_b32 m0, s5
	s_waitcnt vmcnt(8)
	s_waitcnt lgkmcnt(0)
	s_barrier
	s_waitcnt lgkmcnt(7)
	v_mfma_i32_16x16x64_i8 v[160:163], v[104:107], v[144:147], v[160:163]
	v_mfma_i32_16x16x64_i8 v[152:155], v[120:123], v[144:147], v[152:155]
	s_waitcnt lgkmcnt(5)
	v_mfma_i32_16x16x64_i8 v[52:55], v[104:107], v[168:171], v[52:55]
	v_mfma_i32_16x16x64_i8 v[80:83], v[120:123], v[168:171], v[80:83]
	s_waitcnt lgkmcnt(3)
	v_mfma_i32_16x16x64_i8 v[48:51], v[104:107], v[176:179], v[48:51]
	v_mfma_i32_16x16x64_i8 v[72:75], v[120:123], v[176:179], v[72:75]
	s_waitcnt lgkmcnt(1)
	v_mfma_i32_16x16x64_i8 v[44:47], v[104:107], v[184:187], v[44:47]
	v_mfma_i32_16x16x64_i8 v[68:71], v[120:123], v[184:187], v[68:71]
	v_mfma_i32_16x16x64_i8 v[160:163], v[112:115], v[164:167], v[160:163]
	v_mfma_i32_16x16x64_i8 v[152:155], v[124:127], v[164:167], v[152:155]
	v_mfma_i32_16x16x64_i8 v[52:55], v[112:115], v[172:175], v[52:55]
	v_mfma_i32_16x16x64_i8 v[80:83], v[124:127], v[172:175], v[80:83]
	v_mfma_i32_16x16x64_i8 v[48:51], v[112:115], v[180:183], v[48:51]
	v_mfma_i32_16x16x64_i8 v[72:75], v[124:127], v[180:183], v[72:75]
	s_waitcnt lgkmcnt(0)
	v_mfma_i32_16x16x64_i8 v[44:47], v[112:115], v[188:191], v[44:47]
	v_mfma_i32_16x16x64_i8 v[68:71], v[124:127], v[188:191], v[68:71]
	v_mfma_i32_16x16x64_i8 v[116:119], v[128:131], v[144:147], v[116:119]
	v_mfma_i32_16x16x64_i8 v[28:31], v[136:139], v[144:147], v[28:31]
	v_mfma_i32_16x16x64_i8 v[100:103], v[128:131], v[168:171], v[100:103]
	v_mfma_i32_16x16x64_i8 v[24:27], v[136:139], v[168:171], v[24:27]
	v_mfma_i32_16x16x64_i8 v[96:99], v[128:131], v[176:179], v[96:99]
	v_mfma_i32_16x16x64_i8 v[20:23], v[136:139], v[176:179], v[20:23]
	v_mfma_i32_16x16x64_i8 v[92:95], v[128:131], v[184:187], v[92:95]
	v_mfma_i32_16x16x64_i8 v[16:19], v[136:139], v[184:187], v[16:19]
	v_mfma_i32_16x16x64_i8 v[116:119], v[132:135], v[164:167], v[116:119]
	v_mfma_i32_16x16x64_i8 v[28:31], v[140:143], v[164:167], v[28:31]
	v_mfma_i32_16x16x64_i8 v[100:103], v[132:135], v[172:175], v[100:103]
	v_mfma_i32_16x16x64_i8 v[24:27], v[140:143], v[172:175], v[24:27]
	v_mfma_i32_16x16x64_i8 v[96:99], v[132:135], v[180:183], v[96:99]
	v_mfma_i32_16x16x64_i8 v[20:23], v[140:143], v[180:183], v[20:23]
	v_mfma_i32_16x16x64_i8 v[92:95], v[132:135], v[188:191], v[92:95]
	v_mfma_i32_16x16x64_i8 v[16:19], v[140:143], v[188:191], v[16:19]
	s_barrier
	ds_read_b128 v[144:147], v211 offset:16384
	ds_read_b128 v[164:167], v211 offset:17408
	ds_read_b128 v[168:171], v211 offset:18432
	ds_read_b128 v[172:175], v211 offset:19456
	ds_read_b128 v[176:179], v211 offset:20480
	ds_read_b128 v[180:183], v211 offset:21504
	ds_read_b128 v[184:187], v211 offset:22528
	ds_read_b128 v[188:191], v211 offset:23552
	s_mov_b32 s5, m0
	s_mov_b32 m0, s73
	s_nop 0
	global_load_lds_dwordx4 v217, s[68:69]
	s_mov_b32 m0, s5
	s_add_u32 s6, s68, 0x40000
	s_mov_b32 s5, m0
	s_mov_b32 m0, s74
	s_nop 0
	global_load_lds_dwordx4 v248, s[68:69]
	s_mov_b32 m0, s5
	s_addc_u32 s7, s69, 0
	s_mov_b32 s5, m0
	s_mov_b32 m0, s75
	s_nop 0
	global_load_lds_dwordx4 v217, s[6:7]
	s_mov_b32 m0, s5
	s_nop 0
	s_mov_b32 s5, m0
	s_mov_b32 m0, s80
	s_nop 0
	global_load_lds_dwordx4 v248, s[6:7]
	s_mov_b32 m0, s5
	s_nop 0
	s_mov_b32 s5, m0
	s_mov_b32 m0, s72
	s_nop 0
	global_load_lds_dwordx4 v250, s[62:63]
	s_mov_b32 m0, s5
	s_nop 0
	s_mov_b32 s5, m0
	s_mov_b32 m0, s81
	s_nop 0
	global_load_lds_dwordx4 v247, s[62:63]
	s_mov_b32 m0, s5
	s_waitcnt vmcnt(8)
	s_waitcnt lgkmcnt(0)
	s_barrier
; #define PG8_STAGE(bufoff, gbase, voff) do { _Pragma("unroll") for (int _i = 0; _i < 2; ++_i) glds16_s((gbase), (voff)[_i], ldsb + (unsigned)((bufoff) + _i * 8192)); } while (0)
; #define PG8_LDA(dst, b, h) do { _Pragma("unroll") for (int m = 0; m < 4; ++m) _Pragma("unroll") for (int k = 0; k < 2; ++k) dst[m][k] = *(const LAS h16x8*)(lds + PG8_SA(b, h) + aoff + m * 2048 + k * 1024); } while (0)
; #define PG8_LDB(dst, b, h) do { _Pragma("unroll") for (int n = 0; n < 2; ++n) _Pragma("unroll") for (int k = 0; k < 2; ++k) dst[n][k] = *(const LAS h16x8*)(lds + PG8_SB(b, h) + boff + n * 2048 + k * 1024); } while (0)
; #define PG8_MMA(ai, bj, At, Bt) do { __builtin_amdgcn_s_setprio(1); _Pragma("unroll") for (int m = 0; m < 4; ++m) _Pragma("unroll") for (int n = 0; n < 2; ++n) _Pragma("unroll") for (int k = 0; k < 2; ++k) \
;         acc[ai][bj][m][n] = mma_step<I8>(Bt[n][k], At[m][k], acc[ai][bj][m][n]); __builtin_amdgcn_s_setprio(0); } while (0)
; #define PG8_WAIT_V(n) asm volatile("s_waitcnt vmcnt(" #n ")" ::: "memory")
; #define PG8_WAIT_L(n) asm volatile("s_waitcnt lgkmcnt(" #n ")" ::: "memory")
; #define PG8_BAR __builtin_amdgcn_s_barrier()
; #define PG8_SCHED __builtin_amdgcn_sched_barrier(0)
; template <class Prob, class Epi, bool I8 = false, bool ALIGN_EPI = true, bool SP2 = true>
; __device__ __forceinline__ void gemm_phase(LAS unsigned char* lds, int wave, const Prob& P, const Epi& E) {
;     ...
;             PG8_LDA(At, 0, 1); PG8_STAGE(PG8_SB(0, 0), b2, voffB); PG8_STAGE(PG8_SB(0, 1), b2 + hstepB, voffB); PG8_STAGE(PG8_SA(0, 0), a2, voffA);
;             PG8_WAIT_V(8); PG8_WAIT_L(0); PG8_BAR; PG8_MMA(1, 0, At, B0); PG8_MMA(1, 1, At, B1); PG8_BAR; PG8_SCHED;
;             PG8_LDB(B0, 1, 0); PG8_LDB(B1, 1, 1); PG8_SCHED; PG8_LDA(At, 1, 0); PG8_STAGE(PG8_SA(0, 1), a2 + hstepA, voffA);
;             PG8_WAIT_V(8); PG8_WAIT_L(0); PG8_BAR; PG8_MMA(0, 0, At, B0); PG8_MMA(0, 1, At, B1); PG8_BAR; PG8_SCHED;
	s_waitcnt lgkmcnt(7)
	v_mfma_i32_16x16x64_i8 v[40:43], v[104:107], v[144:147], v[40:43]
	v_mfma_i32_16x16x64_i8 v[64:67], v[120:123], v[144:147], v[64:67]
	s_waitcnt lgkmcnt(5)
	v_mfma_i32_16x16x64_i8 v[36:39], v[104:107], v[168:171], v[36:39]
	v_mfma_i32_16x16x64_i8 v[60:63], v[120:123], v[168:171], v[60:63]
	s_waitcnt lgkmcnt(3)
	v_mfma_i32_16x16x64_i8 v[32:35], v[104:107], v[176:179], v[32:35]
	v_mfma_i32_16x16x64_i8 v[56:59], v[120:123], v[176:179], v[56:59]
	s_waitcnt lgkmcnt(1)
	v_mfma_i32_16x16x64_i8 v[104:107], v[104:107], v[184:187], v[156:159]
	v_mfma_i32_16x16x64_i8 v[40:43], v[112:115], v[164:167], v[40:43]
	v_mfma_i32_16x16x64_i8 v[64:67], v[124:127], v[164:167], v[64:67]
	v_mfma_i32_16x16x64_i8 v[36:39], v[112:115], v[172:175], v[36:39]
	v_mfma_i32_16x16x64_i8 v[60:63], v[124:127], v[172:175], v[60:63]
	v_mfma_i32_16x16x64_i8 v[32:35], v[112:115], v[180:183], v[32:35]
	v_mfma_i32_16x16x64_i8 v[56:59], v[124:127], v[180:183], v[56:59]
	s_waitcnt lgkmcnt(0)
	v_mfma_i32_16x16x64_i8 v[104:107], v[112:115], v[188:191], v[104:107]
	v_mfma_i32_16x16x64_i8 v[112:115], v[120:123], v[184:187], v[148:151]
	v_mfma_i32_16x16x64_i8 v[112:115], v[124:127], v[188:191], v[112:115]
	v_mfma_i32_16x16x64_i8 v[88:91], v[128:131], v[144:147], v[88:91]
	v_mfma_i32_16x16x64_i8 v[12:15], v[136:139], v[144:147], v[12:15]
	v_mfma_i32_16x16x64_i8 v[84:87], v[128:131], v[168:171], v[84:87]
	v_mfma_i32_16x16x64_i8 v[8:11], v[136:139], v[168:171], v[8:11]
	v_mfma_i32_16x16x64_i8 v[76:79], v[128:131], v[176:179], v[76:79]
	v_mfma_i32_16x16x64_i8 v[4:7], v[136:139], v[176:179], v[4:7]
	v_mfma_i32_16x16x64_i8 v[108:111], v[128:131], v[184:187], v[108:111]
	v_mfma_i32_16x16x64_i8 v[0:3], v[136:139], v[184:187], v[0:3]
	v_mfma_i32_16x16x64_i8 v[88:91], v[132:135], v[164:167], v[88:91]
	v_mfma_i32_16x16x64_i8 v[12:15], v[140:143], v[164:167], v[12:15]
	v_mfma_i32_16x16x64_i8 v[84:87], v[132:135], v[172:175], v[84:87]
	v_mfma_i32_16x16x64_i8 v[8:11], v[140:143], v[172:175], v[8:11]
	v_mfma_i32_16x16x64_i8 v[76:79], v[132:135], v[180:183], v[76:79]
	v_mfma_i32_16x16x64_i8 v[4:7], v[140:143], v[180:183], v[4:7]
	v_mfma_i32_16x16x64_i8 v[108:111], v[132:135], v[188:191], v[108:111]
	v_mfma_i32_16x16x64_i8 v[0:3], v[140:143], v[188:191], v[0:3]
	s_barrier
	v_add_u32_e32 v132, 0x18000, v210
	v_add_u32_e32 v148, 0x1c000, v210
	ds_read_b128 v[120:123], v132
	ds_read_b128 v[124:127], v132 offset:1024
	ds_read_b128 v[128:131], v132 offset:2048
	ds_read_b128 v[132:135], v132 offset:3072
	ds_read_b128 v[136:139], v148
	ds_read_b128 v[140:143], v148 offset:1024
	ds_read_b128 v[144:147], v148 offset:2048
	ds_read_b128 v[164:167], v148 offset:3072
	ds_read_b128 v[148:151], v211 offset:32768
	ds_read_b128 v[156:159], v211 offset:33792
	ds_read_b128 v[168:171], v211 offset:34816
	ds_read_b128 v[172:175], v211 offset:35840
	ds_read_b128 v[176:179], v211 offset:36864
	ds_read_b128 v[180:183], v211 offset:37888
	ds_read_b128 v[184:187], v211 offset:38912
	ds_read_b128 v[188:191], v211 offset:39936
	s_add_u32 s6, s62, 0x2000
	s_addc_u32 s7, s63, 0
	s_mov_b32 s5, m0
	s_mov_b32 m0, s82
	s_nop 0
	global_load_lds_dwordx4 v250, s[6:7]
	s_mov_b32 m0, s5
	s_nop 0
	s_mov_b32 s5, m0
	s_mov_b32 m0, s83
	s_nop 0
	global_load_lds_dwordx4 v247, s[6:7]
	s_mov_b32 m0, s5
	s_waitcnt vmcnt(8)
	s_waitcnt lgkmcnt(0)
	s_barrier
	s_waitcnt lgkmcnt(7)
	v_mfma_i32_16x16x64_i8 v[160:163], v[120:123], v[148:151], v[160:163]
	v_mfma_i32_16x16x64_i8 v[152:155], v[128:131], v[148:151], v[152:155]
	s_waitcnt lgkmcnt(5)
	v_mfma_i32_16x16x64_i8 v[52:55], v[120:123], v[168:171], v[52:55]
	v_mfma_i32_16x16x64_i8 v[80:83], v[128:131], v[168:171], v[80:83]
	s_waitcnt lgkmcnt(3)
	v_mfma_i32_16x16x64_i8 v[48:51], v[120:123], v[176:179], v[48:51]
	v_mfma_i32_16x16x64_i8 v[72:75], v[128:131], v[176:179], v[72:75]
	s_waitcnt lgkmcnt(1)
	v_mfma_i32_16x16x64_i8 v[44:47], v[120:123], v[184:187], v[44:47]
	v_mfma_i32_16x16x64_i8 v[68:71], v[128:131], v[184:187], v[68:71]
	v_mfma_i32_16x16x64_i8 v[160:163], v[124:127], v[156:159], v[160:163]
	v_mfma_i32_16x16x64_i8 v[152:155], v[132:135], v[156:159], v[152:155]
	v_mfma_i32_16x16x64_i8 v[52:55], v[124:127], v[172:175], v[52:55]
	v_mfma_i32_16x16x64_i8 v[80:83], v[132:135], v[172:175], v[80:83]
	v_mfma_i32_16x16x64_i8 v[48:51], v[124:127], v[180:183], v[48:51]
	v_mfma_i32_16x16x64_i8 v[72:75], v[132:135], v[180:183], v[72:75]
	s_waitcnt lgkmcnt(0)
	v_mfma_i32_16x16x64_i8 v[44:47], v[124:127], v[188:191], v[44:47]
	v_mfma_i32_16x16x64_i8 v[68:71], v[132:135], v[188:191], v[68:71]
	v_mfma_i32_16x16x64_i8 v[116:119], v[136:139], v[148:151], v[116:119]
	v_mfma_i32_16x16x64_i8 v[28:31], v[144:147], v[148:151], v[28:31]
	v_mfma_i32_16x16x64_i8 v[100:103], v[136:139], v[168:171], v[100:103]
	v_mfma_i32_16x16x64_i8 v[24:27], v[144:147], v[168:171], v[24:27]
	v_mfma_i32_16x16x64_i8 v[96:99], v[136:139], v[176:179], v[96:99]
	v_mfma_i32_16x16x64_i8 v[20:23], v[144:147], v[176:179], v[20:23]
	v_mfma_i32_16x16x64_i8 v[92:95], v[136:139], v[184:187], v[92:95]
	v_mfma_i32_16x16x64_i8 v[16:19], v[144:147], v[184:187], v[16:19]
	v_mfma_i32_16x16x64_i8 v[116:119], v[140:143], v[156:159], v[116:119]
	v_mfma_i32_16x16x64_i8 v[28:31], v[164:167], v[156:159], v[28:31]
	v_mfma_i32_16x16x64_i8 v[100:103], v[140:143], v[172:175], v[100:103]
	v_mfma_i32_16x16x64_i8 v[24:27], v[164:167], v[172:175], v[24:27]
	v_mfma_i32_16x16x64_i8 v[96:99], v[140:143], v[180:183], v[96:99]
	v_mfma_i32_16x16x64_i8 v[20:23], v[164:167], v[180:183], v[20:23]
	v_mfma_i32_16x16x64_i8 v[92:95], v[140:143], v[188:191], v[92:95]
	v_mfma_i32_16x16x64_i8 v[16:19], v[164:167], v[188:191], v[16:19]
	s_barrier
; #define PG8_STAGE(bufoff, gbase, voff) do { _Pragma("unroll") for (int _i = 0; _i < 2; ++_i) glds16_s((gbase), (voff)[_i], ldsb + (unsigned)((bufoff) + _i * 8192)); } while (0)
; #define PG8_LDA(dst, b, h) do { _Pragma("unroll") for (int m = 0; m < 4; ++m) _Pragma("unroll") for (int k = 0; k < 2; ++k) dst[m][k] = *(const LAS h16x8*)(lds + PG8_SA(b, h) + aoff + m * 2048 + k * 1024); } while (0)
; #define PG8_WAIT_V(n) asm volatile("s_waitcnt vmcnt(" #n ")" ::: "memory")
; #define PG8_WAIT_L(n) asm volatile("s_waitcnt lgkmcnt(" #n ")" ::: "memory")
; template <class Prob, class Epi, bool I8 = false, bool ALIGN_EPI = true, bool SP2 = true>
; __device__ __forceinline__ void gemm_phase(LAS unsigned char* lds, int wave, const Prob& P, const Epi& E) {
;     ...
;             PG8_LDA(At, 1, 1); PG8_STAGE(PG8_SB(1, 0), b3, voffB); PG8_STAGE(PG8_SB(1, 1), b3 + hstepB, voffB); PG8_STAGE(PG8_SA(1, 0), a3, voffA);
;             PG8_WAIT_V(8); PG8_WAIT_L(0); PG8_BAR; PG8_MMA(1, 0, At, B0); PG8_MMA(1, 1, At, B1); PG8_BAR; PG8_SCHED;
;             } else {
;             PG8_LDB(B0, 0, 0); PG8_SCHED; PG8_LDA(At, 0, 0); PG8_STAGE(PG8_SA(1, 1), a1 + hstepA, voffA);
;             PG8_WAIT_L(8); PG8_BAR; PG8_WAIT_L(0); PG8_MMA(0, 0, At, B0); PG8_BAR; PG8_SCHED;
;             PG8_LDB(B1, 0, 1); PG8_STAGE(PG8_SB(0, 0), b2, voffB);
;             PG8_BAR; PG8_WAIT_L(0); PG8_MMA(0, 1, At, B1); PG8_BAR;
;             PG8_LDA(At, 0, 1); PG8_STAGE(PG8_SA(0, 0), a2, voffA);
;             PG8_BAR; PG8_WAIT_L(0); PG8_MMA(1, 0, At, B0); PG8_BAR; PG8_SCHED;
;             PG8_STAGE(PG8_SB(0, 1), b2 + hstepB, voffB);
;             PG8_WAIT_V(6); PG8_BAR; PG8_MMA(1, 1, At, B1); PG8_BAR;
;             PG8_LDB(B0, 1, 0); PG8_SCHED; PG8_LDA(At, 1, 0); PG8_STAGE(PG8_SA(0, 1), a2 + hstepA, voffA);
;             PG8_WAIT_L(8); PG8_BAR; PG8_WAIT_L(0); PG8_MMA(0, 0, At, B0); PG8_BAR; PG8_SCHED;
;             PG8_LDB(B1, 1, 1); PG8_STAGE(PG8_SB(1, 0), b3, voffB);
;             PG8_BAR; PG8_WAIT_L(0); PG8_MMA(0, 1, At, B1); PG8_BAR;
;             PG8_LDA(At, 1, 1); PG8_STAGE(PG8_SA(1, 0), a3, voffA);
;             PG8_BAR; PG8_WAIT_L(0); PG8_MMA(1, 0, At, B0); PG8_BAR; PG8_SCHED;
;             PG8_STAGE(PG8_SB(1, 1), b3 + hstepB, voffB);
;             PG8_WAIT_V(6); PG8_BAR; PG8_MMA(1, 1, At, B1); PG8_BAR;
;             }
;         }
;         if constexpr (ALIGN_EPI) { if (wr == 0) PG8_BAR; }
	ds_read_b128 v[168:171], v211 offset:49152
	ds_read_b128 v[172:175], v211 offset:50176
	ds_read_b128 v[176:179], v211 offset:51200
	ds_read_b128 v[180:183], v211 offset:52224
	ds_read_b128 v[184:187], v211 offset:53248
	ds_read_b128 v[188:191], v211 offset:54272
	ds_read_b128 v[192:195], v211 offset:55296
	ds_read_b128 v[196:199], v211 offset:56320
	s_add_u32 s6, s68, 0x80
	s_addc_u32 s7, s69, 0
	s_mov_b32 s5, m0
	s_mov_b32 m0, s2
	s_nop 0
	global_load_lds_dwordx4 v217, s[6:7]
	s_mov_b32 m0, s5
	s_nop 0
	s_mov_b32 s5, m0
	s_mov_b32 m0, s85
	s_nop 0
	global_load_lds_dwordx4 v248, s[6:7]
	s_mov_b32 m0, s5
	s_add_u32 s6, s68, 0x40080
	s_addc_u32 s7, s69, 0
	s_mov_b32 s5, m0
	s_mov_b32 m0, s88
	s_nop 0
	global_load_lds_dwordx4 v217, s[6:7]
	s_mov_b32 m0, s5
	s_nop 0
	s_mov_b32 s5, m0
	s_mov_b32 m0, s89
	s_nop 0
	global_load_lds_dwordx4 v248, s[6:7]
	s_mov_b32 m0, s5
	s_nop 0
	s_mov_b32 s5, m0
	s_mov_b32 m0, s86
	s_nop 0
	global_load_lds_dwordx4 v250, s[60:61]
	s_mov_b32 m0, s5
	s_nop 0
	s_mov_b32 s5, m0
	s_mov_b32 m0, s87
	s_nop 0
	global_load_lds_dwordx4 v247, s[60:61]
	s_mov_b32 m0, s5
	s_waitcnt vmcnt(8)
	s_waitcnt lgkmcnt(0)
	s_barrier
	s_waitcnt lgkmcnt(1)
	v_mfma_i32_16x16x64_i8 v[104:107], v[120:123], v[192:195], v[104:107]
	v_mfma_i32_16x16x64_i8 v[40:43], v[120:123], v[168:171], v[40:43]
	v_mfma_i32_16x16x64_i8 v[64:67], v[128:131], v[168:171], v[64:67]
	v_mfma_i32_16x16x64_i8 v[36:39], v[120:123], v[176:179], v[36:39]
	v_mfma_i32_16x16x64_i8 v[60:63], v[128:131], v[176:179], v[60:63]
	v_mfma_i32_16x16x64_i8 v[32:35], v[120:123], v[184:187], v[32:35]
	v_mfma_i32_16x16x64_i8 v[56:59], v[128:131], v[184:187], v[56:59]
	s_waitcnt lgkmcnt(0)
	v_mfma_i32_16x16x64_i8 v[156:159], v[124:127], v[196:199], v[104:107]
	v_mfma_i32_16x16x64_i8 v[104:107], v[128:131], v[192:195], v[112:115]
	v_mfma_i32_16x16x64_i8 v[40:43], v[124:127], v[172:175], v[40:43]
	v_mfma_i32_16x16x64_i8 v[64:67], v[132:135], v[172:175], v[64:67]
	v_mfma_i32_16x16x64_i8 v[36:39], v[124:127], v[180:183], v[36:39]
	v_mfma_i32_16x16x64_i8 v[60:63], v[132:135], v[180:183], v[60:63]
	v_mfma_i32_16x16x64_i8 v[32:35], v[124:127], v[188:191], v[32:35]
	v_mfma_i32_16x16x64_i8 v[56:59], v[132:135], v[188:191], v[56:59]
	v_mfma_i32_16x16x64_i8 v[148:151], v[132:135], v[196:199], v[104:107]
	v_mfma_i32_16x16x64_i8 v[88:91], v[136:139], v[168:171], v[88:91]
	v_mfma_i32_16x16x64_i8 v[12:15], v[144:147], v[168:171], v[12:15]
	v_mfma_i32_16x16x64_i8 v[84:87], v[136:139], v[176:179], v[84:87]
	v_mfma_i32_16x16x64_i8 v[8:11], v[144:147], v[176:179], v[8:11]
	v_mfma_i32_16x16x64_i8 v[76:79], v[136:139], v[184:187], v[76:79]
	v_mfma_i32_16x16x64_i8 v[4:7], v[144:147], v[184:187], v[4:7]
	v_mfma_i32_16x16x64_i8 v[104:107], v[136:139], v[192:195], v[108:111]
	v_mfma_i32_16x16x64_i8 v[0:3], v[144:147], v[192:195], v[0:3]
	v_mfma_i32_16x16x64_i8 v[88:91], v[140:143], v[172:175], v[88:91]
	v_mfma_i32_16x16x64_i8 v[12:15], v[164:167], v[172:175], v[12:15]
	v_mfma_i32_16x16x64_i8 v[84:87], v[140:143], v[180:183], v[84:87]
	v_mfma_i32_16x16x64_i8 v[8:11], v[164:167], v[180:183], v[8:11]
	v_mfma_i32_16x16x64_i8 v[76:79], v[140:143], v[188:191], v[76:79]
	v_mfma_i32_16x16x64_i8 v[4:7], v[164:167], v[188:191], v[4:7]
	v_mfma_i32_16x16x64_i8 v[108:111], v[140:143], v[196:199], v[104:107]
	v_mfma_i32_16x16x64_i8 v[0:3], v[164:167], v[196:199], v[0:3]
	s_barrier
	s_add_i32 s4, s4, 2
	s_add_u32 vcc_lo, vcc_lo, 0x100
	s_addc_u32 vcc_hi, vcc_hi, 0
	s_add_u32 s0, s0, 0x100
	s_addc_u32 s1, s1, 0
	s_add_u32 s44, s44, 0x100
	s_addc_u32 s45, s45, 0
	s_cmp_gt_u32 s4, 13
	s_cbranch_scc0 .LBB0_1065
	s_mov_b32 s100, 0xbfb8aa3b
	s_mov_b32 s101, 0
	s_and_b64 vcc, exec, s[46:47]
	s_cbranch_vccz .LBB0_1068
	s_barrier

; __device__ __forceinline__ int mk_lane() { int l; asm volatile("v_mbcnt_lo_u32_b32 %0, -1, 0\n\tv_mbcnt_hi_u32_b32 %0, -1, %0" : "=v"(l)); return l; }
; #define PG8_STAGE(bufoff, gbase, voff) do { _Pragma("unroll") for (int _i = 0; _i < 2; ++_i) glds16_s((gbase), (voff)[_i], ldsb + (unsigned)((bufoff) + _i * 8192)); } while (0)
; #define PG8_WAIT_V(n) asm volatile("s_waitcnt vmcnt(" #n ")" ::: "memory")
; template <class Prob, class Epi, bool I8 = false, bool ALIGN_EPI = true, bool SP2 = true>
; __device__ __forceinline__ void gemm_phase(LAS unsigned char* lds, int wave, const Prob& P, const Epi& E) {
;     const int tid_ = wave * 64 + mk_lane();
;     const int tid = tid_, wid = __builtin_amdgcn_readfirstlane(tid >> 6), lane = tid & 63, wr = wid >> 2, wc = wid & 3, fr = lane & 15, fq = lane >> 4;
;     const int K = P.K, nt = K / BK;
;     unsigned voffA[2], voffB[2];
; #pragma unroll
;     for (int i = 0; i < 2; ++i) { int R, C; stage_rc(tid * 16 + i * 8192, R, C); const int Rb = (R & ~31) + perm32(R & 31);
;         voffA[i] = P.a_rowoff(R) + (unsigned)C * 2u; voffB[i] = P.b_rowoff(Rb) + (unsigned)C * 2u; }
;     const size_t kstep = (size_t)(BK * 2);
;     const size_t hstepA = P.a_hstep(), hstepB = P.b_hstep();
;     const unsigned ldsw = (unsigned)wid * 1024u;
;     const unsigned ldsb = (unsigned)(size_t)lds + ldsw;
;     const int aoff = lds_byte(wr * 64 + fr, fq * 8), boff = lds_byte(wc * 32 + fr, fq * 8);
;     ...
;     Unit cur, nxt; int ui = 0;
;     if (!P.next(0, cur)) return;
;     Acc acc;
; #pragma unroll
;     for (int a = 0; a < 2; ++a)
; #pragma unroll
;         for (int b = 0; b < 2; ++b)
; #pragma unroll
;             for (int m = 0; m < 4; ++m)
; #pragma unroll
;                 for (int n = 0; n < 2; ++n) acc[a][b][m][n] = (f32x4){0.f, 0.f, 0.f, 0.f};
;     h16x8 At[4][2], B0[2][2], B1[2][2];
;     const char* cA = P.a_tile(cur); const char* cB = P.b_tile(cur);
;     if constexpr (SP2) {
;         PG8_STAGE(PG8_SB(0, 0), cB, voffB); PG8_STAGE(PG8_SB(0, 1), cB + hstepB, voffB); PG8_STAGE(PG8_SA(0, 0), cA, voffA); PG8_STAGE(PG8_SA(0, 1), cA + hstepA, voffA);
;         if (wr == 1) PG8_BAR;
;         PG8_WAIT_V(2); PG8_BAR;
;         PG8_STAGE(PG8_SB(1, 0), cB + kstep, voffB); PG8_STAGE(PG8_SA(1, 0), cA + kstep, voffA); PG8_STAGE(PG8_SB(1, 1), cB + hstepB + kstep, voffB);
;         PG8_WAIT_V(6); PG8_BAR;
.LBB0_1203:
	v_readlane_b32 s0, v254, 42
	v_readlane_b32 s4, v254, 43
	s_waitcnt lgkmcnt(0)
	s_barrier
	v_mbcnt_lo_u32_b32 v0, -1, 0
	v_mbcnt_hi_u32_b32 v0, -1, v0
	v_readlane_b32 s5, v254, 44
	v_add_u32_e32 v1, s0, v0
	s_and_b64 vcc, exec, s[4:5]
	v_readfirstlane_b32 s0, v1
	s_cbranch_vccz .LBB0_1223
	v_ashrrev_i32_e32 v2, 31, v1
	v_lshrrev_b32_e32 v2, 26, v2
	v_lshlrev_b32_e32 v3, 4, v1
	v_add_u32_e32 v2, v1, v2
	v_bfe_i32 v1, v1, 27, 1
	v_lshrrev_b32_e32 v1, 22, v1
	v_add_u32_e32 v1, v3, v1
	v_and_b32_e32 v1, 0xfffffc00, v1
	v_sub_u32_e32 v1, v3, v1
	v_lshrrev_b32_e32 v4, 4, v1
	v_bitop3_b32 v1, v4, v1, 32 bitop3:0x6c
	v_ashrrev_i32_e32 v5, 31, v1
	v_lshrrev_b32_e32 v5, 26, v5
	v_ashrrev_i32_e32 v2, 6, v2
	v_add_u32_e32 v5, v1, v5
	v_readlane_b32 s1, v255, 1
	v_lshlrev_b32_e32 v4, 3, v2
	v_ashrrev_i32_e32 v6, 6, v5
	v_and_b32_e32 v5, 0xc0, v5
	s_mul_i32 s1, s1, 0xb00000
	v_and_b32_e32 v4, -16, v4
	v_sub_u32_e32 v1, v1, v5
	v_mov_b32_e32 v8, 1
	s_add_u32 s1, s30, s1
	v_add_u32_e32 v4, v6, v4
	v_lshlrev_b32_e32 v2, 5, v2
	v_ashrrev_i16_sdwa v1, v8, sext(v1) dst_sel:DWORD dst_unused:UNUSED_PAD src0_sel:DWORD src1_sel:BYTE_0
	s_addc_u32 s4, s31, 0
	v_and_b32_e32 v2, 32, v2
	v_bfe_i32 v1, v1, 0, 16
	v_lshlrev_b32_e32 v5, 1, v4
	v_lshrrev_b32_e32 v7, 2, v4
	v_and_b32_e32 v6, 3, v6
	s_mov_b32 s7, 0x7fffe0
	s_add_u32 s2, s1, 0xba00000
	v_and_b32_e32 v5, 24, v5
	v_and_b32_e32 v7, 4, v7
	v_and_or_b32 v6, v4, s7, v6
	v_add_lshl_u32 v2, v2, v1, 1
	s_movk_i32 s6, 0x1600
	s_addc_u32 s19, s4, 0
	v_or3_b32 v5, v6, v7, v5
	v_mad_u64_u32 v[160:161], s[4:5], v4, s6, v[2:3]
	v_add_u32_e32 v1, 0x2000, v3
	v_mad_u32_u24 v161, v5, s6, v2
	v_ashrrev_i32_e32 v2, 31, v1
	v_lshrrev_b32_e32 v2, 22, v2
	v_add_u32_e32 v2, v1, v2
	v_ashrrev_i32_e32 v2, 10, v2
	v_mul_i32_i24_e32 v3, 0x400, v2
	v_sub_u32_e32 v1, v1, v3
	v_lshrrev_b32_e32 v3, 4, v1
	v_bitop3_b32 v1, v3, v1, 32 bitop3:0x6c
	v_ashrrev_i32_e32 v4, 31, v1
	v_lshrrev_b32_e32 v4, 26, v4
	v_add_u32_e32 v4, v1, v4
	v_ashrrev_i32_e32 v5, 6, v4
	v_and_b32_e32 v4, 0xc0, v4
	v_lshlrev_b32_e32 v3, 3, v2
	v_sub_u32_e32 v1, v1, v4
	v_and_b32_e32 v3, -16, v3
	v_lshlrev_b32_e32 v2, 5, v2
	v_ashrrev_i16_sdwa v1, v8, sext(v1) dst_sel:DWORD dst_unused:UNUSED_PAD src0_sel:DWORD src1_sel:BYTE_0
	v_add_u32_e32 v3, v5, v3
	v_and_b32_e32 v2, 32, v2
	v_bfe_i32 v1, v1, 0, 16
	v_lshlrev_b32_e32 v4, 1, v3
	v_lshrrev_b32_e32 v6, 2, v3
	v_and_b32_e32 v5, 3, v5
	v_add_lshl_u32 v2, v2, v1, 1
	v_and_b32_e32 v4, 24, v4
	v_and_b32_e32 v6, 4, v6
	v_and_or_b32 v5, v3, s7, v5
	v_mad_u64_u32 v[162:163], s[4:5], v3, s6, v[2:3]
	v_or3_b32 v4, v5, v6, v4
	s_ashr_i32 s4, s0, 6
	v_mad_u32_u24 v163, v4, s6, v2
	s_lshl_b32 s5, s4, 10
	v_readlane_b32 s6, v252, 31
	s_ashr_i32 s1, s0, 8
	s_add_i32 s40, s5, 0
	s_mul_i32 s5, s6, 0x160000
	s_add_u32 s14, s2, s5
	s_mul_hi_i32 s5, s6, 0x160000
	s_addc_u32 s15, s19, s5
	s_add_i32 s41, s40, 0x10000
	s_mov_b32 s5, m0
	s_mov_b32 m0, s41
	s_nop 0
	global_load_lds_dwordx4 v161, s[14:15]
	s_mov_b32 m0, s5
	s_add_i32 s62, s40, 0x12000
	s_mov_b32 s5, m0
	s_mov_b32 m0, s62
	s_nop 0
	global_load_lds_dwordx4 v163, s[14:15]
	s_mov_b32 m0, s5
	s_add_u32 s6, s14, 0xb0000
	s_addc_u32 s7, s15, 0
	s_add_i32 s63, s40, 0x14000
	s_mov_b32 s5, m0
	s_mov_b32 m0, s63
	s_nop 0
	global_load_lds_dwordx4 v161, s[6:7]
	s_mov_b32 m0, s5
	s_add_i32 s64, s40, 0x16000
	s_mov_b32 s5, m0
	s_mov_b32 m0, s64
	s_nop 0
	global_load_lds_dwordx4 v163, s[6:7]
	s_mov_b32 m0, s5
	v_readlane_b32 s6, v252, 42
	v_readlane_b32 s7, v252, 43
	s_mov_b32 s5, m0
	s_mov_b32 m0, s40
	s_nop 0
	global_load_lds_dwordx4 v160, s[6:7]
	s_mov_b32 m0, s5
	s_add_i32 s68, s40, 0x2000
	s_mov_b32 s5, m0
	s_mov_b32 m0, s68
	s_nop 0
	global_load_lds_dwordx4 v162, s[6:7]
	s_mov_b32 m0, s5
	v_readlane_b32 s6, v252, 40
	s_add_i32 s69, s40, 0x4000
	v_readlane_b32 s7, v252, 41
	s_mov_b32 s5, m0
	s_mov_b32 m0, s69
	s_nop 0
	global_load_lds_dwordx4 v160, s[6:7]
	s_mov_b32 m0, s5
	s_add_i32 s76, s40, 0x6000
	s_mov_b32 s5, m0
	s_mov_b32 m0, s76
	s_nop 0
	global_load_lds_dwordx4 v162, s[6:7]
	s_mov_b32 m0, s5
	s_cmp_eq_u32 s1, 1
	s_cselect_b64 s[16:17], -1, 0
	s_cmp_lg_u32 s1, 1
	s_cbranch_scc1 .LBB0_1206
	s_barrier
	s_setprio 1

; #define PG8_STAGE(bufoff, gbase, voff) do { _Pragma("unroll") for (int _i = 0; _i < 2; ++_i) glds16_s((gbase), (voff)[_i], ldsb + (unsigned)((bufoff) + _i * 8192)); } while (0)
; #define PG8_LDA(dst, b, h) do { _Pragma("unroll") for (int m = 0; m < 4; ++m) _Pragma("unroll") for (int k = 0; k < 2; ++k) dst[m][k] = *(const LAS h16x8*)(lds + PG8_SA(b, h) + aoff + m * 2048 + k * 1024); } while (0)
; #define PG8_LDB(dst, b, h) do { _Pragma("unroll") for (int n = 0; n < 2; ++n) _Pragma("unroll") for (int k = 0; k < 2; ++k) dst[n][k] = *(const LAS h16x8*)(lds + PG8_SB(b, h) + boff + n * 2048 + k * 1024); } while (0)
; #define PG8_MMA(ai, bj, At, Bt) do { __builtin_amdgcn_s_setprio(1); _Pragma("unroll") for (int m = 0; m < 4; ++m) _Pragma("unroll") for (int n = 0; n < 2; ++n) _Pragma("unroll") for (int k = 0; k < 2; ++k) \
;         acc[ai][bj][m][n] = mma_step<I8>(Bt[n][k], At[m][k], acc[ai][bj][m][n]); __builtin_amdgcn_s_setprio(0); } while (0)
; #define PG8_WAIT_V(n) asm volatile("s_waitcnt vmcnt(" #n ")" ::: "memory")
; #define PG8_WAIT_L(n) asm volatile("s_waitcnt lgkmcnt(" #n ")" ::: "memory")
; #define PG8_BAR __builtin_amdgcn_s_barrier()
; #define PG8_SCHED __builtin_amdgcn_sched_barrier(0)
; template <class Prob, class Epi, bool I8 = false, bool ALIGN_EPI = true, bool SP2 = true>
; __device__ __forceinline__ void gemm_phase(LAS unsigned char* lds, int wave, const Prob& P, const Epi& E) {
;     ...
;             PG8_LDB(B0, 0, 0); PG8_LDB(B1, 0, 1); PG8_SCHED; PG8_LDA(At, 0, 0); PG8_STAGE(PG8_SA(1, 1), a1 + hstepA, voffA);
;             PG8_WAIT_V(8); PG8_WAIT_L(0); PG8_BAR; PG8_MMA(0, 0, At, B0); PG8_MMA(0, 1, At, B1); PG8_BAR; PG8_SCHED;
;             PG8_LDA(At, 0, 1); PG8_STAGE(PG8_SB(0, 0), b2, voffB); PG8_STAGE(PG8_SB(0, 1), b2 + hstepB, voffB); PG8_STAGE(PG8_SA(0, 0), a2, voffA);
;             PG8_WAIT_V(8); PG8_WAIT_L(0); PG8_BAR; PG8_MMA(1, 0, At, B0); PG8_MMA(1, 1, At, B1); PG8_BAR; PG8_SCHED;
.Lpeel_1216:
	v_add_u32_e32 v140, 0x10000, v179
	v_add_u32_e32 v156, 0x14000, v179
	ds_read_b128 v[100:103], v140
	ds_read_b128 v[108:111], v140 offset:1024
	ds_read_b128 v[136:139], v140 offset:2048
	ds_read_b128 v[140:143], v140 offset:3072
	ds_read_b128 v[144:147], v156
	ds_read_b128 v[148:151], v156 offset:1024
	ds_read_b128 v[152:155], v156 offset:2048
	ds_read_b128 v[156:159], v156 offset:3072
	s_cmp_eq_u32 s4, 40
	s_cselect_b32 s60, s38, s74
	s_cselect_b32 s61, s39, s75
	s_cselect_b32 s56, s50, s0
	s_cselect_b32 s57, s51, s1
	s_add_u32 s44, s60, 0x80
	s_addc_u32 s45, s61, 0
	ds_read_b128 v[164:167], v185
	ds_read_b128 v[168:171], v185 offset:1024
	ds_read_b128 v[172:175], v185 offset:2048
	ds_read_b128 v[180:183], v185 offset:3072
	ds_read_b128 v[186:189], v185 offset:4096
	ds_read_b128 v[190:193], v185 offset:5120
	ds_read_b128 v[194:197], v185 offset:6144
	ds_read_b128 v[198:201], v185 offset:7168
	s_mov_b32 s5, m0
	s_mov_b32 m0, s86
	s_nop 0
	global_load_lds_dwordx4 v160, s[14:15]
	s_mov_b32 m0, s5
	s_nop 0
	s_mov_b32 s5, m0
	s_mov_b32 m0, s87
	s_nop 0
	global_load_lds_dwordx4 v162, s[14:15]
	s_mov_b32 m0, s5
	s_waitcnt vmcnt(8)
	s_waitcnt lgkmcnt(0)
	s_barrier
	s_waitcnt lgkmcnt(7)
	v_mfma_i32_16x16x64_i8 v[132:135], v[100:103], v[164:167], 0
	v_mfma_i32_16x16x64_i8 v[128:131], v[136:139], v[164:167], 0
	s_waitcnt lgkmcnt(5)
	v_mfma_i32_16x16x64_i8 v[124:127], v[100:103], v[172:175], 0
	v_mfma_i32_16x16x64_i8 v[120:123], v[136:139], v[172:175], 0
	s_waitcnt lgkmcnt(3)
	v_mfma_i32_16x16x64_i8 v[116:119], v[100:103], v[186:189], 0
	v_mfma_i32_16x16x64_i8 v[112:115], v[136:139], v[186:189], 0
	s_waitcnt lgkmcnt(1)
	v_mfma_i32_16x16x64_i8 v[104:107], v[100:103], v[194:197], 0
	v_mfma_i32_16x16x64_i8 v[96:99], v[136:139], v[194:197], 0
	v_mfma_i32_16x16x64_i8 v[132:135], v[108:111], v[168:171], v[132:135]
	v_mfma_i32_16x16x64_i8 v[128:131], v[140:143], v[168:171], v[128:131]
	v_mfma_i32_16x16x64_i8 v[124:127], v[108:111], v[180:183], v[124:127]
	v_mfma_i32_16x16x64_i8 v[120:123], v[140:143], v[180:183], v[120:123]
	v_mfma_i32_16x16x64_i8 v[116:119], v[108:111], v[190:193], v[116:119]
	v_mfma_i32_16x16x64_i8 v[112:115], v[140:143], v[190:193], v[112:115]
	s_waitcnt lgkmcnt(0)
	v_mfma_i32_16x16x64_i8 v[104:107], v[108:111], v[198:201], v[104:107]
	v_mfma_i32_16x16x64_i8 v[96:99], v[140:143], v[198:201], v[96:99]
	v_mfma_i32_16x16x64_i8 v[60:63], v[144:147], v[164:167], 0
	v_mfma_i32_16x16x64_i8 v[56:59], v[152:155], v[164:167], 0
	v_mfma_i32_16x16x64_i8 v[52:55], v[144:147], v[172:175], 0
	v_mfma_i32_16x16x64_i8 v[48:51], v[152:155], v[172:175], 0
	v_mfma_i32_16x16x64_i8 v[44:47], v[144:147], v[186:189], 0
	v_mfma_i32_16x16x64_i8 v[40:43], v[152:155], v[186:189], 0
	v_mfma_i32_16x16x64_i8 v[36:39], v[144:147], v[194:197], 0
	v_mfma_i32_16x16x64_i8 v[32:35], v[152:155], v[194:197], 0
	v_mfma_i32_16x16x64_i8 v[60:63], v[148:151], v[168:171], v[60:63]
	v_mfma_i32_16x16x64_i8 v[56:59], v[156:159], v[168:171], v[56:59]
	v_mfma_i32_16x16x64_i8 v[52:55], v[148:151], v[180:183], v[52:55]
	v_mfma_i32_16x16x64_i8 v[48:51], v[156:159], v[180:183], v[48:51]
	v_mfma_i32_16x16x64_i8 v[44:47], v[148:151], v[190:193], v[44:47]
	v_mfma_i32_16x16x64_i8 v[40:43], v[156:159], v[190:193], v[40:43]
	v_mfma_i32_16x16x64_i8 v[36:39], v[148:151], v[198:201], v[36:39]
	v_mfma_i32_16x16x64_i8 v[32:35], v[156:159], v[198:201], v[32:35]
	s_barrier
	ds_read_b128 v[164:167], v185 offset:16384
	ds_read_b128 v[168:171], v185 offset:17408
	ds_read_b128 v[172:175], v185 offset:18432
	ds_read_b128 v[180:183], v185 offset:19456
	ds_read_b128 v[186:189], v185 offset:20480
	ds_read_b128 v[190:193], v185 offset:21504
	ds_read_b128 v[194:197], v185 offset:22528
	ds_read_b128 v[198:201], v185 offset:23552
	s_mov_b32 s5, m0
	s_mov_b32 m0, s41
	s_nop 0
	global_load_lds_dwordx4 v161, s[56:57]
	s_mov_b32 m0, s5
	s_add_u32 s6, s56, 0xb0000
	s_mov_b32 s5, m0
	s_mov_b32 m0, s62
	s_nop 0
	global_load_lds_dwordx4 v163, s[56:57]
	s_mov_b32 m0, s5
	s_addc_u32 s7, s57, 0
	s_mov_b32 s5, m0
	s_mov_b32 m0, s63
	s_nop 0
	global_load_lds_dwordx4 v161, s[6:7]
	s_mov_b32 m0, s5
	s_nop 0
	s_mov_b32 s5, m0
	s_mov_b32 m0, s64
	s_nop 0
	global_load_lds_dwordx4 v163, s[6:7]
	s_mov_b32 m0, s5
	s_nop 0
	s_mov_b32 s5, m0
	s_mov_b32 m0, s40
	s_nop 0
	global_load_lds_dwordx4 v160, s[60:61]
	s_mov_b32 m0, s5
	s_nop 0
	s_mov_b32 s5, m0
	s_mov_b32 m0, s68
	s_nop 0
	global_load_lds_dwordx4 v162, s[60:61]
	s_mov_b32 m0, s5
	s_waitcnt vmcnt(8)
	s_waitcnt lgkmcnt(0)
	s_barrier
	s_waitcnt lgkmcnt(7)
	v_mfma_i32_16x16x64_i8 v[92:95], v[100:103], v[164:167], 0
	v_mfma_i32_16x16x64_i8 v[88:91], v[136:139], v[164:167], 0
	s_waitcnt lgkmcnt(5)
	v_mfma_i32_16x16x64_i8 v[84:87], v[100:103], v[172:175], 0
	v_mfma_i32_16x16x64_i8 v[80:83], v[136:139], v[172:175], 0
	s_waitcnt lgkmcnt(3)
	v_mfma_i32_16x16x64_i8 v[76:79], v[100:103], v[186:189], 0
	v_mfma_i32_16x16x64_i8 v[72:75], v[136:139], v[186:189], 0
	s_waitcnt lgkmcnt(1)
	v_mfma_i32_16x16x64_i8 v[68:71], v[100:103], v[194:197], 0
	v_mfma_i32_16x16x64_i8 v[64:67], v[136:139], v[194:197], 0
	v_mfma_i32_16x16x64_i8 v[92:95], v[108:111], v[168:171], v[92:95]
	v_mfma_i32_16x16x64_i8 v[88:91], v[140:143], v[168:171], v[88:91]
	v_mfma_i32_16x16x64_i8 v[84:87], v[108:111], v[180:183], v[84:87]
	v_mfma_i32_16x16x64_i8 v[80:83], v[140:143], v[180:183], v[80:83]
	v_mfma_i32_16x16x64_i8 v[76:79], v[108:111], v[190:193], v[76:79]
	v_mfma_i32_16x16x64_i8 v[72:75], v[140:143], v[190:193], v[72:75]
	s_waitcnt lgkmcnt(0)
	v_mfma_i32_16x16x64_i8 v[68:71], v[108:111], v[198:201], v[68:71]
	v_mfma_i32_16x16x64_i8 v[64:67], v[140:143], v[198:201], v[64:67]
	v_mfma_i32_16x16x64_i8 v[28:31], v[144:147], v[164:167], 0
	v_mfma_i32_16x16x64_i8 v[24:27], v[152:155], v[164:167], 0
	v_mfma_i32_16x16x64_i8 v[20:23], v[144:147], v[172:175], 0
	v_mfma_i32_16x16x64_i8 v[16:19], v[152:155], v[172:175], 0
	v_mfma_i32_16x16x64_i8 v[12:15], v[144:147], v[186:189], 0
	v_mfma_i32_16x16x64_i8 v[8:11], v[152:155], v[186:189], 0
	v_mfma_i32_16x16x64_i8 v[4:7], v[144:147], v[194:197], 0
	v_mfma_i32_16x16x64_i8 v[0:3], v[152:155], v[194:197], 0
	v_mfma_i32_16x16x64_i8 v[28:31], v[148:151], v[168:171], v[28:31]
	v_mfma_i32_16x16x64_i8 v[24:27], v[156:159], v[168:171], v[24:27]
	v_mfma_i32_16x16x64_i8 v[20:23], v[148:151], v[180:183], v[20:23]
	v_mfma_i32_16x16x64_i8 v[16:19], v[156:159], v[180:183], v[16:19]
	v_mfma_i32_16x16x64_i8 v[12:15], v[148:151], v[190:193], v[12:15]
	v_mfma_i32_16x16x64_i8 v[8:11], v[156:159], v[190:193], v[8:11]
	v_mfma_i32_16x16x64_i8 v[4:7], v[148:151], v[198:201], v[4:7]
	v_mfma_i32_16x16x64_i8 v[0:3], v[156:159], v[198:201], v[0:3]
	s_barrier
; #define PG8_STAGE(bufoff, gbase, voff) do { _Pragma("unroll") for (int _i = 0; _i < 2; ++_i) glds16_s((gbase), (voff)[_i], ldsb + (unsigned)((bufoff) + _i * 8192)); } while (0)
; #define PG8_LDA(dst, b, h) do { _Pragma("unroll") for (int m = 0; m < 4; ++m) _Pragma("unroll") for (int k = 0; k < 2; ++k) dst[m][k] = *(const LAS h16x8*)(lds + PG8_SA(b, h) + aoff + m * 2048 + k * 1024); } while (0)
; #define PG8_LDB(dst, b, h) do { _Pragma("unroll") for (int n = 0; n < 2; ++n) _Pragma("unroll") for (int k = 0; k < 2; ++k) dst[n][k] = *(const LAS h16x8*)(lds + PG8_SB(b, h) + boff + n * 2048 + k * 1024); } while (0)
; #define PG8_MMA(ai, bj, At, Bt) do { __builtin_amdgcn_s_setprio(1); _Pragma("unroll") for (int m = 0; m < 4; ++m) _Pragma("unroll") for (int n = 0; n < 2; ++n) _Pragma("unroll") for (int k = 0; k < 2; ++k) \
;         acc[ai][bj][m][n] = mma_step<I8>(Bt[n][k], At[m][k], acc[ai][bj][m][n]); __builtin_amdgcn_s_setprio(0); } while (0)
; #define PG8_WAIT_V(n) asm volatile("s_waitcnt vmcnt(" #n ")" ::: "memory")
; #define PG8_WAIT_L(n) asm volatile("s_waitcnt lgkmcnt(" #n ")" ::: "memory")
; #define PG8_BAR __builtin_amdgcn_s_barrier()
; #define PG8_SCHED __builtin_amdgcn_sched_barrier(0)
; template <class Prob, class Epi, bool I8 = false, bool ALIGN_EPI = true, bool SP2 = true>
; __device__ __forceinline__ void gemm_phase(LAS unsigned char* lds, int wave, const Prob& P, const Epi& E) {
;     ...
;             PG8_LDB(B0, 1, 0); PG8_LDB(B1, 1, 1); PG8_SCHED; PG8_LDA(At, 1, 0); PG8_STAGE(PG8_SA(0, 1), a2 + hstepA, voffA);
;             PG8_WAIT_V(8); PG8_WAIT_L(0); PG8_BAR; PG8_MMA(0, 0, At, B0); PG8_MMA(0, 1, At, B1); PG8_BAR; PG8_SCHED;
;             PG8_LDA(At, 1, 1); PG8_STAGE(PG8_SB(1, 0), b3, voffB); PG8_STAGE(PG8_SB(1, 1), b3 + hstepB, voffB); PG8_STAGE(PG8_SA(1, 0), a3, voffA);
;             PG8_WAIT_V(8); PG8_WAIT_L(0); PG8_BAR; PG8_MMA(1, 0, At, B0); PG8_MMA(1, 1, At, B1); PG8_BAR; PG8_SCHED;
	v_add_u32_e32 v140, 0x18000, v179
	v_add_u32_e32 v156, 0x1c000, v179
	ds_read_b128 v[100:103], v140
	ds_read_b128 v[108:111], v140 offset:1024
	ds_read_b128 v[136:139], v140 offset:2048
	ds_read_b128 v[140:143], v140 offset:3072
	ds_read_b128 v[144:147], v156
	ds_read_b128 v[148:151], v156 offset:1024
	ds_read_b128 v[152:155], v156 offset:2048
	ds_read_b128 v[156:159], v156 offset:3072
	ds_read_b128 v[164:167], v185 offset:32768
	ds_read_b128 v[168:171], v185 offset:33792
	ds_read_b128 v[172:175], v185 offset:34816
	ds_read_b128 v[180:183], v185 offset:35840
	ds_read_b128 v[186:189], v185 offset:36864
	ds_read_b128 v[190:193], v185 offset:37888
	ds_read_b128 v[194:197], v185 offset:38912
	ds_read_b128 v[198:201], v185 offset:39936
	s_add_u32 s6, s60, 0xb0000
	s_addc_u32 s7, s61, 0
	s_mov_b32 s5, m0
	s_mov_b32 m0, s69
	s_nop 0
	global_load_lds_dwordx4 v160, s[6:7]
	s_mov_b32 m0, s5
	s_nop 0
	s_mov_b32 s5, m0
	s_mov_b32 m0, s76
	s_nop 0
	global_load_lds_dwordx4 v162, s[6:7]
	s_mov_b32 m0, s5
	s_waitcnt vmcnt(8)
	s_waitcnt lgkmcnt(0)
	s_barrier
	s_waitcnt lgkmcnt(7)
	v_mfma_i32_16x16x64_i8 v[132:135], v[100:103], v[164:167], v[132:135]
	v_mfma_i32_16x16x64_i8 v[128:131], v[136:139], v[164:167], v[128:131]
	s_waitcnt lgkmcnt(5)
	v_mfma_i32_16x16x64_i8 v[124:127], v[100:103], v[172:175], v[124:127]
	v_mfma_i32_16x16x64_i8 v[120:123], v[136:139], v[172:175], v[120:123]
	s_waitcnt lgkmcnt(3)
	v_mfma_i32_16x16x64_i8 v[116:119], v[100:103], v[186:189], v[116:119]
	v_mfma_i32_16x16x64_i8 v[112:115], v[136:139], v[186:189], v[112:115]
	s_waitcnt lgkmcnt(1)
	v_mfma_i32_16x16x64_i8 v[104:107], v[100:103], v[194:197], v[104:107]
	v_mfma_i32_16x16x64_i8 v[96:99], v[136:139], v[194:197], v[96:99]
	v_mfma_i32_16x16x64_i8 v[132:135], v[108:111], v[168:171], v[132:135]
	v_mfma_i32_16x16x64_i8 v[128:131], v[140:143], v[168:171], v[128:131]
	v_mfma_i32_16x16x64_i8 v[124:127], v[108:111], v[180:183], v[124:127]
	v_mfma_i32_16x16x64_i8 v[120:123], v[140:143], v[180:183], v[120:123]
	v_mfma_i32_16x16x64_i8 v[116:119], v[108:111], v[190:193], v[116:119]
	v_mfma_i32_16x16x64_i8 v[112:115], v[140:143], v[190:193], v[112:115]
	s_waitcnt lgkmcnt(0)
	v_mfma_i32_16x16x64_i8 v[104:107], v[108:111], v[198:201], v[104:107]
	v_mfma_i32_16x16x64_i8 v[96:99], v[140:143], v[198:201], v[96:99]
	v_mfma_i32_16x16x64_i8 v[60:63], v[144:147], v[164:167], v[60:63]
	v_mfma_i32_16x16x64_i8 v[56:59], v[152:155], v[164:167], v[56:59]
	v_mfma_i32_16x16x64_i8 v[52:55], v[144:147], v[172:175], v[52:55]
	v_mfma_i32_16x16x64_i8 v[48:51], v[152:155], v[172:175], v[48:51]
	v_mfma_i32_16x16x64_i8 v[44:47], v[144:147], v[186:189], v[44:47]
	v_mfma_i32_16x16x64_i8 v[40:43], v[152:155], v[186:189], v[40:43]
	v_mfma_i32_16x16x64_i8 v[36:39], v[144:147], v[194:197], v[36:39]
	v_mfma_i32_16x16x64_i8 v[32:35], v[152:155], v[194:197], v[32:35]
	v_mfma_i32_16x16x64_i8 v[60:63], v[148:151], v[168:171], v[60:63]
	v_mfma_i32_16x16x64_i8 v[56:59], v[156:159], v[168:171], v[56:59]
	v_mfma_i32_16x16x64_i8 v[52:55], v[148:151], v[180:183], v[52:55]
	v_mfma_i32_16x16x64_i8 v[48:51], v[156:159], v[180:183], v[48:51]
	v_mfma_i32_16x16x64_i8 v[44:47], v[148:151], v[190:193], v[44:47]
	v_mfma_i32_16x16x64_i8 v[40:43], v[156:159], v[190:193], v[40:43]
	v_mfma_i32_16x16x64_i8 v[36:39], v[148:151], v[198:201], v[36:39]
	v_mfma_i32_16x16x64_i8 v[32:35], v[156:159], v[198:201], v[32:35]
	s_barrier
	ds_read_b128 v[164:167], v185 offset:49152
	ds_read_b128 v[168:171], v185 offset:50176
	ds_read_b128 v[172:175], v185 offset:51200
	ds_read_b128 v[180:183], v185 offset:52224
	ds_read_b128 v[186:189], v185 offset:53248
	ds_read_b128 v[190:193], v185 offset:54272
	ds_read_b128 v[194:197], v185 offset:55296
	ds_read_b128 v[198:201], v185 offset:56320
	s_add_u32 s6, s56, 0x80
	s_addc_u32 s7, s57, 0
	s_mov_b32 s5, m0
	s_mov_b32 m0, s80
	s_nop 0
	global_load_lds_dwordx4 v161, s[6:7]
	s_mov_b32 m0, s5
	s_nop 0
	s_mov_b32 s5, m0
	s_mov_b32 m0, s81
	s_nop 0
	global_load_lds_dwordx4 v163, s[6:7]
	s_mov_b32 m0, s5
	s_add_u32 s6, s56, 0xb0080
	s_addc_u32 s7, s57, 0
	s_mov_b32 s5, m0
	s_mov_b32 m0, s84
	s_nop 0
	global_load_lds_dwordx4 v161, s[6:7]
	s_mov_b32 m0, s5
	s_nop 0
	s_mov_b32 s5, m0
	s_mov_b32 m0, s85
	s_nop 0
	global_load_lds_dwordx4 v163, s[6:7]
	s_mov_b32 m0, s5
	s_nop 0
	s_mov_b32 s5, m0
	s_mov_b32 m0, s82
	s_nop 0
	global_load_lds_dwordx4 v160, s[44:45]
	s_mov_b32 m0, s5
	s_nop 0
	s_mov_b32 s5, m0
	s_mov_b32 m0, s83
	s_nop 0
	global_load_lds_dwordx4 v162, s[44:45]
	s_mov_b32 m0, s5
	s_waitcnt vmcnt(8)
	s_waitcnt lgkmcnt(0)
	s_barrier
	s_waitcnt lgkmcnt(7)
	v_mfma_i32_16x16x64_i8 v[92:95], v[100:103], v[164:167], v[92:95]
	v_mfma_i32_16x16x64_i8 v[88:91], v[136:139], v[164:167], v[88:91]
	s_waitcnt lgkmcnt(5)
	v_mfma_i32_16x16x64_i8 v[84:87], v[100:103], v[172:175], v[84:87]
	v_mfma_i32_16x16x64_i8 v[80:83], v[136:139], v[172:175], v[80:83]
	s_waitcnt lgkmcnt(3)
	v_mfma_i32_16x16x64_i8 v[76:79], v[100:103], v[186:189], v[76:79]
	v_mfma_i32_16x16x64_i8 v[72:75], v[136:139], v[186:189], v[72:75]
	s_waitcnt lgkmcnt(1)
	v_mfma_i32_16x16x64_i8 v[68:71], v[100:103], v[194:197], v[68:71]
	v_mfma_i32_16x16x64_i8 v[64:67], v[136:139], v[194:197], v[64:67]
	v_mfma_i32_16x16x64_i8 v[92:95], v[108:111], v[168:171], v[92:95]
	v_mfma_i32_16x16x64_i8 v[88:91], v[140:143], v[168:171], v[88:91]
	v_mfma_i32_16x16x64_i8 v[84:87], v[108:111], v[180:183], v[84:87]
	v_mfma_i32_16x16x64_i8 v[80:83], v[140:143], v[180:183], v[80:83]
	v_mfma_i32_16x16x64_i8 v[76:79], v[108:111], v[190:193], v[76:79]
	v_mfma_i32_16x16x64_i8 v[72:75], v[140:143], v[190:193], v[72:75]
	s_waitcnt lgkmcnt(0)
	v_mfma_i32_16x16x64_i8 v[68:71], v[108:111], v[198:201], v[68:71]
	v_mfma_i32_16x16x64_i8 v[64:67], v[140:143], v[198:201], v[64:67]
	v_mfma_i32_16x16x64_i8 v[28:31], v[144:147], v[164:167], v[28:31]
	v_mfma_i32_16x16x64_i8 v[24:27], v[152:155], v[164:167], v[24:27]
	v_mfma_i32_16x16x64_i8 v[20:23], v[144:147], v[172:175], v[20:23]
	v_mfma_i32_16x16x64_i8 v[16:19], v[152:155], v[172:175], v[16:19]
	v_mfma_i32_16x16x64_i8 v[12:15], v[144:147], v[186:189], v[12:15]
	v_mfma_i32_16x16x64_i8 v[8:11], v[152:155], v[186:189], v[8:11]
	v_mfma_i32_16x16x64_i8 v[4:7], v[144:147], v[194:197], v[4:7]
	v_mfma_i32_16x16x64_i8 v[0:3], v[152:155], v[194:197], v[0:3]
	v_mfma_i32_16x16x64_i8 v[28:31], v[148:151], v[168:171], v[28:31]
	v_mfma_i32_16x16x64_i8 v[24:27], v[156:159], v[168:171], v[24:27]
	v_mfma_i32_16x16x64_i8 v[20:23], v[148:151], v[180:183], v[20:23]
	v_mfma_i32_16x16x64_i8 v[16:19], v[156:159], v[180:183], v[16:19]
	v_mfma_i32_16x16x64_i8 v[12:15], v[148:151], v[190:193], v[12:15]
	v_mfma_i32_16x16x64_i8 v[8:11], v[156:159], v[190:193], v[8:11]
	v_mfma_i32_16x16x64_i8 v[4:7], v[148:151], v[198:201], v[4:7]
	v_mfma_i32_16x16x64_i8 v[0:3], v[156:159], v[198:201], v[0:3]
	s_barrier
	s_add_i32 s4, s4, 2
	s_add_u32 s74, s74, 0x100
	s_addc_u32 s75, s75, 0
	s_add_u32 s0, s0, 0x100
	s_addc_u32 s1, s1, 0
	s_add_u32 s14, s14, 0x100
	s_addc_u32 s15, s15, 0
	s_cmp_gt_u32 s4, 41
; #define PG8_STAGE(bufoff, gbase, voff) do { _Pragma("unroll") for (int _i = 0; _i < 2; ++_i) glds16_s((gbase), (voff)[_i], ldsb + (unsigned)((bufoff) + _i * 8192)); } while (0)
; #define PG8_LDA(dst, b, h) do { _Pragma("unroll") for (int m = 0; m < 4; ++m) _Pragma("unroll") for (int k = 0; k < 2; ++k) dst[m][k] = *(const LAS h16x8*)(lds + PG8_SA(b, h) + aoff + m * 2048 + k * 1024); } while (0)
; #define PG8_LDB(dst, b, h) do { _Pragma("unroll") for (int n = 0; n < 2; ++n) _Pragma("unroll") for (int k = 0; k < 2; ++k) dst[n][k] = *(const LAS h16x8*)(lds + PG8_SB(b, h) + boff + n * 2048 + k * 1024); } while (0)
; #define PG8_MMA(ai, bj, At, Bt) do { __builtin_amdgcn_s_setprio(1); _Pragma("unroll") for (int m = 0; m < 4; ++m) _Pragma("unroll") for (int n = 0; n < 2; ++n) _Pragma("unroll") for (int k = 0; k < 2; ++k) \
;         acc[ai][bj][m][n] = mma_step<I8>(Bt[n][k], At[m][k], acc[ai][bj][m][n]); __builtin_amdgcn_s_setprio(0); } while (0)
; #define PG8_WAIT_V(n) asm volatile("s_waitcnt vmcnt(" #n ")" ::: "memory")
; #define PG8_WAIT_L(n) asm volatile("s_waitcnt lgkmcnt(" #n ")" ::: "memory")
; #define PG8_BAR __builtin_amdgcn_s_barrier()
; #define PG8_SCHED __builtin_amdgcn_sched_barrier(0)
; template <class Prob, class Epi, bool I8 = false, bool ALIGN_EPI = true, bool SP2 = true>
; __device__ __forceinline__ void gemm_phase(LAS unsigned char* lds, int wave, const Prob& P, const Epi& E) {
;     ...
;             PG8_LDB(B0, 0, 0); PG8_LDB(B1, 0, 1); PG8_SCHED; PG8_LDA(At, 0, 0); PG8_STAGE(PG8_SA(1, 1), a1 + hstepA, voffA);
;             PG8_WAIT_V(8); PG8_WAIT_L(0); PG8_BAR; PG8_MMA(0, 0, At, B0); PG8_MMA(0, 1, At, B1); PG8_BAR; PG8_SCHED;
;             PG8_LDA(At, 0, 1); PG8_STAGE(PG8_SB(0, 0), b2, voffB); PG8_STAGE(PG8_SB(0, 1), b2 + hstepB, voffB); PG8_STAGE(PG8_SA(0, 0), a2, voffA);
;             PG8_WAIT_V(8); PG8_WAIT_L(0); PG8_BAR; PG8_MMA(1, 0, At, B0); PG8_MMA(1, 1, At, B1); PG8_BAR; PG8_SCHED;
.LBB0_1216:
	v_add_u32_e32 v140, 0x10000, v179
	v_add_u32_e32 v156, 0x14000, v179
	ds_read_b128 v[100:103], v140
	ds_read_b128 v[108:111], v140 offset:1024
	ds_read_b128 v[136:139], v140 offset:2048
	ds_read_b128 v[140:143], v140 offset:3072
	ds_read_b128 v[144:147], v156
	ds_read_b128 v[148:151], v156 offset:1024
	ds_read_b128 v[152:155], v156 offset:2048
	ds_read_b128 v[156:159], v156 offset:3072
	s_cmp_eq_u32 s4, 40
	s_cselect_b32 s60, s38, s74
	s_cselect_b32 s61, s39, s75
	s_cselect_b32 s56, s50, s0
	s_cselect_b32 s57, s51, s1
	s_add_u32 s44, s60, 0x80
	s_addc_u32 s45, s61, 0
	ds_read_b128 v[164:167], v185
	ds_read_b128 v[168:171], v185 offset:1024
	ds_read_b128 v[172:175], v185 offset:2048
	ds_read_b128 v[180:183], v185 offset:3072
	ds_read_b128 v[186:189], v185 offset:4096
	ds_read_b128 v[190:193], v185 offset:5120
	ds_read_b128 v[194:197], v185 offset:6144
	ds_read_b128 v[198:201], v185 offset:7168
	s_mov_b32 s5, m0
	s_mov_b32 m0, s86
	s_nop 0
	global_load_lds_dwordx4 v160, s[14:15]
	s_mov_b32 m0, s5
	s_nop 0
	s_mov_b32 s5, m0
	s_mov_b32 m0, s87
	s_nop 0
	global_load_lds_dwordx4 v162, s[14:15]
	s_mov_b32 m0, s5
	s_waitcnt vmcnt(8)
	s_waitcnt lgkmcnt(0)
	s_barrier
	s_waitcnt lgkmcnt(7)
	v_mfma_i32_16x16x64_i8 v[132:135], v[100:103], v[164:167], v[132:135]
	v_mfma_i32_16x16x64_i8 v[128:131], v[136:139], v[164:167], v[128:131]
	s_waitcnt lgkmcnt(5)
	v_mfma_i32_16x16x64_i8 v[124:127], v[100:103], v[172:175], v[124:127]
	v_mfma_i32_16x16x64_i8 v[120:123], v[136:139], v[172:175], v[120:123]
	s_waitcnt lgkmcnt(3)
	v_mfma_i32_16x16x64_i8 v[116:119], v[100:103], v[186:189], v[116:119]
	v_mfma_i32_16x16x64_i8 v[112:115], v[136:139], v[186:189], v[112:115]
	s_waitcnt lgkmcnt(1)
	v_mfma_i32_16x16x64_i8 v[104:107], v[100:103], v[194:197], v[104:107]
	v_mfma_i32_16x16x64_i8 v[96:99], v[136:139], v[194:197], v[96:99]
	v_mfma_i32_16x16x64_i8 v[132:135], v[108:111], v[168:171], v[132:135]
	v_mfma_i32_16x16x64_i8 v[128:131], v[140:143], v[168:171], v[128:131]
	v_mfma_i32_16x16x64_i8 v[124:127], v[108:111], v[180:183], v[124:127]
	v_mfma_i32_16x16x64_i8 v[120:123], v[140:143], v[180:183], v[120:123]
	v_mfma_i32_16x16x64_i8 v[116:119], v[108:111], v[190:193], v[116:119]
	v_mfma_i32_16x16x64_i8 v[112:115], v[140:143], v[190:193], v[112:115]
	s_waitcnt lgkmcnt(0)
	v_mfma_i32_16x16x64_i8 v[104:107], v[108:111], v[198:201], v[104:107]
	v_mfma_i32_16x16x64_i8 v[96:99], v[140:143], v[198:201], v[96:99]
	v_mfma_i32_16x16x64_i8 v[60:63], v[144:147], v[164:167], v[60:63]
	v_mfma_i32_16x16x64_i8 v[56:59], v[152:155], v[164:167], v[56:59]
	v_mfma_i32_16x16x64_i8 v[52:55], v[144:147], v[172:175], v[52:55]
	v_mfma_i32_16x16x64_i8 v[48:51], v[152:155], v[172:175], v[48:51]
	v_mfma_i32_16x16x64_i8 v[44:47], v[144:147], v[186:189], v[44:47]
	v_mfma_i32_16x16x64_i8 v[40:43], v[152:155], v[186:189], v[40:43]
	v_mfma_i32_16x16x64_i8 v[36:39], v[144:147], v[194:197], v[36:39]
	v_mfma_i32_16x16x64_i8 v[32:35], v[152:155], v[194:197], v[32:35]
	v_mfma_i32_16x16x64_i8 v[60:63], v[148:151], v[168:171], v[60:63]
	v_mfma_i32_16x16x64_i8 v[56:59], v[156:159], v[168:171], v[56:59]
	v_mfma_i32_16x16x64_i8 v[52:55], v[148:151], v[180:183], v[52:55]
	v_mfma_i32_16x16x64_i8 v[48:51], v[156:159], v[180:183], v[48:51]
	v_mfma_i32_16x16x64_i8 v[44:47], v[148:151], v[190:193], v[44:47]
	v_mfma_i32_16x16x64_i8 v[40:43], v[156:159], v[190:193], v[40:43]
	v_mfma_i32_16x16x64_i8 v[36:39], v[148:151], v[198:201], v[36:39]
	v_mfma_i32_16x16x64_i8 v[32:35], v[156:159], v[198:201], v[32:35]
	s_barrier
	ds_read_b128 v[164:167], v185 offset:16384
	ds_read_b128 v[168:171], v185 offset:17408
	ds_read_b128 v[172:175], v185 offset:18432
	ds_read_b128 v[180:183], v185 offset:19456
	ds_read_b128 v[186:189], v185 offset:20480
	ds_read_b128 v[190:193], v185 offset:21504
	ds_read_b128 v[194:197], v185 offset:22528
	ds_read_b128 v[198:201], v185 offset:23552
	s_mov_b32 s5, m0
	s_mov_b32 m0, s41
	s_nop 0
	global_load_lds_dwordx4 v161, s[56:57]
	s_mov_b32 m0, s5
	s_add_u32 s6, s56, 0xb0000
	s_mov_b32 s5, m0
	s_mov_b32 m0, s62
	s_nop 0
	global_load_lds_dwordx4 v163, s[56:57]
	s_mov_b32 m0, s5
	s_addc_u32 s7, s57, 0
	s_mov_b32 s5, m0
	s_mov_b32 m0, s63
	s_nop 0
	global_load_lds_dwordx4 v161, s[6:7]
	s_mov_b32 m0, s5
	s_nop 0
	s_mov_b32 s5, m0
	s_mov_b32 m0, s64
	s_nop 0
	global_load_lds_dwordx4 v163, s[6:7]
	s_mov_b32 m0, s5
	s_nop 0
	s_mov_b32 s5, m0
	s_mov_b32 m0, s40
	s_nop 0
	global_load_lds_dwordx4 v160, s[60:61]
	s_mov_b32 m0, s5
	s_nop 0
	s_mov_b32 s5, m0
	s_mov_b32 m0, s68
	s_nop 0
	global_load_lds_dwordx4 v162, s[60:61]
	s_mov_b32 m0, s5
	s_waitcnt vmcnt(8)
	s_waitcnt lgkmcnt(0)
	s_barrier
; #define PG8_STAGE(bufoff, gbase, voff) do { _Pragma("unroll") for (int _i = 0; _i < 2; ++_i) glds16_s((gbase), (voff)[_i], ldsb + (unsigned)((bufoff) + _i * 8192)); } while (0)
; #define PG8_LDA(dst, b, h) do { _Pragma("unroll") for (int m = 0; m < 4; ++m) _Pragma("unroll") for (int k = 0; k < 2; ++k) dst[m][k] = *(const LAS h16x8*)(lds + PG8_SA(b, h) + aoff + m * 2048 + k * 1024); } while (0)
; #define PG8_LDB(dst, b, h) do { _Pragma("unroll") for (int n = 0; n < 2; ++n) _Pragma("unroll") for (int k = 0; k < 2; ++k) dst[n][k] = *(const LAS h16x8*)(lds + PG8_SB(b, h) + boff + n * 2048 + k * 1024); } while (0)
; #define PG8_MMA(ai, bj, At, Bt) do { __builtin_amdgcn_s_setprio(1); _Pragma("unroll") for (int m = 0; m < 4; ++m) _Pragma("unroll") for (int n = 0; n < 2; ++n) _Pragma("unroll") for (int k = 0; k < 2; ++k) \
;         acc[ai][bj][m][n] = mma_step<I8>(Bt[n][k], At[m][k], acc[ai][bj][m][n]); __builtin_amdgcn_s_setprio(0); } while (0)
; #define PG8_WAIT_V(n) asm volatile("s_waitcnt vmcnt(" #n ")" ::: "memory")
; #define PG8_WAIT_L(n) asm volatile("s_waitcnt lgkmcnt(" #n ")" ::: "memory")
; #define PG8_BAR __builtin_amdgcn_s_barrier()
; #define PG8_SCHED __builtin_amdgcn_sched_barrier(0)
; template <class Prob, class Epi, bool I8 = false, bool ALIGN_EPI = true, bool SP2 = true>
; __device__ __forceinline__ void gemm_phase(LAS unsigned char* lds, int wave, const Prob& P, const Epi& E) {
;     ...
;             PG8_LDA(At, 0, 1); PG8_STAGE(PG8_SB(0, 0), b2, voffB); PG8_STAGE(PG8_SB(0, 1), b2 + hstepB, voffB); PG8_STAGE(PG8_SA(0, 0), a2, voffA);
;             PG8_WAIT_V(8); PG8_WAIT_L(0); PG8_BAR; PG8_MMA(1, 0, At, B0); PG8_MMA(1, 1, At, B1); PG8_BAR; PG8_SCHED;
;             PG8_LDB(B0, 1, 0); PG8_LDB(B1, 1, 1); PG8_SCHED; PG8_LDA(At, 1, 0); PG8_STAGE(PG8_SA(0, 1), a2 + hstepA, voffA);
;             PG8_WAIT_V(8); PG8_WAIT_L(0); PG8_BAR; PG8_MMA(0, 0, At, B0); PG8_MMA(0, 1, At, B1); PG8_BAR; PG8_SCHED;
	s_waitcnt lgkmcnt(7)
	v_mfma_i32_16x16x64_i8 v[92:95], v[100:103], v[164:167], v[92:95]
	v_mfma_i32_16x16x64_i8 v[88:91], v[136:139], v[164:167], v[88:91]
	s_waitcnt lgkmcnt(5)
	v_mfma_i32_16x16x64_i8 v[84:87], v[100:103], v[172:175], v[84:87]
	v_mfma_i32_16x16x64_i8 v[80:83], v[136:139], v[172:175], v[80:83]
	s_waitcnt lgkmcnt(3)
	v_mfma_i32_16x16x64_i8 v[76:79], v[100:103], v[186:189], v[76:79]
	v_mfma_i32_16x16x64_i8 v[72:75], v[136:139], v[186:189], v[72:75]
	s_waitcnt lgkmcnt(1)
	v_mfma_i32_16x16x64_i8 v[68:71], v[100:103], v[194:197], v[68:71]
	v_mfma_i32_16x16x64_i8 v[64:67], v[136:139], v[194:197], v[64:67]
	v_mfma_i32_16x16x64_i8 v[92:95], v[108:111], v[168:171], v[92:95]
	v_mfma_i32_16x16x64_i8 v[88:91], v[140:143], v[168:171], v[88:91]
	v_mfma_i32_16x16x64_i8 v[84:87], v[108:111], v[180:183], v[84:87]
	v_mfma_i32_16x16x64_i8 v[80:83], v[140:143], v[180:183], v[80:83]
	v_mfma_i32_16x16x64_i8 v[76:79], v[108:111], v[190:193], v[76:79]
	v_mfma_i32_16x16x64_i8 v[72:75], v[140:143], v[190:193], v[72:75]
	s_waitcnt lgkmcnt(0)
	v_mfma_i32_16x16x64_i8 v[68:71], v[108:111], v[198:201], v[68:71]
	v_mfma_i32_16x16x64_i8 v[64:67], v[140:143], v[198:201], v[64:67]
	v_mfma_i32_16x16x64_i8 v[28:31], v[144:147], v[164:167], v[28:31]
	v_mfma_i32_16x16x64_i8 v[24:27], v[152:155], v[164:167], v[24:27]
	v_mfma_i32_16x16x64_i8 v[20:23], v[144:147], v[172:175], v[20:23]
	v_mfma_i32_16x16x64_i8 v[16:19], v[152:155], v[172:175], v[16:19]
	v_mfma_i32_16x16x64_i8 v[12:15], v[144:147], v[186:189], v[12:15]
	v_mfma_i32_16x16x64_i8 v[8:11], v[152:155], v[186:189], v[8:11]
	v_mfma_i32_16x16x64_i8 v[4:7], v[144:147], v[194:197], v[4:7]
	v_mfma_i32_16x16x64_i8 v[0:3], v[152:155], v[194:197], v[0:3]
	v_mfma_i32_16x16x64_i8 v[28:31], v[148:151], v[168:171], v[28:31]
	v_mfma_i32_16x16x64_i8 v[24:27], v[156:159], v[168:171], v[24:27]
	v_mfma_i32_16x16x64_i8 v[20:23], v[148:151], v[180:183], v[20:23]
	v_mfma_i32_16x16x64_i8 v[16:19], v[156:159], v[180:183], v[16:19]
	v_mfma_i32_16x16x64_i8 v[12:15], v[148:151], v[190:193], v[12:15]
	v_mfma_i32_16x16x64_i8 v[8:11], v[156:159], v[190:193], v[8:11]
	v_mfma_i32_16x16x64_i8 v[4:7], v[148:151], v[198:201], v[4:7]
	v_mfma_i32_16x16x64_i8 v[0:3], v[156:159], v[198:201], v[0:3]
	s_barrier
	v_add_u32_e32 v140, 0x18000, v179
	v_add_u32_e32 v156, 0x1c000, v179
	ds_read_b128 v[100:103], v140
	ds_read_b128 v[108:111], v140 offset:1024
	ds_read_b128 v[136:139], v140 offset:2048
	ds_read_b128 v[140:143], v140 offset:3072
	ds_read_b128 v[144:147], v156
	ds_read_b128 v[148:151], v156 offset:1024
	ds_read_b128 v[152:155], v156 offset:2048
	ds_read_b128 v[156:159], v156 offset:3072
	ds_read_b128 v[164:167], v185 offset:32768
	ds_read_b128 v[168:171], v185 offset:33792
	ds_read_b128 v[172:175], v185 offset:34816
	ds_read_b128 v[180:183], v185 offset:35840
	ds_read_b128 v[186:189], v185 offset:36864
	ds_read_b128 v[190:193], v185 offset:37888
	ds_read_b128 v[194:197], v185 offset:38912
	ds_read_b128 v[198:201], v185 offset:39936
	s_add_u32 s6, s60, 0xb0000
	s_addc_u32 s7, s61, 0
	s_mov_b32 s5, m0
	s_mov_b32 m0, s69
	s_nop 0
	global_load_lds_dwordx4 v160, s[6:7]
	s_mov_b32 m0, s5
	s_nop 0
	s_mov_b32 s5, m0
	s_mov_b32 m0, s76
	s_nop 0
	global_load_lds_dwordx4 v162, s[6:7]
	s_mov_b32 m0, s5
	s_waitcnt vmcnt(8)
	s_waitcnt lgkmcnt(0)
	s_barrier
	s_waitcnt lgkmcnt(7)
	v_mfma_i32_16x16x64_i8 v[132:135], v[100:103], v[164:167], v[132:135]
	v_mfma_i32_16x16x64_i8 v[128:131], v[136:139], v[164:167], v[128:131]
	s_waitcnt lgkmcnt(5)
	v_mfma_i32_16x16x64_i8 v[124:127], v[100:103], v[172:175], v[124:127]
	v_mfma_i32_16x16x64_i8 v[120:123], v[136:139], v[172:175], v[120:123]
	s_waitcnt lgkmcnt(3)
	v_mfma_i32_16x16x64_i8 v[116:119], v[100:103], v[186:189], v[116:119]
	v_mfma_i32_16x16x64_i8 v[112:115], v[136:139], v[186:189], v[112:115]
	s_waitcnt lgkmcnt(1)
	v_mfma_i32_16x16x64_i8 v[104:107], v[100:103], v[194:197], v[104:107]
	v_mfma_i32_16x16x64_i8 v[96:99], v[136:139], v[194:197], v[96:99]
	v_mfma_i32_16x16x64_i8 v[132:135], v[108:111], v[168:171], v[132:135]
	v_mfma_i32_16x16x64_i8 v[128:131], v[140:143], v[168:171], v[128:131]
	v_mfma_i32_16x16x64_i8 v[124:127], v[108:111], v[180:183], v[124:127]
	v_mfma_i32_16x16x64_i8 v[120:123], v[140:143], v[180:183], v[120:123]
	v_mfma_i32_16x16x64_i8 v[116:119], v[108:111], v[190:193], v[116:119]
	v_mfma_i32_16x16x64_i8 v[112:115], v[140:143], v[190:193], v[112:115]
	s_waitcnt lgkmcnt(0)
	v_mfma_i32_16x16x64_i8 v[104:107], v[108:111], v[198:201], v[104:107]
	v_mfma_i32_16x16x64_i8 v[96:99], v[140:143], v[198:201], v[96:99]
	v_mfma_i32_16x16x64_i8 v[60:63], v[144:147], v[164:167], v[60:63]
	v_mfma_i32_16x16x64_i8 v[56:59], v[152:155], v[164:167], v[56:59]
	v_mfma_i32_16x16x64_i8 v[52:55], v[144:147], v[172:175], v[52:55]
	v_mfma_i32_16x16x64_i8 v[48:51], v[152:155], v[172:175], v[48:51]
	v_mfma_i32_16x16x64_i8 v[44:47], v[144:147], v[186:189], v[44:47]
	v_mfma_i32_16x16x64_i8 v[40:43], v[152:155], v[186:189], v[40:43]
	v_mfma_i32_16x16x64_i8 v[36:39], v[144:147], v[194:197], v[36:39]
	v_mfma_i32_16x16x64_i8 v[32:35], v[152:155], v[194:197], v[32:35]
	v_mfma_i32_16x16x64_i8 v[60:63], v[148:151], v[168:171], v[60:63]
	v_mfma_i32_16x16x64_i8 v[56:59], v[156:159], v[168:171], v[56:59]
	v_mfma_i32_16x16x64_i8 v[52:55], v[148:151], v[180:183], v[52:55]
	v_mfma_i32_16x16x64_i8 v[48:51], v[156:159], v[180:183], v[48:51]
	v_mfma_i32_16x16x64_i8 v[44:47], v[148:151], v[190:193], v[44:47]
	v_mfma_i32_16x16x64_i8 v[40:43], v[156:159], v[190:193], v[40:43]
	v_mfma_i32_16x16x64_i8 v[36:39], v[148:151], v[198:201], v[36:39]
	v_mfma_i32_16x16x64_i8 v[32:35], v[156:159], v[198:201], v[32:35]
	s_barrier
; #define PG8_STAGE(bufoff, gbase, voff) do { _Pragma("unroll") for (int _i = 0; _i < 2; ++_i) glds16_s((gbase), (voff)[_i], ldsb + (unsigned)((bufoff) + _i * 8192)); } while (0)
; #define PG8_LDA(dst, b, h) do { _Pragma("unroll") for (int m = 0; m < 4; ++m) _Pragma("unroll") for (int k = 0; k < 2; ++k) dst[m][k] = *(const LAS h16x8*)(lds + PG8_SA(b, h) + aoff + m * 2048 + k * 1024); } while (0)
; #define PG8_WAIT_V(n) asm volatile("s_waitcnt vmcnt(" #n ")" ::: "memory")
; #define PG8_WAIT_L(n) asm volatile("s_waitcnt lgkmcnt(" #n ")" ::: "memory")
; template <class Prob, class Epi, bool I8 = false, bool ALIGN_EPI = true, bool SP2 = true>
; __device__ __forceinline__ void gemm_phase(LAS unsigned char* lds, int wave, const Prob& P, const Epi& E) {
;     ...
;             PG8_LDA(At, 1, 1); PG8_STAGE(PG8_SB(1, 0), b3, voffB); PG8_STAGE(PG8_SB(1, 1), b3 + hstepB, voffB); PG8_STAGE(PG8_SA(1, 0), a3, voffA);
;             PG8_WAIT_V(8); PG8_WAIT_L(0); PG8_BAR; PG8_MMA(1, 0, At, B0); PG8_MMA(1, 1, At, B1); PG8_BAR; PG8_SCHED;
;             } else {
;             PG8_LDB(B0, 0, 0); PG8_SCHED; PG8_LDA(At, 0, 0); PG8_STAGE(PG8_SA(1, 1), a1 + hstepA, voffA);
;             PG8_WAIT_L(8); PG8_BAR; PG8_WAIT_L(0); PG8_MMA(0, 0, At, B0); PG8_BAR; PG8_SCHED;
;             PG8_LDB(B1, 0, 1); PG8_STAGE(PG8_SB(0, 0), b2, voffB);
;             PG8_BAR; PG8_WAIT_L(0); PG8_MMA(0, 1, At, B1); PG8_BAR;
;             PG8_LDA(At, 0, 1); PG8_STAGE(PG8_SA(0, 0), a2, voffA);
;             PG8_BAR; PG8_WAIT_L(0); PG8_MMA(1, 0, At, B0); PG8_BAR; PG8_SCHED;
;             PG8_STAGE(PG8_SB(0, 1), b2 + hstepB, voffB);
;             PG8_WAIT_V(6); PG8_BAR; PG8_MMA(1, 1, At, B1); PG8_BAR;
;             PG8_LDB(B0, 1, 0); PG8_SCHED; PG8_LDA(At, 1, 0); PG8_STAGE(PG8_SA(0, 1), a2 + hstepA, voffA);
;             PG8_WAIT_L(8); PG8_BAR; PG8_WAIT_L(0); PG8_MMA(0, 0, At, B0); PG8_BAR; PG8_SCHED;
;             PG8_LDB(B1, 1, 1); PG8_STAGE(PG8_SB(1, 0), b3, voffB);
;             PG8_BAR; PG8_WAIT_L(0); PG8_MMA(0, 1, At, B1); PG8_BAR;
;             PG8_LDA(At, 1, 1); PG8_STAGE(PG8_SA(1, 0), a3, voffA);
;             PG8_BAR; PG8_WAIT_L(0); PG8_MMA(1, 0, At, B0); PG8_BAR; PG8_SCHED;
;             PG8_STAGE(PG8_SB(1, 1), b3 + hstepB, voffB);
;             PG8_WAIT_V(6); PG8_BAR; PG8_MMA(1, 1, At, B1); PG8_BAR;
;             }
;         }
;         if constexpr (ALIGN_EPI) { if (wr == 0) PG8_BAR; }
	ds_read_b128 v[164:167], v185 offset:49152
	ds_read_b128 v[168:171], v185 offset:50176
	ds_read_b128 v[172:175], v185 offset:51200
	ds_read_b128 v[180:183], v185 offset:52224
	ds_read_b128 v[186:189], v185 offset:53248
	ds_read_b128 v[190:193], v185 offset:54272
	ds_read_b128 v[194:197], v185 offset:55296
	ds_read_b128 v[198:201], v185 offset:56320
	s_add_u32 s6, s56, 0x80
	s_addc_u32 s7, s57, 0
	s_mov_b32 s5, m0
	s_mov_b32 m0, s80
	s_nop 0
	global_load_lds_dwordx4 v161, s[6:7]
	s_mov_b32 m0, s5
	s_nop 0
	s_mov_b32 s5, m0
	s_mov_b32 m0, s81
	s_nop 0
	global_load_lds_dwordx4 v163, s[6:7]
	s_mov_b32 m0, s5
	s_add_u32 s6, s56, 0xb0080
	s_addc_u32 s7, s57, 0
	s_mov_b32 s5, m0
	s_mov_b32 m0, s84
	s_nop 0
	global_load_lds_dwordx4 v161, s[6:7]
	s_mov_b32 m0, s5
	s_nop 0
	s_mov_b32 s5, m0
	s_mov_b32 m0, s85
	s_nop 0
	global_load_lds_dwordx4 v163, s[6:7]
	s_mov_b32 m0, s5
	s_nop 0
	s_mov_b32 s5, m0
	s_mov_b32 m0, s82
	s_nop 0
	global_load_lds_dwordx4 v160, s[44:45]
	s_mov_b32 m0, s5
	s_nop 0
	s_mov_b32 s5, m0
	s_mov_b32 m0, s83
	s_nop 0
	global_load_lds_dwordx4 v162, s[44:45]
	s_mov_b32 m0, s5
	s_waitcnt vmcnt(8)
	s_waitcnt lgkmcnt(0)
	s_barrier
	s_waitcnt lgkmcnt(7)
	v_mfma_i32_16x16x64_i8 v[92:95], v[100:103], v[164:167], v[92:95]
	v_mfma_i32_16x16x64_i8 v[88:91], v[136:139], v[164:167], v[88:91]
	s_waitcnt lgkmcnt(5)
	v_mfma_i32_16x16x64_i8 v[84:87], v[100:103], v[172:175], v[84:87]
	v_mfma_i32_16x16x64_i8 v[80:83], v[136:139], v[172:175], v[80:83]
	s_waitcnt lgkmcnt(3)
	v_mfma_i32_16x16x64_i8 v[76:79], v[100:103], v[186:189], v[76:79]
	v_mfma_i32_16x16x64_i8 v[72:75], v[136:139], v[186:189], v[72:75]
	s_waitcnt lgkmcnt(1)
	v_mfma_i32_16x16x64_i8 v[68:71], v[100:103], v[194:197], v[68:71]
	v_mfma_i32_16x16x64_i8 v[64:67], v[136:139], v[194:197], v[64:67]
	v_mfma_i32_16x16x64_i8 v[92:95], v[108:111], v[168:171], v[92:95]
	v_mfma_i32_16x16x64_i8 v[88:91], v[140:143], v[168:171], v[88:91]
	v_mfma_i32_16x16x64_i8 v[84:87], v[108:111], v[180:183], v[84:87]
	v_mfma_i32_16x16x64_i8 v[80:83], v[140:143], v[180:183], v[80:83]
	v_mfma_i32_16x16x64_i8 v[76:79], v[108:111], v[190:193], v[76:79]
	v_mfma_i32_16x16x64_i8 v[72:75], v[140:143], v[190:193], v[72:75]
	s_waitcnt lgkmcnt(0)
	v_mfma_i32_16x16x64_i8 v[68:71], v[108:111], v[198:201], v[68:71]
	v_mfma_i32_16x16x64_i8 v[64:67], v[140:143], v[198:201], v[64:67]
	v_mfma_i32_16x16x64_i8 v[28:31], v[144:147], v[164:167], v[28:31]
	v_mfma_i32_16x16x64_i8 v[24:27], v[152:155], v[164:167], v[24:27]
	v_mfma_i32_16x16x64_i8 v[20:23], v[144:147], v[172:175], v[20:23]
	v_mfma_i32_16x16x64_i8 v[16:19], v[152:155], v[172:175], v[16:19]
	v_mfma_i32_16x16x64_i8 v[12:15], v[144:147], v[186:189], v[12:15]
	v_mfma_i32_16x16x64_i8 v[8:11], v[152:155], v[186:189], v[8:11]
	v_mfma_i32_16x16x64_i8 v[4:7], v[144:147], v[194:197], v[4:7]
	v_mfma_i32_16x16x64_i8 v[0:3], v[152:155], v[194:197], v[0:3]
	v_mfma_i32_16x16x64_i8 v[28:31], v[148:151], v[168:171], v[28:31]
	v_mfma_i32_16x16x64_i8 v[24:27], v[156:159], v[168:171], v[24:27]
	v_mfma_i32_16x16x64_i8 v[20:23], v[148:151], v[180:183], v[20:23]
	v_mfma_i32_16x16x64_i8 v[16:19], v[156:159], v[180:183], v[16:19]
	v_mfma_i32_16x16x64_i8 v[12:15], v[148:151], v[190:193], v[12:15]
	v_mfma_i32_16x16x64_i8 v[8:11], v[156:159], v[190:193], v[8:11]
	v_mfma_i32_16x16x64_i8 v[4:7], v[148:151], v[198:201], v[4:7]
	v_mfma_i32_16x16x64_i8 v[0:3], v[156:159], v[198:201], v[0:3]
	s_barrier
	s_add_i32 s4, s4, 2
	s_add_u32 s74, s74, 0x100
	s_addc_u32 s75, s75, 0
	s_add_u32 s0, s0, 0x100
	s_addc_u32 s1, s1, 0
	s_add_u32 s14, s14, 0x100
	s_addc_u32 s15, s15, 0
	s_cmp_gt_u32 s4, 41
	s_cbranch_scc0 .LBB0_1216
	s_and_b64 vcc, exec, s[48:49]
	s_cbranch_vccz .LBB0_1219
	s_barrier
